# x1 recompute: P6 no longer stores the f32 residual x1 (latent rows); P11 recomputes x1 = x + gate0*pn0*rmsnorm(y0) from x and y0 then adds the MLA branch; V buffer relocated into d_out, P10 output y1
# speedup vs baseline: 1.0136x; 1.0086x over previous
; __device__ __forceinline__ float bf_lo(unsigned w) { return __uint_as_float(w << 16); }
; __device__ __forceinline__ float bf_hi(unsigned w) { return __uint_as_float(w & 0xffff0000u); }
; __global__ void __launch_bounds__(NWAVES * 64, 2) mk_fwd(Args args) {
;     ...
;             for (int q = 0; q < 3; ++q) { const int row = row0 + q; const bool lat = row < ML; const int r = lat ? row / SEQ : 8;
;                 float sy = 0.f;
; #pragma unroll
;                 for (int j = 0; j < 8; ++j) { const float a = bf_lo(yw[q][j].x), b = bf_hi(yw[q][j].x), c2 = bf_lo(yw[q][j].y), d = bf_hi(yw[q][j].y); sy += (a * a + b * b) + (c2 * c2 + d * d); }
;                 const float rsy = __builtin_amdgcn_rsqf(wave_sum(sy) * (1.f / DM) + EPS);
;                 const float* m0 = mod + (size_t)r * 6144;
; #pragma unroll
;                 for (int j = 0; j < 8; ++j) { const int col = 4 * F.lane + 256 * j; const f32x4 gt = *(const f32x4*)(m0 + 2 * DM + col), pn = *(const f32x4*)(post_norm + col);
;                     const f32x4 y4 = (f32x4){bf_lo(yw[q][j].x), bf_hi(yw[q][j].x), bf_lo(yw[q][j].y), bf_hi(yw[q][j].y)};
;                     v[q][j] = v[q][j] + gt * (y4 * rsy * pn);
;                     if (lat) *(f32x4*)(args.out + (size_t)row * DM + col) = v[q][j]; }
;                 const float rstd = __builtin_amdgcn_rsqf(sumsq8(v[q]) * (1.f / DM) + EPS);
.Lp6_np0:
	s_waitcnt vmcnt(16)
	v_lshlrev_b32_e32 v216, 16, v32
	v_and_b32_e32 v217, 0xffff0000, v32
	v_lshlrev_b32_e32 v218, 16, v33
	v_and_b32_e32 v219, 0xffff0000, v33
	v_mul_f32_e32 v222, v216, v216
	v_mul_f32_e32 v223, v217, v217
	v_fmac_f32_e32 v222, v218, v218
	v_fmac_f32_e32 v223, v219, v219
	v_lshlrev_b32_e32 v216, 16, v34
	v_and_b32_e32 v217, 0xffff0000, v34
	v_lshlrev_b32_e32 v218, 16, v35
	v_and_b32_e32 v219, 0xffff0000, v35
	v_fmac_f32_e32 v222, v216, v216
	v_fmac_f32_e32 v223, v217, v217
	v_fmac_f32_e32 v222, v218, v218
	v_fmac_f32_e32 v223, v219, v219
	v_lshlrev_b32_e32 v216, 16, v36
	v_and_b32_e32 v217, 0xffff0000, v36
	v_lshlrev_b32_e32 v218, 16, v37
	v_and_b32_e32 v219, 0xffff0000, v37
	v_fmac_f32_e32 v222, v216, v216
	v_fmac_f32_e32 v223, v217, v217
	v_fmac_f32_e32 v222, v218, v218
	v_fmac_f32_e32 v223, v219, v219
	v_lshlrev_b32_e32 v216, 16, v38
	v_and_b32_e32 v217, 0xffff0000, v38
	v_lshlrev_b32_e32 v218, 16, v39
	v_and_b32_e32 v219, 0xffff0000, v39
	v_fmac_f32_e32 v222, v216, v216
	v_fmac_f32_e32 v223, v217, v217
	v_fmac_f32_e32 v222, v218, v218
	v_fmac_f32_e32 v223, v219, v219
	v_lshlrev_b32_e32 v216, 16, v40
	v_and_b32_e32 v217, 0xffff0000, v40
	v_lshlrev_b32_e32 v218, 16, v41
	v_and_b32_e32 v219, 0xffff0000, v41
	v_fmac_f32_e32 v222, v216, v216
	v_fmac_f32_e32 v223, v217, v217
	v_fmac_f32_e32 v222, v218, v218
	v_fmac_f32_e32 v223, v219, v219
	v_lshlrev_b32_e32 v216, 16, v42
	v_and_b32_e32 v217, 0xffff0000, v42
	v_lshlrev_b32_e32 v218, 16, v43
	v_and_b32_e32 v219, 0xffff0000, v43
	v_fmac_f32_e32 v222, v216, v216
	v_fmac_f32_e32 v223, v217, v217
	v_fmac_f32_e32 v222, v218, v218
	v_fmac_f32_e32 v223, v219, v219
	v_lshlrev_b32_e32 v216, 16, v44
	v_and_b32_e32 v217, 0xffff0000, v44
	v_lshlrev_b32_e32 v218, 16, v45
	v_and_b32_e32 v219, 0xffff0000, v45
	v_fmac_f32_e32 v222, v216, v216
	v_fmac_f32_e32 v223, v217, v217
	v_fmac_f32_e32 v222, v218, v218
	v_fmac_f32_e32 v223, v219, v219
	v_lshlrev_b32_e32 v216, 16, v46
	v_and_b32_e32 v217, 0xffff0000, v46
	v_lshlrev_b32_e32 v218, 16, v47
	v_and_b32_e32 v219, 0xffff0000, v47
	v_fmac_f32_e32 v222, v216, v216
	v_fmac_f32_e32 v223, v217, v217
	v_fmac_f32_e32 v222, v218, v218
	v_fmac_f32_e32 v223, v219, v219
	v_add_f32_e32 v222, v222, v223
	s_nop 1
	v_add_f32_dpp v224, v222, v222 quad_perm:[1,0,3,2] row_mask:0xf bank_mask:0xf
	s_nop 1
	v_add_f32_dpp v224, v224, v224 quad_perm:[2,3,0,1] row_mask:0xf bank_mask:0xf
	s_nop 1
	v_add_f32_dpp v224, v224, v224 row_half_mirror row_mask:0xf bank_mask:0xf
	s_nop 1
	v_add_f32_dpp v224, v224, v224 row_mirror row_mask:0xf bank_mask:0xf
	s_nop 1
	v_readlane_b32 s40, v224, 0
	v_readlane_b32 s41, v224, 16
	v_readlane_b32 s42, v224, 32
	v_readlane_b32 s43, v224, 48
	s_nop 1
	v_mov_b32_e32 v225, s40
	v_add_f32_e32 v225, s41, v225
	v_add_f32_e32 v225, s42, v225
	v_add_f32_e32 v225, s43, v225
	v_fmamk_f32 v225, v225, 0x3a000000, v195
	v_rsq_f32_e32 v225, v225
	s_nop 0
	v_lshlrev_b32_e32 v216, 16, v32
	v_and_b32_e32 v217, 0xffff0000, v32
	v_lshlrev_b32_e32 v218, 16, v33
	v_and_b32_e32 v219, 0xffff0000, v33
	v_mul_f32_e32 v216, v225, v216
	v_mul_f32_e32 v217, v225, v217
	v_mul_f32_e32 v218, v225, v218
	v_mul_f32_e32 v219, v225, v219
	v_fmac_f32_e32 v0, v96, v216
	v_fmac_f32_e32 v1, v97, v217
	v_fmac_f32_e32 v2, v98, v218
	v_fmac_f32_e32 v3, v99, v219
	v_lshlrev_b32_e32 v216, 16, v34
	v_and_b32_e32 v217, 0xffff0000, v34
	v_lshlrev_b32_e32 v218, 16, v35
	v_and_b32_e32 v219, 0xffff0000, v35
	v_mul_f32_e32 v216, v225, v216
	v_mul_f32_e32 v217, v225, v217
	v_mul_f32_e32 v218, v225, v218
	v_mul_f32_e32 v219, v225, v219
	v_fmac_f32_e32 v4, v100, v216
	v_fmac_f32_e32 v5, v101, v217
	v_fmac_f32_e32 v6, v102, v218
	v_fmac_f32_e32 v7, v103, v219
	v_lshlrev_b32_e32 v216, 16, v36
	v_and_b32_e32 v217, 0xffff0000, v36
	v_lshlrev_b32_e32 v218, 16, v37
	v_and_b32_e32 v219, 0xffff0000, v37
	v_mul_f32_e32 v216, v225, v216
	v_mul_f32_e32 v217, v225, v217
	v_mul_f32_e32 v218, v225, v218
	v_mul_f32_e32 v219, v225, v219
	v_fmac_f32_e32 v8, v104, v216
	v_fmac_f32_e32 v9, v105, v217
	v_fmac_f32_e32 v10, v106, v218
	v_fmac_f32_e32 v11, v107, v219
	v_lshlrev_b32_e32 v216, 16, v38
	v_and_b32_e32 v217, 0xffff0000, v38
	v_lshlrev_b32_e32 v218, 16, v39
	v_and_b32_e32 v219, 0xffff0000, v39
	v_mul_f32_e32 v216, v225, v216
	v_mul_f32_e32 v217, v225, v217
	v_mul_f32_e32 v218, v225, v218
	v_mul_f32_e32 v219, v225, v219
	v_fmac_f32_e32 v12, v108, v216
	v_fmac_f32_e32 v13, v109, v217
	v_fmac_f32_e32 v14, v110, v218
	v_fmac_f32_e32 v15, v111, v219
	v_lshlrev_b32_e32 v216, 16, v40
	v_and_b32_e32 v217, 0xffff0000, v40
	v_lshlrev_b32_e32 v218, 16, v41
	v_and_b32_e32 v219, 0xffff0000, v41
	v_mul_f32_e32 v216, v225, v216
	v_mul_f32_e32 v217, v225, v217
	v_mul_f32_e32 v218, v225, v218
	v_mul_f32_e32 v219, v225, v219
	v_fmac_f32_e32 v16, v112, v216
	v_fmac_f32_e32 v17, v113, v217
	v_fmac_f32_e32 v18, v114, v218
	v_fmac_f32_e32 v19, v115, v219
	v_lshlrev_b32_e32 v216, 16, v42
	v_and_b32_e32 v217, 0xffff0000, v42
	v_lshlrev_b32_e32 v218, 16, v43
	v_and_b32_e32 v219, 0xffff0000, v43
	v_mul_f32_e32 v216, v225, v216
	v_mul_f32_e32 v217, v225, v217
	v_mul_f32_e32 v218, v225, v218
	v_mul_f32_e32 v219, v225, v219
	v_fmac_f32_e32 v20, v116, v216
	v_fmac_f32_e32 v21, v117, v217
	v_fmac_f32_e32 v22, v118, v218
	v_fmac_f32_e32 v23, v119, v219
	v_lshlrev_b32_e32 v216, 16, v44
	v_and_b32_e32 v217, 0xffff0000, v44
	v_lshlrev_b32_e32 v218, 16, v45
	v_and_b32_e32 v219, 0xffff0000, v45
	v_mul_f32_e32 v216, v225, v216
	v_mul_f32_e32 v217, v225, v217
	v_mul_f32_e32 v218, v225, v218
	v_mul_f32_e32 v219, v225, v219
	v_fmac_f32_e32 v24, v120, v216
	v_fmac_f32_e32 v25, v121, v217
	v_fmac_f32_e32 v26, v122, v218
; __device__ __forceinline__ unsigned cvt_pk_bf16(float lo, float hi) { unsigned r; asm volatile("v_cvt_pk_bf16_f32 %0, %1, %2" : "=v"(r) : "v"(lo), "v"(hi)); return r; }
; __device__ __forceinline__ float bf_lo(unsigned w) { return __uint_as_float(w << 16); }
; __device__ __forceinline__ float bf_hi(unsigned w) { return __uint_as_float(w & 0xffff0000u); }
; __device__ __forceinline__ float sumsq8(const f32x4 (&v)[8]) {
;     float s = 0.f;
; #pragma unroll
;     for (int j = 0; j < 8; ++j) s += (v[j][0] * v[j][0] + v[j][1] * v[j][1]) + (v[j][2] * v[j][2] + v[j][3] * v[j][3]);
;     return wave_sum(s);
; }
; __device__ __forceinline__ void modulate_store(const f32x4 (&v)[8], float rstd, const float* pn, const float* modr, bf16_t* orow, int lane) {
; #pragma unroll
;     for (int j = 0; j < 8; ++j) { const int col = 4 * lane + 256 * j;
;         const f32x4 g = *(const f32x4*)(pn + col), sh = *(const f32x4*)(modr + col), sc = *(const f32x4*)(modr + DM + col);
;         const f32x4 hh = v[j] * rstd * g * (sc + 1.f) + sh;
;         u32x2 w; w.x = cvt_pk_bf16(hh[0], hh[1]); w.y = cvt_pk_bf16(hh[2], hh[3]);
;         *(u32x2*)(orow + col) = w; }
; __global__ void __launch_bounds__(NWAVES * 64, 2) mk_fwd(Args args) {
;     ...
;             for (int q = 0; q < 3; ++q) { const int row = row0 + q; const float* src = row < ML ? x + (size_t)row * DM : ctx + (size_t)(row - ML) * DM; load_row_f32(src, F.lane, v[q]);
;                 const bf16_t* yr = Y + (size_t)row * DM;
; #pragma unroll
;                 for (int j = 0; j < 8; ++j) yw[q][j] = *(const u32x2*)(yr + 4 * F.lane + 256 * j); }
;     ...
;                 for (int j = 0; j < 8; ++j) { const int col = 4 * F.lane + 256 * j; const f32x4 gt = *(const f32x4*)(m0 + 2 * DM + col), pn = *(const f32x4*)(post_norm + col);
;                     const f32x4 y4 = (f32x4){bf_lo(yw[q][j].x), bf_hi(yw[q][j].x), bf_lo(yw[q][j].y), bf_hi(yw[q][j].y)};
;                     v[q][j] = v[q][j] + gt * (y4 * rsy * pn);
;                     if (lat) *(f32x4*)(args.out + (size_t)row * DM + col) = v[q][j]; }
;                 const float rstd = __builtin_amdgcn_rsqf(sumsq8(v[q]) * (1.f / DM) + EPS);
;                 modulate_store(v[q], rstd, pre_norm + DM, mod + (size_t)(9 + r) * 6144, H + (size_t)row * DM, F.lane); }
	v_fmac_f32_e32 v27, v123, v219
	v_lshlrev_b32_e32 v216, 16, v46
	v_and_b32_e32 v217, 0xffff0000, v46
	v_lshlrev_b32_e32 v218, 16, v47
	v_and_b32_e32 v219, 0xffff0000, v47
	v_mul_f32_e32 v216, v225, v216
	v_mul_f32_e32 v217, v225, v217
	v_mul_f32_e32 v218, v225, v218
	v_mul_f32_e32 v219, v225, v219
	v_fmac_f32_e32 v28, v124, v216
	v_fmac_f32_e32 v29, v125, v217
	v_fmac_f32_e32 v30, v126, v218
	v_fmac_f32_e32 v31, v127, v219
	v_mul_f32_e32 v222, v0, v0
	v_mul_f32_e32 v223, v1, v1
	v_fmac_f32_e32 v222, v2, v2
	v_fmac_f32_e32 v223, v3, v3
	v_fmac_f32_e32 v222, v4, v4
	v_fmac_f32_e32 v223, v5, v5
	v_fmac_f32_e32 v222, v6, v6
	v_fmac_f32_e32 v223, v7, v7
	v_fmac_f32_e32 v222, v8, v8
	v_fmac_f32_e32 v223, v9, v9
	v_fmac_f32_e32 v222, v10, v10
	v_fmac_f32_e32 v223, v11, v11
	v_fmac_f32_e32 v222, v12, v12
	v_fmac_f32_e32 v223, v13, v13
	v_fmac_f32_e32 v222, v14, v14
	v_fmac_f32_e32 v223, v15, v15
	v_fmac_f32_e32 v222, v16, v16
	v_fmac_f32_e32 v223, v17, v17
	v_fmac_f32_e32 v222, v18, v18
	v_fmac_f32_e32 v223, v19, v19
	v_fmac_f32_e32 v222, v20, v20
	v_fmac_f32_e32 v223, v21, v21
	v_fmac_f32_e32 v222, v22, v22
	v_fmac_f32_e32 v223, v23, v23
	v_fmac_f32_e32 v222, v24, v24
	v_fmac_f32_e32 v223, v25, v25
	v_fmac_f32_e32 v222, v26, v26
	v_fmac_f32_e32 v223, v27, v27
	v_fmac_f32_e32 v222, v28, v28
	v_fmac_f32_e32 v223, v29, v29
	v_fmac_f32_e32 v222, v30, v30
	v_fmac_f32_e32 v223, v31, v31
	v_add_f32_e32 v222, v222, v223
	s_nop 1
	v_add_f32_dpp v224, v222, v222 quad_perm:[1,0,3,2] row_mask:0xf bank_mask:0xf
	s_nop 1
	v_add_f32_dpp v224, v224, v224 quad_perm:[2,3,0,1] row_mask:0xf bank_mask:0xf
	s_nop 1
	v_add_f32_dpp v224, v224, v224 row_half_mirror row_mask:0xf bank_mask:0xf
	s_nop 1
	v_add_f32_dpp v224, v224, v224 row_mirror row_mask:0xf bank_mask:0xf
	s_nop 1
	v_readlane_b32 s40, v224, 0
	v_readlane_b32 s41, v224, 16
	v_readlane_b32 s42, v224, 32
	v_readlane_b32 s43, v224, 48
	s_nop 1
	v_mov_b32_e32 v225, s40
	v_add_f32_e32 v225, s41, v225
	v_add_f32_e32 v225, s42, v225
	v_add_f32_e32 v225, s43, v225
	v_fmamk_f32 v225, v225, 0x3a000000, v195
	v_rsq_f32_e32 v225, v225
	s_nop 0
	s_add_i32 s0, s6, 0
	s_lshl_b32 s1, s0, 12
	s_add_u32 s26, s84, s1
	s_addc_u32 s27, s85, 0
	s_add_u32 s26, s26, 0x4000000
	s_addc_u32 s27, s27, 0
	v_mul_f32_e32 v216, v225, v0
	v_mul_f32_e32 v217, v225, v1
	v_mul_f32_e32 v218, v225, v2
	v_mul_f32_e32 v219, v225, v3
	v_fma_f32 v216, v216, v128, v160
	v_fma_f32 v217, v217, v129, v161
	v_fma_f32 v218, v218, v130, v162
	v_fma_f32 v219, v219, v131, v163
	v_cvt_pk_bf16_f32 v196, v216, v217
	v_cvt_pk_bf16_f32 v197, v218, v219
	global_store_dwordx2 v194, v[196:197], s[26:27] offset:0
	v_mul_f32_e32 v216, v225, v4
	v_mul_f32_e32 v217, v225, v5
	v_mul_f32_e32 v218, v225, v6
	v_mul_f32_e32 v219, v225, v7
	v_fma_f32 v216, v216, v132, v164
	v_fma_f32 v217, v217, v133, v165
	v_fma_f32 v218, v218, v134, v166
	v_fma_f32 v219, v219, v135, v167
	v_cvt_pk_bf16_f32 v220, v216, v217
	v_cvt_pk_bf16_f32 v221, v218, v219
	global_store_dwordx2 v194, v[220:221], s[26:27] offset:512
	v_mul_f32_e32 v216, v225, v8
	v_mul_f32_e32 v217, v225, v9
	v_mul_f32_e32 v218, v225, v10
	v_mul_f32_e32 v219, v225, v11
	v_fma_f32 v216, v216, v136, v168
	v_fma_f32 v217, v217, v137, v169
	v_fma_f32 v218, v218, v138, v170
	v_fma_f32 v219, v219, v139, v171
	v_cvt_pk_bf16_f32 v196, v216, v217
	v_cvt_pk_bf16_f32 v197, v218, v219
	global_store_dwordx2 v194, v[196:197], s[26:27] offset:1024
	v_mul_f32_e32 v216, v225, v12
	v_mul_f32_e32 v217, v225, v13
	v_mul_f32_e32 v218, v225, v14
	v_mul_f32_e32 v219, v225, v15
	v_fma_f32 v216, v216, v140, v172
	v_fma_f32 v217, v217, v141, v173
	v_fma_f32 v218, v218, v142, v174
	v_fma_f32 v219, v219, v143, v175
	v_cvt_pk_bf16_f32 v220, v216, v217
	v_cvt_pk_bf16_f32 v221, v218, v219
	global_store_dwordx2 v194, v[220:221], s[26:27] offset:1536
	v_mul_f32_e32 v216, v225, v16
	v_mul_f32_e32 v217, v225, v17
	v_mul_f32_e32 v218, v225, v18
	v_mul_f32_e32 v219, v225, v19
	v_fma_f32 v216, v216, v144, v176
	v_fma_f32 v217, v217, v145, v177
	v_fma_f32 v218, v218, v146, v178
	v_fma_f32 v219, v219, v147, v179
	v_cvt_pk_bf16_f32 v196, v216, v217
	v_cvt_pk_bf16_f32 v197, v218, v219
	global_store_dwordx2 v194, v[196:197], s[26:27] offset:2048
	v_mul_f32_e32 v216, v225, v20
	v_mul_f32_e32 v217, v225, v21
	v_mul_f32_e32 v218, v225, v22
	v_mul_f32_e32 v219, v225, v23
	v_fma_f32 v216, v216, v148, v180
	v_fma_f32 v217, v217, v149, v181
	v_fma_f32 v218, v218, v150, v182
	v_fma_f32 v219, v219, v151, v183
	v_cvt_pk_bf16_f32 v220, v216, v217
	v_cvt_pk_bf16_f32 v221, v218, v219
	global_store_dwordx2 v194, v[220:221], s[26:27] offset:2560
	v_mul_f32_e32 v216, v225, v24
	v_mul_f32_e32 v217, v225, v25
	v_mul_f32_e32 v218, v225, v26
	v_mul_f32_e32 v219, v225, v27
	v_fma_f32 v216, v216, v152, v184
	v_fma_f32 v217, v217, v153, v185
	v_fma_f32 v218, v218, v154, v186
	v_fma_f32 v219, v219, v155, v187
	v_cvt_pk_bf16_f32 v196, v216, v217
	v_cvt_pk_bf16_f32 v197, v218, v219
	global_store_dwordx2 v194, v[196:197], s[26:27] offset:3072
	v_mul_f32_e32 v216, v225, v28
	v_mul_f32_e32 v217, v225, v29
	v_mul_f32_e32 v218, v225, v30
	v_mul_f32_e32 v219, v225, v31
	v_fma_f32 v216, v216, v156, v188
	v_fma_f32 v217, v217, v157, v189
	v_fma_f32 v218, v218, v158, v190
	v_fma_f32 v219, v219, v159, v191
	v_cvt_pk_bf16_f32 v220, v216, v217
	v_cvt_pk_bf16_f32 v221, v218, v219
	global_store_dwordx2 v194, v[220:221], s[26:27] offset:3584
	s_add_i32 s0, s6, 2
	s_cmp_lt_u32 s0, 0x4000
	s_cselect_b32 s10, s68, s72
	s_cselect_b32 s11, s69, s73
	s_cselect_b32 s1, 0, 0x4000
	s_sub_i32 s1, s0, s1
	s_lshl_b32 s1, s1, 13
	s_add_u32 s10, s10, s1
	s_addc_u32 s11, s11, 0
	s_add_i32 s0, s6, 2
	s_lshl_b32 s1, s0, 12
	s_add_u32 s22, s84, s1
	s_addc_u32 s23, s85, 0
	s_add_u32 s22, s22, 0x11800000
	s_addc_u32 s23, s23, 0
	global_load_dwordx4 v[0:3], v192, s[10:11] offset:0
	global_load_dwordx4 v[4:7], v192, s[10:11] offset:1024
	global_load_dwordx4 v[8:11], v192, s[10:11] offset:2048
	global_load_dwordx4 v[12:15], v192, s[10:11] offset:3072
	global_load_dwordx4 v[16:19], v193, s[10:11] offset:0
	global_load_dwordx4 v[20:23], v193, s[10:11] offset:1024
	global_load_dwordx4 v[24:27], v193, s[10:11] offset:2048
	global_load_dwordx4 v[28:31], v193, s[10:11] offset:3072
	global_load_dwordx2 v[32:33], v194, s[22:23] offset:0
	global_load_dwordx2 v[34:35], v194, s[22:23] offset:512
	global_load_dwordx2 v[36:37], v194, s[22:23] offset:1024
	global_load_dwordx2 v[38:39], v194, s[22:23] offset:1536
	global_load_dwordx2 v[40:41], v194, s[22:23] offset:2048
	global_load_dwordx2 v[42:43], v194, s[22:23] offset:2560
	global_load_dwordx2 v[44:45], v194, s[22:23] offset:3072
	global_load_dwordx2 v[46:47], v194, s[22:23] offset:3584
	s_add_i32 s0, s6, 1
	s_add_i32 s0, s6, 1
	s_lshr_b32 s8, s0, 11
	s_cmp_lt_u32 s0, 0x4000
	s_cselect_b32 s8, s8, 8
	s_cmp_eq_u32 s8, s7
	s_cbranch_scc1 .Lp6_np1
; __device__ __forceinline__ unsigned cvt_pk_bf16(float lo, float hi) { unsigned r; asm volatile("v_cvt_pk_bf16_f32 %0, %1, %2" : "=v"(r) : "v"(lo), "v"(hi)); return r; }
; __device__ __forceinline__ void modulate_store(const f32x4 (&v)[8], float rstd, const float* pn, const float* modr, bf16_t* orow, int lane) {
; #pragma unroll
;     for (int j = 0; j < 8; ++j) { const int col = 4 * lane + 256 * j;
;         const f32x4 g = *(const f32x4*)(pn + col), sh = *(const f32x4*)(modr + col), sc = *(const f32x4*)(modr + DM + col);
;         const f32x4 hh = v[j] * rstd * g * (sc + 1.f) + sh;
;         u32x2 w; w.x = cvt_pk_bf16(hh[0], hh[1]); w.y = cvt_pk_bf16(hh[2], hh[3]);
;         *(u32x2*)(orow + col) = w; }
; __global__ void __launch_bounds__(NWAVES * 64, 2) mk_fwd(Args args) {
;     ...
;                 const float* m0 = mod + (size_t)r * 6144;
; #pragma unroll
;                 for (int j = 0; j < 8; ++j) { const int col = 4 * F.lane + 256 * j; const f32x4 gt = *(const f32x4*)(m0 + 2 * DM + col), pn = *(const f32x4*)(post_norm + col);
	s_mov_b32 s7, s8
	s_add_i32 s1, s8, 9
	s_mul_i32 s1, s1, 0x6000
	s_add_u32 s44, s84, s1
	s_addc_u32 s45, s85, 0
	s_add_u32 s44, s44, 0x2000
	s_addc_u32 s45, s45, 0
	s_add_i32 s1, s8, 9
	s_mul_i32 s1, s1, 0x6000
	s_add_u32 s36, s84, s1
	s_addc_u32 s37, s85, 0
	s_add_u32 s38, s80, 0x2000
	s_addc_u32 s39, s81, 0
	s_mul_i32 s1, s8, 0x6000
	s_add_u32 s34, s84, s1
	s_addc_u32 s35, s85, 0
	s_add_u32 s34, s34, 0x4000
	s_addc_u32 s35, s35, 0
	global_load_dwordx4 v[96:99], v192, s[34:35] offset:0
	global_load_dwordx4 v[200:203], v192, s[82:83] offset:0
	global_load_dwordx4 v[100:103], v192, s[34:35] offset:1024
	global_load_dwordx4 v[204:207], v192, s[82:83] offset:1024
	global_load_dwordx4 v[104:107], v192, s[34:35] offset:2048
	global_load_dwordx4 v[208:211], v192, s[82:83] offset:2048
	global_load_dwordx4 v[108:111], v192, s[34:35] offset:3072
	global_load_dwordx4 v[212:215], v192, s[82:83] offset:3072
	s_waitcnt vmcnt(0)
	v_mul_f32_e32 v96, v96, v200
	v_mul_f32_e32 v97, v97, v201
	v_mul_f32_e32 v98, v98, v202
	v_mul_f32_e32 v99, v99, v203
	v_mul_f32_e32 v100, v100, v204
	v_mul_f32_e32 v101, v101, v205
	v_mul_f32_e32 v102, v102, v206
	v_mul_f32_e32 v103, v103, v207
	v_mul_f32_e32 v104, v104, v208
	v_mul_f32_e32 v105, v105, v209
	v_mul_f32_e32 v106, v106, v210
	v_mul_f32_e32 v107, v107, v211
	v_mul_f32_e32 v108, v108, v212
	v_mul_f32_e32 v109, v109, v213
	v_mul_f32_e32 v110, v110, v214
	v_mul_f32_e32 v111, v111, v215
	global_load_dwordx4 v[128:131], v192, s[38:39] offset:0
	global_load_dwordx4 v[200:203], v192, s[44:45] offset:0
	global_load_dwordx4 v[160:163], v192, s[36:37] offset:0
	global_load_dwordx4 v[132:135], v192, s[38:39] offset:1024
	global_load_dwordx4 v[204:207], v192, s[44:45] offset:1024
	global_load_dwordx4 v[164:167], v192, s[36:37] offset:1024
	global_load_dwordx4 v[136:139], v192, s[38:39] offset:2048
	global_load_dwordx4 v[208:211], v192, s[44:45] offset:2048
	global_load_dwordx4 v[168:171], v192, s[36:37] offset:2048
	global_load_dwordx4 v[140:143], v192, s[38:39] offset:3072
	global_load_dwordx4 v[212:215], v192, s[44:45] offset:3072
	global_load_dwordx4 v[172:175], v192, s[36:37] offset:3072
	s_waitcnt vmcnt(0)
	v_add_f32_e32 v200, 1.0, v200
	v_add_f32_e32 v201, 1.0, v201
	v_add_f32_e32 v202, 1.0, v202
	v_add_f32_e32 v203, 1.0, v203
	v_mul_f32_e32 v128, v128, v200
	v_mul_f32_e32 v129, v129, v201
	v_mul_f32_e32 v130, v130, v202
	v_mul_f32_e32 v131, v131, v203
	v_add_f32_e32 v204, 1.0, v204
	v_add_f32_e32 v205, 1.0, v205
	v_add_f32_e32 v206, 1.0, v206
	v_add_f32_e32 v207, 1.0, v207
	v_mul_f32_e32 v132, v132, v204
	v_mul_f32_e32 v133, v133, v205
	v_mul_f32_e32 v134, v134, v206
	v_mul_f32_e32 v135, v135, v207
	v_add_f32_e32 v208, 1.0, v208
	v_add_f32_e32 v209, 1.0, v209
	v_add_f32_e32 v210, 1.0, v210
	v_add_f32_e32 v211, 1.0, v211
	v_mul_f32_e32 v136, v136, v208
	v_mul_f32_e32 v137, v137, v209
	v_mul_f32_e32 v138, v138, v210
	v_mul_f32_e32 v139, v139, v211
	v_add_f32_e32 v212, 1.0, v212
	v_add_f32_e32 v213, 1.0, v213
	v_add_f32_e32 v214, 1.0, v214
	v_add_f32_e32 v215, 1.0, v215
	v_mul_f32_e32 v140, v140, v212
	v_mul_f32_e32 v141, v141, v213
	v_mul_f32_e32 v142, v142, v214
	v_mul_f32_e32 v143, v143, v215
	global_load_dwordx4 v[112:115], v193, s[34:35] offset:0
	global_load_dwordx4 v[200:203], v193, s[82:83] offset:0
	global_load_dwordx4 v[116:119], v193, s[34:35] offset:1024
	global_load_dwordx4 v[204:207], v193, s[82:83] offset:1024
	global_load_dwordx4 v[120:123], v193, s[34:35] offset:2048
	global_load_dwordx4 v[208:211], v193, s[82:83] offset:2048
	global_load_dwordx4 v[124:127], v193, s[34:35] offset:3072
	global_load_dwordx4 v[212:215], v193, s[82:83] offset:3072
	s_waitcnt vmcnt(0)
	v_mul_f32_e32 v112, v112, v200
	v_mul_f32_e32 v113, v113, v201
	v_mul_f32_e32 v114, v114, v202
	v_mul_f32_e32 v115, v115, v203
	v_mul_f32_e32 v116, v116, v204
	v_mul_f32_e32 v117, v117, v205
	v_mul_f32_e32 v118, v118, v206
	v_mul_f32_e32 v119, v119, v207
	v_mul_f32_e32 v120, v120, v208
	v_mul_f32_e32 v121, v121, v209
	v_mul_f32_e32 v122, v122, v210
	v_mul_f32_e32 v123, v123, v211
	v_mul_f32_e32 v124, v124, v212
	v_mul_f32_e32 v125, v125, v213
	v_mul_f32_e32 v126, v126, v214
	v_mul_f32_e32 v127, v127, v215
	global_load_dwordx4 v[144:147], v193, s[38:39] offset:0
	global_load_dwordx4 v[200:203], v193, s[44:45] offset:0
	global_load_dwordx4 v[176:179], v193, s[36:37] offset:0
	global_load_dwordx4 v[148:151], v193, s[38:39] offset:1024
	global_load_dwordx4 v[204:207], v193, s[44:45] offset:1024
	global_load_dwordx4 v[180:183], v193, s[36:37] offset:1024
	global_load_dwordx4 v[152:155], v193, s[38:39] offset:2048
	global_load_dwordx4 v[208:211], v193, s[44:45] offset:2048
	global_load_dwordx4 v[184:187], v193, s[36:37] offset:2048
	global_load_dwordx4 v[156:159], v193, s[38:39] offset:3072
	global_load_dwordx4 v[212:215], v193, s[44:45] offset:3072
	global_load_dwordx4 v[188:191], v193, s[36:37] offset:3072
	s_waitcnt vmcnt(0)
	v_add_f32_e32 v200, 1.0, v200
	v_add_f32_e32 v201, 1.0, v201
	v_add_f32_e32 v202, 1.0, v202
	v_add_f32_e32 v203, 1.0, v203
	v_mul_f32_e32 v144, v144, v200
	v_mul_f32_e32 v145, v145, v201
	v_mul_f32_e32 v146, v146, v202
	v_mul_f32_e32 v147, v147, v203
	v_add_f32_e32 v204, 1.0, v204
	v_add_f32_e32 v205, 1.0, v205
	v_add_f32_e32 v206, 1.0, v206
	v_add_f32_e32 v207, 1.0, v207
	v_mul_f32_e32 v148, v148, v204
	v_mul_f32_e32 v149, v149, v205
	v_mul_f32_e32 v150, v150, v206
	v_mul_f32_e32 v151, v151, v207
	v_add_f32_e32 v208, 1.0, v208
	v_add_f32_e32 v209, 1.0, v209
	v_add_f32_e32 v210, 1.0, v210
	v_add_f32_e32 v211, 1.0, v211
	v_mul_f32_e32 v152, v152, v208
	v_mul_f32_e32 v153, v153, v209
	v_mul_f32_e32 v154, v154, v210
	v_mul_f32_e32 v155, v155, v211
	v_add_f32_e32 v212, 1.0, v212
	v_add_f32_e32 v213, 1.0, v213
	v_add_f32_e32 v214, 1.0, v214
	v_add_f32_e32 v215, 1.0, v215
	v_mul_f32_e32 v156, v156, v212
	v_mul_f32_e32 v157, v157, v213
	v_mul_f32_e32 v158, v158, v214
	v_mul_f32_e32 v159, v159, v215
; __device__ __forceinline__ float bf_lo(unsigned w) { return __uint_as_float(w << 16); }
; __device__ __forceinline__ float bf_hi(unsigned w) { return __uint_as_float(w & 0xffff0000u); }
; __global__ void __launch_bounds__(NWAVES * 64, 2) mk_fwd(Args args) {
;     ...
;             for (int q = 0; q < 3; ++q) { const int row = row0 + q; const bool lat = row < ML; const int r = lat ? row / SEQ : 8;
;                 float sy = 0.f;
; #pragma unroll
;                 for (int j = 0; j < 8; ++j) { const float a = bf_lo(yw[q][j].x), b = bf_hi(yw[q][j].x), c2 = bf_lo(yw[q][j].y), d = bf_hi(yw[q][j].y); sy += (a * a + b * b) + (c2 * c2 + d * d); }
;                 const float rsy = __builtin_amdgcn_rsqf(wave_sum(sy) * (1.f / DM) + EPS);
;                 const float* m0 = mod + (size_t)r * 6144;
; #pragma unroll
;                 for (int j = 0; j < 8; ++j) { const int col = 4 * F.lane + 256 * j; const f32x4 gt = *(const f32x4*)(m0 + 2 * DM + col), pn = *(const f32x4*)(post_norm + col);
;                     const f32x4 y4 = (f32x4){bf_lo(yw[q][j].x), bf_hi(yw[q][j].x), bf_lo(yw[q][j].y), bf_hi(yw[q][j].y)};
;                     v[q][j] = v[q][j] + gt * (y4 * rsy * pn);
;                     if (lat) *(f32x4*)(args.out + (size_t)row * DM + col) = v[q][j]; }
;                 const float rstd = __builtin_amdgcn_rsqf(sumsq8(v[q]) * (1.f / DM) + EPS);
.Lp6_np1:
	s_waitcnt vmcnt(24)
	v_lshlrev_b32_e32 v216, 16, v80
	v_and_b32_e32 v217, 0xffff0000, v80
	v_lshlrev_b32_e32 v218, 16, v81
	v_and_b32_e32 v219, 0xffff0000, v81
	v_mul_f32_e32 v222, v216, v216
	v_mul_f32_e32 v223, v217, v217
	v_fmac_f32_e32 v222, v218, v218
	v_fmac_f32_e32 v223, v219, v219
	v_lshlrev_b32_e32 v216, 16, v82
	v_and_b32_e32 v217, 0xffff0000, v82
	v_lshlrev_b32_e32 v218, 16, v83
	v_and_b32_e32 v219, 0xffff0000, v83
	v_fmac_f32_e32 v222, v216, v216
	v_fmac_f32_e32 v223, v217, v217
	v_fmac_f32_e32 v222, v218, v218
	v_fmac_f32_e32 v223, v219, v219
	v_lshlrev_b32_e32 v216, 16, v84
	v_and_b32_e32 v217, 0xffff0000, v84
	v_lshlrev_b32_e32 v218, 16, v85
	v_and_b32_e32 v219, 0xffff0000, v85
	v_fmac_f32_e32 v222, v216, v216
	v_fmac_f32_e32 v223, v217, v217
	v_fmac_f32_e32 v222, v218, v218
	v_fmac_f32_e32 v223, v219, v219
	v_lshlrev_b32_e32 v216, 16, v86
	v_and_b32_e32 v217, 0xffff0000, v86
	v_lshlrev_b32_e32 v218, 16, v87
	v_and_b32_e32 v219, 0xffff0000, v87
	v_fmac_f32_e32 v222, v216, v216
	v_fmac_f32_e32 v223, v217, v217
	v_fmac_f32_e32 v222, v218, v218
	v_fmac_f32_e32 v223, v219, v219
	v_lshlrev_b32_e32 v216, 16, v88
	v_and_b32_e32 v217, 0xffff0000, v88
	v_lshlrev_b32_e32 v218, 16, v89
	v_and_b32_e32 v219, 0xffff0000, v89
	v_fmac_f32_e32 v222, v216, v216
	v_fmac_f32_e32 v223, v217, v217
	v_fmac_f32_e32 v222, v218, v218
	v_fmac_f32_e32 v223, v219, v219
	v_lshlrev_b32_e32 v216, 16, v90
	v_and_b32_e32 v217, 0xffff0000, v90
	v_lshlrev_b32_e32 v218, 16, v91
	v_and_b32_e32 v219, 0xffff0000, v91
	v_fmac_f32_e32 v222, v216, v216
	v_fmac_f32_e32 v223, v217, v217
	v_fmac_f32_e32 v222, v218, v218
	v_fmac_f32_e32 v223, v219, v219
	v_lshlrev_b32_e32 v216, 16, v92
	v_and_b32_e32 v217, 0xffff0000, v92
	v_lshlrev_b32_e32 v218, 16, v93
	v_and_b32_e32 v219, 0xffff0000, v93
	v_fmac_f32_e32 v222, v216, v216
	v_fmac_f32_e32 v223, v217, v217
	v_fmac_f32_e32 v222, v218, v218
	v_fmac_f32_e32 v223, v219, v219
	v_lshlrev_b32_e32 v216, 16, v94
	v_and_b32_e32 v217, 0xffff0000, v94
	v_lshlrev_b32_e32 v218, 16, v95
	v_and_b32_e32 v219, 0xffff0000, v95
	v_fmac_f32_e32 v222, v216, v216
	v_fmac_f32_e32 v223, v217, v217
	v_fmac_f32_e32 v222, v218, v218
	v_fmac_f32_e32 v223, v219, v219
	v_add_f32_e32 v222, v222, v223
	s_nop 1
	v_add_f32_dpp v224, v222, v222 quad_perm:[1,0,3,2] row_mask:0xf bank_mask:0xf
	s_nop 1
	v_add_f32_dpp v224, v224, v224 quad_perm:[2,3,0,1] row_mask:0xf bank_mask:0xf
	s_nop 1
	v_add_f32_dpp v224, v224, v224 row_half_mirror row_mask:0xf bank_mask:0xf
	s_nop 1
	v_add_f32_dpp v224, v224, v224 row_mirror row_mask:0xf bank_mask:0xf
	s_nop 1
	v_readlane_b32 s40, v224, 0
	v_readlane_b32 s41, v224, 16
	v_readlane_b32 s42, v224, 32
	v_readlane_b32 s43, v224, 48
	s_nop 1
	v_mov_b32_e32 v225, s40
	v_add_f32_e32 v225, s41, v225
	v_add_f32_e32 v225, s42, v225
	v_add_f32_e32 v225, s43, v225
	v_fmamk_f32 v225, v225, 0x3a000000, v195
	v_rsq_f32_e32 v225, v225
	s_nop 0
	v_lshlrev_b32_e32 v216, 16, v80
	v_and_b32_e32 v217, 0xffff0000, v80
	v_lshlrev_b32_e32 v218, 16, v81
	v_and_b32_e32 v219, 0xffff0000, v81
	v_mul_f32_e32 v216, v225, v216
	v_mul_f32_e32 v217, v225, v217
	v_mul_f32_e32 v218, v225, v218
	v_mul_f32_e32 v219, v225, v219
	v_fmac_f32_e32 v48, v96, v216
	v_fmac_f32_e32 v49, v97, v217
	v_fmac_f32_e32 v50, v98, v218
	v_fmac_f32_e32 v51, v99, v219
	v_lshlrev_b32_e32 v216, 16, v82
	v_and_b32_e32 v217, 0xffff0000, v82
	v_lshlrev_b32_e32 v218, 16, v83
	v_and_b32_e32 v219, 0xffff0000, v83
	v_mul_f32_e32 v216, v225, v216
	v_mul_f32_e32 v217, v225, v217
	v_mul_f32_e32 v218, v225, v218
	v_mul_f32_e32 v219, v225, v219
	v_fmac_f32_e32 v52, v100, v216
	v_fmac_f32_e32 v53, v101, v217
	v_fmac_f32_e32 v54, v102, v218
	v_fmac_f32_e32 v55, v103, v219
	v_lshlrev_b32_e32 v216, 16, v84
	v_and_b32_e32 v217, 0xffff0000, v84
	v_lshlrev_b32_e32 v218, 16, v85
	v_and_b32_e32 v219, 0xffff0000, v85
	v_mul_f32_e32 v216, v225, v216
	v_mul_f32_e32 v217, v225, v217
	v_mul_f32_e32 v218, v225, v218
	v_mul_f32_e32 v219, v225, v219
	v_fmac_f32_e32 v56, v104, v216
	v_fmac_f32_e32 v57, v105, v217
	v_fmac_f32_e32 v58, v106, v218
	v_fmac_f32_e32 v59, v107, v219
	v_lshlrev_b32_e32 v216, 16, v86
	v_and_b32_e32 v217, 0xffff0000, v86
	v_lshlrev_b32_e32 v218, 16, v87
	v_and_b32_e32 v219, 0xffff0000, v87
	v_mul_f32_e32 v216, v225, v216
	v_mul_f32_e32 v217, v225, v217
	v_mul_f32_e32 v218, v225, v218
	v_mul_f32_e32 v219, v225, v219
	v_fmac_f32_e32 v60, v108, v216
	v_fmac_f32_e32 v61, v109, v217
	v_fmac_f32_e32 v62, v110, v218
	v_fmac_f32_e32 v63, v111, v219
	v_lshlrev_b32_e32 v216, 16, v88
	v_and_b32_e32 v217, 0xffff0000, v88
	v_lshlrev_b32_e32 v218, 16, v89
	v_and_b32_e32 v219, 0xffff0000, v89
	v_mul_f32_e32 v216, v225, v216
	v_mul_f32_e32 v217, v225, v217
	v_mul_f32_e32 v218, v225, v218
	v_mul_f32_e32 v219, v225, v219
	v_fmac_f32_e32 v64, v112, v216
	v_fmac_f32_e32 v65, v113, v217
	v_fmac_f32_e32 v66, v114, v218
	v_fmac_f32_e32 v67, v115, v219
	v_lshlrev_b32_e32 v216, 16, v90
	v_and_b32_e32 v217, 0xffff0000, v90
	v_lshlrev_b32_e32 v218, 16, v91
	v_and_b32_e32 v219, 0xffff0000, v91
	v_mul_f32_e32 v216, v225, v216
	v_mul_f32_e32 v217, v225, v217
	v_mul_f32_e32 v218, v225, v218
	v_mul_f32_e32 v219, v225, v219
	v_fmac_f32_e32 v68, v116, v216
	v_fmac_f32_e32 v69, v117, v217
	v_fmac_f32_e32 v70, v118, v218
	v_fmac_f32_e32 v71, v119, v219
	v_lshlrev_b32_e32 v216, 16, v92
	v_and_b32_e32 v217, 0xffff0000, v92
	v_lshlrev_b32_e32 v218, 16, v93
	v_and_b32_e32 v219, 0xffff0000, v93
	v_mul_f32_e32 v216, v225, v216
	v_mul_f32_e32 v217, v225, v217
	v_mul_f32_e32 v218, v225, v218
	v_mul_f32_e32 v219, v225, v219
	v_fmac_f32_e32 v72, v120, v216
	v_fmac_f32_e32 v73, v121, v217
	v_fmac_f32_e32 v74, v122, v218
; __device__ __forceinline__ unsigned cvt_pk_bf16(float lo, float hi) { unsigned r; asm volatile("v_cvt_pk_bf16_f32 %0, %1, %2" : "=v"(r) : "v"(lo), "v"(hi)); return r; }
; __device__ __forceinline__ float bf_lo(unsigned w) { return __uint_as_float(w << 16); }
; __device__ __forceinline__ float bf_hi(unsigned w) { return __uint_as_float(w & 0xffff0000u); }
; __device__ __forceinline__ float sumsq8(const f32x4 (&v)[8]) {
;     float s = 0.f;
; #pragma unroll
;     for (int j = 0; j < 8; ++j) s += (v[j][0] * v[j][0] + v[j][1] * v[j][1]) + (v[j][2] * v[j][2] + v[j][3] * v[j][3]);
;     return wave_sum(s);
; }
; __device__ __forceinline__ void modulate_store(const f32x4 (&v)[8], float rstd, const float* pn, const float* modr, bf16_t* orow, int lane) {
; #pragma unroll
;     for (int j = 0; j < 8; ++j) { const int col = 4 * lane + 256 * j;
;         const f32x4 g = *(const f32x4*)(pn + col), sh = *(const f32x4*)(modr + col), sc = *(const f32x4*)(modr + DM + col);
;         const f32x4 hh = v[j] * rstd * g * (sc + 1.f) + sh;
;         u32x2 w; w.x = cvt_pk_bf16(hh[0], hh[1]); w.y = cvt_pk_bf16(hh[2], hh[3]);
;         *(u32x2*)(orow + col) = w; }
; __global__ void __launch_bounds__(NWAVES * 64, 2) mk_fwd(Args args) {
;     ...
;             for (int q = 0; q < 3; ++q) { const int row = row0 + q; const float* src = row < ML ? x + (size_t)row * DM : ctx + (size_t)(row - ML) * DM; load_row_f32(src, F.lane, v[q]);
;                 const bf16_t* yr = Y + (size_t)row * DM;
; #pragma unroll
;                 for (int j = 0; j < 8; ++j) yw[q][j] = *(const u32x2*)(yr + 4 * F.lane + 256 * j); }
;     ...
;                 for (int j = 0; j < 8; ++j) { const int col = 4 * F.lane + 256 * j; const f32x4 gt = *(const f32x4*)(m0 + 2 * DM + col), pn = *(const f32x4*)(post_norm + col);
;                     const f32x4 y4 = (f32x4){bf_lo(yw[q][j].x), bf_hi(yw[q][j].x), bf_lo(yw[q][j].y), bf_hi(yw[q][j].y)};
;                     v[q][j] = v[q][j] + gt * (y4 * rsy * pn);
;                     if (lat) *(f32x4*)(args.out + (size_t)row * DM + col) = v[q][j]; }
;                 const float rstd = __builtin_amdgcn_rsqf(sumsq8(v[q]) * (1.f / DM) + EPS);
;                 modulate_store(v[q], rstd, pre_norm + DM, mod + (size_t)(9 + r) * 6144, H + (size_t)row * DM, F.lane); }
	v_fmac_f32_e32 v75, v123, v219
	v_lshlrev_b32_e32 v216, 16, v94
	v_and_b32_e32 v217, 0xffff0000, v94
	v_lshlrev_b32_e32 v218, 16, v95
	v_and_b32_e32 v219, 0xffff0000, v95
	v_mul_f32_e32 v216, v225, v216
	v_mul_f32_e32 v217, v225, v217
	v_mul_f32_e32 v218, v225, v218
	v_mul_f32_e32 v219, v225, v219
	v_fmac_f32_e32 v76, v124, v216
	v_fmac_f32_e32 v77, v125, v217
	v_fmac_f32_e32 v78, v126, v218
	v_fmac_f32_e32 v79, v127, v219
	v_mul_f32_e32 v222, v48, v48
	v_mul_f32_e32 v223, v49, v49
	v_fmac_f32_e32 v222, v50, v50
	v_fmac_f32_e32 v223, v51, v51
	v_fmac_f32_e32 v222, v52, v52
	v_fmac_f32_e32 v223, v53, v53
	v_fmac_f32_e32 v222, v54, v54
	v_fmac_f32_e32 v223, v55, v55
	v_fmac_f32_e32 v222, v56, v56
	v_fmac_f32_e32 v223, v57, v57
	v_fmac_f32_e32 v222, v58, v58
	v_fmac_f32_e32 v223, v59, v59
	v_fmac_f32_e32 v222, v60, v60
	v_fmac_f32_e32 v223, v61, v61
	v_fmac_f32_e32 v222, v62, v62
	v_fmac_f32_e32 v223, v63, v63
	v_fmac_f32_e32 v222, v64, v64
	v_fmac_f32_e32 v223, v65, v65
	v_fmac_f32_e32 v222, v66, v66
	v_fmac_f32_e32 v223, v67, v67
	v_fmac_f32_e32 v222, v68, v68
	v_fmac_f32_e32 v223, v69, v69
	v_fmac_f32_e32 v222, v70, v70
	v_fmac_f32_e32 v223, v71, v71
	v_fmac_f32_e32 v222, v72, v72
	v_fmac_f32_e32 v223, v73, v73
	v_fmac_f32_e32 v222, v74, v74
	v_fmac_f32_e32 v223, v75, v75
	v_fmac_f32_e32 v222, v76, v76
	v_fmac_f32_e32 v223, v77, v77
	v_fmac_f32_e32 v222, v78, v78
	v_fmac_f32_e32 v223, v79, v79
	v_add_f32_e32 v222, v222, v223
	s_nop 1
	v_add_f32_dpp v224, v222, v222 quad_perm:[1,0,3,2] row_mask:0xf bank_mask:0xf
	s_nop 1
	v_add_f32_dpp v224, v224, v224 quad_perm:[2,3,0,1] row_mask:0xf bank_mask:0xf
	s_nop 1
	v_add_f32_dpp v224, v224, v224 row_half_mirror row_mask:0xf bank_mask:0xf
	s_nop 1
	v_add_f32_dpp v224, v224, v224 row_mirror row_mask:0xf bank_mask:0xf
	s_nop 1
	v_readlane_b32 s40, v224, 0
	v_readlane_b32 s41, v224, 16
	v_readlane_b32 s42, v224, 32
	v_readlane_b32 s43, v224, 48
	s_nop 1
	v_mov_b32_e32 v225, s40
	v_add_f32_e32 v225, s41, v225
	v_add_f32_e32 v225, s42, v225
	v_add_f32_e32 v225, s43, v225
	v_fmamk_f32 v225, v225, 0x3a000000, v195
	v_rsq_f32_e32 v225, v225
	s_nop 0
	s_add_i32 s0, s6, 1
	s_lshl_b32 s1, s0, 12
	s_add_u32 s26, s84, s1
	s_addc_u32 s27, s85, 0
	s_add_u32 s26, s26, 0x4000000
	s_addc_u32 s27, s27, 0
	v_mul_f32_e32 v216, v225, v48
	v_mul_f32_e32 v217, v225, v49
	v_mul_f32_e32 v218, v225, v50
	v_mul_f32_e32 v219, v225, v51
	v_fma_f32 v216, v216, v128, v160
	v_fma_f32 v217, v217, v129, v161
	v_fma_f32 v218, v218, v130, v162
	v_fma_f32 v219, v219, v131, v163
	v_cvt_pk_bf16_f32 v196, v216, v217
	v_cvt_pk_bf16_f32 v197, v218, v219
	global_store_dwordx2 v194, v[196:197], s[26:27] offset:0
	v_mul_f32_e32 v216, v225, v52
	v_mul_f32_e32 v217, v225, v53
	v_mul_f32_e32 v218, v225, v54
	v_mul_f32_e32 v219, v225, v55
	v_fma_f32 v216, v216, v132, v164
	v_fma_f32 v217, v217, v133, v165
	v_fma_f32 v218, v218, v134, v166
	v_fma_f32 v219, v219, v135, v167
	v_cvt_pk_bf16_f32 v220, v216, v217
	v_cvt_pk_bf16_f32 v221, v218, v219
	global_store_dwordx2 v194, v[220:221], s[26:27] offset:512
	v_mul_f32_e32 v216, v225, v56
	v_mul_f32_e32 v217, v225, v57
	v_mul_f32_e32 v218, v225, v58
	v_mul_f32_e32 v219, v225, v59
	v_fma_f32 v216, v216, v136, v168
	v_fma_f32 v217, v217, v137, v169
	v_fma_f32 v218, v218, v138, v170
	v_fma_f32 v219, v219, v139, v171
	v_cvt_pk_bf16_f32 v196, v216, v217
	v_cvt_pk_bf16_f32 v197, v218, v219
	global_store_dwordx2 v194, v[196:197], s[26:27] offset:1024
	v_mul_f32_e32 v216, v225, v60
	v_mul_f32_e32 v217, v225, v61
	v_mul_f32_e32 v218, v225, v62
	v_mul_f32_e32 v219, v225, v63
	v_fma_f32 v216, v216, v140, v172
	v_fma_f32 v217, v217, v141, v173
	v_fma_f32 v218, v218, v142, v174
	v_fma_f32 v219, v219, v143, v175
	v_cvt_pk_bf16_f32 v220, v216, v217
	v_cvt_pk_bf16_f32 v221, v218, v219
	global_store_dwordx2 v194, v[220:221], s[26:27] offset:1536
	v_mul_f32_e32 v216, v225, v64
	v_mul_f32_e32 v217, v225, v65
	v_mul_f32_e32 v218, v225, v66
	v_mul_f32_e32 v219, v225, v67
	v_fma_f32 v216, v216, v144, v176
	v_fma_f32 v217, v217, v145, v177
	v_fma_f32 v218, v218, v146, v178
	v_fma_f32 v219, v219, v147, v179
	v_cvt_pk_bf16_f32 v196, v216, v217
	v_cvt_pk_bf16_f32 v197, v218, v219
	global_store_dwordx2 v194, v[196:197], s[26:27] offset:2048
	v_mul_f32_e32 v216, v225, v68
	v_mul_f32_e32 v217, v225, v69
	v_mul_f32_e32 v218, v225, v70
	v_mul_f32_e32 v219, v225, v71
	v_fma_f32 v216, v216, v148, v180
	v_fma_f32 v217, v217, v149, v181
	v_fma_f32 v218, v218, v150, v182
	v_fma_f32 v219, v219, v151, v183
	v_cvt_pk_bf16_f32 v220, v216, v217
	v_cvt_pk_bf16_f32 v221, v218, v219
	global_store_dwordx2 v194, v[220:221], s[26:27] offset:2560
	v_mul_f32_e32 v216, v225, v72
	v_mul_f32_e32 v217, v225, v73
	v_mul_f32_e32 v218, v225, v74
	v_mul_f32_e32 v219, v225, v75
	v_fma_f32 v216, v216, v152, v184
	v_fma_f32 v217, v217, v153, v185
	v_fma_f32 v218, v218, v154, v186
	v_fma_f32 v219, v219, v155, v187
	v_cvt_pk_bf16_f32 v196, v216, v217
	v_cvt_pk_bf16_f32 v197, v218, v219
	global_store_dwordx2 v194, v[196:197], s[26:27] offset:3072
	v_mul_f32_e32 v216, v225, v76
	v_mul_f32_e32 v217, v225, v77
	v_mul_f32_e32 v218, v225, v78
	v_mul_f32_e32 v219, v225, v79
	v_fma_f32 v216, v216, v156, v188
	v_fma_f32 v217, v217, v157, v189
	v_fma_f32 v218, v218, v158, v190
	v_fma_f32 v219, v219, v159, v191
	v_cvt_pk_bf16_f32 v220, v216, v217
	v_cvt_pk_bf16_f32 v221, v218, v219
	global_store_dwordx2 v194, v[220:221], s[26:27] offset:3584
	s_add_i32 s0, s6, 3
	s_cmp_lt_u32 s0, 0x4000
	s_cselect_b32 s10, s68, s72
	s_cselect_b32 s11, s69, s73
	s_cselect_b32 s1, 0, 0x4000
	s_sub_i32 s1, s0, s1
	s_lshl_b32 s1, s1, 13
	s_add_u32 s10, s10, s1
	s_addc_u32 s11, s11, 0
	s_add_i32 s0, s6, 3
	s_lshl_b32 s1, s0, 12
	s_add_u32 s22, s84, s1
	s_addc_u32 s23, s85, 0
	s_add_u32 s22, s22, 0x11800000
	s_addc_u32 s23, s23, 0
	global_load_dwordx4 v[48:51], v192, s[10:11] offset:0
	global_load_dwordx4 v[52:55], v192, s[10:11] offset:1024
	global_load_dwordx4 v[56:59], v192, s[10:11] offset:2048
	global_load_dwordx4 v[60:63], v192, s[10:11] offset:3072
	global_load_dwordx4 v[64:67], v193, s[10:11] offset:0
	global_load_dwordx4 v[68:71], v193, s[10:11] offset:1024
	global_load_dwordx4 v[72:75], v193, s[10:11] offset:2048
	global_load_dwordx4 v[76:79], v193, s[10:11] offset:3072
	global_load_dwordx2 v[80:81], v194, s[22:23] offset:0
	global_load_dwordx2 v[82:83], v194, s[22:23] offset:512
	global_load_dwordx2 v[84:85], v194, s[22:23] offset:1024
	global_load_dwordx2 v[86:87], v194, s[22:23] offset:1536
	global_load_dwordx2 v[88:89], v194, s[22:23] offset:2048
	global_load_dwordx2 v[90:91], v194, s[22:23] offset:2560
	global_load_dwordx2 v[92:93], v194, s[22:23] offset:3072
	global_load_dwordx2 v[94:95], v194, s[22:23] offset:3584
	s_add_i32 s0, s6, 2
	s_add_i32 s0, s6, 2
	s_lshr_b32 s8, s0, 11
	s_cmp_lt_u32 s0, 0x4000
	s_cselect_b32 s8, s8, 8
	s_cmp_eq_u32 s8, s7
	s_cbranch_scc1 .Lp6_np2
; __device__ __forceinline__ unsigned cvt_pk_bf16(float lo, float hi) { unsigned r; asm volatile("v_cvt_pk_bf16_f32 %0, %1, %2" : "=v"(r) : "v"(lo), "v"(hi)); return r; }
; __device__ __forceinline__ void modulate_store(const f32x4 (&v)[8], float rstd, const float* pn, const float* modr, bf16_t* orow, int lane) {
; #pragma unroll
;     for (int j = 0; j < 8; ++j) { const int col = 4 * lane + 256 * j;
;         const f32x4 g = *(const f32x4*)(pn + col), sh = *(const f32x4*)(modr + col), sc = *(const f32x4*)(modr + DM + col);
;         const f32x4 hh = v[j] * rstd * g * (sc + 1.f) + sh;
;         u32x2 w; w.x = cvt_pk_bf16(hh[0], hh[1]); w.y = cvt_pk_bf16(hh[2], hh[3]);
;         *(u32x2*)(orow + col) = w; }
; __global__ void __launch_bounds__(NWAVES * 64, 2) mk_fwd(Args args) {
;     ...
;                 const float* m0 = mod + (size_t)r * 6144;
; #pragma unroll
;                 for (int j = 0; j < 8; ++j) { const int col = 4 * F.lane + 256 * j; const f32x4 gt = *(const f32x4*)(m0 + 2 * DM + col), pn = *(const f32x4*)(post_norm + col);
	s_mov_b32 s7, s8
	s_add_i32 s1, s8, 9
	s_mul_i32 s1, s1, 0x6000
	s_add_u32 s44, s84, s1
	s_addc_u32 s45, s85, 0
	s_add_u32 s44, s44, 0x2000
	s_addc_u32 s45, s45, 0
	s_add_i32 s1, s8, 9
	s_mul_i32 s1, s1, 0x6000
	s_add_u32 s36, s84, s1
	s_addc_u32 s37, s85, 0
	s_add_u32 s38, s80, 0x2000
	s_addc_u32 s39, s81, 0
	s_mul_i32 s1, s8, 0x6000
	s_add_u32 s34, s84, s1
	s_addc_u32 s35, s85, 0
	s_add_u32 s34, s34, 0x4000
	s_addc_u32 s35, s35, 0
	global_load_dwordx4 v[96:99], v192, s[34:35] offset:0
	global_load_dwordx4 v[200:203], v192, s[82:83] offset:0
	global_load_dwordx4 v[100:103], v192, s[34:35] offset:1024
	global_load_dwordx4 v[204:207], v192, s[82:83] offset:1024
	global_load_dwordx4 v[104:107], v192, s[34:35] offset:2048
	global_load_dwordx4 v[208:211], v192, s[82:83] offset:2048
	global_load_dwordx4 v[108:111], v192, s[34:35] offset:3072
	global_load_dwordx4 v[212:215], v192, s[82:83] offset:3072
	s_waitcnt vmcnt(0)
	v_mul_f32_e32 v96, v96, v200
	v_mul_f32_e32 v97, v97, v201
	v_mul_f32_e32 v98, v98, v202
	v_mul_f32_e32 v99, v99, v203
	v_mul_f32_e32 v100, v100, v204
	v_mul_f32_e32 v101, v101, v205
	v_mul_f32_e32 v102, v102, v206
	v_mul_f32_e32 v103, v103, v207
	v_mul_f32_e32 v104, v104, v208
	v_mul_f32_e32 v105, v105, v209
	v_mul_f32_e32 v106, v106, v210
	v_mul_f32_e32 v107, v107, v211
	v_mul_f32_e32 v108, v108, v212
	v_mul_f32_e32 v109, v109, v213
	v_mul_f32_e32 v110, v110, v214
	v_mul_f32_e32 v111, v111, v215
	global_load_dwordx4 v[128:131], v192, s[38:39] offset:0
	global_load_dwordx4 v[200:203], v192, s[44:45] offset:0
	global_load_dwordx4 v[160:163], v192, s[36:37] offset:0
	global_load_dwordx4 v[132:135], v192, s[38:39] offset:1024
	global_load_dwordx4 v[204:207], v192, s[44:45] offset:1024
	global_load_dwordx4 v[164:167], v192, s[36:37] offset:1024
	global_load_dwordx4 v[136:139], v192, s[38:39] offset:2048
	global_load_dwordx4 v[208:211], v192, s[44:45] offset:2048
	global_load_dwordx4 v[168:171], v192, s[36:37] offset:2048
	global_load_dwordx4 v[140:143], v192, s[38:39] offset:3072
	global_load_dwordx4 v[212:215], v192, s[44:45] offset:3072
	global_load_dwordx4 v[172:175], v192, s[36:37] offset:3072
	s_waitcnt vmcnt(0)
	v_add_f32_e32 v200, 1.0, v200
	v_add_f32_e32 v201, 1.0, v201
	v_add_f32_e32 v202, 1.0, v202
	v_add_f32_e32 v203, 1.0, v203
	v_mul_f32_e32 v128, v128, v200
	v_mul_f32_e32 v129, v129, v201
	v_mul_f32_e32 v130, v130, v202
	v_mul_f32_e32 v131, v131, v203
	v_add_f32_e32 v204, 1.0, v204
	v_add_f32_e32 v205, 1.0, v205
	v_add_f32_e32 v206, 1.0, v206
	v_add_f32_e32 v207, 1.0, v207
	v_mul_f32_e32 v132, v132, v204
	v_mul_f32_e32 v133, v133, v205
	v_mul_f32_e32 v134, v134, v206
	v_mul_f32_e32 v135, v135, v207
	v_add_f32_e32 v208, 1.0, v208
	v_add_f32_e32 v209, 1.0, v209
	v_add_f32_e32 v210, 1.0, v210
	v_add_f32_e32 v211, 1.0, v211
	v_mul_f32_e32 v136, v136, v208
	v_mul_f32_e32 v137, v137, v209
	v_mul_f32_e32 v138, v138, v210
	v_mul_f32_e32 v139, v139, v211
	v_add_f32_e32 v212, 1.0, v212
	v_add_f32_e32 v213, 1.0, v213
	v_add_f32_e32 v214, 1.0, v214
	v_add_f32_e32 v215, 1.0, v215
	v_mul_f32_e32 v140, v140, v212
	v_mul_f32_e32 v141, v141, v213
	v_mul_f32_e32 v142, v142, v214
	v_mul_f32_e32 v143, v143, v215
	global_load_dwordx4 v[112:115], v193, s[34:35] offset:0
	global_load_dwordx4 v[200:203], v193, s[82:83] offset:0
	global_load_dwordx4 v[116:119], v193, s[34:35] offset:1024
	global_load_dwordx4 v[204:207], v193, s[82:83] offset:1024
	global_load_dwordx4 v[120:123], v193, s[34:35] offset:2048
	global_load_dwordx4 v[208:211], v193, s[82:83] offset:2048
	global_load_dwordx4 v[124:127], v193, s[34:35] offset:3072
	global_load_dwordx4 v[212:215], v193, s[82:83] offset:3072
	s_waitcnt vmcnt(0)
	v_mul_f32_e32 v112, v112, v200
	v_mul_f32_e32 v113, v113, v201
	v_mul_f32_e32 v114, v114, v202
	v_mul_f32_e32 v115, v115, v203
	v_mul_f32_e32 v116, v116, v204
	v_mul_f32_e32 v117, v117, v205
	v_mul_f32_e32 v118, v118, v206
	v_mul_f32_e32 v119, v119, v207
	v_mul_f32_e32 v120, v120, v208
	v_mul_f32_e32 v121, v121, v209
	v_mul_f32_e32 v122, v122, v210
	v_mul_f32_e32 v123, v123, v211
	v_mul_f32_e32 v124, v124, v212
	v_mul_f32_e32 v125, v125, v213
	v_mul_f32_e32 v126, v126, v214
	v_mul_f32_e32 v127, v127, v215
	global_load_dwordx4 v[144:147], v193, s[38:39] offset:0
	global_load_dwordx4 v[200:203], v193, s[44:45] offset:0
	global_load_dwordx4 v[176:179], v193, s[36:37] offset:0
	global_load_dwordx4 v[148:151], v193, s[38:39] offset:1024
	global_load_dwordx4 v[204:207], v193, s[44:45] offset:1024
	global_load_dwordx4 v[180:183], v193, s[36:37] offset:1024
	global_load_dwordx4 v[152:155], v193, s[38:39] offset:2048
	global_load_dwordx4 v[208:211], v193, s[44:45] offset:2048
	global_load_dwordx4 v[184:187], v193, s[36:37] offset:2048
	global_load_dwordx4 v[156:159], v193, s[38:39] offset:3072
	global_load_dwordx4 v[212:215], v193, s[44:45] offset:3072
	global_load_dwordx4 v[188:191], v193, s[36:37] offset:3072
	s_waitcnt vmcnt(0)
	v_add_f32_e32 v200, 1.0, v200
	v_add_f32_e32 v201, 1.0, v201
	v_add_f32_e32 v202, 1.0, v202
	v_add_f32_e32 v203, 1.0, v203
	v_mul_f32_e32 v144, v144, v200
	v_mul_f32_e32 v145, v145, v201
	v_mul_f32_e32 v146, v146, v202
	v_mul_f32_e32 v147, v147, v203
	v_add_f32_e32 v204, 1.0, v204
	v_add_f32_e32 v205, 1.0, v205
	v_add_f32_e32 v206, 1.0, v206
	v_add_f32_e32 v207, 1.0, v207
	v_mul_f32_e32 v148, v148, v204
	v_mul_f32_e32 v149, v149, v205
	v_mul_f32_e32 v150, v150, v206
	v_mul_f32_e32 v151, v151, v207
	v_add_f32_e32 v208, 1.0, v208
	v_add_f32_e32 v209, 1.0, v209
	v_add_f32_e32 v210, 1.0, v210
	v_add_f32_e32 v211, 1.0, v211
	v_mul_f32_e32 v152, v152, v208
	v_mul_f32_e32 v153, v153, v209
	v_mul_f32_e32 v154, v154, v210
	v_mul_f32_e32 v155, v155, v211
	v_add_f32_e32 v212, 1.0, v212
	v_add_f32_e32 v213, 1.0, v213
	v_add_f32_e32 v214, 1.0, v214
	v_add_f32_e32 v215, 1.0, v215
	v_mul_f32_e32 v156, v156, v212
	v_mul_f32_e32 v157, v157, v213
	v_mul_f32_e32 v158, v158, v214
	v_mul_f32_e32 v159, v159, v215
; __device__ __forceinline__ float bf_lo(unsigned w) { return __uint_as_float(w << 16); }
; __device__ __forceinline__ float bf_hi(unsigned w) { return __uint_as_float(w & 0xffff0000u); }
; __global__ void __launch_bounds__(NWAVES * 64, 2) mk_fwd(Args args) {
;     ...
;             for (int q = 0; q < 3; ++q) { const int row = row0 + q; const bool lat = row < ML; const int r = lat ? row / SEQ : 8;
;                 float sy = 0.f;
; #pragma unroll
;                 for (int j = 0; j < 8; ++j) { const float a = bf_lo(yw[q][j].x), b = bf_hi(yw[q][j].x), c2 = bf_lo(yw[q][j].y), d = bf_hi(yw[q][j].y); sy += (a * a + b * b) + (c2 * c2 + d * d); }
;                 const float rsy = __builtin_amdgcn_rsqf(wave_sum(sy) * (1.f / DM) + EPS);
;                 const float* m0 = mod + (size_t)r * 6144;
; #pragma unroll
;                 for (int j = 0; j < 8; ++j) { const int col = 4 * F.lane + 256 * j; const f32x4 gt = *(const f32x4*)(m0 + 2 * DM + col), pn = *(const f32x4*)(post_norm + col);
;                     const f32x4 y4 = (f32x4){bf_lo(yw[q][j].x), bf_hi(yw[q][j].x), bf_lo(yw[q][j].y), bf_hi(yw[q][j].y)};
;                     v[q][j] = v[q][j] + gt * (y4 * rsy * pn);
;                     if (lat) *(f32x4*)(args.out + (size_t)row * DM + col) = v[q][j]; }
;                 const float rstd = __builtin_amdgcn_rsqf(sumsq8(v[q]) * (1.f / DM) + EPS);
.Lp6_np2:
	s_waitcnt vmcnt(24)
	v_lshlrev_b32_e32 v216, 16, v32
	v_and_b32_e32 v217, 0xffff0000, v32
	v_lshlrev_b32_e32 v218, 16, v33
	v_and_b32_e32 v219, 0xffff0000, v33
	v_mul_f32_e32 v222, v216, v216
	v_mul_f32_e32 v223, v217, v217
	v_fmac_f32_e32 v222, v218, v218
	v_fmac_f32_e32 v223, v219, v219
	v_lshlrev_b32_e32 v216, 16, v34
	v_and_b32_e32 v217, 0xffff0000, v34
	v_lshlrev_b32_e32 v218, 16, v35
	v_and_b32_e32 v219, 0xffff0000, v35
	v_fmac_f32_e32 v222, v216, v216
	v_fmac_f32_e32 v223, v217, v217
	v_fmac_f32_e32 v222, v218, v218
	v_fmac_f32_e32 v223, v219, v219
	v_lshlrev_b32_e32 v216, 16, v36
	v_and_b32_e32 v217, 0xffff0000, v36
	v_lshlrev_b32_e32 v218, 16, v37
	v_and_b32_e32 v219, 0xffff0000, v37
	v_fmac_f32_e32 v222, v216, v216
	v_fmac_f32_e32 v223, v217, v217
	v_fmac_f32_e32 v222, v218, v218
	v_fmac_f32_e32 v223, v219, v219
	v_lshlrev_b32_e32 v216, 16, v38
	v_and_b32_e32 v217, 0xffff0000, v38
	v_lshlrev_b32_e32 v218, 16, v39
	v_and_b32_e32 v219, 0xffff0000, v39
	v_fmac_f32_e32 v222, v216, v216
	v_fmac_f32_e32 v223, v217, v217
	v_fmac_f32_e32 v222, v218, v218
	v_fmac_f32_e32 v223, v219, v219
	v_lshlrev_b32_e32 v216, 16, v40
	v_and_b32_e32 v217, 0xffff0000, v40
	v_lshlrev_b32_e32 v218, 16, v41
	v_and_b32_e32 v219, 0xffff0000, v41
	v_fmac_f32_e32 v222, v216, v216
	v_fmac_f32_e32 v223, v217, v217
	v_fmac_f32_e32 v222, v218, v218
	v_fmac_f32_e32 v223, v219, v219
	v_lshlrev_b32_e32 v216, 16, v42
	v_and_b32_e32 v217, 0xffff0000, v42
	v_lshlrev_b32_e32 v218, 16, v43
	v_and_b32_e32 v219, 0xffff0000, v43
	v_fmac_f32_e32 v222, v216, v216
	v_fmac_f32_e32 v223, v217, v217
	v_fmac_f32_e32 v222, v218, v218
	v_fmac_f32_e32 v223, v219, v219
	v_lshlrev_b32_e32 v216, 16, v44
	v_and_b32_e32 v217, 0xffff0000, v44
	v_lshlrev_b32_e32 v218, 16, v45
	v_and_b32_e32 v219, 0xffff0000, v45
	v_fmac_f32_e32 v222, v216, v216
	v_fmac_f32_e32 v223, v217, v217
	v_fmac_f32_e32 v222, v218, v218
	v_fmac_f32_e32 v223, v219, v219
	v_lshlrev_b32_e32 v216, 16, v46
	v_and_b32_e32 v217, 0xffff0000, v46
	v_lshlrev_b32_e32 v218, 16, v47
	v_and_b32_e32 v219, 0xffff0000, v47
	v_fmac_f32_e32 v222, v216, v216
	v_fmac_f32_e32 v223, v217, v217
	v_fmac_f32_e32 v222, v218, v218
	v_fmac_f32_e32 v223, v219, v219
	v_add_f32_e32 v222, v222, v223
	s_nop 1
	v_add_f32_dpp v224, v222, v222 quad_perm:[1,0,3,2] row_mask:0xf bank_mask:0xf
	s_nop 1
	v_add_f32_dpp v224, v224, v224 quad_perm:[2,3,0,1] row_mask:0xf bank_mask:0xf
	s_nop 1
	v_add_f32_dpp v224, v224, v224 row_half_mirror row_mask:0xf bank_mask:0xf
	s_nop 1
	v_add_f32_dpp v224, v224, v224 row_mirror row_mask:0xf bank_mask:0xf
	s_nop 1
	v_readlane_b32 s40, v224, 0
	v_readlane_b32 s41, v224, 16
	v_readlane_b32 s42, v224, 32
	v_readlane_b32 s43, v224, 48
	s_nop 1
	v_mov_b32_e32 v225, s40
	v_add_f32_e32 v225, s41, v225
	v_add_f32_e32 v225, s42, v225
	v_add_f32_e32 v225, s43, v225
	v_fmamk_f32 v225, v225, 0x3a000000, v195
	v_rsq_f32_e32 v225, v225
	s_nop 0
	v_lshlrev_b32_e32 v216, 16, v32
	v_and_b32_e32 v217, 0xffff0000, v32
	v_lshlrev_b32_e32 v218, 16, v33
	v_and_b32_e32 v219, 0xffff0000, v33
	v_mul_f32_e32 v216, v225, v216
	v_mul_f32_e32 v217, v225, v217
	v_mul_f32_e32 v218, v225, v218
	v_mul_f32_e32 v219, v225, v219
	v_fmac_f32_e32 v0, v96, v216
	v_fmac_f32_e32 v1, v97, v217
	v_fmac_f32_e32 v2, v98, v218
	v_fmac_f32_e32 v3, v99, v219
	v_lshlrev_b32_e32 v216, 16, v34
	v_and_b32_e32 v217, 0xffff0000, v34
	v_lshlrev_b32_e32 v218, 16, v35
	v_and_b32_e32 v219, 0xffff0000, v35
	v_mul_f32_e32 v216, v225, v216
	v_mul_f32_e32 v217, v225, v217
	v_mul_f32_e32 v218, v225, v218
	v_mul_f32_e32 v219, v225, v219
	v_fmac_f32_e32 v4, v100, v216
	v_fmac_f32_e32 v5, v101, v217
	v_fmac_f32_e32 v6, v102, v218
	v_fmac_f32_e32 v7, v103, v219
	v_lshlrev_b32_e32 v216, 16, v36
	v_and_b32_e32 v217, 0xffff0000, v36
	v_lshlrev_b32_e32 v218, 16, v37
	v_and_b32_e32 v219, 0xffff0000, v37
	v_mul_f32_e32 v216, v225, v216
	v_mul_f32_e32 v217, v225, v217
	v_mul_f32_e32 v218, v225, v218
	v_mul_f32_e32 v219, v225, v219
	v_fmac_f32_e32 v8, v104, v216
	v_fmac_f32_e32 v9, v105, v217
	v_fmac_f32_e32 v10, v106, v218
	v_fmac_f32_e32 v11, v107, v219
	v_lshlrev_b32_e32 v216, 16, v38
	v_and_b32_e32 v217, 0xffff0000, v38
	v_lshlrev_b32_e32 v218, 16, v39
	v_and_b32_e32 v219, 0xffff0000, v39
	v_mul_f32_e32 v216, v225, v216
	v_mul_f32_e32 v217, v225, v217
	v_mul_f32_e32 v218, v225, v218
	v_mul_f32_e32 v219, v225, v219
	v_fmac_f32_e32 v12, v108, v216
	v_fmac_f32_e32 v13, v109, v217
	v_fmac_f32_e32 v14, v110, v218
	v_fmac_f32_e32 v15, v111, v219
	v_lshlrev_b32_e32 v216, 16, v40
	v_and_b32_e32 v217, 0xffff0000, v40
	v_lshlrev_b32_e32 v218, 16, v41
	v_and_b32_e32 v219, 0xffff0000, v41
	v_mul_f32_e32 v216, v225, v216
	v_mul_f32_e32 v217, v225, v217
	v_mul_f32_e32 v218, v225, v218
	v_mul_f32_e32 v219, v225, v219
	v_fmac_f32_e32 v16, v112, v216
	v_fmac_f32_e32 v17, v113, v217
	v_fmac_f32_e32 v18, v114, v218
	v_fmac_f32_e32 v19, v115, v219
	v_lshlrev_b32_e32 v216, 16, v42
	v_and_b32_e32 v217, 0xffff0000, v42
	v_lshlrev_b32_e32 v218, 16, v43
	v_and_b32_e32 v219, 0xffff0000, v43
	v_mul_f32_e32 v216, v225, v216
	v_mul_f32_e32 v217, v225, v217
	v_mul_f32_e32 v218, v225, v218
	v_mul_f32_e32 v219, v225, v219
	v_fmac_f32_e32 v20, v116, v216
	v_fmac_f32_e32 v21, v117, v217
	v_fmac_f32_e32 v22, v118, v218
	v_fmac_f32_e32 v23, v119, v219
	v_lshlrev_b32_e32 v216, 16, v44
	v_and_b32_e32 v217, 0xffff0000, v44
	v_lshlrev_b32_e32 v218, 16, v45
	v_and_b32_e32 v219, 0xffff0000, v45
	v_mul_f32_e32 v216, v225, v216
	v_mul_f32_e32 v217, v225, v217
	v_mul_f32_e32 v218, v225, v218
	v_mul_f32_e32 v219, v225, v219
	v_fmac_f32_e32 v24, v120, v216
	v_fmac_f32_e32 v25, v121, v217
	v_fmac_f32_e32 v26, v122, v218
; __device__ __forceinline__ unsigned cvt_pk_bf16(float lo, float hi) { unsigned r; asm volatile("v_cvt_pk_bf16_f32 %0, %1, %2" : "=v"(r) : "v"(lo), "v"(hi)); return r; }
; __device__ __forceinline__ float bf_lo(unsigned w) { return __uint_as_float(w << 16); }
; __device__ __forceinline__ float bf_hi(unsigned w) { return __uint_as_float(w & 0xffff0000u); }
; __device__ __forceinline__ float sumsq8(const f32x4 (&v)[8]) {
;     float s = 0.f;
; #pragma unroll
;     for (int j = 0; j < 8; ++j) s += (v[j][0] * v[j][0] + v[j][1] * v[j][1]) + (v[j][2] * v[j][2] + v[j][3] * v[j][3]);
;     return wave_sum(s);
; }
; __device__ __forceinline__ void modulate_store(const f32x4 (&v)[8], float rstd, const float* pn, const float* modr, bf16_t* orow, int lane) {
; #pragma unroll
;     for (int j = 0; j < 8; ++j) { const int col = 4 * lane + 256 * j;
;         const f32x4 g = *(const f32x4*)(pn + col), sh = *(const f32x4*)(modr + col), sc = *(const f32x4*)(modr + DM + col);
;         const f32x4 hh = v[j] * rstd * g * (sc + 1.f) + sh;
;         u32x2 w; w.x = cvt_pk_bf16(hh[0], hh[1]); w.y = cvt_pk_bf16(hh[2], hh[3]);
;         *(u32x2*)(orow + col) = w; }
; __global__ void __launch_bounds__(NWAVES * 64, 2) mk_fwd(Args args) {
;     ...
;             for (int q = 0; q < 3; ++q) { const int row = row0 + q; const float* src = row < ML ? x + (size_t)row * DM : ctx + (size_t)(row - ML) * DM; load_row_f32(src, F.lane, v[q]);
;                 const bf16_t* yr = Y + (size_t)row * DM;
; #pragma unroll
;                 for (int j = 0; j < 8; ++j) yw[q][j] = *(const u32x2*)(yr + 4 * F.lane + 256 * j); }
;     ...
;                 for (int j = 0; j < 8; ++j) { const int col = 4 * F.lane + 256 * j; const f32x4 gt = *(const f32x4*)(m0 + 2 * DM + col), pn = *(const f32x4*)(post_norm + col);
;                     const f32x4 y4 = (f32x4){bf_lo(yw[q][j].x), bf_hi(yw[q][j].x), bf_lo(yw[q][j].y), bf_hi(yw[q][j].y)};
;                     v[q][j] = v[q][j] + gt * (y4 * rsy * pn);
;                     if (lat) *(f32x4*)(args.out + (size_t)row * DM + col) = v[q][j]; }
;                 const float rstd = __builtin_amdgcn_rsqf(sumsq8(v[q]) * (1.f / DM) + EPS);
;                 modulate_store(v[q], rstd, pre_norm + DM, mod + (size_t)(9 + r) * 6144, H + (size_t)row * DM, F.lane); }
	v_fmac_f32_e32 v27, v123, v219
	v_lshlrev_b32_e32 v216, 16, v46
	v_and_b32_e32 v217, 0xffff0000, v46
	v_lshlrev_b32_e32 v218, 16, v47
	v_and_b32_e32 v219, 0xffff0000, v47
	v_mul_f32_e32 v216, v225, v216
	v_mul_f32_e32 v217, v225, v217
	v_mul_f32_e32 v218, v225, v218
	v_mul_f32_e32 v219, v225, v219
	v_fmac_f32_e32 v28, v124, v216
	v_fmac_f32_e32 v29, v125, v217
	v_fmac_f32_e32 v30, v126, v218
	v_fmac_f32_e32 v31, v127, v219
	v_mul_f32_e32 v222, v0, v0
	v_mul_f32_e32 v223, v1, v1
	v_fmac_f32_e32 v222, v2, v2
	v_fmac_f32_e32 v223, v3, v3
	v_fmac_f32_e32 v222, v4, v4
	v_fmac_f32_e32 v223, v5, v5
	v_fmac_f32_e32 v222, v6, v6
	v_fmac_f32_e32 v223, v7, v7
	v_fmac_f32_e32 v222, v8, v8
	v_fmac_f32_e32 v223, v9, v9
	v_fmac_f32_e32 v222, v10, v10
	v_fmac_f32_e32 v223, v11, v11
	v_fmac_f32_e32 v222, v12, v12
	v_fmac_f32_e32 v223, v13, v13
	v_fmac_f32_e32 v222, v14, v14
	v_fmac_f32_e32 v223, v15, v15
	v_fmac_f32_e32 v222, v16, v16
	v_fmac_f32_e32 v223, v17, v17
	v_fmac_f32_e32 v222, v18, v18
	v_fmac_f32_e32 v223, v19, v19
	v_fmac_f32_e32 v222, v20, v20
	v_fmac_f32_e32 v223, v21, v21
	v_fmac_f32_e32 v222, v22, v22
	v_fmac_f32_e32 v223, v23, v23
	v_fmac_f32_e32 v222, v24, v24
	v_fmac_f32_e32 v223, v25, v25
	v_fmac_f32_e32 v222, v26, v26
	v_fmac_f32_e32 v223, v27, v27
	v_fmac_f32_e32 v222, v28, v28
	v_fmac_f32_e32 v223, v29, v29
	v_fmac_f32_e32 v222, v30, v30
	v_fmac_f32_e32 v223, v31, v31
	v_add_f32_e32 v222, v222, v223
	s_nop 1
	v_add_f32_dpp v224, v222, v222 quad_perm:[1,0,3,2] row_mask:0xf bank_mask:0xf
	s_nop 1
	v_add_f32_dpp v224, v224, v224 quad_perm:[2,3,0,1] row_mask:0xf bank_mask:0xf
	s_nop 1
	v_add_f32_dpp v224, v224, v224 row_half_mirror row_mask:0xf bank_mask:0xf
	s_nop 1
	v_add_f32_dpp v224, v224, v224 row_mirror row_mask:0xf bank_mask:0xf
	s_nop 1
	v_readlane_b32 s40, v224, 0
	v_readlane_b32 s41, v224, 16
	v_readlane_b32 s42, v224, 32
	v_readlane_b32 s43, v224, 48
	s_nop 1
	v_mov_b32_e32 v225, s40
	v_add_f32_e32 v225, s41, v225
	v_add_f32_e32 v225, s42, v225
	v_add_f32_e32 v225, s43, v225
	v_fmamk_f32 v225, v225, 0x3a000000, v195
	v_rsq_f32_e32 v225, v225
	s_nop 0
	s_add_i32 s0, s6, 2
	s_lshl_b32 s1, s0, 12
	s_add_u32 s26, s84, s1
	s_addc_u32 s27, s85, 0
	s_add_u32 s26, s26, 0x4000000
	s_addc_u32 s27, s27, 0
	v_mul_f32_e32 v216, v225, v0
	v_mul_f32_e32 v217, v225, v1
	v_mul_f32_e32 v218, v225, v2
	v_mul_f32_e32 v219, v225, v3
	v_fma_f32 v216, v216, v128, v160
	v_fma_f32 v217, v217, v129, v161
	v_fma_f32 v218, v218, v130, v162
	v_fma_f32 v219, v219, v131, v163
	v_cvt_pk_bf16_f32 v196, v216, v217
	v_cvt_pk_bf16_f32 v197, v218, v219
	global_store_dwordx2 v194, v[196:197], s[26:27] offset:0
	v_mul_f32_e32 v216, v225, v4
	v_mul_f32_e32 v217, v225, v5
	v_mul_f32_e32 v218, v225, v6
	v_mul_f32_e32 v219, v225, v7
	v_fma_f32 v216, v216, v132, v164
	v_fma_f32 v217, v217, v133, v165
	v_fma_f32 v218, v218, v134, v166
	v_fma_f32 v219, v219, v135, v167
	v_cvt_pk_bf16_f32 v220, v216, v217
	v_cvt_pk_bf16_f32 v221, v218, v219
	global_store_dwordx2 v194, v[220:221], s[26:27] offset:512
	v_mul_f32_e32 v216, v225, v8
	v_mul_f32_e32 v217, v225, v9
	v_mul_f32_e32 v218, v225, v10
	v_mul_f32_e32 v219, v225, v11
	v_fma_f32 v216, v216, v136, v168
	v_fma_f32 v217, v217, v137, v169
	v_fma_f32 v218, v218, v138, v170
	v_fma_f32 v219, v219, v139, v171
	v_cvt_pk_bf16_f32 v196, v216, v217
	v_cvt_pk_bf16_f32 v197, v218, v219
	global_store_dwordx2 v194, v[196:197], s[26:27] offset:1024
	v_mul_f32_e32 v216, v225, v12
	v_mul_f32_e32 v217, v225, v13
	v_mul_f32_e32 v218, v225, v14
	v_mul_f32_e32 v219, v225, v15
	v_fma_f32 v216, v216, v140, v172
	v_fma_f32 v217, v217, v141, v173
	v_fma_f32 v218, v218, v142, v174
	v_fma_f32 v219, v219, v143, v175
	v_cvt_pk_bf16_f32 v220, v216, v217
	v_cvt_pk_bf16_f32 v221, v218, v219
	global_store_dwordx2 v194, v[220:221], s[26:27] offset:1536
	v_mul_f32_e32 v216, v225, v16
	v_mul_f32_e32 v217, v225, v17
	v_mul_f32_e32 v218, v225, v18
	v_mul_f32_e32 v219, v225, v19
	v_fma_f32 v216, v216, v144, v176
	v_fma_f32 v217, v217, v145, v177
	v_fma_f32 v218, v218, v146, v178
	v_fma_f32 v219, v219, v147, v179
	v_cvt_pk_bf16_f32 v196, v216, v217
	v_cvt_pk_bf16_f32 v197, v218, v219
	global_store_dwordx2 v194, v[196:197], s[26:27] offset:2048
	v_mul_f32_e32 v216, v225, v20
	v_mul_f32_e32 v217, v225, v21
	v_mul_f32_e32 v218, v225, v22
	v_mul_f32_e32 v219, v225, v23
	v_fma_f32 v216, v216, v148, v180
	v_fma_f32 v217, v217, v149, v181
	v_fma_f32 v218, v218, v150, v182
	v_fma_f32 v219, v219, v151, v183
	v_cvt_pk_bf16_f32 v220, v216, v217
	v_cvt_pk_bf16_f32 v221, v218, v219
	global_store_dwordx2 v194, v[220:221], s[26:27] offset:2560
	v_mul_f32_e32 v216, v225, v24
	v_mul_f32_e32 v217, v225, v25
	v_mul_f32_e32 v218, v225, v26
	v_mul_f32_e32 v219, v225, v27
	v_fma_f32 v216, v216, v152, v184
	v_fma_f32 v217, v217, v153, v185
	v_fma_f32 v218, v218, v154, v186
	v_fma_f32 v219, v219, v155, v187
	v_cvt_pk_bf16_f32 v196, v216, v217
	v_cvt_pk_bf16_f32 v197, v218, v219
	global_store_dwordx2 v194, v[196:197], s[26:27] offset:3072
	v_mul_f32_e32 v216, v225, v28
	v_mul_f32_e32 v217, v225, v29
	v_mul_f32_e32 v218, v225, v30
	v_mul_f32_e32 v219, v225, v31
	v_fma_f32 v216, v216, v156, v188
	v_fma_f32 v217, v217, v157, v189
	v_fma_f32 v218, v218, v158, v190
	v_fma_f32 v219, v219, v159, v191
	v_cvt_pk_bf16_f32 v220, v216, v217
	v_cvt_pk_bf16_f32 v221, v218, v219
	global_store_dwordx2 v194, v[220:221], s[26:27] offset:3584
	s_add_i32 s0, s6, 4
	s_cmp_lt_u32 s0, 0x4000
	s_cselect_b32 s10, s68, s72
	s_cselect_b32 s11, s69, s73
	s_cselect_b32 s1, 0, 0x4000
	s_sub_i32 s1, s0, s1
	s_lshl_b32 s1, s1, 13
	s_add_u32 s10, s10, s1
	s_addc_u32 s11, s11, 0
	s_add_i32 s0, s6, 4
	s_lshl_b32 s1, s0, 12
	s_add_u32 s22, s84, s1
	s_addc_u32 s23, s85, 0
	s_add_u32 s22, s22, 0x11800000
	s_addc_u32 s23, s23, 0
	global_load_dwordx4 v[0:3], v192, s[10:11] offset:0
	global_load_dwordx4 v[4:7], v192, s[10:11] offset:1024
	global_load_dwordx4 v[8:11], v192, s[10:11] offset:2048
	global_load_dwordx4 v[12:15], v192, s[10:11] offset:3072
	global_load_dwordx4 v[16:19], v193, s[10:11] offset:0
	global_load_dwordx4 v[20:23], v193, s[10:11] offset:1024
	global_load_dwordx4 v[24:27], v193, s[10:11] offset:2048
	global_load_dwordx4 v[28:31], v193, s[10:11] offset:3072
	global_load_dwordx2 v[32:33], v194, s[22:23] offset:0
	global_load_dwordx2 v[34:35], v194, s[22:23] offset:512
	global_load_dwordx2 v[36:37], v194, s[22:23] offset:1024
	global_load_dwordx2 v[38:39], v194, s[22:23] offset:1536
	global_load_dwordx2 v[40:41], v194, s[22:23] offset:2048
	global_load_dwordx2 v[42:43], v194, s[22:23] offset:2560
	global_load_dwordx2 v[44:45], v194, s[22:23] offset:3072
	global_load_dwordx2 v[46:47], v194, s[22:23] offset:3584
	s_add_i32 s0, s6, 3
	s_add_i32 s0, s6, 3
	s_lshr_b32 s8, s0, 11
	s_cmp_lt_u32 s0, 0x4000
	s_cselect_b32 s8, s8, 8
	s_cmp_eq_u32 s8, s7
	s_cbranch_scc1 .Lp6_np3
; __device__ __forceinline__ unsigned cvt_pk_bf16(float lo, float hi) { unsigned r; asm volatile("v_cvt_pk_bf16_f32 %0, %1, %2" : "=v"(r) : "v"(lo), "v"(hi)); return r; }
; __device__ __forceinline__ void modulate_store(const f32x4 (&v)[8], float rstd, const float* pn, const float* modr, bf16_t* orow, int lane) {
; #pragma unroll
;     for (int j = 0; j < 8; ++j) { const int col = 4 * lane + 256 * j;
;         const f32x4 g = *(const f32x4*)(pn + col), sh = *(const f32x4*)(modr + col), sc = *(const f32x4*)(modr + DM + col);
;         const f32x4 hh = v[j] * rstd * g * (sc + 1.f) + sh;
;         u32x2 w; w.x = cvt_pk_bf16(hh[0], hh[1]); w.y = cvt_pk_bf16(hh[2], hh[3]);
;         *(u32x2*)(orow + col) = w; }
; __global__ void __launch_bounds__(NWAVES * 64, 2) mk_fwd(Args args) {
;     ...
;                 const float* m0 = mod + (size_t)r * 6144;
; #pragma unroll
;                 for (int j = 0; j < 8; ++j) { const int col = 4 * F.lane + 256 * j; const f32x4 gt = *(const f32x4*)(m0 + 2 * DM + col), pn = *(const f32x4*)(post_norm + col);
	s_mov_b32 s7, s8
	s_add_i32 s1, s8, 9
	s_mul_i32 s1, s1, 0x6000
	s_add_u32 s44, s84, s1
	s_addc_u32 s45, s85, 0
	s_add_u32 s44, s44, 0x2000
	s_addc_u32 s45, s45, 0
	s_add_i32 s1, s8, 9
	s_mul_i32 s1, s1, 0x6000
	s_add_u32 s36, s84, s1
	s_addc_u32 s37, s85, 0
	s_add_u32 s38, s80, 0x2000
	s_addc_u32 s39, s81, 0
	s_mul_i32 s1, s8, 0x6000
	s_add_u32 s34, s84, s1
	s_addc_u32 s35, s85, 0
	s_add_u32 s34, s34, 0x4000
	s_addc_u32 s35, s35, 0
	global_load_dwordx4 v[96:99], v192, s[34:35] offset:0
	global_load_dwordx4 v[200:203], v192, s[82:83] offset:0
	global_load_dwordx4 v[100:103], v192, s[34:35] offset:1024
	global_load_dwordx4 v[204:207], v192, s[82:83] offset:1024
	global_load_dwordx4 v[104:107], v192, s[34:35] offset:2048
	global_load_dwordx4 v[208:211], v192, s[82:83] offset:2048
	global_load_dwordx4 v[108:111], v192, s[34:35] offset:3072
	global_load_dwordx4 v[212:215], v192, s[82:83] offset:3072
	s_waitcnt vmcnt(0)
	v_mul_f32_e32 v96, v96, v200
	v_mul_f32_e32 v97, v97, v201
	v_mul_f32_e32 v98, v98, v202
	v_mul_f32_e32 v99, v99, v203
	v_mul_f32_e32 v100, v100, v204
	v_mul_f32_e32 v101, v101, v205
	v_mul_f32_e32 v102, v102, v206
	v_mul_f32_e32 v103, v103, v207
	v_mul_f32_e32 v104, v104, v208
	v_mul_f32_e32 v105, v105, v209
	v_mul_f32_e32 v106, v106, v210
	v_mul_f32_e32 v107, v107, v211
	v_mul_f32_e32 v108, v108, v212
	v_mul_f32_e32 v109, v109, v213
	v_mul_f32_e32 v110, v110, v214
	v_mul_f32_e32 v111, v111, v215
	global_load_dwordx4 v[128:131], v192, s[38:39] offset:0
	global_load_dwordx4 v[200:203], v192, s[44:45] offset:0
	global_load_dwordx4 v[160:163], v192, s[36:37] offset:0
	global_load_dwordx4 v[132:135], v192, s[38:39] offset:1024
	global_load_dwordx4 v[204:207], v192, s[44:45] offset:1024
	global_load_dwordx4 v[164:167], v192, s[36:37] offset:1024
	global_load_dwordx4 v[136:139], v192, s[38:39] offset:2048
	global_load_dwordx4 v[208:211], v192, s[44:45] offset:2048
	global_load_dwordx4 v[168:171], v192, s[36:37] offset:2048
	global_load_dwordx4 v[140:143], v192, s[38:39] offset:3072
	global_load_dwordx4 v[212:215], v192, s[44:45] offset:3072
	global_load_dwordx4 v[172:175], v192, s[36:37] offset:3072
	s_waitcnt vmcnt(0)
	v_add_f32_e32 v200, 1.0, v200
	v_add_f32_e32 v201, 1.0, v201
	v_add_f32_e32 v202, 1.0, v202
	v_add_f32_e32 v203, 1.0, v203
	v_mul_f32_e32 v128, v128, v200
	v_mul_f32_e32 v129, v129, v201
	v_mul_f32_e32 v130, v130, v202
	v_mul_f32_e32 v131, v131, v203
	v_add_f32_e32 v204, 1.0, v204
	v_add_f32_e32 v205, 1.0, v205
	v_add_f32_e32 v206, 1.0, v206
	v_add_f32_e32 v207, 1.0, v207
	v_mul_f32_e32 v132, v132, v204
	v_mul_f32_e32 v133, v133, v205
	v_mul_f32_e32 v134, v134, v206
	v_mul_f32_e32 v135, v135, v207
	v_add_f32_e32 v208, 1.0, v208
	v_add_f32_e32 v209, 1.0, v209
	v_add_f32_e32 v210, 1.0, v210
	v_add_f32_e32 v211, 1.0, v211
	v_mul_f32_e32 v136, v136, v208
	v_mul_f32_e32 v137, v137, v209
	v_mul_f32_e32 v138, v138, v210
	v_mul_f32_e32 v139, v139, v211
	v_add_f32_e32 v212, 1.0, v212
	v_add_f32_e32 v213, 1.0, v213
	v_add_f32_e32 v214, 1.0, v214
	v_add_f32_e32 v215, 1.0, v215
	v_mul_f32_e32 v140, v140, v212
	v_mul_f32_e32 v141, v141, v213
	v_mul_f32_e32 v142, v142, v214
	v_mul_f32_e32 v143, v143, v215
	global_load_dwordx4 v[112:115], v193, s[34:35] offset:0
	global_load_dwordx4 v[200:203], v193, s[82:83] offset:0
	global_load_dwordx4 v[116:119], v193, s[34:35] offset:1024
	global_load_dwordx4 v[204:207], v193, s[82:83] offset:1024
	global_load_dwordx4 v[120:123], v193, s[34:35] offset:2048
	global_load_dwordx4 v[208:211], v193, s[82:83] offset:2048
	global_load_dwordx4 v[124:127], v193, s[34:35] offset:3072
	global_load_dwordx4 v[212:215], v193, s[82:83] offset:3072
	s_waitcnt vmcnt(0)
	v_mul_f32_e32 v112, v112, v200
	v_mul_f32_e32 v113, v113, v201
	v_mul_f32_e32 v114, v114, v202
	v_mul_f32_e32 v115, v115, v203
	v_mul_f32_e32 v116, v116, v204
	v_mul_f32_e32 v117, v117, v205
	v_mul_f32_e32 v118, v118, v206
	v_mul_f32_e32 v119, v119, v207
	v_mul_f32_e32 v120, v120, v208
	v_mul_f32_e32 v121, v121, v209
	v_mul_f32_e32 v122, v122, v210
	v_mul_f32_e32 v123, v123, v211
	v_mul_f32_e32 v124, v124, v212
	v_mul_f32_e32 v125, v125, v213
	v_mul_f32_e32 v126, v126, v214
	v_mul_f32_e32 v127, v127, v215
	global_load_dwordx4 v[144:147], v193, s[38:39] offset:0
	global_load_dwordx4 v[200:203], v193, s[44:45] offset:0
	global_load_dwordx4 v[176:179], v193, s[36:37] offset:0
	global_load_dwordx4 v[148:151], v193, s[38:39] offset:1024
	global_load_dwordx4 v[204:207], v193, s[44:45] offset:1024
	global_load_dwordx4 v[180:183], v193, s[36:37] offset:1024
	global_load_dwordx4 v[152:155], v193, s[38:39] offset:2048
	global_load_dwordx4 v[208:211], v193, s[44:45] offset:2048
	global_load_dwordx4 v[184:187], v193, s[36:37] offset:2048
	global_load_dwordx4 v[156:159], v193, s[38:39] offset:3072
	global_load_dwordx4 v[212:215], v193, s[44:45] offset:3072
	global_load_dwordx4 v[188:191], v193, s[36:37] offset:3072
	s_waitcnt vmcnt(0)
	v_add_f32_e32 v200, 1.0, v200
	v_add_f32_e32 v201, 1.0, v201
	v_add_f32_e32 v202, 1.0, v202
	v_add_f32_e32 v203, 1.0, v203
	v_mul_f32_e32 v144, v144, v200
	v_mul_f32_e32 v145, v145, v201
	v_mul_f32_e32 v146, v146, v202
	v_mul_f32_e32 v147, v147, v203
	v_add_f32_e32 v204, 1.0, v204
	v_add_f32_e32 v205, 1.0, v205
	v_add_f32_e32 v206, 1.0, v206
	v_add_f32_e32 v207, 1.0, v207
	v_mul_f32_e32 v148, v148, v204
	v_mul_f32_e32 v149, v149, v205
	v_mul_f32_e32 v150, v150, v206
	v_mul_f32_e32 v151, v151, v207
	v_add_f32_e32 v208, 1.0, v208
	v_add_f32_e32 v209, 1.0, v209
	v_add_f32_e32 v210, 1.0, v210
	v_add_f32_e32 v211, 1.0, v211
	v_mul_f32_e32 v152, v152, v208
	v_mul_f32_e32 v153, v153, v209
	v_mul_f32_e32 v154, v154, v210
	v_mul_f32_e32 v155, v155, v211
	v_add_f32_e32 v212, 1.0, v212
	v_add_f32_e32 v213, 1.0, v213
	v_add_f32_e32 v214, 1.0, v214
	v_add_f32_e32 v215, 1.0, v215
	v_mul_f32_e32 v156, v156, v212
	v_mul_f32_e32 v157, v157, v213
	v_mul_f32_e32 v158, v158, v214
	v_mul_f32_e32 v159, v159, v215
; __device__ __forceinline__ float bf_lo(unsigned w) { return __uint_as_float(w << 16); }
; __device__ __forceinline__ float bf_hi(unsigned w) { return __uint_as_float(w & 0xffff0000u); }
; __global__ void __launch_bounds__(NWAVES * 64, 2) mk_fwd(Args args) {
;     ...
;             for (int q = 0; q < 3; ++q) { const int row = row0 + q; const bool lat = row < ML; const int r = lat ? row / SEQ : 8;
;                 float sy = 0.f;
; #pragma unroll
;                 for (int j = 0; j < 8; ++j) { const float a = bf_lo(yw[q][j].x), b = bf_hi(yw[q][j].x), c2 = bf_lo(yw[q][j].y), d = bf_hi(yw[q][j].y); sy += (a * a + b * b) + (c2 * c2 + d * d); }
;                 const float rsy = __builtin_amdgcn_rsqf(wave_sum(sy) * (1.f / DM) + EPS);
;                 const float* m0 = mod + (size_t)r * 6144;
; #pragma unroll
;                 for (int j = 0; j < 8; ++j) { const int col = 4 * F.lane + 256 * j; const f32x4 gt = *(const f32x4*)(m0 + 2 * DM + col), pn = *(const f32x4*)(post_norm + col);
;                     const f32x4 y4 = (f32x4){bf_lo(yw[q][j].x), bf_hi(yw[q][j].x), bf_lo(yw[q][j].y), bf_hi(yw[q][j].y)};
;                     v[q][j] = v[q][j] + gt * (y4 * rsy * pn);
;                     if (lat) *(f32x4*)(args.out + (size_t)row * DM + col) = v[q][j]; }
;                 const float rstd = __builtin_amdgcn_rsqf(sumsq8(v[q]) * (1.f / DM) + EPS);
.Lp6_np3:
	s_waitcnt vmcnt(24)
	v_lshlrev_b32_e32 v216, 16, v80
	v_and_b32_e32 v217, 0xffff0000, v80
	v_lshlrev_b32_e32 v218, 16, v81
	v_and_b32_e32 v219, 0xffff0000, v81
	v_mul_f32_e32 v222, v216, v216
	v_mul_f32_e32 v223, v217, v217
	v_fmac_f32_e32 v222, v218, v218
	v_fmac_f32_e32 v223, v219, v219
	v_lshlrev_b32_e32 v216, 16, v82
	v_and_b32_e32 v217, 0xffff0000, v82
	v_lshlrev_b32_e32 v218, 16, v83
	v_and_b32_e32 v219, 0xffff0000, v83
	v_fmac_f32_e32 v222, v216, v216
	v_fmac_f32_e32 v223, v217, v217
	v_fmac_f32_e32 v222, v218, v218
	v_fmac_f32_e32 v223, v219, v219
	v_lshlrev_b32_e32 v216, 16, v84
	v_and_b32_e32 v217, 0xffff0000, v84
	v_lshlrev_b32_e32 v218, 16, v85
	v_and_b32_e32 v219, 0xffff0000, v85
	v_fmac_f32_e32 v222, v216, v216
	v_fmac_f32_e32 v223, v217, v217
	v_fmac_f32_e32 v222, v218, v218
	v_fmac_f32_e32 v223, v219, v219
	v_lshlrev_b32_e32 v216, 16, v86
	v_and_b32_e32 v217, 0xffff0000, v86
	v_lshlrev_b32_e32 v218, 16, v87
	v_and_b32_e32 v219, 0xffff0000, v87
	v_fmac_f32_e32 v222, v216, v216
	v_fmac_f32_e32 v223, v217, v217
	v_fmac_f32_e32 v222, v218, v218
	v_fmac_f32_e32 v223, v219, v219
	v_lshlrev_b32_e32 v216, 16, v88
	v_and_b32_e32 v217, 0xffff0000, v88
	v_lshlrev_b32_e32 v218, 16, v89
	v_and_b32_e32 v219, 0xffff0000, v89
	v_fmac_f32_e32 v222, v216, v216
	v_fmac_f32_e32 v223, v217, v217
	v_fmac_f32_e32 v222, v218, v218
	v_fmac_f32_e32 v223, v219, v219
	v_lshlrev_b32_e32 v216, 16, v90
	v_and_b32_e32 v217, 0xffff0000, v90
	v_lshlrev_b32_e32 v218, 16, v91
	v_and_b32_e32 v219, 0xffff0000, v91
	v_fmac_f32_e32 v222, v216, v216
	v_fmac_f32_e32 v223, v217, v217
	v_fmac_f32_e32 v222, v218, v218
	v_fmac_f32_e32 v223, v219, v219
	v_lshlrev_b32_e32 v216, 16, v92
	v_and_b32_e32 v217, 0xffff0000, v92
	v_lshlrev_b32_e32 v218, 16, v93
	v_and_b32_e32 v219, 0xffff0000, v93
	v_fmac_f32_e32 v222, v216, v216
	v_fmac_f32_e32 v223, v217, v217
	v_fmac_f32_e32 v222, v218, v218
	v_fmac_f32_e32 v223, v219, v219
	v_lshlrev_b32_e32 v216, 16, v94
	v_and_b32_e32 v217, 0xffff0000, v94
	v_lshlrev_b32_e32 v218, 16, v95
	v_and_b32_e32 v219, 0xffff0000, v95
	v_fmac_f32_e32 v222, v216, v216
	v_fmac_f32_e32 v223, v217, v217
	v_fmac_f32_e32 v222, v218, v218
	v_fmac_f32_e32 v223, v219, v219
	v_add_f32_e32 v222, v222, v223
	s_nop 1
	v_add_f32_dpp v224, v222, v222 quad_perm:[1,0,3,2] row_mask:0xf bank_mask:0xf
	s_nop 1
	v_add_f32_dpp v224, v224, v224 quad_perm:[2,3,0,1] row_mask:0xf bank_mask:0xf
	s_nop 1
	v_add_f32_dpp v224, v224, v224 row_half_mirror row_mask:0xf bank_mask:0xf
	s_nop 1
	v_add_f32_dpp v224, v224, v224 row_mirror row_mask:0xf bank_mask:0xf
	s_nop 1
	v_readlane_b32 s40, v224, 0
	v_readlane_b32 s41, v224, 16
	v_readlane_b32 s42, v224, 32
	v_readlane_b32 s43, v224, 48
	s_nop 1
	v_mov_b32_e32 v225, s40
	v_add_f32_e32 v225, s41, v225
	v_add_f32_e32 v225, s42, v225
	v_add_f32_e32 v225, s43, v225
	v_fmamk_f32 v225, v225, 0x3a000000, v195
	v_rsq_f32_e32 v225, v225
	s_nop 0
	v_lshlrev_b32_e32 v216, 16, v80
	v_and_b32_e32 v217, 0xffff0000, v80
	v_lshlrev_b32_e32 v218, 16, v81
	v_and_b32_e32 v219, 0xffff0000, v81
	v_mul_f32_e32 v216, v225, v216
	v_mul_f32_e32 v217, v225, v217
	v_mul_f32_e32 v218, v225, v218
	v_mul_f32_e32 v219, v225, v219
	v_fmac_f32_e32 v48, v96, v216
	v_fmac_f32_e32 v49, v97, v217
	v_fmac_f32_e32 v50, v98, v218
	v_fmac_f32_e32 v51, v99, v219
	v_lshlrev_b32_e32 v216, 16, v82
	v_and_b32_e32 v217, 0xffff0000, v82
	v_lshlrev_b32_e32 v218, 16, v83
	v_and_b32_e32 v219, 0xffff0000, v83
	v_mul_f32_e32 v216, v225, v216
	v_mul_f32_e32 v217, v225, v217
	v_mul_f32_e32 v218, v225, v218
	v_mul_f32_e32 v219, v225, v219
	v_fmac_f32_e32 v52, v100, v216
	v_fmac_f32_e32 v53, v101, v217
	v_fmac_f32_e32 v54, v102, v218
	v_fmac_f32_e32 v55, v103, v219
	v_lshlrev_b32_e32 v216, 16, v84
	v_and_b32_e32 v217, 0xffff0000, v84
	v_lshlrev_b32_e32 v218, 16, v85
	v_and_b32_e32 v219, 0xffff0000, v85
	v_mul_f32_e32 v216, v225, v216
	v_mul_f32_e32 v217, v225, v217
	v_mul_f32_e32 v218, v225, v218
	v_mul_f32_e32 v219, v225, v219
	v_fmac_f32_e32 v56, v104, v216
	v_fmac_f32_e32 v57, v105, v217
	v_fmac_f32_e32 v58, v106, v218
	v_fmac_f32_e32 v59, v107, v219
	v_lshlrev_b32_e32 v216, 16, v86
	v_and_b32_e32 v217, 0xffff0000, v86
	v_lshlrev_b32_e32 v218, 16, v87
	v_and_b32_e32 v219, 0xffff0000, v87
	v_mul_f32_e32 v216, v225, v216
	v_mul_f32_e32 v217, v225, v217
	v_mul_f32_e32 v218, v225, v218
	v_mul_f32_e32 v219, v225, v219
	v_fmac_f32_e32 v60, v108, v216
	v_fmac_f32_e32 v61, v109, v217
	v_fmac_f32_e32 v62, v110, v218
	v_fmac_f32_e32 v63, v111, v219
	v_lshlrev_b32_e32 v216, 16, v88
	v_and_b32_e32 v217, 0xffff0000, v88
	v_lshlrev_b32_e32 v218, 16, v89
	v_and_b32_e32 v219, 0xffff0000, v89
	v_mul_f32_e32 v216, v225, v216
	v_mul_f32_e32 v217, v225, v217
	v_mul_f32_e32 v218, v225, v218
	v_mul_f32_e32 v219, v225, v219
	v_fmac_f32_e32 v64, v112, v216
	v_fmac_f32_e32 v65, v113, v217
	v_fmac_f32_e32 v66, v114, v218
	v_fmac_f32_e32 v67, v115, v219
	v_lshlrev_b32_e32 v216, 16, v90
	v_and_b32_e32 v217, 0xffff0000, v90
	v_lshlrev_b32_e32 v218, 16, v91
	v_and_b32_e32 v219, 0xffff0000, v91
	v_mul_f32_e32 v216, v225, v216
	v_mul_f32_e32 v217, v225, v217
	v_mul_f32_e32 v218, v225, v218
	v_mul_f32_e32 v219, v225, v219
	v_fmac_f32_e32 v68, v116, v216
	v_fmac_f32_e32 v69, v117, v217
	v_fmac_f32_e32 v70, v118, v218
	v_fmac_f32_e32 v71, v119, v219
	v_lshlrev_b32_e32 v216, 16, v92
	v_and_b32_e32 v217, 0xffff0000, v92
	v_lshlrev_b32_e32 v218, 16, v93
	v_and_b32_e32 v219, 0xffff0000, v93
	v_mul_f32_e32 v216, v225, v216
	v_mul_f32_e32 v217, v225, v217
	v_mul_f32_e32 v218, v225, v218
	v_mul_f32_e32 v219, v225, v219
	v_fmac_f32_e32 v72, v120, v216
	v_fmac_f32_e32 v73, v121, v217
	v_fmac_f32_e32 v74, v122, v218
; __device__ __forceinline__ unsigned cvt_pk_bf16(float lo, float hi) { unsigned r; asm volatile("v_cvt_pk_bf16_f32 %0, %1, %2" : "=v"(r) : "v"(lo), "v"(hi)); return r; }
; __device__ __forceinline__ float bf_lo(unsigned w) { return __uint_as_float(w << 16); }
; __device__ __forceinline__ float bf_hi(unsigned w) { return __uint_as_float(w & 0xffff0000u); }
; __device__ __forceinline__ float sumsq8(const f32x4 (&v)[8]) {
;     float s = 0.f;
; #pragma unroll
;     for (int j = 0; j < 8; ++j) s += (v[j][0] * v[j][0] + v[j][1] * v[j][1]) + (v[j][2] * v[j][2] + v[j][3] * v[j][3]);
;     return wave_sum(s);
; }
; __device__ __forceinline__ void modulate_store(const f32x4 (&v)[8], float rstd, const float* pn, const float* modr, bf16_t* orow, int lane) {
; #pragma unroll
;     for (int j = 0; j < 8; ++j) { const int col = 4 * lane + 256 * j;
;         const f32x4 g = *(const f32x4*)(pn + col), sh = *(const f32x4*)(modr + col), sc = *(const f32x4*)(modr + DM + col);
;         const f32x4 hh = v[j] * rstd * g * (sc + 1.f) + sh;
;         u32x2 w; w.x = cvt_pk_bf16(hh[0], hh[1]); w.y = cvt_pk_bf16(hh[2], hh[3]);
;         *(u32x2*)(orow + col) = w; }
; __global__ void __launch_bounds__(NWAVES * 64, 2) mk_fwd(Args args) {
;     ...
;             for (int q = 0; q < 3; ++q) { const int row = row0 + q; const float* src = row < ML ? x + (size_t)row * DM : ctx + (size_t)(row - ML) * DM; load_row_f32(src, F.lane, v[q]);
;                 const bf16_t* yr = Y + (size_t)row * DM;
; #pragma unroll
;                 for (int j = 0; j < 8; ++j) yw[q][j] = *(const u32x2*)(yr + 4 * F.lane + 256 * j); }
;     ...
;                 for (int j = 0; j < 8; ++j) { const int col = 4 * F.lane + 256 * j; const f32x4 gt = *(const f32x4*)(m0 + 2 * DM + col), pn = *(const f32x4*)(post_norm + col);
;                     const f32x4 y4 = (f32x4){bf_lo(yw[q][j].x), bf_hi(yw[q][j].x), bf_lo(yw[q][j].y), bf_hi(yw[q][j].y)};
;                     v[q][j] = v[q][j] + gt * (y4 * rsy * pn);
;                     if (lat) *(f32x4*)(args.out + (size_t)row * DM + col) = v[q][j]; }
;                 const float rstd = __builtin_amdgcn_rsqf(sumsq8(v[q]) * (1.f / DM) + EPS);
;                 modulate_store(v[q], rstd, pre_norm + DM, mod + (size_t)(9 + r) * 6144, H + (size_t)row * DM, F.lane); }
	v_fmac_f32_e32 v75, v123, v219
	v_lshlrev_b32_e32 v216, 16, v94
	v_and_b32_e32 v217, 0xffff0000, v94
	v_lshlrev_b32_e32 v218, 16, v95
	v_and_b32_e32 v219, 0xffff0000, v95
	v_mul_f32_e32 v216, v225, v216
	v_mul_f32_e32 v217, v225, v217
	v_mul_f32_e32 v218, v225, v218
	v_mul_f32_e32 v219, v225, v219
	v_fmac_f32_e32 v76, v124, v216
	v_fmac_f32_e32 v77, v125, v217
	v_fmac_f32_e32 v78, v126, v218
	v_fmac_f32_e32 v79, v127, v219
	v_mul_f32_e32 v222, v48, v48
	v_mul_f32_e32 v223, v49, v49
	v_fmac_f32_e32 v222, v50, v50
	v_fmac_f32_e32 v223, v51, v51
	v_fmac_f32_e32 v222, v52, v52
	v_fmac_f32_e32 v223, v53, v53
	v_fmac_f32_e32 v222, v54, v54
	v_fmac_f32_e32 v223, v55, v55
	v_fmac_f32_e32 v222, v56, v56
	v_fmac_f32_e32 v223, v57, v57
	v_fmac_f32_e32 v222, v58, v58
	v_fmac_f32_e32 v223, v59, v59
	v_fmac_f32_e32 v222, v60, v60
	v_fmac_f32_e32 v223, v61, v61
	v_fmac_f32_e32 v222, v62, v62
	v_fmac_f32_e32 v223, v63, v63
	v_fmac_f32_e32 v222, v64, v64
	v_fmac_f32_e32 v223, v65, v65
	v_fmac_f32_e32 v222, v66, v66
	v_fmac_f32_e32 v223, v67, v67
	v_fmac_f32_e32 v222, v68, v68
	v_fmac_f32_e32 v223, v69, v69
	v_fmac_f32_e32 v222, v70, v70
	v_fmac_f32_e32 v223, v71, v71
	v_fmac_f32_e32 v222, v72, v72
	v_fmac_f32_e32 v223, v73, v73
	v_fmac_f32_e32 v222, v74, v74
	v_fmac_f32_e32 v223, v75, v75
	v_fmac_f32_e32 v222, v76, v76
	v_fmac_f32_e32 v223, v77, v77
	v_fmac_f32_e32 v222, v78, v78
	v_fmac_f32_e32 v223, v79, v79
	v_add_f32_e32 v222, v222, v223
	s_nop 1
	v_add_f32_dpp v224, v222, v222 quad_perm:[1,0,3,2] row_mask:0xf bank_mask:0xf
	s_nop 1
	v_add_f32_dpp v224, v224, v224 quad_perm:[2,3,0,1] row_mask:0xf bank_mask:0xf
	s_nop 1
	v_add_f32_dpp v224, v224, v224 row_half_mirror row_mask:0xf bank_mask:0xf
	s_nop 1
	v_add_f32_dpp v224, v224, v224 row_mirror row_mask:0xf bank_mask:0xf
	s_nop 1
	v_readlane_b32 s40, v224, 0
	v_readlane_b32 s41, v224, 16
	v_readlane_b32 s42, v224, 32
	v_readlane_b32 s43, v224, 48
	s_nop 1
	v_mov_b32_e32 v225, s40
	v_add_f32_e32 v225, s41, v225
	v_add_f32_e32 v225, s42, v225
	v_add_f32_e32 v225, s43, v225
	v_fmamk_f32 v225, v225, 0x3a000000, v195
	v_rsq_f32_e32 v225, v225
	s_nop 0
	s_add_i32 s0, s6, 3
	s_lshl_b32 s1, s0, 12
	s_add_u32 s26, s84, s1
	s_addc_u32 s27, s85, 0
	s_add_u32 s26, s26, 0x4000000
	s_addc_u32 s27, s27, 0
	v_mul_f32_e32 v216, v225, v48
	v_mul_f32_e32 v217, v225, v49
	v_mul_f32_e32 v218, v225, v50
	v_mul_f32_e32 v219, v225, v51
	v_fma_f32 v216, v216, v128, v160
	v_fma_f32 v217, v217, v129, v161
	v_fma_f32 v218, v218, v130, v162
	v_fma_f32 v219, v219, v131, v163
	v_cvt_pk_bf16_f32 v196, v216, v217
	v_cvt_pk_bf16_f32 v197, v218, v219
	global_store_dwordx2 v194, v[196:197], s[26:27] offset:0
	v_mul_f32_e32 v216, v225, v52
	v_mul_f32_e32 v217, v225, v53
	v_mul_f32_e32 v218, v225, v54
	v_mul_f32_e32 v219, v225, v55
	v_fma_f32 v216, v216, v132, v164
	v_fma_f32 v217, v217, v133, v165
	v_fma_f32 v218, v218, v134, v166
	v_fma_f32 v219, v219, v135, v167
	v_cvt_pk_bf16_f32 v220, v216, v217
	v_cvt_pk_bf16_f32 v221, v218, v219
	global_store_dwordx2 v194, v[220:221], s[26:27] offset:512
	v_mul_f32_e32 v216, v225, v56
	v_mul_f32_e32 v217, v225, v57
	v_mul_f32_e32 v218, v225, v58
	v_mul_f32_e32 v219, v225, v59
	v_fma_f32 v216, v216, v136, v168
	v_fma_f32 v217, v217, v137, v169
	v_fma_f32 v218, v218, v138, v170
	v_fma_f32 v219, v219, v139, v171
	v_cvt_pk_bf16_f32 v196, v216, v217
	v_cvt_pk_bf16_f32 v197, v218, v219
	global_store_dwordx2 v194, v[196:197], s[26:27] offset:1024
	v_mul_f32_e32 v216, v225, v60
	v_mul_f32_e32 v217, v225, v61
	v_mul_f32_e32 v218, v225, v62
	v_mul_f32_e32 v219, v225, v63
	v_fma_f32 v216, v216, v140, v172
	v_fma_f32 v217, v217, v141, v173
	v_fma_f32 v218, v218, v142, v174
	v_fma_f32 v219, v219, v143, v175
	v_cvt_pk_bf16_f32 v220, v216, v217
	v_cvt_pk_bf16_f32 v221, v218, v219
	global_store_dwordx2 v194, v[220:221], s[26:27] offset:1536
	v_mul_f32_e32 v216, v225, v64
	v_mul_f32_e32 v217, v225, v65
	v_mul_f32_e32 v218, v225, v66
	v_mul_f32_e32 v219, v225, v67
	v_fma_f32 v216, v216, v144, v176
	v_fma_f32 v217, v217, v145, v177
	v_fma_f32 v218, v218, v146, v178
	v_fma_f32 v219, v219, v147, v179
	v_cvt_pk_bf16_f32 v196, v216, v217
	v_cvt_pk_bf16_f32 v197, v218, v219
	global_store_dwordx2 v194, v[196:197], s[26:27] offset:2048
	v_mul_f32_e32 v216, v225, v68
	v_mul_f32_e32 v217, v225, v69
	v_mul_f32_e32 v218, v225, v70
	v_mul_f32_e32 v219, v225, v71
	v_fma_f32 v216, v216, v148, v180
	v_fma_f32 v217, v217, v149, v181
	v_fma_f32 v218, v218, v150, v182
	v_fma_f32 v219, v219, v151, v183
	v_cvt_pk_bf16_f32 v220, v216, v217
	v_cvt_pk_bf16_f32 v221, v218, v219
	global_store_dwordx2 v194, v[220:221], s[26:27] offset:2560
	v_mul_f32_e32 v216, v225, v72
	v_mul_f32_e32 v217, v225, v73
	v_mul_f32_e32 v218, v225, v74
	v_mul_f32_e32 v219, v225, v75
	v_fma_f32 v216, v216, v152, v184
	v_fma_f32 v217, v217, v153, v185
	v_fma_f32 v218, v218, v154, v186
	v_fma_f32 v219, v219, v155, v187
	v_cvt_pk_bf16_f32 v196, v216, v217
	v_cvt_pk_bf16_f32 v197, v218, v219
	global_store_dwordx2 v194, v[196:197], s[26:27] offset:3072
	v_mul_f32_e32 v216, v225, v76
	v_mul_f32_e32 v217, v225, v77
	v_mul_f32_e32 v218, v225, v78
	v_mul_f32_e32 v219, v225, v79
	v_fma_f32 v216, v216, v156, v188
	v_fma_f32 v217, v217, v157, v189
	v_fma_f32 v218, v218, v158, v190
	v_fma_f32 v219, v219, v159, v191
	v_cvt_pk_bf16_f32 v220, v216, v217
	v_cvt_pk_bf16_f32 v221, v218, v219
	global_store_dwordx2 v194, v[220:221], s[26:27] offset:3584
	s_add_i32 s0, s6, 5
	s_cmp_lt_u32 s0, 0x4000
	s_cselect_b32 s10, s68, s72
	s_cselect_b32 s11, s69, s73
	s_cselect_b32 s1, 0, 0x4000
	s_sub_i32 s1, s0, s1
	s_lshl_b32 s1, s1, 13
	s_add_u32 s10, s10, s1
	s_addc_u32 s11, s11, 0
	s_add_i32 s0, s6, 5
	s_lshl_b32 s1, s0, 12
	s_add_u32 s22, s84, s1
	s_addc_u32 s23, s85, 0
	s_add_u32 s22, s22, 0x11800000
	s_addc_u32 s23, s23, 0
	global_load_dwordx4 v[48:51], v192, s[10:11] offset:0
	global_load_dwordx4 v[52:55], v192, s[10:11] offset:1024
	global_load_dwordx4 v[56:59], v192, s[10:11] offset:2048
	global_load_dwordx4 v[60:63], v192, s[10:11] offset:3072
	global_load_dwordx4 v[64:67], v193, s[10:11] offset:0
	global_load_dwordx4 v[68:71], v193, s[10:11] offset:1024
	global_load_dwordx4 v[72:75], v193, s[10:11] offset:2048
	global_load_dwordx4 v[76:79], v193, s[10:11] offset:3072
	global_load_dwordx2 v[80:81], v194, s[22:23] offset:0
	global_load_dwordx2 v[82:83], v194, s[22:23] offset:512
	global_load_dwordx2 v[84:85], v194, s[22:23] offset:1024
	global_load_dwordx2 v[86:87], v194, s[22:23] offset:1536
	global_load_dwordx2 v[88:89], v194, s[22:23] offset:2048
	global_load_dwordx2 v[90:91], v194, s[22:23] offset:2560
	global_load_dwordx2 v[92:93], v194, s[22:23] offset:3072
	global_load_dwordx2 v[94:95], v194, s[22:23] offset:3584
	s_add_i32 s0, s6, 4
	s_add_i32 s0, s6, 4
	s_lshr_b32 s8, s0, 11
	s_cmp_lt_u32 s0, 0x4000
	s_cselect_b32 s8, s8, 8
	s_cmp_eq_u32 s8, s7
	s_cbranch_scc1 .Lp6_np4
; __device__ __forceinline__ unsigned cvt_pk_bf16(float lo, float hi) { unsigned r; asm volatile("v_cvt_pk_bf16_f32 %0, %1, %2" : "=v"(r) : "v"(lo), "v"(hi)); return r; }
; __device__ __forceinline__ void modulate_store(const f32x4 (&v)[8], float rstd, const float* pn, const float* modr, bf16_t* orow, int lane) {
; #pragma unroll
;     for (int j = 0; j < 8; ++j) { const int col = 4 * lane + 256 * j;
;         const f32x4 g = *(const f32x4*)(pn + col), sh = *(const f32x4*)(modr + col), sc = *(const f32x4*)(modr + DM + col);
;         const f32x4 hh = v[j] * rstd * g * (sc + 1.f) + sh;
;         u32x2 w; w.x = cvt_pk_bf16(hh[0], hh[1]); w.y = cvt_pk_bf16(hh[2], hh[3]);
;         *(u32x2*)(orow + col) = w; }
; __global__ void __launch_bounds__(NWAVES * 64, 2) mk_fwd(Args args) {
;     ...
;                 const float* m0 = mod + (size_t)r * 6144;
; #pragma unroll
;                 for (int j = 0; j < 8; ++j) { const int col = 4 * F.lane + 256 * j; const f32x4 gt = *(const f32x4*)(m0 + 2 * DM + col), pn = *(const f32x4*)(post_norm + col);
	s_mov_b32 s7, s8
	s_add_i32 s1, s8, 9
	s_mul_i32 s1, s1, 0x6000
	s_add_u32 s44, s84, s1
	s_addc_u32 s45, s85, 0
	s_add_u32 s44, s44, 0x2000
	s_addc_u32 s45, s45, 0
	s_add_i32 s1, s8, 9
	s_mul_i32 s1, s1, 0x6000
	s_add_u32 s36, s84, s1
	s_addc_u32 s37, s85, 0
	s_add_u32 s38, s80, 0x2000
	s_addc_u32 s39, s81, 0
	s_mul_i32 s1, s8, 0x6000
	s_add_u32 s34, s84, s1
	s_addc_u32 s35, s85, 0
	s_add_u32 s34, s34, 0x4000
	s_addc_u32 s35, s35, 0
	global_load_dwordx4 v[96:99], v192, s[34:35] offset:0
	global_load_dwordx4 v[200:203], v192, s[82:83] offset:0
	global_load_dwordx4 v[100:103], v192, s[34:35] offset:1024
	global_load_dwordx4 v[204:207], v192, s[82:83] offset:1024
	global_load_dwordx4 v[104:107], v192, s[34:35] offset:2048
	global_load_dwordx4 v[208:211], v192, s[82:83] offset:2048
	global_load_dwordx4 v[108:111], v192, s[34:35] offset:3072
	global_load_dwordx4 v[212:215], v192, s[82:83] offset:3072
	s_waitcnt vmcnt(0)
	v_mul_f32_e32 v96, v96, v200
	v_mul_f32_e32 v97, v97, v201
	v_mul_f32_e32 v98, v98, v202
	v_mul_f32_e32 v99, v99, v203
	v_mul_f32_e32 v100, v100, v204
	v_mul_f32_e32 v101, v101, v205
	v_mul_f32_e32 v102, v102, v206
	v_mul_f32_e32 v103, v103, v207
	v_mul_f32_e32 v104, v104, v208
	v_mul_f32_e32 v105, v105, v209
	v_mul_f32_e32 v106, v106, v210
	v_mul_f32_e32 v107, v107, v211
	v_mul_f32_e32 v108, v108, v212
	v_mul_f32_e32 v109, v109, v213
	v_mul_f32_e32 v110, v110, v214
	v_mul_f32_e32 v111, v111, v215
	global_load_dwordx4 v[128:131], v192, s[38:39] offset:0
	global_load_dwordx4 v[200:203], v192, s[44:45] offset:0
	global_load_dwordx4 v[160:163], v192, s[36:37] offset:0
	global_load_dwordx4 v[132:135], v192, s[38:39] offset:1024
	global_load_dwordx4 v[204:207], v192, s[44:45] offset:1024
	global_load_dwordx4 v[164:167], v192, s[36:37] offset:1024
	global_load_dwordx4 v[136:139], v192, s[38:39] offset:2048
	global_load_dwordx4 v[208:211], v192, s[44:45] offset:2048
	global_load_dwordx4 v[168:171], v192, s[36:37] offset:2048
	global_load_dwordx4 v[140:143], v192, s[38:39] offset:3072
	global_load_dwordx4 v[212:215], v192, s[44:45] offset:3072
	global_load_dwordx4 v[172:175], v192, s[36:37] offset:3072
	s_waitcnt vmcnt(0)
	v_add_f32_e32 v200, 1.0, v200
	v_add_f32_e32 v201, 1.0, v201
	v_add_f32_e32 v202, 1.0, v202
	v_add_f32_e32 v203, 1.0, v203
	v_mul_f32_e32 v128, v128, v200
	v_mul_f32_e32 v129, v129, v201
	v_mul_f32_e32 v130, v130, v202
	v_mul_f32_e32 v131, v131, v203
	v_add_f32_e32 v204, 1.0, v204
	v_add_f32_e32 v205, 1.0, v205
	v_add_f32_e32 v206, 1.0, v206
	v_add_f32_e32 v207, 1.0, v207
	v_mul_f32_e32 v132, v132, v204
	v_mul_f32_e32 v133, v133, v205
	v_mul_f32_e32 v134, v134, v206
	v_mul_f32_e32 v135, v135, v207
	v_add_f32_e32 v208, 1.0, v208
	v_add_f32_e32 v209, 1.0, v209
	v_add_f32_e32 v210, 1.0, v210
	v_add_f32_e32 v211, 1.0, v211
	v_mul_f32_e32 v136, v136, v208
	v_mul_f32_e32 v137, v137, v209
	v_mul_f32_e32 v138, v138, v210
	v_mul_f32_e32 v139, v139, v211
	v_add_f32_e32 v212, 1.0, v212
	v_add_f32_e32 v213, 1.0, v213
	v_add_f32_e32 v214, 1.0, v214
	v_add_f32_e32 v215, 1.0, v215
	v_mul_f32_e32 v140, v140, v212
	v_mul_f32_e32 v141, v141, v213
	v_mul_f32_e32 v142, v142, v214
	v_mul_f32_e32 v143, v143, v215
	global_load_dwordx4 v[112:115], v193, s[34:35] offset:0
	global_load_dwordx4 v[200:203], v193, s[82:83] offset:0
	global_load_dwordx4 v[116:119], v193, s[34:35] offset:1024
	global_load_dwordx4 v[204:207], v193, s[82:83] offset:1024
	global_load_dwordx4 v[120:123], v193, s[34:35] offset:2048
	global_load_dwordx4 v[208:211], v193, s[82:83] offset:2048
	global_load_dwordx4 v[124:127], v193, s[34:35] offset:3072
	global_load_dwordx4 v[212:215], v193, s[82:83] offset:3072
	s_waitcnt vmcnt(0)
	v_mul_f32_e32 v112, v112, v200
	v_mul_f32_e32 v113, v113, v201
	v_mul_f32_e32 v114, v114, v202
	v_mul_f32_e32 v115, v115, v203
	v_mul_f32_e32 v116, v116, v204
	v_mul_f32_e32 v117, v117, v205
	v_mul_f32_e32 v118, v118, v206
	v_mul_f32_e32 v119, v119, v207
	v_mul_f32_e32 v120, v120, v208
	v_mul_f32_e32 v121, v121, v209
	v_mul_f32_e32 v122, v122, v210
	v_mul_f32_e32 v123, v123, v211
	v_mul_f32_e32 v124, v124, v212
	v_mul_f32_e32 v125, v125, v213
	v_mul_f32_e32 v126, v126, v214
	v_mul_f32_e32 v127, v127, v215
	global_load_dwordx4 v[144:147], v193, s[38:39] offset:0
	global_load_dwordx4 v[200:203], v193, s[44:45] offset:0
	global_load_dwordx4 v[176:179], v193, s[36:37] offset:0
	global_load_dwordx4 v[148:151], v193, s[38:39] offset:1024
	global_load_dwordx4 v[204:207], v193, s[44:45] offset:1024
	global_load_dwordx4 v[180:183], v193, s[36:37] offset:1024
	global_load_dwordx4 v[152:155], v193, s[38:39] offset:2048
	global_load_dwordx4 v[208:211], v193, s[44:45] offset:2048
	global_load_dwordx4 v[184:187], v193, s[36:37] offset:2048
	global_load_dwordx4 v[156:159], v193, s[38:39] offset:3072
	global_load_dwordx4 v[212:215], v193, s[44:45] offset:3072
	global_load_dwordx4 v[188:191], v193, s[36:37] offset:3072
	s_waitcnt vmcnt(0)
	v_add_f32_e32 v200, 1.0, v200
	v_add_f32_e32 v201, 1.0, v201
	v_add_f32_e32 v202, 1.0, v202
	v_add_f32_e32 v203, 1.0, v203
	v_mul_f32_e32 v144, v144, v200
	v_mul_f32_e32 v145, v145, v201
	v_mul_f32_e32 v146, v146, v202
	v_mul_f32_e32 v147, v147, v203
	v_add_f32_e32 v204, 1.0, v204
	v_add_f32_e32 v205, 1.0, v205
	v_add_f32_e32 v206, 1.0, v206
	v_add_f32_e32 v207, 1.0, v207
	v_mul_f32_e32 v148, v148, v204
	v_mul_f32_e32 v149, v149, v205
	v_mul_f32_e32 v150, v150, v206
	v_mul_f32_e32 v151, v151, v207
	v_add_f32_e32 v208, 1.0, v208
	v_add_f32_e32 v209, 1.0, v209
	v_add_f32_e32 v210, 1.0, v210
	v_add_f32_e32 v211, 1.0, v211
	v_mul_f32_e32 v152, v152, v208
	v_mul_f32_e32 v153, v153, v209
	v_mul_f32_e32 v154, v154, v210
	v_mul_f32_e32 v155, v155, v211
	v_add_f32_e32 v212, 1.0, v212
	v_add_f32_e32 v213, 1.0, v213
	v_add_f32_e32 v214, 1.0, v214
	v_add_f32_e32 v215, 1.0, v215
	v_mul_f32_e32 v156, v156, v212
	v_mul_f32_e32 v157, v157, v213
	v_mul_f32_e32 v158, v158, v214
	v_mul_f32_e32 v159, v159, v215
; __device__ __forceinline__ float bf_lo(unsigned w) { return __uint_as_float(w << 16); }
; __device__ __forceinline__ float bf_hi(unsigned w) { return __uint_as_float(w & 0xffff0000u); }
; __global__ void __launch_bounds__(NWAVES * 64, 2) mk_fwd(Args args) {
;     ...
;             for (int q = 0; q < 3; ++q) { const int row = row0 + q; const bool lat = row < ML; const int r = lat ? row / SEQ : 8;
;                 float sy = 0.f;
; #pragma unroll
;                 for (int j = 0; j < 8; ++j) { const float a = bf_lo(yw[q][j].x), b = bf_hi(yw[q][j].x), c2 = bf_lo(yw[q][j].y), d = bf_hi(yw[q][j].y); sy += (a * a + b * b) + (c2 * c2 + d * d); }
;                 const float rsy = __builtin_amdgcn_rsqf(wave_sum(sy) * (1.f / DM) + EPS);
;                 const float* m0 = mod + (size_t)r * 6144;
; #pragma unroll
;                 for (int j = 0; j < 8; ++j) { const int col = 4 * F.lane + 256 * j; const f32x4 gt = *(const f32x4*)(m0 + 2 * DM + col), pn = *(const f32x4*)(post_norm + col);
;                     const f32x4 y4 = (f32x4){bf_lo(yw[q][j].x), bf_hi(yw[q][j].x), bf_lo(yw[q][j].y), bf_hi(yw[q][j].y)};
;                     v[q][j] = v[q][j] + gt * (y4 * rsy * pn);
;                     if (lat) *(f32x4*)(args.out + (size_t)row * DM + col) = v[q][j]; }
;                 const float rstd = __builtin_amdgcn_rsqf(sumsq8(v[q]) * (1.f / DM) + EPS);
.Lp6_np4:
	s_waitcnt vmcnt(24)
	v_lshlrev_b32_e32 v216, 16, v32
	v_and_b32_e32 v217, 0xffff0000, v32
	v_lshlrev_b32_e32 v218, 16, v33
	v_and_b32_e32 v219, 0xffff0000, v33
	v_mul_f32_e32 v222, v216, v216
	v_mul_f32_e32 v223, v217, v217
	v_fmac_f32_e32 v222, v218, v218
	v_fmac_f32_e32 v223, v219, v219
	v_lshlrev_b32_e32 v216, 16, v34
	v_and_b32_e32 v217, 0xffff0000, v34
	v_lshlrev_b32_e32 v218, 16, v35
	v_and_b32_e32 v219, 0xffff0000, v35
	v_fmac_f32_e32 v222, v216, v216
	v_fmac_f32_e32 v223, v217, v217
	v_fmac_f32_e32 v222, v218, v218
	v_fmac_f32_e32 v223, v219, v219
	v_lshlrev_b32_e32 v216, 16, v36
	v_and_b32_e32 v217, 0xffff0000, v36
	v_lshlrev_b32_e32 v218, 16, v37
	v_and_b32_e32 v219, 0xffff0000, v37
	v_fmac_f32_e32 v222, v216, v216
	v_fmac_f32_e32 v223, v217, v217
	v_fmac_f32_e32 v222, v218, v218
	v_fmac_f32_e32 v223, v219, v219
	v_lshlrev_b32_e32 v216, 16, v38
	v_and_b32_e32 v217, 0xffff0000, v38
	v_lshlrev_b32_e32 v218, 16, v39
	v_and_b32_e32 v219, 0xffff0000, v39
	v_fmac_f32_e32 v222, v216, v216
	v_fmac_f32_e32 v223, v217, v217
	v_fmac_f32_e32 v222, v218, v218
	v_fmac_f32_e32 v223, v219, v219
	v_lshlrev_b32_e32 v216, 16, v40
	v_and_b32_e32 v217, 0xffff0000, v40
	v_lshlrev_b32_e32 v218, 16, v41
	v_and_b32_e32 v219, 0xffff0000, v41
	v_fmac_f32_e32 v222, v216, v216
	v_fmac_f32_e32 v223, v217, v217
	v_fmac_f32_e32 v222, v218, v218
	v_fmac_f32_e32 v223, v219, v219
	v_lshlrev_b32_e32 v216, 16, v42
	v_and_b32_e32 v217, 0xffff0000, v42
	v_lshlrev_b32_e32 v218, 16, v43
	v_and_b32_e32 v219, 0xffff0000, v43
	v_fmac_f32_e32 v222, v216, v216
	v_fmac_f32_e32 v223, v217, v217
	v_fmac_f32_e32 v222, v218, v218
	v_fmac_f32_e32 v223, v219, v219
	v_lshlrev_b32_e32 v216, 16, v44
	v_and_b32_e32 v217, 0xffff0000, v44
	v_lshlrev_b32_e32 v218, 16, v45
	v_and_b32_e32 v219, 0xffff0000, v45
	v_fmac_f32_e32 v222, v216, v216
	v_fmac_f32_e32 v223, v217, v217
	v_fmac_f32_e32 v222, v218, v218
	v_fmac_f32_e32 v223, v219, v219
	v_lshlrev_b32_e32 v216, 16, v46
	v_and_b32_e32 v217, 0xffff0000, v46
	v_lshlrev_b32_e32 v218, 16, v47
	v_and_b32_e32 v219, 0xffff0000, v47
	v_fmac_f32_e32 v222, v216, v216
	v_fmac_f32_e32 v223, v217, v217
	v_fmac_f32_e32 v222, v218, v218
	v_fmac_f32_e32 v223, v219, v219
	v_add_f32_e32 v222, v222, v223
	s_nop 1
	v_add_f32_dpp v224, v222, v222 quad_perm:[1,0,3,2] row_mask:0xf bank_mask:0xf
	s_nop 1
	v_add_f32_dpp v224, v224, v224 quad_perm:[2,3,0,1] row_mask:0xf bank_mask:0xf
	s_nop 1
	v_add_f32_dpp v224, v224, v224 row_half_mirror row_mask:0xf bank_mask:0xf
	s_nop 1
	v_add_f32_dpp v224, v224, v224 row_mirror row_mask:0xf bank_mask:0xf
	s_nop 1
	v_readlane_b32 s40, v224, 0
	v_readlane_b32 s41, v224, 16
	v_readlane_b32 s42, v224, 32
	v_readlane_b32 s43, v224, 48
	s_nop 1
	v_mov_b32_e32 v225, s40
	v_add_f32_e32 v225, s41, v225
	v_add_f32_e32 v225, s42, v225
	v_add_f32_e32 v225, s43, v225
	v_fmamk_f32 v225, v225, 0x3a000000, v195
	v_rsq_f32_e32 v225, v225
	s_nop 0
	v_lshlrev_b32_e32 v216, 16, v32
	v_and_b32_e32 v217, 0xffff0000, v32
	v_lshlrev_b32_e32 v218, 16, v33
	v_and_b32_e32 v219, 0xffff0000, v33
	v_mul_f32_e32 v216, v225, v216
	v_mul_f32_e32 v217, v225, v217
	v_mul_f32_e32 v218, v225, v218
	v_mul_f32_e32 v219, v225, v219
	v_fmac_f32_e32 v0, v96, v216
	v_fmac_f32_e32 v1, v97, v217
	v_fmac_f32_e32 v2, v98, v218
	v_fmac_f32_e32 v3, v99, v219
	v_lshlrev_b32_e32 v216, 16, v34
	v_and_b32_e32 v217, 0xffff0000, v34
	v_lshlrev_b32_e32 v218, 16, v35
	v_and_b32_e32 v219, 0xffff0000, v35
	v_mul_f32_e32 v216, v225, v216
	v_mul_f32_e32 v217, v225, v217
	v_mul_f32_e32 v218, v225, v218
	v_mul_f32_e32 v219, v225, v219
	v_fmac_f32_e32 v4, v100, v216
	v_fmac_f32_e32 v5, v101, v217
	v_fmac_f32_e32 v6, v102, v218
	v_fmac_f32_e32 v7, v103, v219
	v_lshlrev_b32_e32 v216, 16, v36
	v_and_b32_e32 v217, 0xffff0000, v36
	v_lshlrev_b32_e32 v218, 16, v37
	v_and_b32_e32 v219, 0xffff0000, v37
	v_mul_f32_e32 v216, v225, v216
	v_mul_f32_e32 v217, v225, v217
	v_mul_f32_e32 v218, v225, v218
	v_mul_f32_e32 v219, v225, v219
	v_fmac_f32_e32 v8, v104, v216
	v_fmac_f32_e32 v9, v105, v217
	v_fmac_f32_e32 v10, v106, v218
	v_fmac_f32_e32 v11, v107, v219
	v_lshlrev_b32_e32 v216, 16, v38
	v_and_b32_e32 v217, 0xffff0000, v38
	v_lshlrev_b32_e32 v218, 16, v39
	v_and_b32_e32 v219, 0xffff0000, v39
	v_mul_f32_e32 v216, v225, v216
	v_mul_f32_e32 v217, v225, v217
	v_mul_f32_e32 v218, v225, v218
	v_mul_f32_e32 v219, v225, v219
	v_fmac_f32_e32 v12, v108, v216
	v_fmac_f32_e32 v13, v109, v217
	v_fmac_f32_e32 v14, v110, v218
	v_fmac_f32_e32 v15, v111, v219
	v_lshlrev_b32_e32 v216, 16, v40
	v_and_b32_e32 v217, 0xffff0000, v40
	v_lshlrev_b32_e32 v218, 16, v41
	v_and_b32_e32 v219, 0xffff0000, v41
	v_mul_f32_e32 v216, v225, v216
	v_mul_f32_e32 v217, v225, v217
	v_mul_f32_e32 v218, v225, v218
	v_mul_f32_e32 v219, v225, v219
	v_fmac_f32_e32 v16, v112, v216
	v_fmac_f32_e32 v17, v113, v217
	v_fmac_f32_e32 v18, v114, v218
	v_fmac_f32_e32 v19, v115, v219
	v_lshlrev_b32_e32 v216, 16, v42
	v_and_b32_e32 v217, 0xffff0000, v42
	v_lshlrev_b32_e32 v218, 16, v43
	v_and_b32_e32 v219, 0xffff0000, v43
	v_mul_f32_e32 v216, v225, v216
	v_mul_f32_e32 v217, v225, v217
	v_mul_f32_e32 v218, v225, v218
	v_mul_f32_e32 v219, v225, v219
	v_fmac_f32_e32 v20, v116, v216
	v_fmac_f32_e32 v21, v117, v217
	v_fmac_f32_e32 v22, v118, v218
	v_fmac_f32_e32 v23, v119, v219
	v_lshlrev_b32_e32 v216, 16, v44
	v_and_b32_e32 v217, 0xffff0000, v44
	v_lshlrev_b32_e32 v218, 16, v45
	v_and_b32_e32 v219, 0xffff0000, v45
	v_mul_f32_e32 v216, v225, v216
	v_mul_f32_e32 v217, v225, v217
	v_mul_f32_e32 v218, v225, v218
	v_mul_f32_e32 v219, v225, v219
	v_fmac_f32_e32 v24, v120, v216
	v_fmac_f32_e32 v25, v121, v217
	v_fmac_f32_e32 v26, v122, v218
; __device__ __forceinline__ unsigned cvt_pk_bf16(float lo, float hi) { unsigned r; asm volatile("v_cvt_pk_bf16_f32 %0, %1, %2" : "=v"(r) : "v"(lo), "v"(hi)); return r; }
; __device__ __forceinline__ float bf_lo(unsigned w) { return __uint_as_float(w << 16); }
; __device__ __forceinline__ float bf_hi(unsigned w) { return __uint_as_float(w & 0xffff0000u); }
; __device__ __forceinline__ float sumsq8(const f32x4 (&v)[8]) {
;     float s = 0.f;
; #pragma unroll
;     for (int j = 0; j < 8; ++j) s += (v[j][0] * v[j][0] + v[j][1] * v[j][1]) + (v[j][2] * v[j][2] + v[j][3] * v[j][3]);
;     return wave_sum(s);
; }
; __device__ __forceinline__ void modulate_store(const f32x4 (&v)[8], float rstd, const float* pn, const float* modr, bf16_t* orow, int lane) {
; #pragma unroll
;     for (int j = 0; j < 8; ++j) { const int col = 4 * lane + 256 * j;
;         const f32x4 g = *(const f32x4*)(pn + col), sh = *(const f32x4*)(modr + col), sc = *(const f32x4*)(modr + DM + col);
;         const f32x4 hh = v[j] * rstd * g * (sc + 1.f) + sh;
;         u32x2 w; w.x = cvt_pk_bf16(hh[0], hh[1]); w.y = cvt_pk_bf16(hh[2], hh[3]);
;         *(u32x2*)(orow + col) = w; }
; __global__ void __launch_bounds__(NWAVES * 64, 2) mk_fwd(Args args) {
;     ...
;             for (int q = 0; q < 3; ++q) { const int row = row0 + q; const float* src = row < ML ? x + (size_t)row * DM : ctx + (size_t)(row - ML) * DM; load_row_f32(src, F.lane, v[q]);
;                 const bf16_t* yr = Y + (size_t)row * DM;
; #pragma unroll
;                 for (int j = 0; j < 8; ++j) yw[q][j] = *(const u32x2*)(yr + 4 * F.lane + 256 * j); }
;     ...
;                 for (int j = 0; j < 8; ++j) { const int col = 4 * F.lane + 256 * j; const f32x4 gt = *(const f32x4*)(m0 + 2 * DM + col), pn = *(const f32x4*)(post_norm + col);
;                     const f32x4 y4 = (f32x4){bf_lo(yw[q][j].x), bf_hi(yw[q][j].x), bf_lo(yw[q][j].y), bf_hi(yw[q][j].y)};
;                     v[q][j] = v[q][j] + gt * (y4 * rsy * pn);
;                     if (lat) *(f32x4*)(args.out + (size_t)row * DM + col) = v[q][j]; }
;                 const float rstd = __builtin_amdgcn_rsqf(sumsq8(v[q]) * (1.f / DM) + EPS);
;                 modulate_store(v[q], rstd, pre_norm + DM, mod + (size_t)(9 + r) * 6144, H + (size_t)row * DM, F.lane); }
	v_fmac_f32_e32 v27, v123, v219
	v_lshlrev_b32_e32 v216, 16, v46
	v_and_b32_e32 v217, 0xffff0000, v46
	v_lshlrev_b32_e32 v218, 16, v47
	v_and_b32_e32 v219, 0xffff0000, v47
	v_mul_f32_e32 v216, v225, v216
	v_mul_f32_e32 v217, v225, v217
	v_mul_f32_e32 v218, v225, v218
	v_mul_f32_e32 v219, v225, v219
	v_fmac_f32_e32 v28, v124, v216
	v_fmac_f32_e32 v29, v125, v217
	v_fmac_f32_e32 v30, v126, v218
	v_fmac_f32_e32 v31, v127, v219
	v_mul_f32_e32 v222, v0, v0
	v_mul_f32_e32 v223, v1, v1
	v_fmac_f32_e32 v222, v2, v2
	v_fmac_f32_e32 v223, v3, v3
	v_fmac_f32_e32 v222, v4, v4
	v_fmac_f32_e32 v223, v5, v5
	v_fmac_f32_e32 v222, v6, v6
	v_fmac_f32_e32 v223, v7, v7
	v_fmac_f32_e32 v222, v8, v8
	v_fmac_f32_e32 v223, v9, v9
	v_fmac_f32_e32 v222, v10, v10
	v_fmac_f32_e32 v223, v11, v11
	v_fmac_f32_e32 v222, v12, v12
	v_fmac_f32_e32 v223, v13, v13
	v_fmac_f32_e32 v222, v14, v14
	v_fmac_f32_e32 v223, v15, v15
	v_fmac_f32_e32 v222, v16, v16
	v_fmac_f32_e32 v223, v17, v17
	v_fmac_f32_e32 v222, v18, v18
	v_fmac_f32_e32 v223, v19, v19
	v_fmac_f32_e32 v222, v20, v20
	v_fmac_f32_e32 v223, v21, v21
	v_fmac_f32_e32 v222, v22, v22
	v_fmac_f32_e32 v223, v23, v23
	v_fmac_f32_e32 v222, v24, v24
	v_fmac_f32_e32 v223, v25, v25
	v_fmac_f32_e32 v222, v26, v26
	v_fmac_f32_e32 v223, v27, v27
	v_fmac_f32_e32 v222, v28, v28
	v_fmac_f32_e32 v223, v29, v29
	v_fmac_f32_e32 v222, v30, v30
	v_fmac_f32_e32 v223, v31, v31
	v_add_f32_e32 v222, v222, v223
	s_nop 1
	v_add_f32_dpp v224, v222, v222 quad_perm:[1,0,3,2] row_mask:0xf bank_mask:0xf
	s_nop 1
	v_add_f32_dpp v224, v224, v224 quad_perm:[2,3,0,1] row_mask:0xf bank_mask:0xf
	s_nop 1
	v_add_f32_dpp v224, v224, v224 row_half_mirror row_mask:0xf bank_mask:0xf
	s_nop 1
	v_add_f32_dpp v224, v224, v224 row_mirror row_mask:0xf bank_mask:0xf
	s_nop 1
	v_readlane_b32 s40, v224, 0
	v_readlane_b32 s41, v224, 16
	v_readlane_b32 s42, v224, 32
	v_readlane_b32 s43, v224, 48
	s_nop 1
	v_mov_b32_e32 v225, s40
	v_add_f32_e32 v225, s41, v225
	v_add_f32_e32 v225, s42, v225
	v_add_f32_e32 v225, s43, v225
	v_fmamk_f32 v225, v225, 0x3a000000, v195
	v_rsq_f32_e32 v225, v225
	s_nop 0
	s_add_i32 s0, s6, 4
	s_lshl_b32 s1, s0, 12
	s_add_u32 s26, s84, s1
	s_addc_u32 s27, s85, 0
	s_add_u32 s26, s26, 0x4000000
	s_addc_u32 s27, s27, 0
	v_mul_f32_e32 v216, v225, v0
	v_mul_f32_e32 v217, v225, v1
	v_mul_f32_e32 v218, v225, v2
	v_mul_f32_e32 v219, v225, v3
	v_fma_f32 v216, v216, v128, v160
	v_fma_f32 v217, v217, v129, v161
	v_fma_f32 v218, v218, v130, v162
	v_fma_f32 v219, v219, v131, v163
	v_cvt_pk_bf16_f32 v196, v216, v217
	v_cvt_pk_bf16_f32 v197, v218, v219
	global_store_dwordx2 v194, v[196:197], s[26:27] offset:0
	v_mul_f32_e32 v216, v225, v4
	v_mul_f32_e32 v217, v225, v5
	v_mul_f32_e32 v218, v225, v6
	v_mul_f32_e32 v219, v225, v7
	v_fma_f32 v216, v216, v132, v164
	v_fma_f32 v217, v217, v133, v165
	v_fma_f32 v218, v218, v134, v166
	v_fma_f32 v219, v219, v135, v167
	v_cvt_pk_bf16_f32 v220, v216, v217
	v_cvt_pk_bf16_f32 v221, v218, v219
	global_store_dwordx2 v194, v[220:221], s[26:27] offset:512
	v_mul_f32_e32 v216, v225, v8
	v_mul_f32_e32 v217, v225, v9
	v_mul_f32_e32 v218, v225, v10
	v_mul_f32_e32 v219, v225, v11
	v_fma_f32 v216, v216, v136, v168
	v_fma_f32 v217, v217, v137, v169
	v_fma_f32 v218, v218, v138, v170
	v_fma_f32 v219, v219, v139, v171
	v_cvt_pk_bf16_f32 v196, v216, v217
	v_cvt_pk_bf16_f32 v197, v218, v219
	global_store_dwordx2 v194, v[196:197], s[26:27] offset:1024
	v_mul_f32_e32 v216, v225, v12
	v_mul_f32_e32 v217, v225, v13
	v_mul_f32_e32 v218, v225, v14
	v_mul_f32_e32 v219, v225, v15
	v_fma_f32 v216, v216, v140, v172
	v_fma_f32 v217, v217, v141, v173
	v_fma_f32 v218, v218, v142, v174
	v_fma_f32 v219, v219, v143, v175
	v_cvt_pk_bf16_f32 v220, v216, v217
	v_cvt_pk_bf16_f32 v221, v218, v219
	global_store_dwordx2 v194, v[220:221], s[26:27] offset:1536
	v_mul_f32_e32 v216, v225, v16
	v_mul_f32_e32 v217, v225, v17
	v_mul_f32_e32 v218, v225, v18
	v_mul_f32_e32 v219, v225, v19
	v_fma_f32 v216, v216, v144, v176
	v_fma_f32 v217, v217, v145, v177
	v_fma_f32 v218, v218, v146, v178
	v_fma_f32 v219, v219, v147, v179
	v_cvt_pk_bf16_f32 v196, v216, v217
	v_cvt_pk_bf16_f32 v197, v218, v219
	global_store_dwordx2 v194, v[196:197], s[26:27] offset:2048
	v_mul_f32_e32 v216, v225, v20
	v_mul_f32_e32 v217, v225, v21
	v_mul_f32_e32 v218, v225, v22
	v_mul_f32_e32 v219, v225, v23
	v_fma_f32 v216, v216, v148, v180
	v_fma_f32 v217, v217, v149, v181
	v_fma_f32 v218, v218, v150, v182
	v_fma_f32 v219, v219, v151, v183
	v_cvt_pk_bf16_f32 v220, v216, v217
	v_cvt_pk_bf16_f32 v221, v218, v219
	global_store_dwordx2 v194, v[220:221], s[26:27] offset:2560
	v_mul_f32_e32 v216, v225, v24
	v_mul_f32_e32 v217, v225, v25
	v_mul_f32_e32 v218, v225, v26
	v_mul_f32_e32 v219, v225, v27
	v_fma_f32 v216, v216, v152, v184
	v_fma_f32 v217, v217, v153, v185
	v_fma_f32 v218, v218, v154, v186
	v_fma_f32 v219, v219, v155, v187
	v_cvt_pk_bf16_f32 v196, v216, v217
	v_cvt_pk_bf16_f32 v197, v218, v219
	global_store_dwordx2 v194, v[196:197], s[26:27] offset:3072
	v_mul_f32_e32 v216, v225, v28
	v_mul_f32_e32 v217, v225, v29
	v_mul_f32_e32 v218, v225, v30
	v_mul_f32_e32 v219, v225, v31
	v_fma_f32 v216, v216, v156, v188
	v_fma_f32 v217, v217, v157, v189
	v_fma_f32 v218, v218, v158, v190
	v_fma_f32 v219, v219, v159, v191
	v_cvt_pk_bf16_f32 v220, v216, v217
	v_cvt_pk_bf16_f32 v221, v218, v219
	global_store_dwordx2 v194, v[220:221], s[26:27] offset:3584
	s_add_i32 s0, s6, 6
	s_cmp_lt_u32 s0, 0x4000
	s_cselect_b32 s10, s68, s72
	s_cselect_b32 s11, s69, s73
	s_cselect_b32 s1, 0, 0x4000
	s_sub_i32 s1, s0, s1
	s_lshl_b32 s1, s1, 13
	s_add_u32 s10, s10, s1
	s_addc_u32 s11, s11, 0
	s_add_i32 s0, s6, 6
	s_lshl_b32 s1, s0, 12
	s_add_u32 s22, s84, s1
	s_addc_u32 s23, s85, 0
	s_add_u32 s22, s22, 0x11800000
	s_addc_u32 s23, s23, 0
	global_load_dwordx4 v[0:3], v192, s[10:11] offset:0
	global_load_dwordx4 v[4:7], v192, s[10:11] offset:1024
	global_load_dwordx4 v[8:11], v192, s[10:11] offset:2048
	global_load_dwordx4 v[12:15], v192, s[10:11] offset:3072
	global_load_dwordx4 v[16:19], v193, s[10:11] offset:0
	global_load_dwordx4 v[20:23], v193, s[10:11] offset:1024
	global_load_dwordx4 v[24:27], v193, s[10:11] offset:2048
	global_load_dwordx4 v[28:31], v193, s[10:11] offset:3072
	global_load_dwordx2 v[32:33], v194, s[22:23] offset:0
	global_load_dwordx2 v[34:35], v194, s[22:23] offset:512
	global_load_dwordx2 v[36:37], v194, s[22:23] offset:1024
	global_load_dwordx2 v[38:39], v194, s[22:23] offset:1536
	global_load_dwordx2 v[40:41], v194, s[22:23] offset:2048
	global_load_dwordx2 v[42:43], v194, s[22:23] offset:2560
	global_load_dwordx2 v[44:45], v194, s[22:23] offset:3072
	global_load_dwordx2 v[46:47], v194, s[22:23] offset:3584
	s_add_i32 s0, s6, 5
	s_add_i32 s0, s6, 5
	s_lshr_b32 s8, s0, 11
	s_cmp_lt_u32 s0, 0x4000
	s_cselect_b32 s8, s8, 8
	s_cmp_eq_u32 s8, s7
	s_cbranch_scc1 .Lp6_np5
; __device__ __forceinline__ unsigned cvt_pk_bf16(float lo, float hi) { unsigned r; asm volatile("v_cvt_pk_bf16_f32 %0, %1, %2" : "=v"(r) : "v"(lo), "v"(hi)); return r; }
; __device__ __forceinline__ void modulate_store(const f32x4 (&v)[8], float rstd, const float* pn, const float* modr, bf16_t* orow, int lane) {
; #pragma unroll
;     for (int j = 0; j < 8; ++j) { const int col = 4 * lane + 256 * j;
;         const f32x4 g = *(const f32x4*)(pn + col), sh = *(const f32x4*)(modr + col), sc = *(const f32x4*)(modr + DM + col);
;         const f32x4 hh = v[j] * rstd * g * (sc + 1.f) + sh;
;         u32x2 w; w.x = cvt_pk_bf16(hh[0], hh[1]); w.y = cvt_pk_bf16(hh[2], hh[3]);
;         *(u32x2*)(orow + col) = w; }
; __global__ void __launch_bounds__(NWAVES * 64, 2) mk_fwd(Args args) {
;     ...
;                 const float* m0 = mod + (size_t)r * 6144;
; #pragma unroll
;                 for (int j = 0; j < 8; ++j) { const int col = 4 * F.lane + 256 * j; const f32x4 gt = *(const f32x4*)(m0 + 2 * DM + col), pn = *(const f32x4*)(post_norm + col);
	s_mov_b32 s7, s8
	s_add_i32 s1, s8, 9
	s_mul_i32 s1, s1, 0x6000
	s_add_u32 s44, s84, s1
	s_addc_u32 s45, s85, 0
	s_add_u32 s44, s44, 0x2000
	s_addc_u32 s45, s45, 0
	s_add_i32 s1, s8, 9
	s_mul_i32 s1, s1, 0x6000
	s_add_u32 s36, s84, s1
	s_addc_u32 s37, s85, 0
	s_add_u32 s38, s80, 0x2000
	s_addc_u32 s39, s81, 0
	s_mul_i32 s1, s8, 0x6000
	s_add_u32 s34, s84, s1
	s_addc_u32 s35, s85, 0
	s_add_u32 s34, s34, 0x4000
	s_addc_u32 s35, s35, 0
	global_load_dwordx4 v[96:99], v192, s[34:35] offset:0
	global_load_dwordx4 v[200:203], v192, s[82:83] offset:0
	global_load_dwordx4 v[100:103], v192, s[34:35] offset:1024
	global_load_dwordx4 v[204:207], v192, s[82:83] offset:1024
	global_load_dwordx4 v[104:107], v192, s[34:35] offset:2048
	global_load_dwordx4 v[208:211], v192, s[82:83] offset:2048
	global_load_dwordx4 v[108:111], v192, s[34:35] offset:3072
	global_load_dwordx4 v[212:215], v192, s[82:83] offset:3072
	s_waitcnt vmcnt(0)
	v_mul_f32_e32 v96, v96, v200
	v_mul_f32_e32 v97, v97, v201
	v_mul_f32_e32 v98, v98, v202
	v_mul_f32_e32 v99, v99, v203
	v_mul_f32_e32 v100, v100, v204
	v_mul_f32_e32 v101, v101, v205
	v_mul_f32_e32 v102, v102, v206
	v_mul_f32_e32 v103, v103, v207
	v_mul_f32_e32 v104, v104, v208
	v_mul_f32_e32 v105, v105, v209
	v_mul_f32_e32 v106, v106, v210
	v_mul_f32_e32 v107, v107, v211
	v_mul_f32_e32 v108, v108, v212
	v_mul_f32_e32 v109, v109, v213
	v_mul_f32_e32 v110, v110, v214
	v_mul_f32_e32 v111, v111, v215
	global_load_dwordx4 v[128:131], v192, s[38:39] offset:0
	global_load_dwordx4 v[200:203], v192, s[44:45] offset:0
	global_load_dwordx4 v[160:163], v192, s[36:37] offset:0
	global_load_dwordx4 v[132:135], v192, s[38:39] offset:1024
	global_load_dwordx4 v[204:207], v192, s[44:45] offset:1024
	global_load_dwordx4 v[164:167], v192, s[36:37] offset:1024
	global_load_dwordx4 v[136:139], v192, s[38:39] offset:2048
	global_load_dwordx4 v[208:211], v192, s[44:45] offset:2048
	global_load_dwordx4 v[168:171], v192, s[36:37] offset:2048
	global_load_dwordx4 v[140:143], v192, s[38:39] offset:3072
	global_load_dwordx4 v[212:215], v192, s[44:45] offset:3072
	global_load_dwordx4 v[172:175], v192, s[36:37] offset:3072
	s_waitcnt vmcnt(0)
	v_add_f32_e32 v200, 1.0, v200
	v_add_f32_e32 v201, 1.0, v201
	v_add_f32_e32 v202, 1.0, v202
	v_add_f32_e32 v203, 1.0, v203
	v_mul_f32_e32 v128, v128, v200
	v_mul_f32_e32 v129, v129, v201
	v_mul_f32_e32 v130, v130, v202
	v_mul_f32_e32 v131, v131, v203
	v_add_f32_e32 v204, 1.0, v204
	v_add_f32_e32 v205, 1.0, v205
	v_add_f32_e32 v206, 1.0, v206
	v_add_f32_e32 v207, 1.0, v207
	v_mul_f32_e32 v132, v132, v204
	v_mul_f32_e32 v133, v133, v205
	v_mul_f32_e32 v134, v134, v206
	v_mul_f32_e32 v135, v135, v207
	v_add_f32_e32 v208, 1.0, v208
	v_add_f32_e32 v209, 1.0, v209
	v_add_f32_e32 v210, 1.0, v210
	v_add_f32_e32 v211, 1.0, v211
	v_mul_f32_e32 v136, v136, v208
	v_mul_f32_e32 v137, v137, v209
	v_mul_f32_e32 v138, v138, v210
	v_mul_f32_e32 v139, v139, v211
	v_add_f32_e32 v212, 1.0, v212
	v_add_f32_e32 v213, 1.0, v213
	v_add_f32_e32 v214, 1.0, v214
	v_add_f32_e32 v215, 1.0, v215
	v_mul_f32_e32 v140, v140, v212
	v_mul_f32_e32 v141, v141, v213
	v_mul_f32_e32 v142, v142, v214
	v_mul_f32_e32 v143, v143, v215
	global_load_dwordx4 v[112:115], v193, s[34:35] offset:0
	global_load_dwordx4 v[200:203], v193, s[82:83] offset:0
	global_load_dwordx4 v[116:119], v193, s[34:35] offset:1024
	global_load_dwordx4 v[204:207], v193, s[82:83] offset:1024
	global_load_dwordx4 v[120:123], v193, s[34:35] offset:2048
	global_load_dwordx4 v[208:211], v193, s[82:83] offset:2048
	global_load_dwordx4 v[124:127], v193, s[34:35] offset:3072
	global_load_dwordx4 v[212:215], v193, s[82:83] offset:3072
	s_waitcnt vmcnt(0)
	v_mul_f32_e32 v112, v112, v200
	v_mul_f32_e32 v113, v113, v201
	v_mul_f32_e32 v114, v114, v202
	v_mul_f32_e32 v115, v115, v203
	v_mul_f32_e32 v116, v116, v204
	v_mul_f32_e32 v117, v117, v205
	v_mul_f32_e32 v118, v118, v206
	v_mul_f32_e32 v119, v119, v207
	v_mul_f32_e32 v120, v120, v208
	v_mul_f32_e32 v121, v121, v209
	v_mul_f32_e32 v122, v122, v210
	v_mul_f32_e32 v123, v123, v211
	v_mul_f32_e32 v124, v124, v212
	v_mul_f32_e32 v125, v125, v213
	v_mul_f32_e32 v126, v126, v214
	v_mul_f32_e32 v127, v127, v215
	global_load_dwordx4 v[144:147], v193, s[38:39] offset:0
	global_load_dwordx4 v[200:203], v193, s[44:45] offset:0
	global_load_dwordx4 v[176:179], v193, s[36:37] offset:0
	global_load_dwordx4 v[148:151], v193, s[38:39] offset:1024
	global_load_dwordx4 v[204:207], v193, s[44:45] offset:1024
	global_load_dwordx4 v[180:183], v193, s[36:37] offset:1024
	global_load_dwordx4 v[152:155], v193, s[38:39] offset:2048
	global_load_dwordx4 v[208:211], v193, s[44:45] offset:2048
	global_load_dwordx4 v[184:187], v193, s[36:37] offset:2048
	global_load_dwordx4 v[156:159], v193, s[38:39] offset:3072
	global_load_dwordx4 v[212:215], v193, s[44:45] offset:3072
	global_load_dwordx4 v[188:191], v193, s[36:37] offset:3072
	s_waitcnt vmcnt(0)
	v_add_f32_e32 v200, 1.0, v200
	v_add_f32_e32 v201, 1.0, v201
	v_add_f32_e32 v202, 1.0, v202
	v_add_f32_e32 v203, 1.0, v203
	v_mul_f32_e32 v144, v144, v200
	v_mul_f32_e32 v145, v145, v201
	v_mul_f32_e32 v146, v146, v202
	v_mul_f32_e32 v147, v147, v203
	v_add_f32_e32 v204, 1.0, v204
	v_add_f32_e32 v205, 1.0, v205
	v_add_f32_e32 v206, 1.0, v206
	v_add_f32_e32 v207, 1.0, v207
	v_mul_f32_e32 v148, v148, v204
	v_mul_f32_e32 v149, v149, v205
	v_mul_f32_e32 v150, v150, v206
	v_mul_f32_e32 v151, v151, v207
	v_add_f32_e32 v208, 1.0, v208
	v_add_f32_e32 v209, 1.0, v209
	v_add_f32_e32 v210, 1.0, v210
	v_add_f32_e32 v211, 1.0, v211
	v_mul_f32_e32 v152, v152, v208
	v_mul_f32_e32 v153, v153, v209
	v_mul_f32_e32 v154, v154, v210
	v_mul_f32_e32 v155, v155, v211
	v_add_f32_e32 v212, 1.0, v212
	v_add_f32_e32 v213, 1.0, v213
	v_add_f32_e32 v214, 1.0, v214
	v_add_f32_e32 v215, 1.0, v215
	v_mul_f32_e32 v156, v156, v212
	v_mul_f32_e32 v157, v157, v213
	v_mul_f32_e32 v158, v158, v214
	v_mul_f32_e32 v159, v159, v215
; __device__ __forceinline__ float bf_lo(unsigned w) { return __uint_as_float(w << 16); }
; __device__ __forceinline__ float bf_hi(unsigned w) { return __uint_as_float(w & 0xffff0000u); }
; __global__ void __launch_bounds__(NWAVES * 64, 2) mk_fwd(Args args) {
;     ...
;             for (int q = 0; q < 3; ++q) { const int row = row0 + q; const bool lat = row < ML; const int r = lat ? row / SEQ : 8;
;                 float sy = 0.f;
; #pragma unroll
;                 for (int j = 0; j < 8; ++j) { const float a = bf_lo(yw[q][j].x), b = bf_hi(yw[q][j].x), c2 = bf_lo(yw[q][j].y), d = bf_hi(yw[q][j].y); sy += (a * a + b * b) + (c2 * c2 + d * d); }
;                 const float rsy = __builtin_amdgcn_rsqf(wave_sum(sy) * (1.f / DM) + EPS);
;                 const float* m0 = mod + (size_t)r * 6144;
; #pragma unroll
;                 for (int j = 0; j < 8; ++j) { const int col = 4 * F.lane + 256 * j; const f32x4 gt = *(const f32x4*)(m0 + 2 * DM + col), pn = *(const f32x4*)(post_norm + col);
;                     const f32x4 y4 = (f32x4){bf_lo(yw[q][j].x), bf_hi(yw[q][j].x), bf_lo(yw[q][j].y), bf_hi(yw[q][j].y)};
;                     v[q][j] = v[q][j] + gt * (y4 * rsy * pn);
;                     if (lat) *(f32x4*)(args.out + (size_t)row * DM + col) = v[q][j]; }
;                 const float rstd = __builtin_amdgcn_rsqf(sumsq8(v[q]) * (1.f / DM) + EPS);
.Lp6_np5:
	s_waitcnt vmcnt(24)
	v_lshlrev_b32_e32 v216, 16, v80
	v_and_b32_e32 v217, 0xffff0000, v80
	v_lshlrev_b32_e32 v218, 16, v81
	v_and_b32_e32 v219, 0xffff0000, v81
	v_mul_f32_e32 v222, v216, v216
	v_mul_f32_e32 v223, v217, v217
	v_fmac_f32_e32 v222, v218, v218
	v_fmac_f32_e32 v223, v219, v219
	v_lshlrev_b32_e32 v216, 16, v82
	v_and_b32_e32 v217, 0xffff0000, v82
	v_lshlrev_b32_e32 v218, 16, v83
	v_and_b32_e32 v219, 0xffff0000, v83
	v_fmac_f32_e32 v222, v216, v216
	v_fmac_f32_e32 v223, v217, v217
	v_fmac_f32_e32 v222, v218, v218
	v_fmac_f32_e32 v223, v219, v219
	v_lshlrev_b32_e32 v216, 16, v84
	v_and_b32_e32 v217, 0xffff0000, v84
	v_lshlrev_b32_e32 v218, 16, v85
	v_and_b32_e32 v219, 0xffff0000, v85
	v_fmac_f32_e32 v222, v216, v216
	v_fmac_f32_e32 v223, v217, v217
	v_fmac_f32_e32 v222, v218, v218
	v_fmac_f32_e32 v223, v219, v219
	v_lshlrev_b32_e32 v216, 16, v86
	v_and_b32_e32 v217, 0xffff0000, v86
	v_lshlrev_b32_e32 v218, 16, v87
	v_and_b32_e32 v219, 0xffff0000, v87
	v_fmac_f32_e32 v222, v216, v216
	v_fmac_f32_e32 v223, v217, v217
	v_fmac_f32_e32 v222, v218, v218
	v_fmac_f32_e32 v223, v219, v219
	v_lshlrev_b32_e32 v216, 16, v88
	v_and_b32_e32 v217, 0xffff0000, v88
	v_lshlrev_b32_e32 v218, 16, v89
	v_and_b32_e32 v219, 0xffff0000, v89
	v_fmac_f32_e32 v222, v216, v216
	v_fmac_f32_e32 v223, v217, v217
	v_fmac_f32_e32 v222, v218, v218
	v_fmac_f32_e32 v223, v219, v219
	v_lshlrev_b32_e32 v216, 16, v90
	v_and_b32_e32 v217, 0xffff0000, v90
	v_lshlrev_b32_e32 v218, 16, v91
	v_and_b32_e32 v219, 0xffff0000, v91
	v_fmac_f32_e32 v222, v216, v216
	v_fmac_f32_e32 v223, v217, v217
	v_fmac_f32_e32 v222, v218, v218
	v_fmac_f32_e32 v223, v219, v219
	v_lshlrev_b32_e32 v216, 16, v92
	v_and_b32_e32 v217, 0xffff0000, v92
	v_lshlrev_b32_e32 v218, 16, v93
	v_and_b32_e32 v219, 0xffff0000, v93
	v_fmac_f32_e32 v222, v216, v216
	v_fmac_f32_e32 v223, v217, v217
	v_fmac_f32_e32 v222, v218, v218
	v_fmac_f32_e32 v223, v219, v219
	v_lshlrev_b32_e32 v216, 16, v94
	v_and_b32_e32 v217, 0xffff0000, v94
	v_lshlrev_b32_e32 v218, 16, v95
	v_and_b32_e32 v219, 0xffff0000, v95
	v_fmac_f32_e32 v222, v216, v216
	v_fmac_f32_e32 v223, v217, v217
	v_fmac_f32_e32 v222, v218, v218
	v_fmac_f32_e32 v223, v219, v219
	v_add_f32_e32 v222, v222, v223
	s_nop 1
	v_add_f32_dpp v224, v222, v222 quad_perm:[1,0,3,2] row_mask:0xf bank_mask:0xf
	s_nop 1
	v_add_f32_dpp v224, v224, v224 quad_perm:[2,3,0,1] row_mask:0xf bank_mask:0xf
	s_nop 1
	v_add_f32_dpp v224, v224, v224 row_half_mirror row_mask:0xf bank_mask:0xf
	s_nop 1
	v_add_f32_dpp v224, v224, v224 row_mirror row_mask:0xf bank_mask:0xf
	s_nop 1
	v_readlane_b32 s40, v224, 0
	v_readlane_b32 s41, v224, 16
	v_readlane_b32 s42, v224, 32
	v_readlane_b32 s43, v224, 48
	s_nop 1
	v_mov_b32_e32 v225, s40
	v_add_f32_e32 v225, s41, v225
	v_add_f32_e32 v225, s42, v225
	v_add_f32_e32 v225, s43, v225
	v_fmamk_f32 v225, v225, 0x3a000000, v195
	v_rsq_f32_e32 v225, v225
	s_nop 0
	v_lshlrev_b32_e32 v216, 16, v80
	v_and_b32_e32 v217, 0xffff0000, v80
	v_lshlrev_b32_e32 v218, 16, v81
	v_and_b32_e32 v219, 0xffff0000, v81
	v_mul_f32_e32 v216, v225, v216
	v_mul_f32_e32 v217, v225, v217
	v_mul_f32_e32 v218, v225, v218
	v_mul_f32_e32 v219, v225, v219
	v_fmac_f32_e32 v48, v96, v216
	v_fmac_f32_e32 v49, v97, v217
	v_fmac_f32_e32 v50, v98, v218
	v_fmac_f32_e32 v51, v99, v219
	v_lshlrev_b32_e32 v216, 16, v82
	v_and_b32_e32 v217, 0xffff0000, v82
	v_lshlrev_b32_e32 v218, 16, v83
	v_and_b32_e32 v219, 0xffff0000, v83
	v_mul_f32_e32 v216, v225, v216
	v_mul_f32_e32 v217, v225, v217
	v_mul_f32_e32 v218, v225, v218
	v_mul_f32_e32 v219, v225, v219
	v_fmac_f32_e32 v52, v100, v216
	v_fmac_f32_e32 v53, v101, v217
	v_fmac_f32_e32 v54, v102, v218
	v_fmac_f32_e32 v55, v103, v219
	v_lshlrev_b32_e32 v216, 16, v84
	v_and_b32_e32 v217, 0xffff0000, v84
	v_lshlrev_b32_e32 v218, 16, v85
	v_and_b32_e32 v219, 0xffff0000, v85
	v_mul_f32_e32 v216, v225, v216
	v_mul_f32_e32 v217, v225, v217
	v_mul_f32_e32 v218, v225, v218
	v_mul_f32_e32 v219, v225, v219
	v_fmac_f32_e32 v56, v104, v216
	v_fmac_f32_e32 v57, v105, v217
	v_fmac_f32_e32 v58, v106, v218
	v_fmac_f32_e32 v59, v107, v219
	v_lshlrev_b32_e32 v216, 16, v86
	v_and_b32_e32 v217, 0xffff0000, v86
	v_lshlrev_b32_e32 v218, 16, v87
	v_and_b32_e32 v219, 0xffff0000, v87
	v_mul_f32_e32 v216, v225, v216
	v_mul_f32_e32 v217, v225, v217
	v_mul_f32_e32 v218, v225, v218
	v_mul_f32_e32 v219, v225, v219
	v_fmac_f32_e32 v60, v108, v216
	v_fmac_f32_e32 v61, v109, v217
	v_fmac_f32_e32 v62, v110, v218
	v_fmac_f32_e32 v63, v111, v219
	v_lshlrev_b32_e32 v216, 16, v88
	v_and_b32_e32 v217, 0xffff0000, v88
	v_lshlrev_b32_e32 v218, 16, v89
	v_and_b32_e32 v219, 0xffff0000, v89
	v_mul_f32_e32 v216, v225, v216
	v_mul_f32_e32 v217, v225, v217
	v_mul_f32_e32 v218, v225, v218
	v_mul_f32_e32 v219, v225, v219
	v_fmac_f32_e32 v64, v112, v216
	v_fmac_f32_e32 v65, v113, v217
	v_fmac_f32_e32 v66, v114, v218
	v_fmac_f32_e32 v67, v115, v219
	v_lshlrev_b32_e32 v216, 16, v90
	v_and_b32_e32 v217, 0xffff0000, v90
	v_lshlrev_b32_e32 v218, 16, v91
	v_and_b32_e32 v219, 0xffff0000, v91
	v_mul_f32_e32 v216, v225, v216
	v_mul_f32_e32 v217, v225, v217
	v_mul_f32_e32 v218, v225, v218
	v_mul_f32_e32 v219, v225, v219
	v_fmac_f32_e32 v68, v116, v216
	v_fmac_f32_e32 v69, v117, v217
	v_fmac_f32_e32 v70, v118, v218
	v_fmac_f32_e32 v71, v119, v219
	v_lshlrev_b32_e32 v216, 16, v92
	v_and_b32_e32 v217, 0xffff0000, v92
	v_lshlrev_b32_e32 v218, 16, v93
	v_and_b32_e32 v219, 0xffff0000, v93
	v_mul_f32_e32 v216, v225, v216
	v_mul_f32_e32 v217, v225, v217
	v_mul_f32_e32 v218, v225, v218
	v_mul_f32_e32 v219, v225, v219
	v_fmac_f32_e32 v72, v120, v216
	v_fmac_f32_e32 v73, v121, v217
	v_fmac_f32_e32 v74, v122, v218
; __device__ __forceinline__ float bf_lo(unsigned w) { return __uint_as_float(w << 16); }
; __device__ __forceinline__ float bf_hi(unsigned w) { return __uint_as_float(w & 0xffff0000u); }
; __global__ void __launch_bounds__(NWAVES * 64, 2) mk_fwd(Args args) {
;     ...
;         for (int row0 = F.gw * 3; row0 < MT; row0 += F.NGW * 3) {
;             f32x4 v[3][8]; u32x2 yw[3][8];
; #pragma unroll
;             for (int q = 0; q < 3; ++q) { const int row = row0 + q; const float* src = row < ML ? x + (size_t)row * DM : ctx + (size_t)(row - ML) * DM; load_row_f32(src, F.lane, v[q]);
;                 const bf16_t* yr = Y + (size_t)row * DM;
; #pragma unroll
;                 for (int j = 0; j < 8; ++j) yw[q][j] = *(const u32x2*)(yr + 4 * F.lane + 256 * j); }
;     ...
;             for (int q = 0; q < 3; ++q) { const int row = row0 + q; const bool lat = row < ML; const int r = lat ? row / SEQ : 8;
;                 float sy = 0.f;
; #pragma unroll
;                 for (int j = 0; j < 8; ++j) { const float a = bf_lo(yw[q][j].x), b = bf_hi(yw[q][j].x), c2 = bf_lo(yw[q][j].y), d = bf_hi(yw[q][j].y); sy += (a * a + b * b) + (c2 * c2 + d * d); }
;                 const float rsy = __builtin_amdgcn_rsqf(wave_sum(sy) * (1.f / DM) + EPS);
;                 const float* m0 = mod + (size_t)r * 6144;
; #pragma unroll
;                 for (int j = 0; j < 8; ++j) { const int col = 4 * F.lane + 256 * j; const f32x4 gt = *(const f32x4*)(m0 + 2 * DM + col), pn = *(const f32x4*)(post_norm + col);
;                     const f32x4 y4 = (f32x4){bf_lo(yw[q][j].x), bf_hi(yw[q][j].x), bf_lo(yw[q][j].y), bf_hi(yw[q][j].y)};
;                     v[q][j] = v[q][j] + gt * (y4 * rsy * pn);
;                     if (lat) *(f32x4*)(args.out + (size_t)row * DM + col) = v[q][j]; }
;                 const float rstd = __builtin_amdgcn_rsqf(sumsq8(v[q]) * (1.f / DM) + EPS);
;                 modulate_store(v[q], rstd, pre_norm + DM, mod + (size_t)(9 + r) * 6144, H + (size_t)row * DM, F.lane); }
	v_fmac_f32_e32 v75, v123, v219
	v_lshlrev_b32_e32 v216, 16, v94
	v_and_b32_e32 v217, 0xffff0000, v94
	v_lshlrev_b32_e32 v218, 16, v95
	v_and_b32_e32 v219, 0xffff0000, v95
	v_mul_f32_e32 v216, v225, v216
	v_mul_f32_e32 v217, v225, v217
	v_mul_f32_e32 v218, v225, v218
	v_mul_f32_e32 v219, v225, v219
	v_fmac_f32_e32 v76, v124, v216
	v_fmac_f32_e32 v77, v125, v217
	v_fmac_f32_e32 v78, v126, v218
	v_fmac_f32_e32 v79, v127, v219
	v_mul_f32_e32 v222, v48, v48
	v_mul_f32_e32 v223, v49, v49
	v_fmac_f32_e32 v222, v50, v50
	v_fmac_f32_e32 v223, v51, v51
	v_fmac_f32_e32 v222, v52, v52
	v_fmac_f32_e32 v223, v53, v53
	v_fmac_f32_e32 v222, v54, v54
	v_fmac_f32_e32 v223, v55, v55
	v_fmac_f32_e32 v222, v56, v56
	v_fmac_f32_e32 v223, v57, v57
	v_fmac_f32_e32 v222, v58, v58
	v_fmac_f32_e32 v223, v59, v59
	v_fmac_f32_e32 v222, v60, v60
	v_fmac_f32_e32 v223, v61, v61
	v_fmac_f32_e32 v222, v62, v62
	v_fmac_f32_e32 v223, v63, v63
	v_fmac_f32_e32 v222, v64, v64
	v_fmac_f32_e32 v223, v65, v65
	v_fmac_f32_e32 v222, v66, v66
	v_fmac_f32_e32 v223, v67, v67
	v_fmac_f32_e32 v222, v68, v68
	v_fmac_f32_e32 v223, v69, v69
	v_fmac_f32_e32 v222, v70, v70
	v_fmac_f32_e32 v223, v71, v71
	v_fmac_f32_e32 v222, v72, v72
	v_fmac_f32_e32 v223, v73, v73
	v_fmac_f32_e32 v222, v74, v74
	v_fmac_f32_e32 v223, v75, v75
	v_fmac_f32_e32 v222, v76, v76
	v_fmac_f32_e32 v223, v77, v77
	v_fmac_f32_e32 v222, v78, v78
	v_fmac_f32_e32 v223, v79, v79
	v_add_f32_e32 v222, v222, v223
	s_nop 1
	v_add_f32_dpp v224, v222, v222 quad_perm:[1,0,3,2] row_mask:0xf bank_mask:0xf
	s_nop 1
	v_add_f32_dpp v224, v224, v224 quad_perm:[2,3,0,1] row_mask:0xf bank_mask:0xf
	s_nop 1
	v_add_f32_dpp v224, v224, v224 row_half_mirror row_mask:0xf bank_mask:0xf
	s_nop 1
	v_add_f32_dpp v224, v224, v224 row_mirror row_mask:0xf bank_mask:0xf
	s_nop 1
	v_readlane_b32 s40, v224, 0
	v_readlane_b32 s41, v224, 16
	v_readlane_b32 s42, v224, 32
	v_readlane_b32 s43, v224, 48
	s_nop 1
	v_mov_b32_e32 v225, s40
	v_add_f32_e32 v225, s41, v225
	v_add_f32_e32 v225, s42, v225
	v_add_f32_e32 v225, s43, v225
	v_fmamk_f32 v225, v225, 0x3a000000, v195
	v_rsq_f32_e32 v225, v225
	s_nop 0
	s_add_i32 s0, s6, 5
	s_lshl_b32 s1, s0, 12
	s_add_u32 s26, s84, s1
	s_addc_u32 s27, s85, 0
	s_add_u32 s26, s26, 0x4000000
	s_addc_u32 s27, s27, 0
	v_mul_f32_e32 v216, v225, v48
	v_mul_f32_e32 v217, v225, v49
	v_mul_f32_e32 v218, v225, v50
	v_mul_f32_e32 v219, v225, v51
	v_fma_f32 v216, v216, v128, v160
	v_fma_f32 v217, v217, v129, v161
	v_fma_f32 v218, v218, v130, v162
	v_fma_f32 v219, v219, v131, v163
	v_cvt_pk_bf16_f32 v196, v216, v217
	v_cvt_pk_bf16_f32 v197, v218, v219
	global_store_dwordx2 v194, v[196:197], s[26:27] offset:0
	v_mul_f32_e32 v216, v225, v52
	v_mul_f32_e32 v217, v225, v53
	v_mul_f32_e32 v218, v225, v54
	v_mul_f32_e32 v219, v225, v55
	v_fma_f32 v216, v216, v132, v164
	v_fma_f32 v217, v217, v133, v165
	v_fma_f32 v218, v218, v134, v166
	v_fma_f32 v219, v219, v135, v167
	v_cvt_pk_bf16_f32 v220, v216, v217
	v_cvt_pk_bf16_f32 v221, v218, v219
	global_store_dwordx2 v194, v[220:221], s[26:27] offset:512
	v_mul_f32_e32 v216, v225, v56
	v_mul_f32_e32 v217, v225, v57
	v_mul_f32_e32 v218, v225, v58
	v_mul_f32_e32 v219, v225, v59
	v_fma_f32 v216, v216, v136, v168
	v_fma_f32 v217, v217, v137, v169
	v_fma_f32 v218, v218, v138, v170
	v_fma_f32 v219, v219, v139, v171
	v_cvt_pk_bf16_f32 v196, v216, v217
	v_cvt_pk_bf16_f32 v197, v218, v219
	global_store_dwordx2 v194, v[196:197], s[26:27] offset:1024
	v_mul_f32_e32 v216, v225, v60
	v_mul_f32_e32 v217, v225, v61
	v_mul_f32_e32 v218, v225, v62
	v_mul_f32_e32 v219, v225, v63
	v_fma_f32 v216, v216, v140, v172
	v_fma_f32 v217, v217, v141, v173
	v_fma_f32 v218, v218, v142, v174
	v_fma_f32 v219, v219, v143, v175
	v_cvt_pk_bf16_f32 v220, v216, v217
	v_cvt_pk_bf16_f32 v221, v218, v219
	global_store_dwordx2 v194, v[220:221], s[26:27] offset:1536
	v_mul_f32_e32 v216, v225, v64
	v_mul_f32_e32 v217, v225, v65
	v_mul_f32_e32 v218, v225, v66
	v_mul_f32_e32 v219, v225, v67
	v_fma_f32 v216, v216, v144, v176
	v_fma_f32 v217, v217, v145, v177
	v_fma_f32 v218, v218, v146, v178
	v_fma_f32 v219, v219, v147, v179
	v_cvt_pk_bf16_f32 v196, v216, v217
	v_cvt_pk_bf16_f32 v197, v218, v219
	global_store_dwordx2 v194, v[196:197], s[26:27] offset:2048
	v_mul_f32_e32 v216, v225, v68
	v_mul_f32_e32 v217, v225, v69
	v_mul_f32_e32 v218, v225, v70
	v_mul_f32_e32 v219, v225, v71
	v_fma_f32 v216, v216, v148, v180
	v_fma_f32 v217, v217, v149, v181
	v_fma_f32 v218, v218, v150, v182
	v_fma_f32 v219, v219, v151, v183
	v_cvt_pk_bf16_f32 v220, v216, v217
	v_cvt_pk_bf16_f32 v221, v218, v219
	global_store_dwordx2 v194, v[220:221], s[26:27] offset:2560
	v_mul_f32_e32 v216, v225, v72
	v_mul_f32_e32 v217, v225, v73
	v_mul_f32_e32 v218, v225, v74
	v_mul_f32_e32 v219, v225, v75
	v_fma_f32 v216, v216, v152, v184
	v_fma_f32 v217, v217, v153, v185
	v_fma_f32 v218, v218, v154, v186
	v_fma_f32 v219, v219, v155, v187
	v_cvt_pk_bf16_f32 v196, v216, v217
	v_cvt_pk_bf16_f32 v197, v218, v219
	global_store_dwordx2 v194, v[196:197], s[26:27] offset:3072
	v_mul_f32_e32 v216, v225, v76
	v_mul_f32_e32 v217, v225, v77
	v_mul_f32_e32 v218, v225, v78
	v_mul_f32_e32 v219, v225, v79
	v_fma_f32 v216, v216, v156, v188
	v_fma_f32 v217, v217, v157, v189
	v_fma_f32 v218, v218, v158, v190
	v_fma_f32 v219, v219, v159, v191
	v_cvt_pk_bf16_f32 v220, v216, v217
	v_cvt_pk_bf16_f32 v221, v218, v219
	global_store_dwordx2 v194, v[220:221], s[26:27] offset:3584
	s_add_i32 s0, s6, 7
	s_cmp_lt_u32 s0, 0x4000
	s_cselect_b32 s10, s68, s72
	s_cselect_b32 s11, s69, s73
	s_cselect_b32 s1, 0, 0x4000
	s_sub_i32 s1, s0, s1
	s_lshl_b32 s1, s1, 13
	s_add_u32 s10, s10, s1
	s_addc_u32 s11, s11, 0
	s_add_i32 s0, s6, 7
	s_lshl_b32 s1, s0, 12
	s_add_u32 s22, s84, s1
	s_addc_u32 s23, s85, 0
	s_add_u32 s22, s22, 0x11800000
	s_addc_u32 s23, s23, 0
	global_load_dwordx4 v[48:51], v192, s[10:11] offset:0
	global_load_dwordx4 v[52:55], v192, s[10:11] offset:1024
	global_load_dwordx4 v[56:59], v192, s[10:11] offset:2048
	global_load_dwordx4 v[60:63], v192, s[10:11] offset:3072
	global_load_dwordx4 v[64:67], v193, s[10:11] offset:0
	global_load_dwordx4 v[68:71], v193, s[10:11] offset:1024
	global_load_dwordx4 v[72:75], v193, s[10:11] offset:2048
	global_load_dwordx4 v[76:79], v193, s[10:11] offset:3072
	global_load_dwordx2 v[80:81], v194, s[22:23] offset:0
	global_load_dwordx2 v[82:83], v194, s[22:23] offset:512
	global_load_dwordx2 v[84:85], v194, s[22:23] offset:1024
	global_load_dwordx2 v[86:87], v194, s[22:23] offset:1536
	global_load_dwordx2 v[88:89], v194, s[22:23] offset:2048
	global_load_dwordx2 v[90:91], v194, s[22:23] offset:2560
	global_load_dwordx2 v[92:93], v194, s[22:23] offset:3072
	global_load_dwordx2 v[94:95], v194, s[22:23] offset:3584
	s_add_i32 s0, s6, 6
	s_add_i32 s0, s6, 6
	s_lshr_b32 s8, s0, 11
	s_cmp_lt_u32 s0, 0x4000
	s_cselect_b32 s8, s8, 8
	s_cmp_eq_u32 s8, s7
	s_cbranch_scc1 .Lp6_np6
; __device__ __forceinline__ unsigned cvt_pk_bf16(float lo, float hi) { unsigned r; asm volatile("v_cvt_pk_bf16_f32 %0, %1, %2" : "=v"(r) : "v"(lo), "v"(hi)); return r; }
; __device__ __forceinline__ float bf_lo(unsigned w) { return __uint_as_float(w << 16); }
; __device__ __forceinline__ float bf_hi(unsigned w) { return __uint_as_float(w & 0xffff0000u); }
; __device__ __forceinline__ void modulate_store(const f32x4 (&v)[8], float rstd, const float* pn, const float* modr, bf16_t* orow, int lane) {
; #pragma unroll
;     for (int j = 0; j < 8; ++j) { const int col = 4 * lane + 256 * j;
;         const f32x4 g = *(const f32x4*)(pn + col), sh = *(const f32x4*)(modr + col), sc = *(const f32x4*)(modr + DM + col);
;         const f32x4 hh = v[j] * rstd * g * (sc + 1.f) + sh;
;         u32x2 w; w.x = cvt_pk_bf16(hh[0], hh[1]); w.y = cvt_pk_bf16(hh[2], hh[3]);
;         *(u32x2*)(orow + col) = w; }
; __global__ void __launch_bounds__(NWAVES * 64, 2) mk_fwd(Args args) {
;     ...
;                 const float* m0 = mod + (size_t)r * 6144;
; #pragma unroll
;                 for (int j = 0; j < 8; ++j) { const int col = 4 * F.lane + 256 * j; const f32x4 gt = *(const f32x4*)(m0 + 2 * DM + col), pn = *(const f32x4*)(post_norm + col);
;                     const f32x4 y4 = (f32x4){bf_lo(yw[q][j].x), bf_hi(yw[q][j].x), bf_lo(yw[q][j].y), bf_hi(yw[q][j].y)};
;                     v[q][j] = v[q][j] + gt * (y4 * rsy * pn);
	s_mov_b32 s7, s8
	s_add_i32 s1, s8, 9
	s_mul_i32 s1, s1, 0x6000
	s_add_u32 s44, s84, s1
	s_addc_u32 s45, s85, 0
	s_add_u32 s44, s44, 0x2000
	s_addc_u32 s45, s45, 0
	s_add_i32 s1, s8, 9
	s_mul_i32 s1, s1, 0x6000
	s_add_u32 s36, s84, s1
	s_addc_u32 s37, s85, 0
	s_add_u32 s38, s80, 0x2000
	s_addc_u32 s39, s81, 0
	s_mul_i32 s1, s8, 0x6000
	s_add_u32 s34, s84, s1
	s_addc_u32 s35, s85, 0
	s_add_u32 s34, s34, 0x4000
	s_addc_u32 s35, s35, 0
	global_load_dwordx4 v[96:99], v192, s[34:35] offset:0
	global_load_dwordx4 v[200:203], v192, s[82:83] offset:0
	global_load_dwordx4 v[100:103], v192, s[34:35] offset:1024
	global_load_dwordx4 v[204:207], v192, s[82:83] offset:1024
	global_load_dwordx4 v[104:107], v192, s[34:35] offset:2048
	global_load_dwordx4 v[208:211], v192, s[82:83] offset:2048
	global_load_dwordx4 v[108:111], v192, s[34:35] offset:3072
	global_load_dwordx4 v[212:215], v192, s[82:83] offset:3072
	s_waitcnt vmcnt(0)
	v_mul_f32_e32 v96, v96, v200
	v_mul_f32_e32 v97, v97, v201
	v_mul_f32_e32 v98, v98, v202
	v_mul_f32_e32 v99, v99, v203
	v_mul_f32_e32 v100, v100, v204
	v_mul_f32_e32 v101, v101, v205
	v_mul_f32_e32 v102, v102, v206
	v_mul_f32_e32 v103, v103, v207
	v_mul_f32_e32 v104, v104, v208
	v_mul_f32_e32 v105, v105, v209
	v_mul_f32_e32 v106, v106, v210
	v_mul_f32_e32 v107, v107, v211
	v_mul_f32_e32 v108, v108, v212
	v_mul_f32_e32 v109, v109, v213
	v_mul_f32_e32 v110, v110, v214
	v_mul_f32_e32 v111, v111, v215
	global_load_dwordx4 v[128:131], v192, s[38:39] offset:0
	global_load_dwordx4 v[200:203], v192, s[44:45] offset:0
	global_load_dwordx4 v[160:163], v192, s[36:37] offset:0
	global_load_dwordx4 v[132:135], v192, s[38:39] offset:1024
	global_load_dwordx4 v[204:207], v192, s[44:45] offset:1024
	global_load_dwordx4 v[164:167], v192, s[36:37] offset:1024
	global_load_dwordx4 v[136:139], v192, s[38:39] offset:2048
	global_load_dwordx4 v[208:211], v192, s[44:45] offset:2048
	global_load_dwordx4 v[168:171], v192, s[36:37] offset:2048
	global_load_dwordx4 v[140:143], v192, s[38:39] offset:3072
	global_load_dwordx4 v[212:215], v192, s[44:45] offset:3072
	global_load_dwordx4 v[172:175], v192, s[36:37] offset:3072
	s_waitcnt vmcnt(0)
	v_add_f32_e32 v200, 1.0, v200
	v_add_f32_e32 v201, 1.0, v201
	v_add_f32_e32 v202, 1.0, v202
	v_add_f32_e32 v203, 1.0, v203
	v_mul_f32_e32 v128, v128, v200
	v_mul_f32_e32 v129, v129, v201
	v_mul_f32_e32 v130, v130, v202
	v_mul_f32_e32 v131, v131, v203
	v_add_f32_e32 v204, 1.0, v204
	v_add_f32_e32 v205, 1.0, v205
	v_add_f32_e32 v206, 1.0, v206
	v_add_f32_e32 v207, 1.0, v207
	v_mul_f32_e32 v132, v132, v204
	v_mul_f32_e32 v133, v133, v205
	v_mul_f32_e32 v134, v134, v206
	v_mul_f32_e32 v135, v135, v207
	v_add_f32_e32 v208, 1.0, v208
	v_add_f32_e32 v209, 1.0, v209
	v_add_f32_e32 v210, 1.0, v210
	v_add_f32_e32 v211, 1.0, v211
	v_mul_f32_e32 v136, v136, v208
	v_mul_f32_e32 v137, v137, v209
	v_mul_f32_e32 v138, v138, v210
	v_mul_f32_e32 v139, v139, v211
	v_add_f32_e32 v212, 1.0, v212
	v_add_f32_e32 v213, 1.0, v213
	v_add_f32_e32 v214, 1.0, v214
	v_add_f32_e32 v215, 1.0, v215
	v_mul_f32_e32 v140, v140, v212
	v_mul_f32_e32 v141, v141, v213
	v_mul_f32_e32 v142, v142, v214
	v_mul_f32_e32 v143, v143, v215
	global_load_dwordx4 v[112:115], v193, s[34:35] offset:0
	global_load_dwordx4 v[200:203], v193, s[82:83] offset:0
	global_load_dwordx4 v[116:119], v193, s[34:35] offset:1024
	global_load_dwordx4 v[204:207], v193, s[82:83] offset:1024
	global_load_dwordx4 v[120:123], v193, s[34:35] offset:2048
	global_load_dwordx4 v[208:211], v193, s[82:83] offset:2048
	global_load_dwordx4 v[124:127], v193, s[34:35] offset:3072
	global_load_dwordx4 v[212:215], v193, s[82:83] offset:3072
	s_waitcnt vmcnt(0)
	v_mul_f32_e32 v112, v112, v200
	v_mul_f32_e32 v113, v113, v201
	v_mul_f32_e32 v114, v114, v202
	v_mul_f32_e32 v115, v115, v203
	v_mul_f32_e32 v116, v116, v204
	v_mul_f32_e32 v117, v117, v205
	v_mul_f32_e32 v118, v118, v206
	v_mul_f32_e32 v119, v119, v207
	v_mul_f32_e32 v120, v120, v208
	v_mul_f32_e32 v121, v121, v209
	v_mul_f32_e32 v122, v122, v210
	v_mul_f32_e32 v123, v123, v211
	v_mul_f32_e32 v124, v124, v212
	v_mul_f32_e32 v125, v125, v213
	v_mul_f32_e32 v126, v126, v214
	v_mul_f32_e32 v127, v127, v215
	global_load_dwordx4 v[144:147], v193, s[38:39] offset:0
	global_load_dwordx4 v[200:203], v193, s[44:45] offset:0
	global_load_dwordx4 v[176:179], v193, s[36:37] offset:0
	global_load_dwordx4 v[148:151], v193, s[38:39] offset:1024
	global_load_dwordx4 v[204:207], v193, s[44:45] offset:1024
	global_load_dwordx4 v[180:183], v193, s[36:37] offset:1024
	global_load_dwordx4 v[152:155], v193, s[38:39] offset:2048
	global_load_dwordx4 v[208:211], v193, s[44:45] offset:2048
	global_load_dwordx4 v[184:187], v193, s[36:37] offset:2048
	global_load_dwordx4 v[156:159], v193, s[38:39] offset:3072
	global_load_dwordx4 v[212:215], v193, s[44:45] offset:3072
	global_load_dwordx4 v[188:191], v193, s[36:37] offset:3072
	s_waitcnt vmcnt(0)
	v_add_f32_e32 v200, 1.0, v200
	v_add_f32_e32 v201, 1.0, v201
	v_add_f32_e32 v202, 1.0, v202
	v_add_f32_e32 v203, 1.0, v203
	v_mul_f32_e32 v144, v144, v200
	v_mul_f32_e32 v145, v145, v201
	v_mul_f32_e32 v146, v146, v202
	v_mul_f32_e32 v147, v147, v203
	v_add_f32_e32 v204, 1.0, v204
	v_add_f32_e32 v205, 1.0, v205
	v_add_f32_e32 v206, 1.0, v206
	v_add_f32_e32 v207, 1.0, v207
	v_mul_f32_e32 v148, v148, v204
	v_mul_f32_e32 v149, v149, v205
	v_mul_f32_e32 v150, v150, v206
	v_mul_f32_e32 v151, v151, v207
	v_add_f32_e32 v208, 1.0, v208
	v_add_f32_e32 v209, 1.0, v209
	v_add_f32_e32 v210, 1.0, v210
	v_add_f32_e32 v211, 1.0, v211
	v_mul_f32_e32 v152, v152, v208
	v_mul_f32_e32 v153, v153, v209
	v_mul_f32_e32 v154, v154, v210
	v_mul_f32_e32 v155, v155, v211
	v_add_f32_e32 v212, 1.0, v212
	v_add_f32_e32 v213, 1.0, v213
	v_add_f32_e32 v214, 1.0, v214
	v_add_f32_e32 v215, 1.0, v215
	v_mul_f32_e32 v156, v156, v212
	v_mul_f32_e32 v157, v157, v213
	v_mul_f32_e32 v158, v158, v214
	v_mul_f32_e32 v159, v159, v215
; __device__ __forceinline__ float bf_lo(unsigned w) { return __uint_as_float(w << 16); }
; __device__ __forceinline__ float bf_hi(unsigned w) { return __uint_as_float(w & 0xffff0000u); }
; __global__ void __launch_bounds__(NWAVES * 64, 2) mk_fwd(Args args) {
;     ...
;             for (int q = 0; q < 3; ++q) { const int row = row0 + q; const bool lat = row < ML; const int r = lat ? row / SEQ : 8;
;                 float sy = 0.f;
; #pragma unroll
;                 for (int j = 0; j < 8; ++j) { const float a = bf_lo(yw[q][j].x), b = bf_hi(yw[q][j].x), c2 = bf_lo(yw[q][j].y), d = bf_hi(yw[q][j].y); sy += (a * a + b * b) + (c2 * c2 + d * d); }
;                 const float rsy = __builtin_amdgcn_rsqf(wave_sum(sy) * (1.f / DM) + EPS);
;                 const float* m0 = mod + (size_t)r * 6144;
; #pragma unroll
;                 for (int j = 0; j < 8; ++j) { const int col = 4 * F.lane + 256 * j; const f32x4 gt = *(const f32x4*)(m0 + 2 * DM + col), pn = *(const f32x4*)(post_norm + col);
;                     const f32x4 y4 = (f32x4){bf_lo(yw[q][j].x), bf_hi(yw[q][j].x), bf_lo(yw[q][j].y), bf_hi(yw[q][j].y)};
;                     v[q][j] = v[q][j] + gt * (y4 * rsy * pn);
;                     if (lat) *(f32x4*)(args.out + (size_t)row * DM + col) = v[q][j]; }
.Lp6_np6:
	s_waitcnt vmcnt(24)
	v_lshlrev_b32_e32 v216, 16, v32
	v_and_b32_e32 v217, 0xffff0000, v32
	v_lshlrev_b32_e32 v218, 16, v33
	v_and_b32_e32 v219, 0xffff0000, v33
	v_mul_f32_e32 v222, v216, v216
	v_mul_f32_e32 v223, v217, v217
	v_fmac_f32_e32 v222, v218, v218
	v_fmac_f32_e32 v223, v219, v219
	v_lshlrev_b32_e32 v216, 16, v34
	v_and_b32_e32 v217, 0xffff0000, v34
	v_lshlrev_b32_e32 v218, 16, v35
	v_and_b32_e32 v219, 0xffff0000, v35
	v_fmac_f32_e32 v222, v216, v216
	v_fmac_f32_e32 v223, v217, v217
	v_fmac_f32_e32 v222, v218, v218
	v_fmac_f32_e32 v223, v219, v219
	v_lshlrev_b32_e32 v216, 16, v36
	v_and_b32_e32 v217, 0xffff0000, v36
	v_lshlrev_b32_e32 v218, 16, v37
	v_and_b32_e32 v219, 0xffff0000, v37
	v_fmac_f32_e32 v222, v216, v216
	v_fmac_f32_e32 v223, v217, v217
	v_fmac_f32_e32 v222, v218, v218
	v_fmac_f32_e32 v223, v219, v219
	v_lshlrev_b32_e32 v216, 16, v38
	v_and_b32_e32 v217, 0xffff0000, v38
	v_lshlrev_b32_e32 v218, 16, v39
	v_and_b32_e32 v219, 0xffff0000, v39
	v_fmac_f32_e32 v222, v216, v216
	v_fmac_f32_e32 v223, v217, v217
	v_fmac_f32_e32 v222, v218, v218
	v_fmac_f32_e32 v223, v219, v219
	v_lshlrev_b32_e32 v216, 16, v40
	v_and_b32_e32 v217, 0xffff0000, v40
	v_lshlrev_b32_e32 v218, 16, v41
	v_and_b32_e32 v219, 0xffff0000, v41
	v_fmac_f32_e32 v222, v216, v216
	v_fmac_f32_e32 v223, v217, v217
	v_fmac_f32_e32 v222, v218, v218
	v_fmac_f32_e32 v223, v219, v219
	v_lshlrev_b32_e32 v216, 16, v42
	v_and_b32_e32 v217, 0xffff0000, v42
	v_lshlrev_b32_e32 v218, 16, v43
	v_and_b32_e32 v219, 0xffff0000, v43
	v_fmac_f32_e32 v222, v216, v216
	v_fmac_f32_e32 v223, v217, v217
	v_fmac_f32_e32 v222, v218, v218
	v_fmac_f32_e32 v223, v219, v219
	v_lshlrev_b32_e32 v216, 16, v44
	v_and_b32_e32 v217, 0xffff0000, v44
	v_lshlrev_b32_e32 v218, 16, v45
	v_and_b32_e32 v219, 0xffff0000, v45
	v_fmac_f32_e32 v222, v216, v216
	v_fmac_f32_e32 v223, v217, v217
	v_fmac_f32_e32 v222, v218, v218
	v_fmac_f32_e32 v223, v219, v219
	v_lshlrev_b32_e32 v216, 16, v46
	v_and_b32_e32 v217, 0xffff0000, v46
	v_lshlrev_b32_e32 v218, 16, v47
	v_and_b32_e32 v219, 0xffff0000, v47
	v_fmac_f32_e32 v222, v216, v216
	v_fmac_f32_e32 v223, v217, v217
	v_fmac_f32_e32 v222, v218, v218
	v_fmac_f32_e32 v223, v219, v219
	v_add_f32_e32 v222, v222, v223
	s_nop 1
	v_add_f32_dpp v224, v222, v222 quad_perm:[1,0,3,2] row_mask:0xf bank_mask:0xf
	s_nop 1
	v_add_f32_dpp v224, v224, v224 quad_perm:[2,3,0,1] row_mask:0xf bank_mask:0xf
	s_nop 1
	v_add_f32_dpp v224, v224, v224 row_half_mirror row_mask:0xf bank_mask:0xf
	s_nop 1
	v_add_f32_dpp v224, v224, v224 row_mirror row_mask:0xf bank_mask:0xf
	s_nop 1
	v_readlane_b32 s40, v224, 0
	v_readlane_b32 s41, v224, 16
	v_readlane_b32 s42, v224, 32
	v_readlane_b32 s43, v224, 48
	s_nop 1
	v_mov_b32_e32 v225, s40
	v_add_f32_e32 v225, s41, v225
	v_add_f32_e32 v225, s42, v225
	v_add_f32_e32 v225, s43, v225
	v_fmamk_f32 v225, v225, 0x3a000000, v195
	v_rsq_f32_e32 v225, v225
	s_nop 0
	v_lshlrev_b32_e32 v216, 16, v32
	v_and_b32_e32 v217, 0xffff0000, v32
	v_lshlrev_b32_e32 v218, 16, v33
	v_and_b32_e32 v219, 0xffff0000, v33
	v_mul_f32_e32 v216, v225, v216
	v_mul_f32_e32 v217, v225, v217
	v_mul_f32_e32 v218, v225, v218
	v_mul_f32_e32 v219, v225, v219
	v_fmac_f32_e32 v0, v96, v216
	v_fmac_f32_e32 v1, v97, v217
	v_fmac_f32_e32 v2, v98, v218
	v_fmac_f32_e32 v3, v99, v219
	v_lshlrev_b32_e32 v216, 16, v34
	v_and_b32_e32 v217, 0xffff0000, v34
	v_lshlrev_b32_e32 v218, 16, v35
	v_and_b32_e32 v219, 0xffff0000, v35
	v_mul_f32_e32 v216, v225, v216
	v_mul_f32_e32 v217, v225, v217
	v_mul_f32_e32 v218, v225, v218
	v_mul_f32_e32 v219, v225, v219
	v_fmac_f32_e32 v4, v100, v216
	v_fmac_f32_e32 v5, v101, v217
	v_fmac_f32_e32 v6, v102, v218
	v_fmac_f32_e32 v7, v103, v219
	v_lshlrev_b32_e32 v216, 16, v36
	v_and_b32_e32 v217, 0xffff0000, v36
	v_lshlrev_b32_e32 v218, 16, v37
	v_and_b32_e32 v219, 0xffff0000, v37
	v_mul_f32_e32 v216, v225, v216
	v_mul_f32_e32 v217, v225, v217
	v_mul_f32_e32 v218, v225, v218
	v_mul_f32_e32 v219, v225, v219
	v_fmac_f32_e32 v8, v104, v216
	v_fmac_f32_e32 v9, v105, v217
	v_fmac_f32_e32 v10, v106, v218
	v_fmac_f32_e32 v11, v107, v219
	v_lshlrev_b32_e32 v216, 16, v38
	v_and_b32_e32 v217, 0xffff0000, v38
	v_lshlrev_b32_e32 v218, 16, v39
	v_and_b32_e32 v219, 0xffff0000, v39
	v_mul_f32_e32 v216, v225, v216
	v_mul_f32_e32 v217, v225, v217
	v_mul_f32_e32 v218, v225, v218
	v_mul_f32_e32 v219, v225, v219
	v_fmac_f32_e32 v12, v108, v216
	v_fmac_f32_e32 v13, v109, v217
	v_fmac_f32_e32 v14, v110, v218
	v_fmac_f32_e32 v15, v111, v219
	v_lshlrev_b32_e32 v216, 16, v40
	v_and_b32_e32 v217, 0xffff0000, v40
	v_lshlrev_b32_e32 v218, 16, v41
	v_and_b32_e32 v219, 0xffff0000, v41
	v_mul_f32_e32 v216, v225, v216
	v_mul_f32_e32 v217, v225, v217
	v_mul_f32_e32 v218, v225, v218
	v_mul_f32_e32 v219, v225, v219
	v_fmac_f32_e32 v16, v112, v216
	v_fmac_f32_e32 v17, v113, v217
	v_fmac_f32_e32 v18, v114, v218
	v_fmac_f32_e32 v19, v115, v219
	v_lshlrev_b32_e32 v216, 16, v42
	v_and_b32_e32 v217, 0xffff0000, v42
	v_lshlrev_b32_e32 v218, 16, v43
	v_and_b32_e32 v219, 0xffff0000, v43
	v_mul_f32_e32 v216, v225, v216
	v_mul_f32_e32 v217, v225, v217
	v_mul_f32_e32 v218, v225, v218
	v_mul_f32_e32 v219, v225, v219
	v_fmac_f32_e32 v20, v116, v216
	v_fmac_f32_e32 v21, v117, v217
	v_fmac_f32_e32 v22, v118, v218
	v_fmac_f32_e32 v23, v119, v219
	v_lshlrev_b32_e32 v216, 16, v44
	v_and_b32_e32 v217, 0xffff0000, v44
	v_lshlrev_b32_e32 v218, 16, v45
	v_and_b32_e32 v219, 0xffff0000, v45
	v_mul_f32_e32 v216, v225, v216
	v_mul_f32_e32 v217, v225, v217
	v_mul_f32_e32 v218, v225, v218
	v_mul_f32_e32 v219, v225, v219
	v_fmac_f32_e32 v24, v120, v216
	v_fmac_f32_e32 v25, v121, v217
	v_fmac_f32_e32 v26, v122, v218
; __device__ __forceinline__ unsigned cvt_pk_bf16(float lo, float hi) { unsigned r; asm volatile("v_cvt_pk_bf16_f32 %0, %1, %2" : "=v"(r) : "v"(lo), "v"(hi)); return r; }
; __device__ __forceinline__ void modulate_store(const f32x4 (&v)[8], float rstd, const float* pn, const float* modr, bf16_t* orow, int lane) {
; #pragma unroll
;     for (int j = 0; j < 8; ++j) { const int col = 4 * lane + 256 * j;
;         const f32x4 g = *(const f32x4*)(pn + col), sh = *(const f32x4*)(modr + col), sc = *(const f32x4*)(modr + DM + col);
;         const f32x4 hh = v[j] * rstd * g * (sc + 1.f) + sh;
;         u32x2 w; w.x = cvt_pk_bf16(hh[0], hh[1]); w.y = cvt_pk_bf16(hh[2], hh[3]);
;         *(u32x2*)(orow + col) = w; }
; __global__ void __launch_bounds__(NWAVES * 64, 2) mk_fwd(Args args) {
;     ...
;                     v[q][j] = v[q][j] + gt * (y4 * rsy * pn);
;                     if (lat) *(f32x4*)(args.out + (size_t)row * DM + col) = v[q][j]; }
;                 const float rstd = __builtin_amdgcn_rsqf(sumsq8(v[q]) * (1.f / DM) + EPS);
;                 modulate_store(v[q], rstd, pre_norm + DM, mod + (size_t)(9 + r) * 6144, H + (size_t)row * DM, F.lane); }
	v_fmac_f32_e32 v27, v123, v219
	v_lshlrev_b32_e32 v216, 16, v46
	v_and_b32_e32 v217, 0xffff0000, v46
	v_lshlrev_b32_e32 v218, 16, v47
	v_and_b32_e32 v219, 0xffff0000, v47
	v_mul_f32_e32 v216, v225, v216
	v_mul_f32_e32 v217, v225, v217
	v_mul_f32_e32 v218, v225, v218
	v_mul_f32_e32 v219, v225, v219
	v_fmac_f32_e32 v28, v124, v216
	v_fmac_f32_e32 v29, v125, v217
	v_fmac_f32_e32 v30, v126, v218
	v_fmac_f32_e32 v31, v127, v219
	v_mul_f32_e32 v222, v0, v0
	v_mul_f32_e32 v223, v1, v1
	v_fmac_f32_e32 v222, v2, v2
	v_fmac_f32_e32 v223, v3, v3
	v_fmac_f32_e32 v222, v4, v4
	v_fmac_f32_e32 v223, v5, v5
	v_fmac_f32_e32 v222, v6, v6
	v_fmac_f32_e32 v223, v7, v7
	v_fmac_f32_e32 v222, v8, v8
	v_fmac_f32_e32 v223, v9, v9
	v_fmac_f32_e32 v222, v10, v10
	v_fmac_f32_e32 v223, v11, v11
	v_fmac_f32_e32 v222, v12, v12
	v_fmac_f32_e32 v223, v13, v13
	v_fmac_f32_e32 v222, v14, v14
	v_fmac_f32_e32 v223, v15, v15
	v_fmac_f32_e32 v222, v16, v16
	v_fmac_f32_e32 v223, v17, v17
	v_fmac_f32_e32 v222, v18, v18
	v_fmac_f32_e32 v223, v19, v19
	v_fmac_f32_e32 v222, v20, v20
	v_fmac_f32_e32 v223, v21, v21
	v_fmac_f32_e32 v222, v22, v22
	v_fmac_f32_e32 v223, v23, v23
	v_fmac_f32_e32 v222, v24, v24
	v_fmac_f32_e32 v223, v25, v25
	v_fmac_f32_e32 v222, v26, v26
	v_fmac_f32_e32 v223, v27, v27
	v_fmac_f32_e32 v222, v28, v28
	v_fmac_f32_e32 v223, v29, v29
	v_fmac_f32_e32 v222, v30, v30
	v_fmac_f32_e32 v223, v31, v31
	v_add_f32_e32 v222, v222, v223
	s_nop 1
	v_add_f32_dpp v224, v222, v222 quad_perm:[1,0,3,2] row_mask:0xf bank_mask:0xf
	s_nop 1
	v_add_f32_dpp v224, v224, v224 quad_perm:[2,3,0,1] row_mask:0xf bank_mask:0xf
	s_nop 1
	v_add_f32_dpp v224, v224, v224 row_half_mirror row_mask:0xf bank_mask:0xf
	s_nop 1
	v_add_f32_dpp v224, v224, v224 row_mirror row_mask:0xf bank_mask:0xf
	s_nop 1
	v_readlane_b32 s40, v224, 0
	v_readlane_b32 s41, v224, 16
	v_readlane_b32 s42, v224, 32
	v_readlane_b32 s43, v224, 48
	s_nop 1
	v_mov_b32_e32 v225, s40
	v_add_f32_e32 v225, s41, v225
	v_add_f32_e32 v225, s42, v225
	v_add_f32_e32 v225, s43, v225
	v_fmamk_f32 v225, v225, 0x3a000000, v195
	v_rsq_f32_e32 v225, v225
	s_nop 0
	s_add_i32 s0, s6, 6
	s_lshl_b32 s1, s0, 12
	s_add_u32 s26, s84, s1
	s_addc_u32 s27, s85, 0
	s_add_u32 s26, s26, 0x4000000
	s_addc_u32 s27, s27, 0
	v_mul_f32_e32 v216, v225, v0
	v_mul_f32_e32 v217, v225, v1
	v_mul_f32_e32 v218, v225, v2
	v_mul_f32_e32 v219, v225, v3
	v_fma_f32 v216, v216, v128, v160
	v_fma_f32 v217, v217, v129, v161
	v_fma_f32 v218, v218, v130, v162
	v_fma_f32 v219, v219, v131, v163
	v_cvt_pk_bf16_f32 v196, v216, v217
	v_cvt_pk_bf16_f32 v197, v218, v219
	global_store_dwordx2 v194, v[196:197], s[26:27] offset:0
	v_mul_f32_e32 v216, v225, v4
	v_mul_f32_e32 v217, v225, v5
	v_mul_f32_e32 v218, v225, v6
	v_mul_f32_e32 v219, v225, v7
	v_fma_f32 v216, v216, v132, v164
	v_fma_f32 v217, v217, v133, v165
	v_fma_f32 v218, v218, v134, v166
	v_fma_f32 v219, v219, v135, v167
	v_cvt_pk_bf16_f32 v220, v216, v217
	v_cvt_pk_bf16_f32 v221, v218, v219
	global_store_dwordx2 v194, v[220:221], s[26:27] offset:512
	v_mul_f32_e32 v216, v225, v8
	v_mul_f32_e32 v217, v225, v9
	v_mul_f32_e32 v218, v225, v10
	v_mul_f32_e32 v219, v225, v11
	v_fma_f32 v216, v216, v136, v168
	v_fma_f32 v217, v217, v137, v169
	v_fma_f32 v218, v218, v138, v170
	v_fma_f32 v219, v219, v139, v171
	v_cvt_pk_bf16_f32 v196, v216, v217
	v_cvt_pk_bf16_f32 v197, v218, v219
	global_store_dwordx2 v194, v[196:197], s[26:27] offset:1024
	v_mul_f32_e32 v216, v225, v12
	v_mul_f32_e32 v217, v225, v13
	v_mul_f32_e32 v218, v225, v14
	v_mul_f32_e32 v219, v225, v15
	v_fma_f32 v216, v216, v140, v172
	v_fma_f32 v217, v217, v141, v173
	v_fma_f32 v218, v218, v142, v174
	v_fma_f32 v219, v219, v143, v175
	v_cvt_pk_bf16_f32 v220, v216, v217
	v_cvt_pk_bf16_f32 v221, v218, v219
	global_store_dwordx2 v194, v[220:221], s[26:27] offset:1536
	v_mul_f32_e32 v216, v225, v16
	v_mul_f32_e32 v217, v225, v17
	v_mul_f32_e32 v218, v225, v18
	v_mul_f32_e32 v219, v225, v19
	v_fma_f32 v216, v216, v144, v176
	v_fma_f32 v217, v217, v145, v177
	v_fma_f32 v218, v218, v146, v178
	v_fma_f32 v219, v219, v147, v179
	v_cvt_pk_bf16_f32 v196, v216, v217
	v_cvt_pk_bf16_f32 v197, v218, v219
	global_store_dwordx2 v194, v[196:197], s[26:27] offset:2048
	v_mul_f32_e32 v216, v225, v20
	v_mul_f32_e32 v217, v225, v21
	v_mul_f32_e32 v218, v225, v22
	v_mul_f32_e32 v219, v225, v23
	v_fma_f32 v216, v216, v148, v180
	v_fma_f32 v217, v217, v149, v181
	v_fma_f32 v218, v218, v150, v182
	v_fma_f32 v219, v219, v151, v183
	v_cvt_pk_bf16_f32 v220, v216, v217
	v_cvt_pk_bf16_f32 v221, v218, v219
	global_store_dwordx2 v194, v[220:221], s[26:27] offset:2560
	v_mul_f32_e32 v216, v225, v24
	v_mul_f32_e32 v217, v225, v25
	v_mul_f32_e32 v218, v225, v26
	v_mul_f32_e32 v219, v225, v27
	v_fma_f32 v216, v216, v152, v184
	v_fma_f32 v217, v217, v153, v185
	v_fma_f32 v218, v218, v154, v186
	v_fma_f32 v219, v219, v155, v187
	v_cvt_pk_bf16_f32 v196, v216, v217
	v_cvt_pk_bf16_f32 v197, v218, v219
	global_store_dwordx2 v194, v[196:197], s[26:27] offset:3072
	v_mul_f32_e32 v216, v225, v28
	v_mul_f32_e32 v217, v225, v29
	v_mul_f32_e32 v218, v225, v30
	v_mul_f32_e32 v219, v225, v31
	v_fma_f32 v216, v216, v156, v188
	v_fma_f32 v217, v217, v157, v189
	v_fma_f32 v218, v218, v158, v190
	v_fma_f32 v219, v219, v159, v191
	v_cvt_pk_bf16_f32 v220, v216, v217
	v_cvt_pk_bf16_f32 v221, v218, v219
	global_store_dwordx2 v194, v[220:221], s[26:27] offset:3584
	s_add_i32 s0, s6, 8
	s_cmp_lt_u32 s0, 0x4000
	s_cselect_b32 s10, s68, s72
	s_cselect_b32 s11, s69, s73
	s_cselect_b32 s1, 0, 0x4000
	s_sub_i32 s1, s0, s1
	s_lshl_b32 s1, s1, 13
	s_add_u32 s10, s10, s1
	s_addc_u32 s11, s11, 0
	s_add_i32 s0, s6, 8
	s_lshl_b32 s1, s0, 12
	s_add_u32 s22, s84, s1
	s_addc_u32 s23, s85, 0
	s_add_u32 s22, s22, 0x11800000
	s_addc_u32 s23, s23, 0
	global_load_dwordx4 v[0:3], v192, s[10:11] offset:0
	global_load_dwordx4 v[4:7], v192, s[10:11] offset:1024
	global_load_dwordx4 v[8:11], v192, s[10:11] offset:2048
	global_load_dwordx4 v[12:15], v192, s[10:11] offset:3072
	global_load_dwordx4 v[16:19], v193, s[10:11] offset:0
	global_load_dwordx4 v[20:23], v193, s[10:11] offset:1024
	global_load_dwordx4 v[24:27], v193, s[10:11] offset:2048
	global_load_dwordx4 v[28:31], v193, s[10:11] offset:3072
	global_load_dwordx2 v[32:33], v194, s[22:23] offset:0
	global_load_dwordx2 v[34:35], v194, s[22:23] offset:512
	global_load_dwordx2 v[36:37], v194, s[22:23] offset:1024
	global_load_dwordx2 v[38:39], v194, s[22:23] offset:1536
	global_load_dwordx2 v[40:41], v194, s[22:23] offset:2048
	global_load_dwordx2 v[42:43], v194, s[22:23] offset:2560
	global_load_dwordx2 v[44:45], v194, s[22:23] offset:3072
	global_load_dwordx2 v[46:47], v194, s[22:23] offset:3584
	s_add_i32 s0, s6, 7
	s_add_i32 s0, s6, 7
	s_lshr_b32 s8, s0, 11
	s_cmp_lt_u32 s0, 0x4000
	s_cselect_b32 s8, s8, 8
	s_cmp_eq_u32 s8, s7
	s_cbranch_scc1 .Lp6_np7
; __device__ __forceinline__ unsigned cvt_pk_bf16(float lo, float hi) { unsigned r; asm volatile("v_cvt_pk_bf16_f32 %0, %1, %2" : "=v"(r) : "v"(lo), "v"(hi)); return r; }
; __device__ __forceinline__ float bf_lo(unsigned w) { return __uint_as_float(w << 16); }
; __device__ __forceinline__ float bf_hi(unsigned w) { return __uint_as_float(w & 0xffff0000u); }
; __device__ __forceinline__ void modulate_store(const f32x4 (&v)[8], float rstd, const float* pn, const float* modr, bf16_t* orow, int lane) {
; #pragma unroll
;     for (int j = 0; j < 8; ++j) { const int col = 4 * lane + 256 * j;
;         const f32x4 g = *(const f32x4*)(pn + col), sh = *(const f32x4*)(modr + col), sc = *(const f32x4*)(modr + DM + col);
;         const f32x4 hh = v[j] * rstd * g * (sc + 1.f) + sh;
;         u32x2 w; w.x = cvt_pk_bf16(hh[0], hh[1]); w.y = cvt_pk_bf16(hh[2], hh[3]);
;         *(u32x2*)(orow + col) = w; }
; __global__ void __launch_bounds__(NWAVES * 64, 2) mk_fwd(Args args) {
;     ...
;                 const float* m0 = mod + (size_t)r * 6144;
; #pragma unroll
;                 for (int j = 0; j < 8; ++j) { const int col = 4 * F.lane + 256 * j; const f32x4 gt = *(const f32x4*)(m0 + 2 * DM + col), pn = *(const f32x4*)(post_norm + col);
;                     const f32x4 y4 = (f32x4){bf_lo(yw[q][j].x), bf_hi(yw[q][j].x), bf_lo(yw[q][j].y), bf_hi(yw[q][j].y)};
;                     v[q][j] = v[q][j] + gt * (y4 * rsy * pn);
	s_mov_b32 s7, s8
	s_add_i32 s1, s8, 9
	s_mul_i32 s1, s1, 0x6000
	s_add_u32 s44, s84, s1
	s_addc_u32 s45, s85, 0
	s_add_u32 s44, s44, 0x2000
	s_addc_u32 s45, s45, 0
	s_add_i32 s1, s8, 9
	s_mul_i32 s1, s1, 0x6000
	s_add_u32 s36, s84, s1
	s_addc_u32 s37, s85, 0
	s_add_u32 s38, s80, 0x2000
	s_addc_u32 s39, s81, 0
	s_mul_i32 s1, s8, 0x6000
	s_add_u32 s34, s84, s1
	s_addc_u32 s35, s85, 0
	s_add_u32 s34, s34, 0x4000
	s_addc_u32 s35, s35, 0
	global_load_dwordx4 v[96:99], v192, s[34:35] offset:0
	global_load_dwordx4 v[200:203], v192, s[82:83] offset:0
	global_load_dwordx4 v[100:103], v192, s[34:35] offset:1024
	global_load_dwordx4 v[204:207], v192, s[82:83] offset:1024
	global_load_dwordx4 v[104:107], v192, s[34:35] offset:2048
	global_load_dwordx4 v[208:211], v192, s[82:83] offset:2048
	global_load_dwordx4 v[108:111], v192, s[34:35] offset:3072
	global_load_dwordx4 v[212:215], v192, s[82:83] offset:3072
	s_waitcnt vmcnt(0)
	v_mul_f32_e32 v96, v96, v200
	v_mul_f32_e32 v97, v97, v201
	v_mul_f32_e32 v98, v98, v202
	v_mul_f32_e32 v99, v99, v203
	v_mul_f32_e32 v100, v100, v204
	v_mul_f32_e32 v101, v101, v205
	v_mul_f32_e32 v102, v102, v206
	v_mul_f32_e32 v103, v103, v207
	v_mul_f32_e32 v104, v104, v208
	v_mul_f32_e32 v105, v105, v209
	v_mul_f32_e32 v106, v106, v210
	v_mul_f32_e32 v107, v107, v211
	v_mul_f32_e32 v108, v108, v212
	v_mul_f32_e32 v109, v109, v213
	v_mul_f32_e32 v110, v110, v214
	v_mul_f32_e32 v111, v111, v215
	global_load_dwordx4 v[128:131], v192, s[38:39] offset:0
	global_load_dwordx4 v[200:203], v192, s[44:45] offset:0
	global_load_dwordx4 v[160:163], v192, s[36:37] offset:0
	global_load_dwordx4 v[132:135], v192, s[38:39] offset:1024
	global_load_dwordx4 v[204:207], v192, s[44:45] offset:1024
	global_load_dwordx4 v[164:167], v192, s[36:37] offset:1024
	global_load_dwordx4 v[136:139], v192, s[38:39] offset:2048
	global_load_dwordx4 v[208:211], v192, s[44:45] offset:2048
	global_load_dwordx4 v[168:171], v192, s[36:37] offset:2048
	global_load_dwordx4 v[140:143], v192, s[38:39] offset:3072
	global_load_dwordx4 v[212:215], v192, s[44:45] offset:3072
	global_load_dwordx4 v[172:175], v192, s[36:37] offset:3072
	s_waitcnt vmcnt(0)
	v_add_f32_e32 v200, 1.0, v200
	v_add_f32_e32 v201, 1.0, v201
	v_add_f32_e32 v202, 1.0, v202
	v_add_f32_e32 v203, 1.0, v203
	v_mul_f32_e32 v128, v128, v200
	v_mul_f32_e32 v129, v129, v201
	v_mul_f32_e32 v130, v130, v202
	v_mul_f32_e32 v131, v131, v203
	v_add_f32_e32 v204, 1.0, v204
	v_add_f32_e32 v205, 1.0, v205
	v_add_f32_e32 v206, 1.0, v206
	v_add_f32_e32 v207, 1.0, v207
	v_mul_f32_e32 v132, v132, v204
	v_mul_f32_e32 v133, v133, v205
	v_mul_f32_e32 v134, v134, v206
	v_mul_f32_e32 v135, v135, v207
	v_add_f32_e32 v208, 1.0, v208
	v_add_f32_e32 v209, 1.0, v209
	v_add_f32_e32 v210, 1.0, v210
	v_add_f32_e32 v211, 1.0, v211
	v_mul_f32_e32 v136, v136, v208
	v_mul_f32_e32 v137, v137, v209
	v_mul_f32_e32 v138, v138, v210
	v_mul_f32_e32 v139, v139, v211
	v_add_f32_e32 v212, 1.0, v212
	v_add_f32_e32 v213, 1.0, v213
	v_add_f32_e32 v214, 1.0, v214
	v_add_f32_e32 v215, 1.0, v215
	v_mul_f32_e32 v140, v140, v212
	v_mul_f32_e32 v141, v141, v213
	v_mul_f32_e32 v142, v142, v214
	v_mul_f32_e32 v143, v143, v215
	global_load_dwordx4 v[112:115], v193, s[34:35] offset:0
	global_load_dwordx4 v[200:203], v193, s[82:83] offset:0
	global_load_dwordx4 v[116:119], v193, s[34:35] offset:1024
	global_load_dwordx4 v[204:207], v193, s[82:83] offset:1024
	global_load_dwordx4 v[120:123], v193, s[34:35] offset:2048
	global_load_dwordx4 v[208:211], v193, s[82:83] offset:2048
	global_load_dwordx4 v[124:127], v193, s[34:35] offset:3072
	global_load_dwordx4 v[212:215], v193, s[82:83] offset:3072
	s_waitcnt vmcnt(0)
	v_mul_f32_e32 v112, v112, v200
	v_mul_f32_e32 v113, v113, v201
	v_mul_f32_e32 v114, v114, v202
	v_mul_f32_e32 v115, v115, v203
	v_mul_f32_e32 v116, v116, v204
	v_mul_f32_e32 v117, v117, v205
	v_mul_f32_e32 v118, v118, v206
	v_mul_f32_e32 v119, v119, v207
	v_mul_f32_e32 v120, v120, v208
	v_mul_f32_e32 v121, v121, v209
	v_mul_f32_e32 v122, v122, v210
	v_mul_f32_e32 v123, v123, v211
	v_mul_f32_e32 v124, v124, v212
	v_mul_f32_e32 v125, v125, v213
	v_mul_f32_e32 v126, v126, v214
	v_mul_f32_e32 v127, v127, v215
	global_load_dwordx4 v[144:147], v193, s[38:39] offset:0
	global_load_dwordx4 v[200:203], v193, s[44:45] offset:0
	global_load_dwordx4 v[176:179], v193, s[36:37] offset:0
	global_load_dwordx4 v[148:151], v193, s[38:39] offset:1024
	global_load_dwordx4 v[204:207], v193, s[44:45] offset:1024
	global_load_dwordx4 v[180:183], v193, s[36:37] offset:1024
	global_load_dwordx4 v[152:155], v193, s[38:39] offset:2048
	global_load_dwordx4 v[208:211], v193, s[44:45] offset:2048
	global_load_dwordx4 v[184:187], v193, s[36:37] offset:2048
	global_load_dwordx4 v[156:159], v193, s[38:39] offset:3072
	global_load_dwordx4 v[212:215], v193, s[44:45] offset:3072
	global_load_dwordx4 v[188:191], v193, s[36:37] offset:3072
	s_waitcnt vmcnt(0)
	v_add_f32_e32 v200, 1.0, v200
	v_add_f32_e32 v201, 1.0, v201
	v_add_f32_e32 v202, 1.0, v202
	v_add_f32_e32 v203, 1.0, v203
	v_mul_f32_e32 v144, v144, v200
	v_mul_f32_e32 v145, v145, v201
	v_mul_f32_e32 v146, v146, v202
	v_mul_f32_e32 v147, v147, v203
	v_add_f32_e32 v204, 1.0, v204
	v_add_f32_e32 v205, 1.0, v205
	v_add_f32_e32 v206, 1.0, v206
	v_add_f32_e32 v207, 1.0, v207
	v_mul_f32_e32 v148, v148, v204
	v_mul_f32_e32 v149, v149, v205
	v_mul_f32_e32 v150, v150, v206
	v_mul_f32_e32 v151, v151, v207
	v_add_f32_e32 v208, 1.0, v208
	v_add_f32_e32 v209, 1.0, v209
	v_add_f32_e32 v210, 1.0, v210
	v_add_f32_e32 v211, 1.0, v211
	v_mul_f32_e32 v152, v152, v208
	v_mul_f32_e32 v153, v153, v209
	v_mul_f32_e32 v154, v154, v210
	v_mul_f32_e32 v155, v155, v211
	v_add_f32_e32 v212, 1.0, v212
	v_add_f32_e32 v213, 1.0, v213
	v_add_f32_e32 v214, 1.0, v214
	v_add_f32_e32 v215, 1.0, v215
	v_mul_f32_e32 v156, v156, v212
	v_mul_f32_e32 v157, v157, v213
	v_mul_f32_e32 v158, v158, v214
	v_mul_f32_e32 v159, v159, v215
; __device__ __forceinline__ float bf_lo(unsigned w) { return __uint_as_float(w << 16); }
; __device__ __forceinline__ float bf_hi(unsigned w) { return __uint_as_float(w & 0xffff0000u); }
; __global__ void __launch_bounds__(NWAVES * 64, 2) mk_fwd(Args args) {
;     ...
;             for (int q = 0; q < 3; ++q) { const int row = row0 + q; const bool lat = row < ML; const int r = lat ? row / SEQ : 8;
;                 float sy = 0.f;
; #pragma unroll
;                 for (int j = 0; j < 8; ++j) { const float a = bf_lo(yw[q][j].x), b = bf_hi(yw[q][j].x), c2 = bf_lo(yw[q][j].y), d = bf_hi(yw[q][j].y); sy += (a * a + b * b) + (c2 * c2 + d * d); }
;                 const float rsy = __builtin_amdgcn_rsqf(wave_sum(sy) * (1.f / DM) + EPS);
;                 const float* m0 = mod + (size_t)r * 6144;
; #pragma unroll
;                 for (int j = 0; j < 8; ++j) { const int col = 4 * F.lane + 256 * j; const f32x4 gt = *(const f32x4*)(m0 + 2 * DM + col), pn = *(const f32x4*)(post_norm + col);
;                     const f32x4 y4 = (f32x4){bf_lo(yw[q][j].x), bf_hi(yw[q][j].x), bf_lo(yw[q][j].y), bf_hi(yw[q][j].y)};
;                     v[q][j] = v[q][j] + gt * (y4 * rsy * pn);
;                     if (lat) *(f32x4*)(args.out + (size_t)row * DM + col) = v[q][j]; }
.Lp6_np7:
	s_waitcnt vmcnt(24)
	v_lshlrev_b32_e32 v216, 16, v80
	v_and_b32_e32 v217, 0xffff0000, v80
	v_lshlrev_b32_e32 v218, 16, v81
	v_and_b32_e32 v219, 0xffff0000, v81
	v_mul_f32_e32 v222, v216, v216
	v_mul_f32_e32 v223, v217, v217
	v_fmac_f32_e32 v222, v218, v218
	v_fmac_f32_e32 v223, v219, v219
	v_lshlrev_b32_e32 v216, 16, v82
	v_and_b32_e32 v217, 0xffff0000, v82
	v_lshlrev_b32_e32 v218, 16, v83
	v_and_b32_e32 v219, 0xffff0000, v83
	v_fmac_f32_e32 v222, v216, v216
	v_fmac_f32_e32 v223, v217, v217
	v_fmac_f32_e32 v222, v218, v218
	v_fmac_f32_e32 v223, v219, v219
	v_lshlrev_b32_e32 v216, 16, v84
	v_and_b32_e32 v217, 0xffff0000, v84
	v_lshlrev_b32_e32 v218, 16, v85
	v_and_b32_e32 v219, 0xffff0000, v85
	v_fmac_f32_e32 v222, v216, v216
	v_fmac_f32_e32 v223, v217, v217
	v_fmac_f32_e32 v222, v218, v218
	v_fmac_f32_e32 v223, v219, v219
	v_lshlrev_b32_e32 v216, 16, v86
	v_and_b32_e32 v217, 0xffff0000, v86
	v_lshlrev_b32_e32 v218, 16, v87
	v_and_b32_e32 v219, 0xffff0000, v87
	v_fmac_f32_e32 v222, v216, v216
	v_fmac_f32_e32 v223, v217, v217
	v_fmac_f32_e32 v222, v218, v218
	v_fmac_f32_e32 v223, v219, v219
	v_lshlrev_b32_e32 v216, 16, v88
	v_and_b32_e32 v217, 0xffff0000, v88
	v_lshlrev_b32_e32 v218, 16, v89
	v_and_b32_e32 v219, 0xffff0000, v89
	v_fmac_f32_e32 v222, v216, v216
	v_fmac_f32_e32 v223, v217, v217
	v_fmac_f32_e32 v222, v218, v218
	v_fmac_f32_e32 v223, v219, v219
	v_lshlrev_b32_e32 v216, 16, v90
	v_and_b32_e32 v217, 0xffff0000, v90
	v_lshlrev_b32_e32 v218, 16, v91
	v_and_b32_e32 v219, 0xffff0000, v91
	v_fmac_f32_e32 v222, v216, v216
	v_fmac_f32_e32 v223, v217, v217
	v_fmac_f32_e32 v222, v218, v218
	v_fmac_f32_e32 v223, v219, v219
	v_lshlrev_b32_e32 v216, 16, v92
	v_and_b32_e32 v217, 0xffff0000, v92
	v_lshlrev_b32_e32 v218, 16, v93
	v_and_b32_e32 v219, 0xffff0000, v93
	v_fmac_f32_e32 v222, v216, v216
	v_fmac_f32_e32 v223, v217, v217
	v_fmac_f32_e32 v222, v218, v218
	v_fmac_f32_e32 v223, v219, v219
	v_lshlrev_b32_e32 v216, 16, v94
	v_and_b32_e32 v217, 0xffff0000, v94
	v_lshlrev_b32_e32 v218, 16, v95
	v_and_b32_e32 v219, 0xffff0000, v95
	v_fmac_f32_e32 v222, v216, v216
	v_fmac_f32_e32 v223, v217, v217
	v_fmac_f32_e32 v222, v218, v218
	v_fmac_f32_e32 v223, v219, v219
	v_add_f32_e32 v222, v222, v223
	s_nop 1
	v_add_f32_dpp v224, v222, v222 quad_perm:[1,0,3,2] row_mask:0xf bank_mask:0xf
	s_nop 1
	v_add_f32_dpp v224, v224, v224 quad_perm:[2,3,0,1] row_mask:0xf bank_mask:0xf
	s_nop 1
	v_add_f32_dpp v224, v224, v224 row_half_mirror row_mask:0xf bank_mask:0xf
	s_nop 1
	v_add_f32_dpp v224, v224, v224 row_mirror row_mask:0xf bank_mask:0xf
	s_nop 1
	v_readlane_b32 s40, v224, 0
	v_readlane_b32 s41, v224, 16
	v_readlane_b32 s42, v224, 32
	v_readlane_b32 s43, v224, 48
	s_nop 1
	v_mov_b32_e32 v225, s40
	v_add_f32_e32 v225, s41, v225
	v_add_f32_e32 v225, s42, v225
	v_add_f32_e32 v225, s43, v225
	v_fmamk_f32 v225, v225, 0x3a000000, v195
	v_rsq_f32_e32 v225, v225
	s_nop 0
	v_lshlrev_b32_e32 v216, 16, v80
	v_and_b32_e32 v217, 0xffff0000, v80
	v_lshlrev_b32_e32 v218, 16, v81
	v_and_b32_e32 v219, 0xffff0000, v81
	v_mul_f32_e32 v216, v225, v216
	v_mul_f32_e32 v217, v225, v217
	v_mul_f32_e32 v218, v225, v218
	v_mul_f32_e32 v219, v225, v219
	v_fmac_f32_e32 v48, v96, v216
	v_fmac_f32_e32 v49, v97, v217
	v_fmac_f32_e32 v50, v98, v218
	v_fmac_f32_e32 v51, v99, v219
	v_lshlrev_b32_e32 v216, 16, v82
	v_and_b32_e32 v217, 0xffff0000, v82
	v_lshlrev_b32_e32 v218, 16, v83
	v_and_b32_e32 v219, 0xffff0000, v83
	v_mul_f32_e32 v216, v225, v216
	v_mul_f32_e32 v217, v225, v217
	v_mul_f32_e32 v218, v225, v218
	v_mul_f32_e32 v219, v225, v219
	v_fmac_f32_e32 v52, v100, v216
	v_fmac_f32_e32 v53, v101, v217
	v_fmac_f32_e32 v54, v102, v218
	v_fmac_f32_e32 v55, v103, v219
	v_lshlrev_b32_e32 v216, 16, v84
	v_and_b32_e32 v217, 0xffff0000, v84
	v_lshlrev_b32_e32 v218, 16, v85
	v_and_b32_e32 v219, 0xffff0000, v85
	v_mul_f32_e32 v216, v225, v216
	v_mul_f32_e32 v217, v225, v217
	v_mul_f32_e32 v218, v225, v218
	v_mul_f32_e32 v219, v225, v219
	v_fmac_f32_e32 v56, v104, v216
	v_fmac_f32_e32 v57, v105, v217
	v_fmac_f32_e32 v58, v106, v218
	v_fmac_f32_e32 v59, v107, v219
	v_lshlrev_b32_e32 v216, 16, v86
	v_and_b32_e32 v217, 0xffff0000, v86
	v_lshlrev_b32_e32 v218, 16, v87
	v_and_b32_e32 v219, 0xffff0000, v87
	v_mul_f32_e32 v216, v225, v216
	v_mul_f32_e32 v217, v225, v217
	v_mul_f32_e32 v218, v225, v218
	v_mul_f32_e32 v219, v225, v219
	v_fmac_f32_e32 v60, v108, v216
	v_fmac_f32_e32 v61, v109, v217
	v_fmac_f32_e32 v62, v110, v218
	v_fmac_f32_e32 v63, v111, v219
	v_lshlrev_b32_e32 v216, 16, v88
	v_and_b32_e32 v217, 0xffff0000, v88
	v_lshlrev_b32_e32 v218, 16, v89
	v_and_b32_e32 v219, 0xffff0000, v89
	v_mul_f32_e32 v216, v225, v216
	v_mul_f32_e32 v217, v225, v217
	v_mul_f32_e32 v218, v225, v218
	v_mul_f32_e32 v219, v225, v219
	v_fmac_f32_e32 v64, v112, v216
	v_fmac_f32_e32 v65, v113, v217
	v_fmac_f32_e32 v66, v114, v218
	v_fmac_f32_e32 v67, v115, v219
	v_lshlrev_b32_e32 v216, 16, v90
	v_and_b32_e32 v217, 0xffff0000, v90
	v_lshlrev_b32_e32 v218, 16, v91
	v_and_b32_e32 v219, 0xffff0000, v91
	v_mul_f32_e32 v216, v225, v216
	v_mul_f32_e32 v217, v225, v217
	v_mul_f32_e32 v218, v225, v218
	v_mul_f32_e32 v219, v225, v219
	v_fmac_f32_e32 v68, v116, v216
	v_fmac_f32_e32 v69, v117, v217
	v_fmac_f32_e32 v70, v118, v218
	v_fmac_f32_e32 v71, v119, v219
	v_lshlrev_b32_e32 v216, 16, v92
	v_and_b32_e32 v217, 0xffff0000, v92
	v_lshlrev_b32_e32 v218, 16, v93
	v_and_b32_e32 v219, 0xffff0000, v93
	v_mul_f32_e32 v216, v225, v216
	v_mul_f32_e32 v217, v225, v217
	v_mul_f32_e32 v218, v225, v218
	v_mul_f32_e32 v219, v225, v219
	v_fmac_f32_e32 v72, v120, v216
	v_fmac_f32_e32 v73, v121, v217
	v_fmac_f32_e32 v74, v122, v218
; __device__ __forceinline__ unsigned cvt_pk_bf16(float lo, float hi) { unsigned r; asm volatile("v_cvt_pk_bf16_f32 %0, %1, %2" : "=v"(r) : "v"(lo), "v"(hi)); return r; }
; __device__ __forceinline__ void modulate_store(const f32x4 (&v)[8], float rstd, const float* pn, const float* modr, bf16_t* orow, int lane) {
; #pragma unroll
;     for (int j = 0; j < 8; ++j) { const int col = 4 * lane + 256 * j;
;         const f32x4 g = *(const f32x4*)(pn + col), sh = *(const f32x4*)(modr + col), sc = *(const f32x4*)(modr + DM + col);
;         const f32x4 hh = v[j] * rstd * g * (sc + 1.f) + sh;
;         u32x2 w; w.x = cvt_pk_bf16(hh[0], hh[1]); w.y = cvt_pk_bf16(hh[2], hh[3]);
;         *(u32x2*)(orow + col) = w; }
; __global__ void __launch_bounds__(NWAVES * 64, 2) mk_fwd(Args args) {
;     ...
;                     v[q][j] = v[q][j] + gt * (y4 * rsy * pn);
;                     if (lat) *(f32x4*)(args.out + (size_t)row * DM + col) = v[q][j]; }
;                 const float rstd = __builtin_amdgcn_rsqf(sumsq8(v[q]) * (1.f / DM) + EPS);
;                 modulate_store(v[q], rstd, pre_norm + DM, mod + (size_t)(9 + r) * 6144, H + (size_t)row * DM, F.lane); }
	v_fmac_f32_e32 v75, v123, v219
	v_lshlrev_b32_e32 v216, 16, v94
	v_and_b32_e32 v217, 0xffff0000, v94
	v_lshlrev_b32_e32 v218, 16, v95
	v_and_b32_e32 v219, 0xffff0000, v95
	v_mul_f32_e32 v216, v225, v216
	v_mul_f32_e32 v217, v225, v217
	v_mul_f32_e32 v218, v225, v218
	v_mul_f32_e32 v219, v225, v219
	v_fmac_f32_e32 v76, v124, v216
	v_fmac_f32_e32 v77, v125, v217
	v_fmac_f32_e32 v78, v126, v218
	v_fmac_f32_e32 v79, v127, v219
	v_mul_f32_e32 v222, v48, v48
	v_mul_f32_e32 v223, v49, v49
	v_fmac_f32_e32 v222, v50, v50
	v_fmac_f32_e32 v223, v51, v51
	v_fmac_f32_e32 v222, v52, v52
	v_fmac_f32_e32 v223, v53, v53
	v_fmac_f32_e32 v222, v54, v54
	v_fmac_f32_e32 v223, v55, v55
	v_fmac_f32_e32 v222, v56, v56
	v_fmac_f32_e32 v223, v57, v57
	v_fmac_f32_e32 v222, v58, v58
	v_fmac_f32_e32 v223, v59, v59
	v_fmac_f32_e32 v222, v60, v60
	v_fmac_f32_e32 v223, v61, v61
	v_fmac_f32_e32 v222, v62, v62
	v_fmac_f32_e32 v223, v63, v63
	v_fmac_f32_e32 v222, v64, v64
	v_fmac_f32_e32 v223, v65, v65
	v_fmac_f32_e32 v222, v66, v66
	v_fmac_f32_e32 v223, v67, v67
	v_fmac_f32_e32 v222, v68, v68
	v_fmac_f32_e32 v223, v69, v69
	v_fmac_f32_e32 v222, v70, v70
	v_fmac_f32_e32 v223, v71, v71
	v_fmac_f32_e32 v222, v72, v72
	v_fmac_f32_e32 v223, v73, v73
	v_fmac_f32_e32 v222, v74, v74
	v_fmac_f32_e32 v223, v75, v75
	v_fmac_f32_e32 v222, v76, v76
	v_fmac_f32_e32 v223, v77, v77
	v_fmac_f32_e32 v222, v78, v78
	v_fmac_f32_e32 v223, v79, v79
	v_add_f32_e32 v222, v222, v223
	s_nop 1
	v_add_f32_dpp v224, v222, v222 quad_perm:[1,0,3,2] row_mask:0xf bank_mask:0xf
	s_nop 1
	v_add_f32_dpp v224, v224, v224 quad_perm:[2,3,0,1] row_mask:0xf bank_mask:0xf
	s_nop 1
	v_add_f32_dpp v224, v224, v224 row_half_mirror row_mask:0xf bank_mask:0xf
	s_nop 1
	v_add_f32_dpp v224, v224, v224 row_mirror row_mask:0xf bank_mask:0xf
	s_nop 1
	v_readlane_b32 s40, v224, 0
	v_readlane_b32 s41, v224, 16
	v_readlane_b32 s42, v224, 32
	v_readlane_b32 s43, v224, 48
	s_nop 1
	v_mov_b32_e32 v225, s40
	v_add_f32_e32 v225, s41, v225
	v_add_f32_e32 v225, s42, v225
	v_add_f32_e32 v225, s43, v225
	v_fmamk_f32 v225, v225, 0x3a000000, v195
	v_rsq_f32_e32 v225, v225
	s_nop 0
	s_add_i32 s0, s6, 7
	s_lshl_b32 s1, s0, 12
	s_add_u32 s26, s84, s1
	s_addc_u32 s27, s85, 0
	s_add_u32 s26, s26, 0x4000000
	s_addc_u32 s27, s27, 0
	v_mul_f32_e32 v216, v225, v48
	v_mul_f32_e32 v217, v225, v49
	v_mul_f32_e32 v218, v225, v50
	v_mul_f32_e32 v219, v225, v51
	v_fma_f32 v216, v216, v128, v160
	v_fma_f32 v217, v217, v129, v161
	v_fma_f32 v218, v218, v130, v162
	v_fma_f32 v219, v219, v131, v163
	v_cvt_pk_bf16_f32 v196, v216, v217
	v_cvt_pk_bf16_f32 v197, v218, v219
	global_store_dwordx2 v194, v[196:197], s[26:27] offset:0
	v_mul_f32_e32 v216, v225, v52
	v_mul_f32_e32 v217, v225, v53
	v_mul_f32_e32 v218, v225, v54
	v_mul_f32_e32 v219, v225, v55
	v_fma_f32 v216, v216, v132, v164
	v_fma_f32 v217, v217, v133, v165
	v_fma_f32 v218, v218, v134, v166
	v_fma_f32 v219, v219, v135, v167
	v_cvt_pk_bf16_f32 v220, v216, v217
	v_cvt_pk_bf16_f32 v221, v218, v219
	global_store_dwordx2 v194, v[220:221], s[26:27] offset:512
	v_mul_f32_e32 v216, v225, v56
	v_mul_f32_e32 v217, v225, v57
	v_mul_f32_e32 v218, v225, v58
	v_mul_f32_e32 v219, v225, v59
	v_fma_f32 v216, v216, v136, v168
	v_fma_f32 v217, v217, v137, v169
	v_fma_f32 v218, v218, v138, v170
	v_fma_f32 v219, v219, v139, v171
	v_cvt_pk_bf16_f32 v196, v216, v217
	v_cvt_pk_bf16_f32 v197, v218, v219
	global_store_dwordx2 v194, v[196:197], s[26:27] offset:1024
	v_mul_f32_e32 v216, v225, v60
	v_mul_f32_e32 v217, v225, v61
	v_mul_f32_e32 v218, v225, v62
	v_mul_f32_e32 v219, v225, v63
	v_fma_f32 v216, v216, v140, v172
	v_fma_f32 v217, v217, v141, v173
	v_fma_f32 v218, v218, v142, v174
	v_fma_f32 v219, v219, v143, v175
	v_cvt_pk_bf16_f32 v220, v216, v217
	v_cvt_pk_bf16_f32 v221, v218, v219
	global_store_dwordx2 v194, v[220:221], s[26:27] offset:1536
	v_mul_f32_e32 v216, v225, v64
	v_mul_f32_e32 v217, v225, v65
	v_mul_f32_e32 v218, v225, v66
	v_mul_f32_e32 v219, v225, v67
	v_fma_f32 v216, v216, v144, v176
	v_fma_f32 v217, v217, v145, v177
	v_fma_f32 v218, v218, v146, v178
	v_fma_f32 v219, v219, v147, v179
	v_cvt_pk_bf16_f32 v196, v216, v217
	v_cvt_pk_bf16_f32 v197, v218, v219
	global_store_dwordx2 v194, v[196:197], s[26:27] offset:2048
	v_mul_f32_e32 v216, v225, v68
	v_mul_f32_e32 v217, v225, v69
	v_mul_f32_e32 v218, v225, v70
	v_mul_f32_e32 v219, v225, v71
	v_fma_f32 v216, v216, v148, v180
	v_fma_f32 v217, v217, v149, v181
	v_fma_f32 v218, v218, v150, v182
	v_fma_f32 v219, v219, v151, v183
	v_cvt_pk_bf16_f32 v220, v216, v217
	v_cvt_pk_bf16_f32 v221, v218, v219
	global_store_dwordx2 v194, v[220:221], s[26:27] offset:2560
	v_mul_f32_e32 v216, v225, v72
	v_mul_f32_e32 v217, v225, v73
	v_mul_f32_e32 v218, v225, v74
	v_mul_f32_e32 v219, v225, v75
	v_fma_f32 v216, v216, v152, v184
	v_fma_f32 v217, v217, v153, v185
	v_fma_f32 v218, v218, v154, v186
	v_fma_f32 v219, v219, v155, v187
	v_cvt_pk_bf16_f32 v196, v216, v217
	v_cvt_pk_bf16_f32 v197, v218, v219
	global_store_dwordx2 v194, v[196:197], s[26:27] offset:3072
	v_mul_f32_e32 v216, v225, v76
	v_mul_f32_e32 v217, v225, v77
	v_mul_f32_e32 v218, v225, v78
	v_mul_f32_e32 v219, v225, v79
	v_fma_f32 v216, v216, v156, v188
	v_fma_f32 v217, v217, v157, v189
	v_fma_f32 v218, v218, v158, v190
	v_fma_f32 v219, v219, v159, v191
	v_cvt_pk_bf16_f32 v220, v216, v217
	v_cvt_pk_bf16_f32 v221, v218, v219
	global_store_dwordx2 v194, v[220:221], s[26:27] offset:3584
	s_add_i32 s0, s6, 8
	s_add_i32 s0, s6, 8
	s_lshr_b32 s8, s0, 11
	s_cmp_lt_u32 s0, 0x4000
	s_cselect_b32 s8, s8, 8
	s_cmp_eq_u32 s8, s7
	s_cbranch_scc1 .Lp6_np8
; __device__ __forceinline__ unsigned cvt_pk_bf16(float lo, float hi) { unsigned r; asm volatile("v_cvt_pk_bf16_f32 %0, %1, %2" : "=v"(r) : "v"(lo), "v"(hi)); return r; }
; __device__ __forceinline__ float bf_lo(unsigned w) { return __uint_as_float(w << 16); }
; __device__ __forceinline__ float bf_hi(unsigned w) { return __uint_as_float(w & 0xffff0000u); }
; __device__ __forceinline__ void modulate_store(const f32x4 (&v)[8], float rstd, const float* pn, const float* modr, bf16_t* orow, int lane) {
; #pragma unroll
;     for (int j = 0; j < 8; ++j) { const int col = 4 * lane + 256 * j;
;         const f32x4 g = *(const f32x4*)(pn + col), sh = *(const f32x4*)(modr + col), sc = *(const f32x4*)(modr + DM + col);
;         const f32x4 hh = v[j] * rstd * g * (sc + 1.f) + sh;
;         u32x2 w; w.x = cvt_pk_bf16(hh[0], hh[1]); w.y = cvt_pk_bf16(hh[2], hh[3]);
;         *(u32x2*)(orow + col) = w; }
; __global__ void __launch_bounds__(NWAVES * 64, 2) mk_fwd(Args args) {
;     ...
;                 const float* m0 = mod + (size_t)r * 6144;
; #pragma unroll
;                 for (int j = 0; j < 8; ++j) { const int col = 4 * F.lane + 256 * j; const f32x4 gt = *(const f32x4*)(m0 + 2 * DM + col), pn = *(const f32x4*)(post_norm + col);
;                     const f32x4 y4 = (f32x4){bf_lo(yw[q][j].x), bf_hi(yw[q][j].x), bf_lo(yw[q][j].y), bf_hi(yw[q][j].y)};
;                     v[q][j] = v[q][j] + gt * (y4 * rsy * pn);
	s_mov_b32 s7, s8
	s_add_i32 s1, s8, 9
	s_mul_i32 s1, s1, 0x6000
	s_add_u32 s44, s84, s1
	s_addc_u32 s45, s85, 0
	s_add_u32 s44, s44, 0x2000
	s_addc_u32 s45, s45, 0
	s_add_i32 s1, s8, 9
	s_mul_i32 s1, s1, 0x6000
	s_add_u32 s36, s84, s1
	s_addc_u32 s37, s85, 0
	s_add_u32 s38, s80, 0x2000
	s_addc_u32 s39, s81, 0
	s_mul_i32 s1, s8, 0x6000
	s_add_u32 s34, s84, s1
	s_addc_u32 s35, s85, 0
	s_add_u32 s34, s34, 0x4000
	s_addc_u32 s35, s35, 0
	global_load_dwordx4 v[96:99], v192, s[34:35] offset:0
	global_load_dwordx4 v[200:203], v192, s[82:83] offset:0
	global_load_dwordx4 v[100:103], v192, s[34:35] offset:1024
	global_load_dwordx4 v[204:207], v192, s[82:83] offset:1024
	global_load_dwordx4 v[104:107], v192, s[34:35] offset:2048
	global_load_dwordx4 v[208:211], v192, s[82:83] offset:2048
	global_load_dwordx4 v[108:111], v192, s[34:35] offset:3072
	global_load_dwordx4 v[212:215], v192, s[82:83] offset:3072
	s_waitcnt vmcnt(0)
	v_mul_f32_e32 v96, v96, v200
	v_mul_f32_e32 v97, v97, v201
	v_mul_f32_e32 v98, v98, v202
	v_mul_f32_e32 v99, v99, v203
	v_mul_f32_e32 v100, v100, v204
	v_mul_f32_e32 v101, v101, v205
	v_mul_f32_e32 v102, v102, v206
	v_mul_f32_e32 v103, v103, v207
	v_mul_f32_e32 v104, v104, v208
	v_mul_f32_e32 v105, v105, v209
	v_mul_f32_e32 v106, v106, v210
	v_mul_f32_e32 v107, v107, v211
	v_mul_f32_e32 v108, v108, v212
	v_mul_f32_e32 v109, v109, v213
	v_mul_f32_e32 v110, v110, v214
	v_mul_f32_e32 v111, v111, v215
	global_load_dwordx4 v[128:131], v192, s[38:39] offset:0
	global_load_dwordx4 v[200:203], v192, s[44:45] offset:0
	global_load_dwordx4 v[160:163], v192, s[36:37] offset:0
	global_load_dwordx4 v[132:135], v192, s[38:39] offset:1024
	global_load_dwordx4 v[204:207], v192, s[44:45] offset:1024
	global_load_dwordx4 v[164:167], v192, s[36:37] offset:1024
	global_load_dwordx4 v[136:139], v192, s[38:39] offset:2048
	global_load_dwordx4 v[208:211], v192, s[44:45] offset:2048
	global_load_dwordx4 v[168:171], v192, s[36:37] offset:2048
	global_load_dwordx4 v[140:143], v192, s[38:39] offset:3072
	global_load_dwordx4 v[212:215], v192, s[44:45] offset:3072
	global_load_dwordx4 v[172:175], v192, s[36:37] offset:3072
	s_waitcnt vmcnt(0)
	v_add_f32_e32 v200, 1.0, v200
	v_add_f32_e32 v201, 1.0, v201
	v_add_f32_e32 v202, 1.0, v202
	v_add_f32_e32 v203, 1.0, v203
	v_mul_f32_e32 v128, v128, v200
	v_mul_f32_e32 v129, v129, v201
	v_mul_f32_e32 v130, v130, v202
	v_mul_f32_e32 v131, v131, v203
	v_add_f32_e32 v204, 1.0, v204
	v_add_f32_e32 v205, 1.0, v205
	v_add_f32_e32 v206, 1.0, v206
	v_add_f32_e32 v207, 1.0, v207
	v_mul_f32_e32 v132, v132, v204
	v_mul_f32_e32 v133, v133, v205
	v_mul_f32_e32 v134, v134, v206
	v_mul_f32_e32 v135, v135, v207
	v_add_f32_e32 v208, 1.0, v208
	v_add_f32_e32 v209, 1.0, v209
	v_add_f32_e32 v210, 1.0, v210
	v_add_f32_e32 v211, 1.0, v211
	v_mul_f32_e32 v136, v136, v208
	v_mul_f32_e32 v137, v137, v209
	v_mul_f32_e32 v138, v138, v210
	v_mul_f32_e32 v139, v139, v211
	v_add_f32_e32 v212, 1.0, v212
	v_add_f32_e32 v213, 1.0, v213
	v_add_f32_e32 v214, 1.0, v214
	v_add_f32_e32 v215, 1.0, v215
	v_mul_f32_e32 v140, v140, v212
	v_mul_f32_e32 v141, v141, v213
	v_mul_f32_e32 v142, v142, v214
	v_mul_f32_e32 v143, v143, v215
	global_load_dwordx4 v[112:115], v193, s[34:35] offset:0
	global_load_dwordx4 v[200:203], v193, s[82:83] offset:0
	global_load_dwordx4 v[116:119], v193, s[34:35] offset:1024
	global_load_dwordx4 v[204:207], v193, s[82:83] offset:1024
	global_load_dwordx4 v[120:123], v193, s[34:35] offset:2048
	global_load_dwordx4 v[208:211], v193, s[82:83] offset:2048
	global_load_dwordx4 v[124:127], v193, s[34:35] offset:3072
	global_load_dwordx4 v[212:215], v193, s[82:83] offset:3072
	s_waitcnt vmcnt(0)
	v_mul_f32_e32 v112, v112, v200
	v_mul_f32_e32 v113, v113, v201
	v_mul_f32_e32 v114, v114, v202
	v_mul_f32_e32 v115, v115, v203
	v_mul_f32_e32 v116, v116, v204
	v_mul_f32_e32 v117, v117, v205
	v_mul_f32_e32 v118, v118, v206
	v_mul_f32_e32 v119, v119, v207
	v_mul_f32_e32 v120, v120, v208
	v_mul_f32_e32 v121, v121, v209
	v_mul_f32_e32 v122, v122, v210
	v_mul_f32_e32 v123, v123, v211
	v_mul_f32_e32 v124, v124, v212
	v_mul_f32_e32 v125, v125, v213
	v_mul_f32_e32 v126, v126, v214
	v_mul_f32_e32 v127, v127, v215
	global_load_dwordx4 v[144:147], v193, s[38:39] offset:0
	global_load_dwordx4 v[200:203], v193, s[44:45] offset:0
	global_load_dwordx4 v[176:179], v193, s[36:37] offset:0
	global_load_dwordx4 v[148:151], v193, s[38:39] offset:1024
	global_load_dwordx4 v[204:207], v193, s[44:45] offset:1024
	global_load_dwordx4 v[180:183], v193, s[36:37] offset:1024
	global_load_dwordx4 v[152:155], v193, s[38:39] offset:2048
	global_load_dwordx4 v[208:211], v193, s[44:45] offset:2048
	global_load_dwordx4 v[184:187], v193, s[36:37] offset:2048
	global_load_dwordx4 v[156:159], v193, s[38:39] offset:3072
	global_load_dwordx4 v[212:215], v193, s[44:45] offset:3072
	global_load_dwordx4 v[188:191], v193, s[36:37] offset:3072
	s_waitcnt vmcnt(0)
	v_add_f32_e32 v200, 1.0, v200
	v_add_f32_e32 v201, 1.0, v201
	v_add_f32_e32 v202, 1.0, v202
	v_add_f32_e32 v203, 1.0, v203
	v_mul_f32_e32 v144, v144, v200
	v_mul_f32_e32 v145, v145, v201
	v_mul_f32_e32 v146, v146, v202
	v_mul_f32_e32 v147, v147, v203
	v_add_f32_e32 v204, 1.0, v204
	v_add_f32_e32 v205, 1.0, v205
	v_add_f32_e32 v206, 1.0, v206
	v_add_f32_e32 v207, 1.0, v207
	v_mul_f32_e32 v148, v148, v204
	v_mul_f32_e32 v149, v149, v205
	v_mul_f32_e32 v150, v150, v206
	v_mul_f32_e32 v151, v151, v207
	v_add_f32_e32 v208, 1.0, v208
	v_add_f32_e32 v209, 1.0, v209
	v_add_f32_e32 v210, 1.0, v210
	v_add_f32_e32 v211, 1.0, v211
	v_mul_f32_e32 v152, v152, v208
	v_mul_f32_e32 v153, v153, v209
	v_mul_f32_e32 v154, v154, v210
	v_mul_f32_e32 v155, v155, v211
	v_add_f32_e32 v212, 1.0, v212
	v_add_f32_e32 v213, 1.0, v213
	v_add_f32_e32 v214, 1.0, v214
	v_add_f32_e32 v215, 1.0, v215
	v_mul_f32_e32 v156, v156, v212
	v_mul_f32_e32 v157, v157, v213
	v_mul_f32_e32 v158, v158, v214
	v_mul_f32_e32 v159, v159, v215
; __device__ __forceinline__ float bf_lo(unsigned w) { return __uint_as_float(w << 16); }
; __device__ __forceinline__ float bf_hi(unsigned w) { return __uint_as_float(w & 0xffff0000u); }
; __global__ void __launch_bounds__(NWAVES * 64, 2) mk_fwd(Args args) {
;     ...
;             for (int q = 0; q < 3; ++q) { const int row = row0 + q; const bool lat = row < ML; const int r = lat ? row / SEQ : 8;
;                 float sy = 0.f;
; #pragma unroll
;                 for (int j = 0; j < 8; ++j) { const float a = bf_lo(yw[q][j].x), b = bf_hi(yw[q][j].x), c2 = bf_lo(yw[q][j].y), d = bf_hi(yw[q][j].y); sy += (a * a + b * b) + (c2 * c2 + d * d); }
;                 const float rsy = __builtin_amdgcn_rsqf(wave_sum(sy) * (1.f / DM) + EPS);
;                 const float* m0 = mod + (size_t)r * 6144;
; #pragma unroll
;                 for (int j = 0; j < 8; ++j) { const int col = 4 * F.lane + 256 * j; const f32x4 gt = *(const f32x4*)(m0 + 2 * DM + col), pn = *(const f32x4*)(post_norm + col);
;                     const f32x4 y4 = (f32x4){bf_lo(yw[q][j].x), bf_hi(yw[q][j].x), bf_lo(yw[q][j].y), bf_hi(yw[q][j].y)};
;                     v[q][j] = v[q][j] + gt * (y4 * rsy * pn);
;                     if (lat) *(f32x4*)(args.out + (size_t)row * DM + col) = v[q][j]; }
.Lp6_np8:
	s_waitcnt vmcnt(8)
	v_lshlrev_b32_e32 v216, 16, v32
	v_and_b32_e32 v217, 0xffff0000, v32
	v_lshlrev_b32_e32 v218, 16, v33
	v_and_b32_e32 v219, 0xffff0000, v33
	v_mul_f32_e32 v222, v216, v216
	v_mul_f32_e32 v223, v217, v217
	v_fmac_f32_e32 v222, v218, v218
	v_fmac_f32_e32 v223, v219, v219
	v_lshlrev_b32_e32 v216, 16, v34
	v_and_b32_e32 v217, 0xffff0000, v34
	v_lshlrev_b32_e32 v218, 16, v35
	v_and_b32_e32 v219, 0xffff0000, v35
	v_fmac_f32_e32 v222, v216, v216
	v_fmac_f32_e32 v223, v217, v217
	v_fmac_f32_e32 v222, v218, v218
	v_fmac_f32_e32 v223, v219, v219
	v_lshlrev_b32_e32 v216, 16, v36
	v_and_b32_e32 v217, 0xffff0000, v36
	v_lshlrev_b32_e32 v218, 16, v37
	v_and_b32_e32 v219, 0xffff0000, v37
	v_fmac_f32_e32 v222, v216, v216
	v_fmac_f32_e32 v223, v217, v217
	v_fmac_f32_e32 v222, v218, v218
	v_fmac_f32_e32 v223, v219, v219
	v_lshlrev_b32_e32 v216, 16, v38
	v_and_b32_e32 v217, 0xffff0000, v38
	v_lshlrev_b32_e32 v218, 16, v39
	v_and_b32_e32 v219, 0xffff0000, v39
	v_fmac_f32_e32 v222, v216, v216
	v_fmac_f32_e32 v223, v217, v217
	v_fmac_f32_e32 v222, v218, v218
	v_fmac_f32_e32 v223, v219, v219
	v_lshlrev_b32_e32 v216, 16, v40
	v_and_b32_e32 v217, 0xffff0000, v40
	v_lshlrev_b32_e32 v218, 16, v41
	v_and_b32_e32 v219, 0xffff0000, v41
	v_fmac_f32_e32 v222, v216, v216
	v_fmac_f32_e32 v223, v217, v217
	v_fmac_f32_e32 v222, v218, v218
	v_fmac_f32_e32 v223, v219, v219
	v_lshlrev_b32_e32 v216, 16, v42
	v_and_b32_e32 v217, 0xffff0000, v42
	v_lshlrev_b32_e32 v218, 16, v43
	v_and_b32_e32 v219, 0xffff0000, v43
	v_fmac_f32_e32 v222, v216, v216
	v_fmac_f32_e32 v223, v217, v217
	v_fmac_f32_e32 v222, v218, v218
	v_fmac_f32_e32 v223, v219, v219
	v_lshlrev_b32_e32 v216, 16, v44
	v_and_b32_e32 v217, 0xffff0000, v44
	v_lshlrev_b32_e32 v218, 16, v45
	v_and_b32_e32 v219, 0xffff0000, v45
	v_fmac_f32_e32 v222, v216, v216
	v_fmac_f32_e32 v223, v217, v217
	v_fmac_f32_e32 v222, v218, v218
	v_fmac_f32_e32 v223, v219, v219
	v_lshlrev_b32_e32 v216, 16, v46
	v_and_b32_e32 v217, 0xffff0000, v46
	v_lshlrev_b32_e32 v218, 16, v47
	v_and_b32_e32 v219, 0xffff0000, v47
	v_fmac_f32_e32 v222, v216, v216
	v_fmac_f32_e32 v223, v217, v217
	v_fmac_f32_e32 v222, v218, v218
	v_fmac_f32_e32 v223, v219, v219
	v_add_f32_e32 v222, v222, v223
	s_nop 1
	v_add_f32_dpp v224, v222, v222 quad_perm:[1,0,3,2] row_mask:0xf bank_mask:0xf
	s_nop 1
	v_add_f32_dpp v224, v224, v224 quad_perm:[2,3,0,1] row_mask:0xf bank_mask:0xf
	s_nop 1
	v_add_f32_dpp v224, v224, v224 row_half_mirror row_mask:0xf bank_mask:0xf
	s_nop 1
	v_add_f32_dpp v224, v224, v224 row_mirror row_mask:0xf bank_mask:0xf
	s_nop 1
	v_readlane_b32 s40, v224, 0
	v_readlane_b32 s41, v224, 16
	v_readlane_b32 s42, v224, 32
	v_readlane_b32 s43, v224, 48
	s_nop 1
	v_mov_b32_e32 v225, s40
	v_add_f32_e32 v225, s41, v225
	v_add_f32_e32 v225, s42, v225
	v_add_f32_e32 v225, s43, v225
	v_fmamk_f32 v225, v225, 0x3a000000, v195
	v_rsq_f32_e32 v225, v225
	s_nop 0
	v_lshlrev_b32_e32 v216, 16, v32
	v_and_b32_e32 v217, 0xffff0000, v32
	v_lshlrev_b32_e32 v218, 16, v33
	v_and_b32_e32 v219, 0xffff0000, v33
	v_mul_f32_e32 v216, v225, v216
	v_mul_f32_e32 v217, v225, v217
	v_mul_f32_e32 v218, v225, v218
	v_mul_f32_e32 v219, v225, v219
	v_fmac_f32_e32 v0, v96, v216
	v_fmac_f32_e32 v1, v97, v217
	v_fmac_f32_e32 v2, v98, v218
	v_fmac_f32_e32 v3, v99, v219
	v_lshlrev_b32_e32 v216, 16, v34
	v_and_b32_e32 v217, 0xffff0000, v34
	v_lshlrev_b32_e32 v218, 16, v35
	v_and_b32_e32 v219, 0xffff0000, v35
	v_mul_f32_e32 v216, v225, v216
	v_mul_f32_e32 v217, v225, v217
	v_mul_f32_e32 v218, v225, v218
	v_mul_f32_e32 v219, v225, v219
	v_fmac_f32_e32 v4, v100, v216
	v_fmac_f32_e32 v5, v101, v217
	v_fmac_f32_e32 v6, v102, v218
	v_fmac_f32_e32 v7, v103, v219
	v_lshlrev_b32_e32 v216, 16, v36
	v_and_b32_e32 v217, 0xffff0000, v36
	v_lshlrev_b32_e32 v218, 16, v37
	v_and_b32_e32 v219, 0xffff0000, v37
	v_mul_f32_e32 v216, v225, v216
	v_mul_f32_e32 v217, v225, v217
	v_mul_f32_e32 v218, v225, v218
	v_mul_f32_e32 v219, v225, v219
	v_fmac_f32_e32 v8, v104, v216
	v_fmac_f32_e32 v9, v105, v217
	v_fmac_f32_e32 v10, v106, v218
	v_fmac_f32_e32 v11, v107, v219
	v_lshlrev_b32_e32 v216, 16, v38
	v_and_b32_e32 v217, 0xffff0000, v38
	v_lshlrev_b32_e32 v218, 16, v39
	v_and_b32_e32 v219, 0xffff0000, v39
	v_mul_f32_e32 v216, v225, v216
	v_mul_f32_e32 v217, v225, v217
	v_mul_f32_e32 v218, v225, v218
	v_mul_f32_e32 v219, v225, v219
	v_fmac_f32_e32 v12, v108, v216
	v_fmac_f32_e32 v13, v109, v217
	v_fmac_f32_e32 v14, v110, v218
	v_fmac_f32_e32 v15, v111, v219
	v_lshlrev_b32_e32 v216, 16, v40
	v_and_b32_e32 v217, 0xffff0000, v40
	v_lshlrev_b32_e32 v218, 16, v41
	v_and_b32_e32 v219, 0xffff0000, v41
	v_mul_f32_e32 v216, v225, v216
	v_mul_f32_e32 v217, v225, v217
	v_mul_f32_e32 v218, v225, v218
	v_mul_f32_e32 v219, v225, v219
	v_fmac_f32_e32 v16, v112, v216
	v_fmac_f32_e32 v17, v113, v217
	v_fmac_f32_e32 v18, v114, v218
	v_fmac_f32_e32 v19, v115, v219
	v_lshlrev_b32_e32 v216, 16, v42
	v_and_b32_e32 v217, 0xffff0000, v42
	v_lshlrev_b32_e32 v218, 16, v43
	v_and_b32_e32 v219, 0xffff0000, v43
	v_mul_f32_e32 v216, v225, v216
	v_mul_f32_e32 v217, v225, v217
	v_mul_f32_e32 v218, v225, v218
	v_mul_f32_e32 v219, v225, v219
	v_fmac_f32_e32 v20, v116, v216
	v_fmac_f32_e32 v21, v117, v217
	v_fmac_f32_e32 v22, v118, v218
	v_fmac_f32_e32 v23, v119, v219
	v_lshlrev_b32_e32 v216, 16, v44
	v_and_b32_e32 v217, 0xffff0000, v44
	v_lshlrev_b32_e32 v218, 16, v45
	v_and_b32_e32 v219, 0xffff0000, v45
	v_mul_f32_e32 v216, v225, v216
	v_mul_f32_e32 v217, v225, v217
	v_mul_f32_e32 v218, v225, v218
; __device__ __forceinline__ unsigned cvt_pk_bf16(float lo, float hi) { unsigned r; asm volatile("v_cvt_pk_bf16_f32 %0, %1, %2" : "=v"(r) : "v"(lo), "v"(hi)); return r; }
; __device__ __forceinline__ void modulate_store(const f32x4 (&v)[8], float rstd, const float* pn, const float* modr, bf16_t* orow, int lane) {
; #pragma unroll
;     for (int j = 0; j < 8; ++j) { const int col = 4 * lane + 256 * j;
;         const f32x4 g = *(const f32x4*)(pn + col), sh = *(const f32x4*)(modr + col), sc = *(const f32x4*)(modr + DM + col);
;         const f32x4 hh = v[j] * rstd * g * (sc + 1.f) + sh;
;         u32x2 w; w.x = cvt_pk_bf16(hh[0], hh[1]); w.y = cvt_pk_bf16(hh[2], hh[3]);
;         *(u32x2*)(orow + col) = w; }
; __global__ void __launch_bounds__(NWAVES * 64, 2) mk_fwd(Args args) {
;     ...
;                     v[q][j] = v[q][j] + gt * (y4 * rsy * pn);
;                     if (lat) *(f32x4*)(args.out + (size_t)row * DM + col) = v[q][j]; }
;                 const float rstd = __builtin_amdgcn_rsqf(sumsq8(v[q]) * (1.f / DM) + EPS);
;                 modulate_store(v[q], rstd, pre_norm + DM, mod + (size_t)(9 + r) * 6144, H + (size_t)row * DM, F.lane); }
	v_mul_f32_e32 v219, v225, v219
	v_fmac_f32_e32 v24, v120, v216
	v_fmac_f32_e32 v25, v121, v217
	v_fmac_f32_e32 v26, v122, v218
	v_fmac_f32_e32 v27, v123, v219
	v_lshlrev_b32_e32 v216, 16, v46
	v_and_b32_e32 v217, 0xffff0000, v46
	v_lshlrev_b32_e32 v218, 16, v47
	v_and_b32_e32 v219, 0xffff0000, v47
	v_mul_f32_e32 v216, v225, v216
	v_mul_f32_e32 v217, v225, v217
	v_mul_f32_e32 v218, v225, v218
	v_mul_f32_e32 v219, v225, v219
	v_fmac_f32_e32 v28, v124, v216
	v_fmac_f32_e32 v29, v125, v217
	v_fmac_f32_e32 v30, v126, v218
	v_fmac_f32_e32 v31, v127, v219
	v_mul_f32_e32 v222, v0, v0
	v_mul_f32_e32 v223, v1, v1
	v_fmac_f32_e32 v222, v2, v2
	v_fmac_f32_e32 v223, v3, v3
	v_fmac_f32_e32 v222, v4, v4
	v_fmac_f32_e32 v223, v5, v5
	v_fmac_f32_e32 v222, v6, v6
	v_fmac_f32_e32 v223, v7, v7
	v_fmac_f32_e32 v222, v8, v8
	v_fmac_f32_e32 v223, v9, v9
	v_fmac_f32_e32 v222, v10, v10
	v_fmac_f32_e32 v223, v11, v11
	v_fmac_f32_e32 v222, v12, v12
	v_fmac_f32_e32 v223, v13, v13
	v_fmac_f32_e32 v222, v14, v14
	v_fmac_f32_e32 v223, v15, v15
	v_fmac_f32_e32 v222, v16, v16
	v_fmac_f32_e32 v223, v17, v17
	v_fmac_f32_e32 v222, v18, v18
	v_fmac_f32_e32 v223, v19, v19
	v_fmac_f32_e32 v222, v20, v20
	v_fmac_f32_e32 v223, v21, v21
	v_fmac_f32_e32 v222, v22, v22
	v_fmac_f32_e32 v223, v23, v23
	v_fmac_f32_e32 v222, v24, v24
	v_fmac_f32_e32 v223, v25, v25
	v_fmac_f32_e32 v222, v26, v26
	v_fmac_f32_e32 v223, v27, v27
	v_fmac_f32_e32 v222, v28, v28
	v_fmac_f32_e32 v223, v29, v29
	v_fmac_f32_e32 v222, v30, v30
	v_fmac_f32_e32 v223, v31, v31
	v_add_f32_e32 v222, v222, v223
	s_nop 1
	v_add_f32_dpp v224, v222, v222 quad_perm:[1,0,3,2] row_mask:0xf bank_mask:0xf
	s_nop 1
	v_add_f32_dpp v224, v224, v224 quad_perm:[2,3,0,1] row_mask:0xf bank_mask:0xf
	s_nop 1
	v_add_f32_dpp v224, v224, v224 row_half_mirror row_mask:0xf bank_mask:0xf
	s_nop 1
	v_add_f32_dpp v224, v224, v224 row_mirror row_mask:0xf bank_mask:0xf
	s_nop 1
	v_readlane_b32 s40, v224, 0
	v_readlane_b32 s41, v224, 16
	v_readlane_b32 s42, v224, 32
	v_readlane_b32 s43, v224, 48
	s_nop 1
	v_mov_b32_e32 v225, s40
	v_add_f32_e32 v225, s41, v225
	v_add_f32_e32 v225, s42, v225
	v_add_f32_e32 v225, s43, v225
	v_fmamk_f32 v225, v225, 0x3a000000, v195
	v_rsq_f32_e32 v225, v225
	s_nop 0
	s_add_i32 s0, s6, 8
	s_lshl_b32 s1, s0, 12
	s_add_u32 s26, s84, s1
	s_addc_u32 s27, s85, 0
	s_add_u32 s26, s26, 0x4000000
	s_addc_u32 s27, s27, 0
	v_mul_f32_e32 v216, v225, v0
	v_mul_f32_e32 v217, v225, v1
	v_mul_f32_e32 v218, v225, v2
	v_mul_f32_e32 v219, v225, v3
	v_fma_f32 v216, v216, v128, v160
	v_fma_f32 v217, v217, v129, v161
	v_fma_f32 v218, v218, v130, v162
	v_fma_f32 v219, v219, v131, v163
	v_cvt_pk_bf16_f32 v196, v216, v217
	v_cvt_pk_bf16_f32 v197, v218, v219
	global_store_dwordx2 v194, v[196:197], s[26:27] offset:0
	v_mul_f32_e32 v216, v225, v4
	v_mul_f32_e32 v217, v225, v5
	v_mul_f32_e32 v218, v225, v6
	v_mul_f32_e32 v219, v225, v7
	v_fma_f32 v216, v216, v132, v164
	v_fma_f32 v217, v217, v133, v165
	v_fma_f32 v218, v218, v134, v166
	v_fma_f32 v219, v219, v135, v167
	v_cvt_pk_bf16_f32 v220, v216, v217
	v_cvt_pk_bf16_f32 v221, v218, v219
	global_store_dwordx2 v194, v[220:221], s[26:27] offset:512
	v_mul_f32_e32 v216, v225, v8
	v_mul_f32_e32 v217, v225, v9
	v_mul_f32_e32 v218, v225, v10
	v_mul_f32_e32 v219, v225, v11
	v_fma_f32 v216, v216, v136, v168
	v_fma_f32 v217, v217, v137, v169
	v_fma_f32 v218, v218, v138, v170
	v_fma_f32 v219, v219, v139, v171
	v_cvt_pk_bf16_f32 v196, v216, v217
	v_cvt_pk_bf16_f32 v197, v218, v219
	global_store_dwordx2 v194, v[196:197], s[26:27] offset:1024
	v_mul_f32_e32 v216, v225, v12
	v_mul_f32_e32 v217, v225, v13
	v_mul_f32_e32 v218, v225, v14
	v_mul_f32_e32 v219, v225, v15
	v_fma_f32 v216, v216, v140, v172
	v_fma_f32 v217, v217, v141, v173
	v_fma_f32 v218, v218, v142, v174
	v_fma_f32 v219, v219, v143, v175
	v_cvt_pk_bf16_f32 v220, v216, v217
	v_cvt_pk_bf16_f32 v221, v218, v219
	global_store_dwordx2 v194, v[220:221], s[26:27] offset:1536
	v_mul_f32_e32 v216, v225, v16
	v_mul_f32_e32 v217, v225, v17
	v_mul_f32_e32 v218, v225, v18
	v_mul_f32_e32 v219, v225, v19
	v_fma_f32 v216, v216, v144, v176
	v_fma_f32 v217, v217, v145, v177
	v_fma_f32 v218, v218, v146, v178
	v_fma_f32 v219, v219, v147, v179
	v_cvt_pk_bf16_f32 v196, v216, v217
	v_cvt_pk_bf16_f32 v197, v218, v219
	global_store_dwordx2 v194, v[196:197], s[26:27] offset:2048
	v_mul_f32_e32 v216, v225, v20
	v_mul_f32_e32 v217, v225, v21
	v_mul_f32_e32 v218, v225, v22
	v_mul_f32_e32 v219, v225, v23
	v_fma_f32 v216, v216, v148, v180
	v_fma_f32 v217, v217, v149, v181
	v_fma_f32 v218, v218, v150, v182
	v_fma_f32 v219, v219, v151, v183
	v_cvt_pk_bf16_f32 v220, v216, v217
	v_cvt_pk_bf16_f32 v221, v218, v219
	global_store_dwordx2 v194, v[220:221], s[26:27] offset:2560
	v_mul_f32_e32 v216, v225, v24
	v_mul_f32_e32 v217, v225, v25
	v_mul_f32_e32 v218, v225, v26
	v_mul_f32_e32 v219, v225, v27
	v_fma_f32 v216, v216, v152, v184
	v_fma_f32 v217, v217, v153, v185
	v_fma_f32 v218, v218, v154, v186
	v_fma_f32 v219, v219, v155, v187
	v_cvt_pk_bf16_f32 v196, v216, v217
	v_cvt_pk_bf16_f32 v197, v218, v219
	global_store_dwordx2 v194, v[196:197], s[26:27] offset:3072
	v_mul_f32_e32 v216, v225, v28
	v_mul_f32_e32 v217, v225, v29
	v_mul_f32_e32 v218, v225, v30
	v_mul_f32_e32 v219, v225, v31
	v_fma_f32 v216, v216, v156, v188
	v_fma_f32 v217, v217, v157, v189
	v_fma_f32 v218, v218, v158, v190
	v_fma_f32 v219, v219, v159, v191
	v_cvt_pk_bf16_f32 v220, v216, v217
	v_cvt_pk_bf16_f32 v221, v218, v219
	global_store_dwordx2 v194, v[220:221], s[26:27] offset:3584
	s_branch .LBB0_778

; __global__ void __launch_bounds__(NWAVES * 64, 2) mk_fwd(Args args) {
;     ...
;         { pg8::Gemm g{CKV, WUKV, MT, 4096, 512, 512, 512, 0}; pg8::StaticOrder S; S.init(MT, 4096, F.G, (int)blockIdx.x);
;           pg8::EpiKV E{KN, V, ssq + MT};
;           pg8::gemm_phase<pg8::EpiKV>(F.lds, g, S, E); }
.LBB0_940:
	s_cmpk_lg_i32 s63, 0x100
	s_cbranch_scc1 .Lvreloc_skip
	s_mov_b32 s20, s94
	s_mov_b32 s21, s95

; __global__ void __launch_bounds__(NWAVES * 64, 2) mk_fwd(Args args) {
;     ...
;     if (IN(10)) {
;         pg8::Gemm g{Z, WMO, ML, DM, DM, DM, DM, 0}; pg8::StaticOrder S; S.init(ML, DM, F.G, (int)blockIdx.x);
;         pg8::EpiPlain E{Y, DM};
;         pg8::gemm_phase<pg8::EpiPlain>(F.lds, g, S, E);
.LBB0_1213:
	s_cmpk_lg_i32 s63, 0x100
	s_cbranch_scc1 .Ly1reloc_skip
	s_add_u32 s20, s84, 0x8800000
	s_addc_u32 s21, s85, 0

; #define FRESH() int gtid; do { int t_ = threadIdx.x; asm volatile("" : "+v"(t_)); F.tid = t_; F.lane = t_ & 63; gtid = blockIdx.x * (NWAVES * 64) + t_; (void)gtid; } while (0)
; __global__ void __launch_bounds__(NWAVES * 64, 2) mk_fwd(Args args) {
;     ...
;     if (IN(11)) { FRESH();
;         const int per = (ML + F.NGW - 1) / F.NGW, per2 = (per + 1) & ~1, rbeg = F.gw * per2;
;         int rcur = -1; f32x4 PA[8];
;         for (int row0 = rbeg; row0 < rbeg + per2 && row0 < ML; row0 += 2) {
;             f32x4 v[2][8]; u32x2 yw[2][8];
; #pragma unroll
;             for (int q = 0; q < 2; ++q) { const int row = row0 + q; load_row_f32(args.out + (size_t)row * DM, F.lane, v[q]);
;                 const bf16_t* yr = Y + (size_t)row * DM;
; #pragma unroll
;                 for (int j = 0; j < 8; ++j) yw[q][j] = *(const u32x2*)(yr + 4 * F.lane + 256 * j); }
; #pragma unroll
;             for (int q = 0; q < 2; ++q) { const int row = row0 + q; const int r = row / SEQ;
;                 if (r != rcur) { const float* m1 = mod + (size_t)(9 + r) * 6144; rcur = r;
; #pragma unroll
;                     for (int j = 0; j < 8; ++j) { const int col = 4 * F.lane + 256 * j; PA[j] = *(const f32x4*)(m1 + 2 * DM + col) * *(const f32x4*)(post_norm + DM + col); } }
.LBB0_1288:
	s_cmp_gt_i32 s86, 11
	s_cselect_b64 s[2:3], -1, 0
	s_xor_b64 s[0:1], s[0:1], -1
	s_or_b64 s[0:1], s[2:3], s[0:1]
	s_and_b64 vcc, exec, s[0:1]
	s_cbranch_vccnz .LBB0_1296
	s_cmpk_lg_i32 s63, 0x100
	s_cbranch_scc1 .Lp11_generic
	v_and_b32_e32 v194, 63, v198
	v_lshlrev_b32_e32 v192, 4, v194
	v_add_u32_e32 v193, 0x1000, v192
	v_lshlrev_b32_e32 v194, 3, v194
	v_mov_b32_e32 v195, 0x358637bd
	s_lshr_b32 s0, s33, 8
	s_mul_i32 s1, s0, 0x6000
	s_add_u32 s8, s84, s1
	s_addc_u32 s9, s85, 0
	s_add_u32 s8, s8, 0x4000
	s_addc_u32 s9, s9, 0
	s_add_u32 s10, s8, 0x36000
	s_addc_u32 s11, s9, 0
	s_add_u32 s12, s82, 0x2000
	s_addc_u32 s13, s83, 0
	s_lshl_b32 s0, s33, 16
	s_add_u32 s14, s68, s0
	s_addc_u32 s15, s69, 0
	s_add_u32 s18, s94, s0
	s_addc_u32 s19, s95, 0
	s_lshl_b32 s0, s33, 15
	s_add_u32 s16, s84, s0
	s_addc_u32 s17, s85, 0
	s_add_u32 s22, s16, 0x8800000
	s_addc_u32 s23, s17, 0
	s_add_u32 s16, s16, 0x11800000
	s_addc_u32 s17, s17, 0
	global_load_dwordx4 v[128:131], v192, s[8:9] offset:0
	global_load_dwordx4 v[132:135], v192, s[8:9] offset:1024
	global_load_dwordx4 v[136:139], v192, s[8:9] offset:2048
	global_load_dwordx4 v[140:143], v192, s[8:9] offset:3072
	global_load_dwordx4 v[144:147], v193, s[8:9] offset:0
	global_load_dwordx4 v[148:151], v193, s[8:9] offset:1024
	global_load_dwordx4 v[152:155], v193, s[8:9] offset:2048
	global_load_dwordx4 v[156:159], v193, s[8:9] offset:3072
	global_load_dwordx4 v[32:35], v192, s[82:83] offset:0
	global_load_dwordx4 v[36:39], v192, s[82:83] offset:1024
	global_load_dwordx4 v[40:43], v192, s[82:83] offset:2048
	global_load_dwordx4 v[44:47], v192, s[82:83] offset:3072
	global_load_dwordx4 v[48:51], v193, s[82:83] offset:0
	global_load_dwordx4 v[52:55], v193, s[82:83] offset:1024
	global_load_dwordx4 v[56:59], v193, s[82:83] offset:2048
	global_load_dwordx4 v[60:63], v193, s[82:83] offset:3072
	global_load_dwordx4 v[160:163], v192, s[10:11] offset:0
	global_load_dwordx4 v[164:167], v192, s[10:11] offset:1024
	global_load_dwordx4 v[168:171], v192, s[10:11] offset:2048
	global_load_dwordx4 v[172:175], v192, s[10:11] offset:3072
	global_load_dwordx4 v[176:179], v193, s[10:11] offset:0
	global_load_dwordx4 v[180:183], v193, s[10:11] offset:1024
	global_load_dwordx4 v[184:187], v193, s[10:11] offset:2048
	global_load_dwordx4 v[188:191], v193, s[10:11] offset:3072
	global_load_dwordx4 v[96:99], v192, s[12:13] offset:0
	global_load_dwordx4 v[100:103], v192, s[12:13] offset:1024
	global_load_dwordx4 v[104:107], v192, s[12:13] offset:2048
	global_load_dwordx4 v[108:111], v192, s[12:13] offset:3072
	global_load_dwordx4 v[112:115], v193, s[12:13] offset:0
	global_load_dwordx4 v[116:119], v193, s[12:13] offset:1024
	global_load_dwordx4 v[120:123], v193, s[12:13] offset:2048
	global_load_dwordx4 v[124:127], v193, s[12:13] offset:3072
	s_waitcnt vmcnt(0)
	v_mul_f32_e32 v128, v128, v32
	v_mul_f32_e32 v129, v129, v33
	v_mul_f32_e32 v130, v130, v34
	v_mul_f32_e32 v131, v131, v35
	v_mul_f32_e32 v132, v132, v36
	v_mul_f32_e32 v133, v133, v37
	v_mul_f32_e32 v134, v134, v38
	v_mul_f32_e32 v135, v135, v39
	v_mul_f32_e32 v136, v136, v40
	v_mul_f32_e32 v137, v137, v41
	v_mul_f32_e32 v138, v138, v42
	v_mul_f32_e32 v139, v139, v43
	v_mul_f32_e32 v140, v140, v44
	v_mul_f32_e32 v141, v141, v45
	v_mul_f32_e32 v142, v142, v46
	v_mul_f32_e32 v143, v143, v47
	v_mul_f32_e32 v144, v144, v48
	v_mul_f32_e32 v145, v145, v49
	v_mul_f32_e32 v146, v146, v50
	v_mul_f32_e32 v147, v147, v51
	v_mul_f32_e32 v148, v148, v52
	v_mul_f32_e32 v149, v149, v53
	v_mul_f32_e32 v150, v150, v54
	v_mul_f32_e32 v151, v151, v55
	v_mul_f32_e32 v152, v152, v56
	v_mul_f32_e32 v153, v153, v57
	v_mul_f32_e32 v154, v154, v58
	v_mul_f32_e32 v155, v155, v59
	v_mul_f32_e32 v156, v156, v60
	v_mul_f32_e32 v157, v157, v61
	v_mul_f32_e32 v158, v158, v62
	v_mul_f32_e32 v159, v159, v63
	v_mul_f32_e32 v160, v160, v96
	v_mul_f32_e32 v161, v161, v97
	v_mul_f32_e32 v162, v162, v98
	v_mul_f32_e32 v163, v163, v99
	v_mul_f32_e32 v164, v164, v100
	v_mul_f32_e32 v165, v165, v101
	v_mul_f32_e32 v166, v166, v102
	v_mul_f32_e32 v167, v167, v103
	v_mul_f32_e32 v168, v168, v104
	v_mul_f32_e32 v169, v169, v105
	v_mul_f32_e32 v170, v170, v106
	v_mul_f32_e32 v171, v171, v107
	v_mul_f32_e32 v172, v172, v108
	v_mul_f32_e32 v173, v173, v109
	v_mul_f32_e32 v174, v174, v110
	v_mul_f32_e32 v175, v175, v111
	v_mul_f32_e32 v176, v176, v112
	v_mul_f32_e32 v177, v177, v113
	v_mul_f32_e32 v178, v178, v114
	v_mul_f32_e32 v179, v179, v115
	v_mul_f32_e32 v180, v180, v116
	v_mul_f32_e32 v181, v181, v117
	v_mul_f32_e32 v182, v182, v118
	v_mul_f32_e32 v183, v183, v119
	v_mul_f32_e32 v184, v184, v120
	v_mul_f32_e32 v185, v185, v121
	v_mul_f32_e32 v186, v186, v122
	v_mul_f32_e32 v187, v187, v123
	v_mul_f32_e32 v188, v188, v124
	v_mul_f32_e32 v189, v189, v125
	v_mul_f32_e32 v190, v190, v126
	v_mul_f32_e32 v191, v191, v127
	global_load_dwordx4 v[0:3], v192, s[14:15] offset:0
	global_load_dwordx4 v[4:7], v192, s[14:15] offset:1024
	global_load_dwordx4 v[8:11], v192, s[14:15] offset:2048
	global_load_dwordx4 v[12:15], v192, s[14:15] offset:3072
	global_load_dwordx4 v[16:19], v193, s[14:15] offset:0
	global_load_dwordx4 v[20:23], v193, s[14:15] offset:1024
	global_load_dwordx4 v[24:27], v193, s[14:15] offset:2048
	global_load_dwordx4 v[28:31], v193, s[14:15] offset:3072
	global_load_dwordx2 v[64:65], v194, s[16:17] offset:0
	global_load_dwordx2 v[66:67], v194, s[16:17] offset:512
	global_load_dwordx2 v[68:69], v194, s[16:17] offset:1024
	global_load_dwordx2 v[70:71], v194, s[16:17] offset:1536
	global_load_dwordx2 v[72:73], v194, s[16:17] offset:2048
	global_load_dwordx2 v[74:75], v194, s[16:17] offset:2560
; __device__ __forceinline__ float bf_lo(unsigned w) { return __uint_as_float(w << 16); }
; __device__ __forceinline__ float bf_hi(unsigned w) { return __uint_as_float(w & 0xffff0000u); }
; __global__ void __launch_bounds__(NWAVES * 64, 2) mk_fwd(Args args) {
;     ...
;         for (int row0 = rbeg; row0 < rbeg + per2 && row0 < ML; row0 += 2) {
;             f32x4 v[2][8]; u32x2 yw[2][8];
; #pragma unroll
;             for (int q = 0; q < 2; ++q) { const int row = row0 + q; load_row_f32(args.out + (size_t)row * DM, F.lane, v[q]);
;                 const bf16_t* yr = Y + (size_t)row * DM;
; #pragma unroll
;                 for (int j = 0; j < 8; ++j) yw[q][j] = *(const u32x2*)(yr + 4 * F.lane + 256 * j); }
; #pragma unroll
;             for (int q = 0; q < 2; ++q) { const int row = row0 + q; const int r = row / SEQ;
;                 if (r != rcur) { const float* m1 = mod + (size_t)(9 + r) * 6144; rcur = r;
; #pragma unroll
;                     for (int j = 0; j < 8; ++j) { const int col = 4 * F.lane + 256 * j; PA[j] = *(const f32x4*)(m1 + 2 * DM + col) * *(const f32x4*)(post_norm + DM + col); } }
;                 float sy = 0.f;
; #pragma unroll
;                 for (int j = 0; j < 8; ++j) { const float a = bf_lo(yw[q][j].x), b = bf_hi(yw[q][j].x), c2 = bf_lo(yw[q][j].y), d = bf_hi(yw[q][j].y); sy += (a * a + b * b) + (c2 * c2 + d * d); }
;                 const float rsy = __builtin_amdgcn_rsqf(wave_sum(sy) * (1.f / DM) + EPS);
	global_load_dwordx2 v[76:77], v194, s[16:17] offset:3072
	global_load_dwordx2 v[78:79], v194, s[16:17] offset:3584
	global_load_dwordx2 v[96:97], v194, s[22:23] offset:0
	global_load_dwordx2 v[98:99], v194, s[22:23] offset:512
	global_load_dwordx2 v[100:101], v194, s[22:23] offset:1024
	global_load_dwordx2 v[102:103], v194, s[22:23] offset:1536
	global_load_dwordx2 v[104:105], v194, s[22:23] offset:2048
	global_load_dwordx2 v[106:107], v194, s[22:23] offset:2560
	global_load_dwordx2 v[108:109], v194, s[22:23] offset:3072
	global_load_dwordx2 v[110:111], v194, s[22:23] offset:3584
	s_add_u32 s14, s14, 0x2000
	s_addc_u32 s15, s15, 0
	s_add_u32 s16, s16, 0x1000
	s_addc_u32 s17, s17, 0
	s_add_u32 s22, s22, 0x1000
	s_addc_u32 s23, s23, 0
	global_load_dwordx4 v[32:35], v192, s[14:15] offset:0
	global_load_dwordx4 v[36:39], v192, s[14:15] offset:1024
	global_load_dwordx4 v[40:43], v192, s[14:15] offset:2048
	global_load_dwordx4 v[44:47], v192, s[14:15] offset:3072
	global_load_dwordx4 v[48:51], v193, s[14:15] offset:0
	global_load_dwordx4 v[52:55], v193, s[14:15] offset:1024
	global_load_dwordx4 v[56:59], v193, s[14:15] offset:2048
	global_load_dwordx4 v[60:63], v193, s[14:15] offset:3072
	global_load_dwordx2 v[80:81], v194, s[16:17] offset:0
	global_load_dwordx2 v[82:83], v194, s[16:17] offset:512
	global_load_dwordx2 v[84:85], v194, s[16:17] offset:1024
	global_load_dwordx2 v[86:87], v194, s[16:17] offset:1536
	global_load_dwordx2 v[88:89], v194, s[16:17] offset:2048
	global_load_dwordx2 v[90:91], v194, s[16:17] offset:2560
	global_load_dwordx2 v[92:93], v194, s[16:17] offset:3072
	global_load_dwordx2 v[94:95], v194, s[16:17] offset:3584
	global_load_dwordx2 v[112:113], v194, s[22:23] offset:0
	global_load_dwordx2 v[114:115], v194, s[22:23] offset:512
	global_load_dwordx2 v[116:117], v194, s[22:23] offset:1024
	global_load_dwordx2 v[118:119], v194, s[22:23] offset:1536
	global_load_dwordx2 v[120:121], v194, s[22:23] offset:2048
	global_load_dwordx2 v[122:123], v194, s[22:23] offset:2560
	global_load_dwordx2 v[124:125], v194, s[22:23] offset:3072
	global_load_dwordx2 v[126:127], v194, s[22:23] offset:3584
	s_add_u32 s14, s14, 0x2000
	s_addc_u32 s15, s15, 0
	s_add_u32 s16, s16, 0x1000
	s_addc_u32 s17, s17, 0
	s_add_u32 s22, s22, 0x1000
	s_addc_u32 s23, s23, 0
	s_waitcnt vmcnt(24)
	v_lshlrev_b32_e32 v200, 16, v64
	v_and_b32_e32 v201, 0xffff0000, v64
	v_lshlrev_b32_e32 v202, 16, v65
	v_and_b32_e32 v203, 0xffff0000, v65
	v_mul_f32_e32 v208, v200, v200
	v_mul_f32_e32 v209, v201, v201
	v_fmac_f32_e32 v208, v202, v202
	v_fmac_f32_e32 v209, v203, v203
	v_lshlrev_b32_e32 v204, 16, v96
	v_and_b32_e32 v205, 0xffff0000, v96
	v_lshlrev_b32_e32 v206, 16, v97
	v_and_b32_e32 v207, 0xffff0000, v97
	v_mul_f32_e32 v210, v204, v204
	v_mul_f32_e32 v211, v205, v205
	v_fmac_f32_e32 v210, v206, v206
	v_fmac_f32_e32 v211, v207, v207
	v_lshlrev_b32_e32 v200, 16, v66
	v_and_b32_e32 v201, 0xffff0000, v66
	v_lshlrev_b32_e32 v202, 16, v67
	v_and_b32_e32 v203, 0xffff0000, v67
	v_fmac_f32_e32 v208, v200, v200
	v_fmac_f32_e32 v209, v201, v201
	v_fmac_f32_e32 v208, v202, v202
	v_fmac_f32_e32 v209, v203, v203
	v_lshlrev_b32_e32 v204, 16, v98
	v_and_b32_e32 v205, 0xffff0000, v98
	v_lshlrev_b32_e32 v206, 16, v99
	v_and_b32_e32 v207, 0xffff0000, v99
	v_fmac_f32_e32 v210, v204, v204
	v_fmac_f32_e32 v211, v205, v205
	v_fmac_f32_e32 v210, v206, v206
	v_fmac_f32_e32 v211, v207, v207
	v_lshlrev_b32_e32 v200, 16, v68
	v_and_b32_e32 v201, 0xffff0000, v68
	v_lshlrev_b32_e32 v202, 16, v69
	v_and_b32_e32 v203, 0xffff0000, v69
	v_fmac_f32_e32 v208, v200, v200
	v_fmac_f32_e32 v209, v201, v201
	v_fmac_f32_e32 v208, v202, v202
	v_fmac_f32_e32 v209, v203, v203
	v_lshlrev_b32_e32 v204, 16, v100
	v_and_b32_e32 v205, 0xffff0000, v100
	v_lshlrev_b32_e32 v206, 16, v101
	v_and_b32_e32 v207, 0xffff0000, v101
	v_fmac_f32_e32 v210, v204, v204
	v_fmac_f32_e32 v211, v205, v205
	v_fmac_f32_e32 v210, v206, v206
	v_fmac_f32_e32 v211, v207, v207
	v_lshlrev_b32_e32 v200, 16, v70
	v_and_b32_e32 v201, 0xffff0000, v70
	v_lshlrev_b32_e32 v202, 16, v71
	v_and_b32_e32 v203, 0xffff0000, v71
	v_fmac_f32_e32 v208, v200, v200
	v_fmac_f32_e32 v209, v201, v201
	v_fmac_f32_e32 v208, v202, v202
	v_fmac_f32_e32 v209, v203, v203
	v_lshlrev_b32_e32 v204, 16, v102
	v_and_b32_e32 v205, 0xffff0000, v102
	v_lshlrev_b32_e32 v206, 16, v103
	v_and_b32_e32 v207, 0xffff0000, v103
	v_fmac_f32_e32 v210, v204, v204
	v_fmac_f32_e32 v211, v205, v205
	v_fmac_f32_e32 v210, v206, v206
	v_fmac_f32_e32 v211, v207, v207
	v_lshlrev_b32_e32 v200, 16, v72
	v_and_b32_e32 v201, 0xffff0000, v72
	v_lshlrev_b32_e32 v202, 16, v73
	v_and_b32_e32 v203, 0xffff0000, v73
	v_fmac_f32_e32 v208, v200, v200
	v_fmac_f32_e32 v209, v201, v201
	v_fmac_f32_e32 v208, v202, v202
	v_fmac_f32_e32 v209, v203, v203
	v_lshlrev_b32_e32 v204, 16, v104
	v_and_b32_e32 v205, 0xffff0000, v104
	v_lshlrev_b32_e32 v206, 16, v105
	v_and_b32_e32 v207, 0xffff0000, v105
	v_fmac_f32_e32 v210, v204, v204
	v_fmac_f32_e32 v211, v205, v205
	v_fmac_f32_e32 v210, v206, v206
	v_fmac_f32_e32 v211, v207, v207
	v_lshlrev_b32_e32 v200, 16, v74
	v_and_b32_e32 v201, 0xffff0000, v74
	v_lshlrev_b32_e32 v202, 16, v75
	v_and_b32_e32 v203, 0xffff0000, v75
	v_fmac_f32_e32 v208, v200, v200
	v_fmac_f32_e32 v209, v201, v201
	v_fmac_f32_e32 v208, v202, v202
	v_fmac_f32_e32 v209, v203, v203
	v_lshlrev_b32_e32 v204, 16, v106
	v_and_b32_e32 v205, 0xffff0000, v106
	v_lshlrev_b32_e32 v206, 16, v107
	v_and_b32_e32 v207, 0xffff0000, v107
	v_fmac_f32_e32 v210, v204, v204
	v_fmac_f32_e32 v211, v205, v205
	v_fmac_f32_e32 v210, v206, v206
	v_fmac_f32_e32 v211, v207, v207
	v_lshlrev_b32_e32 v200, 16, v76
; __device__ __forceinline__ float bf_lo(unsigned w) { return __uint_as_float(w << 16); }
; __device__ __forceinline__ float bf_hi(unsigned w) { return __uint_as_float(w & 0xffff0000u); }
; __global__ void __launch_bounds__(NWAVES * 64, 2) mk_fwd(Args args) {
;     ...
;                 float sy = 0.f;
; #pragma unroll
;                 for (int j = 0; j < 8; ++j) { const float a = bf_lo(yw[q][j].x), b = bf_hi(yw[q][j].x), c2 = bf_lo(yw[q][j].y), d = bf_hi(yw[q][j].y); sy += (a * a + b * b) + (c2 * c2 + d * d); }
;                 const float rsy = __builtin_amdgcn_rsqf(wave_sum(sy) * (1.f / DM) + EPS);
; #pragma unroll
;                 for (int j = 0; j < 8; ++j) { const int col = 4 * F.lane + 256 * j;
;                     const f32x4 y4 = (f32x4){bf_lo(yw[q][j].x), bf_hi(yw[q][j].x), bf_lo(yw[q][j].y), bf_hi(yw[q][j].y)};
;                     *(f32x4*)(args.out + (size_t)row * DM + col) = v[q][j] + PA[j] * (y4 * rsy); }
	v_and_b32_e32 v201, 0xffff0000, v76
	v_lshlrev_b32_e32 v202, 16, v77
	v_and_b32_e32 v203, 0xffff0000, v77
	v_fmac_f32_e32 v208, v200, v200
	v_fmac_f32_e32 v209, v201, v201
	v_fmac_f32_e32 v208, v202, v202
	v_fmac_f32_e32 v209, v203, v203
	v_lshlrev_b32_e32 v204, 16, v108
	v_and_b32_e32 v205, 0xffff0000, v108
	v_lshlrev_b32_e32 v206, 16, v109
	v_and_b32_e32 v207, 0xffff0000, v109
	v_fmac_f32_e32 v210, v204, v204
	v_fmac_f32_e32 v211, v205, v205
	v_fmac_f32_e32 v210, v206, v206
	v_fmac_f32_e32 v211, v207, v207
	v_lshlrev_b32_e32 v200, 16, v78
	v_and_b32_e32 v201, 0xffff0000, v78
	v_lshlrev_b32_e32 v202, 16, v79
	v_and_b32_e32 v203, 0xffff0000, v79
	v_fmac_f32_e32 v208, v200, v200
	v_fmac_f32_e32 v209, v201, v201
	v_fmac_f32_e32 v208, v202, v202
	v_fmac_f32_e32 v209, v203, v203
	v_lshlrev_b32_e32 v204, 16, v110
	v_and_b32_e32 v205, 0xffff0000, v110
	v_lshlrev_b32_e32 v206, 16, v111
	v_and_b32_e32 v207, 0xffff0000, v111
	v_fmac_f32_e32 v210, v204, v204
	v_fmac_f32_e32 v211, v205, v205
	v_fmac_f32_e32 v210, v206, v206
	v_fmac_f32_e32 v211, v207, v207
	v_add_f32_e32 v208, v208, v209
	v_add_f32_e32 v210, v210, v211
	s_nop 0
	v_add_f32_dpp v212, v208, v208 quad_perm:[1,0,3,2] row_mask:0xf bank_mask:0xf
	v_add_f32_dpp v213, v210, v210 quad_perm:[1,0,3,2] row_mask:0xf bank_mask:0xf
	s_nop 0
	v_add_f32_dpp v212, v212, v212 quad_perm:[2,3,0,1] row_mask:0xf bank_mask:0xf
	v_add_f32_dpp v213, v213, v213 quad_perm:[2,3,0,1] row_mask:0xf bank_mask:0xf
	s_nop 0
	v_add_f32_dpp v212, v212, v212 row_half_mirror row_mask:0xf bank_mask:0xf
	v_add_f32_dpp v213, v213, v213 row_half_mirror row_mask:0xf bank_mask:0xf
	s_nop 0
	v_add_f32_dpp v212, v212, v212 row_mirror row_mask:0xf bank_mask:0xf
	v_add_f32_dpp v213, v213, v213 row_mirror row_mask:0xf bank_mask:0xf
	s_nop 0
	v_readlane_b32 s4, v212, 0
	v_readlane_b32 s5, v212, 16
	v_readlane_b32 s6, v212, 32
	v_readlane_b32 s7, v212, 48
	v_readlane_b32 s24, v213, 0
	v_readlane_b32 s25, v213, 16
	v_readlane_b32 s26, v213, 32
	v_readlane_b32 s27, v213, 48
	s_nop 1
	v_mov_b32_e32 v214, s4
	v_mov_b32_e32 v215, s24
	v_add_f32_e32 v214, s5, v214
	v_add_f32_e32 v215, s25, v215
	v_add_f32_e32 v214, s6, v214
	v_add_f32_e32 v215, s26, v215
	v_add_f32_e32 v214, s7, v214
	v_add_f32_e32 v215, s27, v215
	v_fmamk_f32 v214, v214, 0x3a000000, v195
	v_fmamk_f32 v215, v215, 0x3a000000, v195
	v_rsq_f32_e32 v214, v214
	v_rsq_f32_e32 v215, v215
	s_nop 0
	v_lshlrev_b32_e32 v200, 16, v64
	v_and_b32_e32 v201, 0xffff0000, v64
	v_lshlrev_b32_e32 v202, 16, v65
	v_and_b32_e32 v203, 0xffff0000, v65
	v_lshlrev_b32_e32 v204, 16, v96
	v_and_b32_e32 v205, 0xffff0000, v96
	v_lshlrev_b32_e32 v206, 16, v97
	v_and_b32_e32 v207, 0xffff0000, v97
	v_mul_f32_e32 v200, v214, v200
	v_mul_f32_e32 v201, v214, v201
	v_mul_f32_e32 v202, v214, v202
	v_mul_f32_e32 v203, v214, v203
	v_mul_f32_e32 v204, v215, v204
	v_mul_f32_e32 v205, v215, v205
	v_mul_f32_e32 v206, v215, v206
	v_mul_f32_e32 v207, v215, v207
	v_fmac_f32_e32 v0, v128, v200
	v_fmac_f32_e32 v1, v129, v201
	v_fmac_f32_e32 v2, v130, v202
	v_fmac_f32_e32 v3, v131, v203
	v_fmac_f32_e32 v0, v160, v204
	v_fmac_f32_e32 v1, v161, v205
	v_fmac_f32_e32 v2, v162, v206
	v_fmac_f32_e32 v3, v163, v207
	global_store_dwordx4 v192, v[0:3], s[18:19] offset:0
	v_lshlrev_b32_e32 v200, 16, v66
	v_and_b32_e32 v201, 0xffff0000, v66
	v_lshlrev_b32_e32 v202, 16, v67
	v_and_b32_e32 v203, 0xffff0000, v67
	v_lshlrev_b32_e32 v204, 16, v98
	v_and_b32_e32 v205, 0xffff0000, v98
	v_lshlrev_b32_e32 v206, 16, v99
	v_and_b32_e32 v207, 0xffff0000, v99
	v_mul_f32_e32 v200, v214, v200
	v_mul_f32_e32 v201, v214, v201
	v_mul_f32_e32 v202, v214, v202
	v_mul_f32_e32 v203, v214, v203
	v_mul_f32_e32 v204, v215, v204
	v_mul_f32_e32 v205, v215, v205
	v_mul_f32_e32 v206, v215, v206
	v_mul_f32_e32 v207, v215, v207
	v_fmac_f32_e32 v4, v132, v200
	v_fmac_f32_e32 v5, v133, v201
	v_fmac_f32_e32 v6, v134, v202
	v_fmac_f32_e32 v7, v135, v203
	v_fmac_f32_e32 v4, v164, v204
	v_fmac_f32_e32 v5, v165, v205
	v_fmac_f32_e32 v6, v166, v206
	v_fmac_f32_e32 v7, v167, v207
	global_store_dwordx4 v192, v[4:7], s[18:19] offset:1024
	v_lshlrev_b32_e32 v200, 16, v68
	v_and_b32_e32 v201, 0xffff0000, v68
	v_lshlrev_b32_e32 v202, 16, v69
	v_and_b32_e32 v203, 0xffff0000, v69
	v_lshlrev_b32_e32 v204, 16, v100
	v_and_b32_e32 v205, 0xffff0000, v100
	v_lshlrev_b32_e32 v206, 16, v101
	v_and_b32_e32 v207, 0xffff0000, v101
	v_mul_f32_e32 v200, v214, v200
	v_mul_f32_e32 v201, v214, v201
	v_mul_f32_e32 v202, v214, v202
	v_mul_f32_e32 v203, v214, v203
	v_mul_f32_e32 v204, v215, v204
	v_mul_f32_e32 v205, v215, v205
	v_mul_f32_e32 v206, v215, v206
	v_mul_f32_e32 v207, v215, v207
	v_fmac_f32_e32 v8, v136, v200
	v_fmac_f32_e32 v9, v137, v201
	v_fmac_f32_e32 v10, v138, v202
	v_fmac_f32_e32 v11, v139, v203
	v_fmac_f32_e32 v8, v168, v204
	v_fmac_f32_e32 v9, v169, v205
	v_fmac_f32_e32 v10, v170, v206
	v_fmac_f32_e32 v11, v171, v207
	global_store_dwordx4 v192, v[8:11], s[18:19] offset:2048
	v_lshlrev_b32_e32 v200, 16, v70
	v_and_b32_e32 v201, 0xffff0000, v70
	v_lshlrev_b32_e32 v202, 16, v71
	v_and_b32_e32 v203, 0xffff0000, v71
	v_lshlrev_b32_e32 v204, 16, v102
	v_and_b32_e32 v205, 0xffff0000, v102
	v_lshlrev_b32_e32 v206, 16, v103
	v_and_b32_e32 v207, 0xffff0000, v103
	v_mul_f32_e32 v200, v214, v200
	v_mul_f32_e32 v201, v214, v201
	v_mul_f32_e32 v202, v214, v202
	v_mul_f32_e32 v203, v214, v203
	v_mul_f32_e32 v204, v215, v204
	v_mul_f32_e32 v205, v215, v205
	v_mul_f32_e32 v206, v215, v206
	v_mul_f32_e32 v207, v215, v207
	v_fmac_f32_e32 v12, v140, v200
	v_fmac_f32_e32 v13, v141, v201
	v_fmac_f32_e32 v14, v142, v202
	v_fmac_f32_e32 v15, v143, v203
	v_fmac_f32_e32 v12, v172, v204
; __device__ __forceinline__ float bf_lo(unsigned w) { return __uint_as_float(w << 16); }
; __device__ __forceinline__ float bf_hi(unsigned w) { return __uint_as_float(w & 0xffff0000u); }
; __global__ void __launch_bounds__(NWAVES * 64, 2) mk_fwd(Args args) {
;     ...
;         for (int row0 = rbeg; row0 < rbeg + per2 && row0 < ML; row0 += 2) {
;             f32x4 v[2][8]; u32x2 yw[2][8];
; #pragma unroll
;             for (int q = 0; q < 2; ++q) { const int row = row0 + q; load_row_f32(args.out + (size_t)row * DM, F.lane, v[q]);
;                 const bf16_t* yr = Y + (size_t)row * DM;
; #pragma unroll
;                 for (int j = 0; j < 8; ++j) yw[q][j] = *(const u32x2*)(yr + 4 * F.lane + 256 * j); }
;     ...
; #pragma unroll
;                 for (int j = 0; j < 8; ++j) { const int col = 4 * F.lane + 256 * j;
;                     const f32x4 y4 = (f32x4){bf_lo(yw[q][j].x), bf_hi(yw[q][j].x), bf_lo(yw[q][j].y), bf_hi(yw[q][j].y)};
;                     *(f32x4*)(args.out + (size_t)row * DM + col) = v[q][j] + PA[j] * (y4 * rsy); }
	v_fmac_f32_e32 v13, v173, v205
	v_fmac_f32_e32 v14, v174, v206
	v_fmac_f32_e32 v15, v175, v207
	global_store_dwordx4 v192, v[12:15], s[18:19] offset:3072
	v_lshlrev_b32_e32 v200, 16, v72
	v_and_b32_e32 v201, 0xffff0000, v72
	v_lshlrev_b32_e32 v202, 16, v73
	v_and_b32_e32 v203, 0xffff0000, v73
	v_lshlrev_b32_e32 v204, 16, v104
	v_and_b32_e32 v205, 0xffff0000, v104
	v_lshlrev_b32_e32 v206, 16, v105
	v_and_b32_e32 v207, 0xffff0000, v105
	v_mul_f32_e32 v200, v214, v200
	v_mul_f32_e32 v201, v214, v201
	v_mul_f32_e32 v202, v214, v202
	v_mul_f32_e32 v203, v214, v203
	v_mul_f32_e32 v204, v215, v204
	v_mul_f32_e32 v205, v215, v205
	v_mul_f32_e32 v206, v215, v206
	v_mul_f32_e32 v207, v215, v207
	v_fmac_f32_e32 v16, v144, v200
	v_fmac_f32_e32 v17, v145, v201
	v_fmac_f32_e32 v18, v146, v202
	v_fmac_f32_e32 v19, v147, v203
	v_fmac_f32_e32 v16, v176, v204
	v_fmac_f32_e32 v17, v177, v205
	v_fmac_f32_e32 v18, v178, v206
	v_fmac_f32_e32 v19, v179, v207
	global_store_dwordx4 v193, v[16:19], s[18:19] offset:0
	v_lshlrev_b32_e32 v200, 16, v74
	v_and_b32_e32 v201, 0xffff0000, v74
	v_lshlrev_b32_e32 v202, 16, v75
	v_and_b32_e32 v203, 0xffff0000, v75
	v_lshlrev_b32_e32 v204, 16, v106
	v_and_b32_e32 v205, 0xffff0000, v106
	v_lshlrev_b32_e32 v206, 16, v107
	v_and_b32_e32 v207, 0xffff0000, v107
	v_mul_f32_e32 v200, v214, v200
	v_mul_f32_e32 v201, v214, v201
	v_mul_f32_e32 v202, v214, v202
	v_mul_f32_e32 v203, v214, v203
	v_mul_f32_e32 v204, v215, v204
	v_mul_f32_e32 v205, v215, v205
	v_mul_f32_e32 v206, v215, v206
	v_mul_f32_e32 v207, v215, v207
	v_fmac_f32_e32 v20, v148, v200
	v_fmac_f32_e32 v21, v149, v201
	v_fmac_f32_e32 v22, v150, v202
	v_fmac_f32_e32 v23, v151, v203
	v_fmac_f32_e32 v20, v180, v204
	v_fmac_f32_e32 v21, v181, v205
	v_fmac_f32_e32 v22, v182, v206
	v_fmac_f32_e32 v23, v183, v207
	global_store_dwordx4 v193, v[20:23], s[18:19] offset:1024
	v_lshlrev_b32_e32 v200, 16, v76
	v_and_b32_e32 v201, 0xffff0000, v76
	v_lshlrev_b32_e32 v202, 16, v77
	v_and_b32_e32 v203, 0xffff0000, v77
	v_lshlrev_b32_e32 v204, 16, v108
	v_and_b32_e32 v205, 0xffff0000, v108
	v_lshlrev_b32_e32 v206, 16, v109
	v_and_b32_e32 v207, 0xffff0000, v109
	v_mul_f32_e32 v200, v214, v200
	v_mul_f32_e32 v201, v214, v201
	v_mul_f32_e32 v202, v214, v202
	v_mul_f32_e32 v203, v214, v203
	v_mul_f32_e32 v204, v215, v204
	v_mul_f32_e32 v205, v215, v205
	v_mul_f32_e32 v206, v215, v206
	v_mul_f32_e32 v207, v215, v207
	v_fmac_f32_e32 v24, v152, v200
	v_fmac_f32_e32 v25, v153, v201
	v_fmac_f32_e32 v26, v154, v202
	v_fmac_f32_e32 v27, v155, v203
	v_fmac_f32_e32 v24, v184, v204
	v_fmac_f32_e32 v25, v185, v205
	v_fmac_f32_e32 v26, v186, v206
	v_fmac_f32_e32 v27, v187, v207
	global_store_dwordx4 v193, v[24:27], s[18:19] offset:2048
	v_lshlrev_b32_e32 v200, 16, v78
	v_and_b32_e32 v201, 0xffff0000, v78
	v_lshlrev_b32_e32 v202, 16, v79
	v_and_b32_e32 v203, 0xffff0000, v79
	v_lshlrev_b32_e32 v204, 16, v110
	v_and_b32_e32 v205, 0xffff0000, v110
	v_lshlrev_b32_e32 v206, 16, v111
	v_and_b32_e32 v207, 0xffff0000, v111
	v_mul_f32_e32 v200, v214, v200
	v_mul_f32_e32 v201, v214, v201
	v_mul_f32_e32 v202, v214, v202
	v_mul_f32_e32 v203, v214, v203
	v_mul_f32_e32 v204, v215, v204
	v_mul_f32_e32 v205, v215, v205
	v_mul_f32_e32 v206, v215, v206
	v_mul_f32_e32 v207, v215, v207
	v_fmac_f32_e32 v28, v156, v200
	v_fmac_f32_e32 v29, v157, v201
	v_fmac_f32_e32 v30, v158, v202
	v_fmac_f32_e32 v31, v159, v203
	v_fmac_f32_e32 v28, v188, v204
	v_fmac_f32_e32 v29, v189, v205
	v_fmac_f32_e32 v30, v190, v206
	v_fmac_f32_e32 v31, v191, v207
	global_store_dwordx4 v193, v[28:31], s[18:19] offset:3072
	s_add_u32 s18, s18, 0x2000
	s_addc_u32 s19, s19, 0
	global_load_dwordx4 v[0:3], v192, s[14:15] offset:0
	global_load_dwordx4 v[4:7], v192, s[14:15] offset:1024
	global_load_dwordx4 v[8:11], v192, s[14:15] offset:2048
	global_load_dwordx4 v[12:15], v192, s[14:15] offset:3072
	global_load_dwordx4 v[16:19], v193, s[14:15] offset:0
	global_load_dwordx4 v[20:23], v193, s[14:15] offset:1024
	global_load_dwordx4 v[24:27], v193, s[14:15] offset:2048
	global_load_dwordx4 v[28:31], v193, s[14:15] offset:3072
	global_load_dwordx2 v[64:65], v194, s[16:17] offset:0
	global_load_dwordx2 v[66:67], v194, s[16:17] offset:512
	global_load_dwordx2 v[68:69], v194, s[16:17] offset:1024
	global_load_dwordx2 v[70:71], v194, s[16:17] offset:1536
	global_load_dwordx2 v[72:73], v194, s[16:17] offset:2048
	global_load_dwordx2 v[74:75], v194, s[16:17] offset:2560
	global_load_dwordx2 v[76:77], v194, s[16:17] offset:3072
	global_load_dwordx2 v[78:79], v194, s[16:17] offset:3584
	global_load_dwordx2 v[96:97], v194, s[22:23] offset:0
	global_load_dwordx2 v[98:99], v194, s[22:23] offset:512
	global_load_dwordx2 v[100:101], v194, s[22:23] offset:1024
	global_load_dwordx2 v[102:103], v194, s[22:23] offset:1536
	global_load_dwordx2 v[104:105], v194, s[22:23] offset:2048
	global_load_dwordx2 v[106:107], v194, s[22:23] offset:2560
	global_load_dwordx2 v[108:109], v194, s[22:23] offset:3072
	global_load_dwordx2 v[110:111], v194, s[22:23] offset:3584
	s_add_u32 s14, s14, 0x2000
	s_addc_u32 s15, s15, 0
	s_add_u32 s16, s16, 0x1000
	s_addc_u32 s17, s17, 0
	s_add_u32 s22, s22, 0x1000
	s_addc_u32 s23, s23, 0
	s_waitcnt vmcnt(32)
; __device__ __forceinline__ float bf_lo(unsigned w) { return __uint_as_float(w << 16); }
; __device__ __forceinline__ float bf_hi(unsigned w) { return __uint_as_float(w & 0xffff0000u); }
; __global__ void __launch_bounds__(NWAVES * 64, 2) mk_fwd(Args args) {
;     ...
;                 float sy = 0.f;
; #pragma unroll
;                 for (int j = 0; j < 8; ++j) { const float a = bf_lo(yw[q][j].x), b = bf_hi(yw[q][j].x), c2 = bf_lo(yw[q][j].y), d = bf_hi(yw[q][j].y); sy += (a * a + b * b) + (c2 * c2 + d * d); }
;                 const float rsy = __builtin_amdgcn_rsqf(wave_sum(sy) * (1.f / DM) + EPS);
	v_lshlrev_b32_e32 v200, 16, v80
	v_and_b32_e32 v201, 0xffff0000, v80
	v_lshlrev_b32_e32 v202, 16, v81
	v_and_b32_e32 v203, 0xffff0000, v81
	v_mul_f32_e32 v208, v200, v200
	v_mul_f32_e32 v209, v201, v201
	v_fmac_f32_e32 v208, v202, v202
	v_fmac_f32_e32 v209, v203, v203
	v_lshlrev_b32_e32 v204, 16, v112
	v_and_b32_e32 v205, 0xffff0000, v112
	v_lshlrev_b32_e32 v206, 16, v113
	v_and_b32_e32 v207, 0xffff0000, v113
	v_mul_f32_e32 v210, v204, v204
	v_mul_f32_e32 v211, v205, v205
	v_fmac_f32_e32 v210, v206, v206
	v_fmac_f32_e32 v211, v207, v207
	v_lshlrev_b32_e32 v200, 16, v82
	v_and_b32_e32 v201, 0xffff0000, v82
	v_lshlrev_b32_e32 v202, 16, v83
	v_and_b32_e32 v203, 0xffff0000, v83
	v_fmac_f32_e32 v208, v200, v200
	v_fmac_f32_e32 v209, v201, v201
	v_fmac_f32_e32 v208, v202, v202
	v_fmac_f32_e32 v209, v203, v203
	v_lshlrev_b32_e32 v204, 16, v114
	v_and_b32_e32 v205, 0xffff0000, v114
	v_lshlrev_b32_e32 v206, 16, v115
	v_and_b32_e32 v207, 0xffff0000, v115
	v_fmac_f32_e32 v210, v204, v204
	v_fmac_f32_e32 v211, v205, v205
	v_fmac_f32_e32 v210, v206, v206
	v_fmac_f32_e32 v211, v207, v207
	v_lshlrev_b32_e32 v200, 16, v84
	v_and_b32_e32 v201, 0xffff0000, v84
	v_lshlrev_b32_e32 v202, 16, v85
	v_and_b32_e32 v203, 0xffff0000, v85
	v_fmac_f32_e32 v208, v200, v200
	v_fmac_f32_e32 v209, v201, v201
	v_fmac_f32_e32 v208, v202, v202
	v_fmac_f32_e32 v209, v203, v203
	v_lshlrev_b32_e32 v204, 16, v116
	v_and_b32_e32 v205, 0xffff0000, v116
	v_lshlrev_b32_e32 v206, 16, v117
	v_and_b32_e32 v207, 0xffff0000, v117
	v_fmac_f32_e32 v210, v204, v204
	v_fmac_f32_e32 v211, v205, v205
	v_fmac_f32_e32 v210, v206, v206
	v_fmac_f32_e32 v211, v207, v207
	v_lshlrev_b32_e32 v200, 16, v86
	v_and_b32_e32 v201, 0xffff0000, v86
	v_lshlrev_b32_e32 v202, 16, v87
	v_and_b32_e32 v203, 0xffff0000, v87
	v_fmac_f32_e32 v208, v200, v200
	v_fmac_f32_e32 v209, v201, v201
	v_fmac_f32_e32 v208, v202, v202
	v_fmac_f32_e32 v209, v203, v203
	v_lshlrev_b32_e32 v204, 16, v118
	v_and_b32_e32 v205, 0xffff0000, v118
	v_lshlrev_b32_e32 v206, 16, v119
	v_and_b32_e32 v207, 0xffff0000, v119
	v_fmac_f32_e32 v210, v204, v204
	v_fmac_f32_e32 v211, v205, v205
	v_fmac_f32_e32 v210, v206, v206
	v_fmac_f32_e32 v211, v207, v207
	v_lshlrev_b32_e32 v200, 16, v88
	v_and_b32_e32 v201, 0xffff0000, v88
	v_lshlrev_b32_e32 v202, 16, v89
	v_and_b32_e32 v203, 0xffff0000, v89
	v_fmac_f32_e32 v208, v200, v200
	v_fmac_f32_e32 v209, v201, v201
	v_fmac_f32_e32 v208, v202, v202
	v_fmac_f32_e32 v209, v203, v203
	v_lshlrev_b32_e32 v204, 16, v120
	v_and_b32_e32 v205, 0xffff0000, v120
	v_lshlrev_b32_e32 v206, 16, v121
	v_and_b32_e32 v207, 0xffff0000, v121
	v_fmac_f32_e32 v210, v204, v204
	v_fmac_f32_e32 v211, v205, v205
	v_fmac_f32_e32 v210, v206, v206
	v_fmac_f32_e32 v211, v207, v207
	v_lshlrev_b32_e32 v200, 16, v90
	v_and_b32_e32 v201, 0xffff0000, v90
	v_lshlrev_b32_e32 v202, 16, v91
	v_and_b32_e32 v203, 0xffff0000, v91
	v_fmac_f32_e32 v208, v200, v200
	v_fmac_f32_e32 v209, v201, v201
	v_fmac_f32_e32 v208, v202, v202
	v_fmac_f32_e32 v209, v203, v203
	v_lshlrev_b32_e32 v204, 16, v122
	v_and_b32_e32 v205, 0xffff0000, v122
	v_lshlrev_b32_e32 v206, 16, v123
	v_and_b32_e32 v207, 0xffff0000, v123
	v_fmac_f32_e32 v210, v204, v204
	v_fmac_f32_e32 v211, v205, v205
	v_fmac_f32_e32 v210, v206, v206
	v_fmac_f32_e32 v211, v207, v207
	v_lshlrev_b32_e32 v200, 16, v92
	v_and_b32_e32 v201, 0xffff0000, v92
	v_lshlrev_b32_e32 v202, 16, v93
	v_and_b32_e32 v203, 0xffff0000, v93
	v_fmac_f32_e32 v208, v200, v200
	v_fmac_f32_e32 v209, v201, v201
	v_fmac_f32_e32 v208, v202, v202
	v_fmac_f32_e32 v209, v203, v203
	v_lshlrev_b32_e32 v204, 16, v124
	v_and_b32_e32 v205, 0xffff0000, v124
	v_lshlrev_b32_e32 v206, 16, v125
	v_and_b32_e32 v207, 0xffff0000, v125
	v_fmac_f32_e32 v210, v204, v204
	v_fmac_f32_e32 v211, v205, v205
	v_fmac_f32_e32 v210, v206, v206
	v_fmac_f32_e32 v211, v207, v207
	v_lshlrev_b32_e32 v200, 16, v94
	v_and_b32_e32 v201, 0xffff0000, v94
	v_lshlrev_b32_e32 v202, 16, v95
	v_and_b32_e32 v203, 0xffff0000, v95
	v_fmac_f32_e32 v208, v200, v200
	v_fmac_f32_e32 v209, v201, v201
	v_fmac_f32_e32 v208, v202, v202
	v_fmac_f32_e32 v209, v203, v203
	v_lshlrev_b32_e32 v204, 16, v126
	v_and_b32_e32 v205, 0xffff0000, v126
	v_lshlrev_b32_e32 v206, 16, v127
	v_and_b32_e32 v207, 0xffff0000, v127
	v_fmac_f32_e32 v210, v204, v204
	v_fmac_f32_e32 v211, v205, v205
	v_fmac_f32_e32 v210, v206, v206
	v_fmac_f32_e32 v211, v207, v207
	v_add_f32_e32 v208, v208, v209
	v_add_f32_e32 v210, v210, v211
	s_nop 0
	v_add_f32_dpp v212, v208, v208 quad_perm:[1,0,3,2] row_mask:0xf bank_mask:0xf
	v_add_f32_dpp v213, v210, v210 quad_perm:[1,0,3,2] row_mask:0xf bank_mask:0xf
	s_nop 0
	v_add_f32_dpp v212, v212, v212 quad_perm:[2,3,0,1] row_mask:0xf bank_mask:0xf
	v_add_f32_dpp v213, v213, v213 quad_perm:[2,3,0,1] row_mask:0xf bank_mask:0xf
	s_nop 0
	v_add_f32_dpp v212, v212, v212 row_half_mirror row_mask:0xf bank_mask:0xf
	v_add_f32_dpp v213, v213, v213 row_half_mirror row_mask:0xf bank_mask:0xf
	s_nop 0
	v_add_f32_dpp v212, v212, v212 row_mirror row_mask:0xf bank_mask:0xf
	v_add_f32_dpp v213, v213, v213 row_mirror row_mask:0xf bank_mask:0xf
	s_nop 0
	v_readlane_b32 s4, v212, 0
	v_readlane_b32 s5, v212, 16
	v_readlane_b32 s6, v212, 32
	v_readlane_b32 s7, v212, 48
	v_readlane_b32 s24, v213, 0
	v_readlane_b32 s25, v213, 16
	v_readlane_b32 s26, v213, 32
	v_readlane_b32 s27, v213, 48
	s_nop 1
	v_mov_b32_e32 v214, s4
	v_mov_b32_e32 v215, s24
	v_add_f32_e32 v214, s5, v214
	v_add_f32_e32 v215, s25, v215
	v_add_f32_e32 v214, s6, v214
	v_add_f32_e32 v215, s26, v215
	v_add_f32_e32 v214, s7, v214
	v_add_f32_e32 v215, s27, v215
	v_fmamk_f32 v214, v214, 0x3a000000, v195
	v_fmamk_f32 v215, v215, 0x3a000000, v195
; __device__ __forceinline__ float bf_lo(unsigned w) { return __uint_as_float(w << 16); }
; __device__ __forceinline__ float bf_hi(unsigned w) { return __uint_as_float(w & 0xffff0000u); }
; __global__ void __launch_bounds__(NWAVES * 64, 2) mk_fwd(Args args) {
;     ...
;                 const float rsy = __builtin_amdgcn_rsqf(wave_sum(sy) * (1.f / DM) + EPS);
; #pragma unroll
;                 for (int j = 0; j < 8; ++j) { const int col = 4 * F.lane + 256 * j;
;                     const f32x4 y4 = (f32x4){bf_lo(yw[q][j].x), bf_hi(yw[q][j].x), bf_lo(yw[q][j].y), bf_hi(yw[q][j].y)};
;                     *(f32x4*)(args.out + (size_t)row * DM + col) = v[q][j] + PA[j] * (y4 * rsy); }
	v_rsq_f32_e32 v214, v214
	v_rsq_f32_e32 v215, v215
	s_nop 0
	v_lshlrev_b32_e32 v200, 16, v80
	v_and_b32_e32 v201, 0xffff0000, v80
	v_lshlrev_b32_e32 v202, 16, v81
	v_and_b32_e32 v203, 0xffff0000, v81
	v_lshlrev_b32_e32 v204, 16, v112
	v_and_b32_e32 v205, 0xffff0000, v112
	v_lshlrev_b32_e32 v206, 16, v113
	v_and_b32_e32 v207, 0xffff0000, v113
	v_mul_f32_e32 v200, v214, v200
	v_mul_f32_e32 v201, v214, v201
	v_mul_f32_e32 v202, v214, v202
	v_mul_f32_e32 v203, v214, v203
	v_mul_f32_e32 v204, v215, v204
	v_mul_f32_e32 v205, v215, v205
	v_mul_f32_e32 v206, v215, v206
	v_mul_f32_e32 v207, v215, v207
	v_fmac_f32_e32 v32, v128, v200
	v_fmac_f32_e32 v33, v129, v201
	v_fmac_f32_e32 v34, v130, v202
	v_fmac_f32_e32 v35, v131, v203
	v_fmac_f32_e32 v32, v160, v204
	v_fmac_f32_e32 v33, v161, v205
	v_fmac_f32_e32 v34, v162, v206
	v_fmac_f32_e32 v35, v163, v207
	global_store_dwordx4 v192, v[32:35], s[18:19] offset:0
	v_lshlrev_b32_e32 v200, 16, v82
	v_and_b32_e32 v201, 0xffff0000, v82
	v_lshlrev_b32_e32 v202, 16, v83
	v_and_b32_e32 v203, 0xffff0000, v83
	v_lshlrev_b32_e32 v204, 16, v114
	v_and_b32_e32 v205, 0xffff0000, v114
	v_lshlrev_b32_e32 v206, 16, v115
	v_and_b32_e32 v207, 0xffff0000, v115
	v_mul_f32_e32 v200, v214, v200
	v_mul_f32_e32 v201, v214, v201
	v_mul_f32_e32 v202, v214, v202
	v_mul_f32_e32 v203, v214, v203
	v_mul_f32_e32 v204, v215, v204
	v_mul_f32_e32 v205, v215, v205
	v_mul_f32_e32 v206, v215, v206
	v_mul_f32_e32 v207, v215, v207
	v_fmac_f32_e32 v36, v132, v200
	v_fmac_f32_e32 v37, v133, v201
	v_fmac_f32_e32 v38, v134, v202
	v_fmac_f32_e32 v39, v135, v203
	v_fmac_f32_e32 v36, v164, v204
	v_fmac_f32_e32 v37, v165, v205
	v_fmac_f32_e32 v38, v166, v206
	v_fmac_f32_e32 v39, v167, v207
	global_store_dwordx4 v192, v[36:39], s[18:19] offset:1024
	v_lshlrev_b32_e32 v200, 16, v84
	v_and_b32_e32 v201, 0xffff0000, v84
	v_lshlrev_b32_e32 v202, 16, v85
	v_and_b32_e32 v203, 0xffff0000, v85
	v_lshlrev_b32_e32 v204, 16, v116
	v_and_b32_e32 v205, 0xffff0000, v116
	v_lshlrev_b32_e32 v206, 16, v117
	v_and_b32_e32 v207, 0xffff0000, v117
	v_mul_f32_e32 v200, v214, v200
	v_mul_f32_e32 v201, v214, v201
	v_mul_f32_e32 v202, v214, v202
	v_mul_f32_e32 v203, v214, v203
	v_mul_f32_e32 v204, v215, v204
	v_mul_f32_e32 v205, v215, v205
	v_mul_f32_e32 v206, v215, v206
	v_mul_f32_e32 v207, v215, v207
	v_fmac_f32_e32 v40, v136, v200
	v_fmac_f32_e32 v41, v137, v201
	v_fmac_f32_e32 v42, v138, v202
	v_fmac_f32_e32 v43, v139, v203
	v_fmac_f32_e32 v40, v168, v204
	v_fmac_f32_e32 v41, v169, v205
	v_fmac_f32_e32 v42, v170, v206
	v_fmac_f32_e32 v43, v171, v207
	global_store_dwordx4 v192, v[40:43], s[18:19] offset:2048
	v_lshlrev_b32_e32 v200, 16, v86
	v_and_b32_e32 v201, 0xffff0000, v86
	v_lshlrev_b32_e32 v202, 16, v87
	v_and_b32_e32 v203, 0xffff0000, v87
	v_lshlrev_b32_e32 v204, 16, v118
	v_and_b32_e32 v205, 0xffff0000, v118
	v_lshlrev_b32_e32 v206, 16, v119
	v_and_b32_e32 v207, 0xffff0000, v119
	v_mul_f32_e32 v200, v214, v200
	v_mul_f32_e32 v201, v214, v201
	v_mul_f32_e32 v202, v214, v202
	v_mul_f32_e32 v203, v214, v203
	v_mul_f32_e32 v204, v215, v204
	v_mul_f32_e32 v205, v215, v205
	v_mul_f32_e32 v206, v215, v206
	v_mul_f32_e32 v207, v215, v207
	v_fmac_f32_e32 v44, v140, v200
	v_fmac_f32_e32 v45, v141, v201
	v_fmac_f32_e32 v46, v142, v202
	v_fmac_f32_e32 v47, v143, v203
	v_fmac_f32_e32 v44, v172, v204
	v_fmac_f32_e32 v45, v173, v205
	v_fmac_f32_e32 v46, v174, v206
	v_fmac_f32_e32 v47, v175, v207
	global_store_dwordx4 v192, v[44:47], s[18:19] offset:3072
	v_lshlrev_b32_e32 v200, 16, v88
	v_and_b32_e32 v201, 0xffff0000, v88
	v_lshlrev_b32_e32 v202, 16, v89
	v_and_b32_e32 v203, 0xffff0000, v89
	v_lshlrev_b32_e32 v204, 16, v120
	v_and_b32_e32 v205, 0xffff0000, v120
	v_lshlrev_b32_e32 v206, 16, v121
	v_and_b32_e32 v207, 0xffff0000, v121
	v_mul_f32_e32 v200, v214, v200
	v_mul_f32_e32 v201, v214, v201
	v_mul_f32_e32 v202, v214, v202
	v_mul_f32_e32 v203, v214, v203
	v_mul_f32_e32 v204, v215, v204
	v_mul_f32_e32 v205, v215, v205
	v_mul_f32_e32 v206, v215, v206
	v_mul_f32_e32 v207, v215, v207
	v_fmac_f32_e32 v48, v144, v200
	v_fmac_f32_e32 v49, v145, v201
	v_fmac_f32_e32 v50, v146, v202
	v_fmac_f32_e32 v51, v147, v203
	v_fmac_f32_e32 v48, v176, v204
	v_fmac_f32_e32 v49, v177, v205
	v_fmac_f32_e32 v50, v178, v206
	v_fmac_f32_e32 v51, v179, v207
	global_store_dwordx4 v193, v[48:51], s[18:19] offset:0
	v_lshlrev_b32_e32 v200, 16, v90
	v_and_b32_e32 v201, 0xffff0000, v90
	v_lshlrev_b32_e32 v202, 16, v91
	v_and_b32_e32 v203, 0xffff0000, v91
	v_lshlrev_b32_e32 v204, 16, v122
	v_and_b32_e32 v205, 0xffff0000, v122
	v_lshlrev_b32_e32 v206, 16, v123
	v_and_b32_e32 v207, 0xffff0000, v123
	v_mul_f32_e32 v200, v214, v200
	v_mul_f32_e32 v201, v214, v201
	v_mul_f32_e32 v202, v214, v202
	v_mul_f32_e32 v203, v214, v203
	v_mul_f32_e32 v204, v215, v204
	v_mul_f32_e32 v205, v215, v205
	v_mul_f32_e32 v206, v215, v206
	v_mul_f32_e32 v207, v215, v207
	v_fmac_f32_e32 v52, v148, v200
	v_fmac_f32_e32 v53, v149, v201
	v_fmac_f32_e32 v54, v150, v202
	v_fmac_f32_e32 v55, v151, v203
	v_fmac_f32_e32 v52, v180, v204
	v_fmac_f32_e32 v53, v181, v205
	v_fmac_f32_e32 v54, v182, v206
	v_fmac_f32_e32 v55, v183, v207
	global_store_dwordx4 v193, v[52:55], s[18:19] offset:1024
	v_lshlrev_b32_e32 v200, 16, v92
	v_and_b32_e32 v201, 0xffff0000, v92
	v_lshlrev_b32_e32 v202, 16, v93
	v_and_b32_e32 v203, 0xffff0000, v93
	v_lshlrev_b32_e32 v204, 16, v124
	v_and_b32_e32 v205, 0xffff0000, v124
	v_lshlrev_b32_e32 v206, 16, v125
	v_and_b32_e32 v207, 0xffff0000, v125
	v_mul_f32_e32 v200, v214, v200
	v_mul_f32_e32 v201, v214, v201
	v_mul_f32_e32 v202, v214, v202
	v_mul_f32_e32 v203, v214, v203
	v_mul_f32_e32 v204, v215, v204
; __device__ __forceinline__ float bf_lo(unsigned w) { return __uint_as_float(w << 16); }
; __device__ __forceinline__ float bf_hi(unsigned w) { return __uint_as_float(w & 0xffff0000u); }
; __global__ void __launch_bounds__(NWAVES * 64, 2) mk_fwd(Args args) {
;     ...
;         for (int row0 = rbeg; row0 < rbeg + per2 && row0 < ML; row0 += 2) {
;             f32x4 v[2][8]; u32x2 yw[2][8];
; #pragma unroll
;             for (int q = 0; q < 2; ++q) { const int row = row0 + q; load_row_f32(args.out + (size_t)row * DM, F.lane, v[q]);
;                 const bf16_t* yr = Y + (size_t)row * DM;
; #pragma unroll
;                 for (int j = 0; j < 8; ++j) yw[q][j] = *(const u32x2*)(yr + 4 * F.lane + 256 * j); }
;     ...
; #pragma unroll
;                 for (int j = 0; j < 8; ++j) { const int col = 4 * F.lane + 256 * j;
;                     const f32x4 y4 = (f32x4){bf_lo(yw[q][j].x), bf_hi(yw[q][j].x), bf_lo(yw[q][j].y), bf_hi(yw[q][j].y)};
;                     *(f32x4*)(args.out + (size_t)row * DM + col) = v[q][j] + PA[j] * (y4 * rsy); }
	v_mul_f32_e32 v205, v215, v205
	v_mul_f32_e32 v206, v215, v206
	v_mul_f32_e32 v207, v215, v207
	v_fmac_f32_e32 v56, v152, v200
	v_fmac_f32_e32 v57, v153, v201
	v_fmac_f32_e32 v58, v154, v202
	v_fmac_f32_e32 v59, v155, v203
	v_fmac_f32_e32 v56, v184, v204
	v_fmac_f32_e32 v57, v185, v205
	v_fmac_f32_e32 v58, v186, v206
	v_fmac_f32_e32 v59, v187, v207
	global_store_dwordx4 v193, v[56:59], s[18:19] offset:2048
	v_lshlrev_b32_e32 v200, 16, v94
	v_and_b32_e32 v201, 0xffff0000, v94
	v_lshlrev_b32_e32 v202, 16, v95
	v_and_b32_e32 v203, 0xffff0000, v95
	v_lshlrev_b32_e32 v204, 16, v126
	v_and_b32_e32 v205, 0xffff0000, v126
	v_lshlrev_b32_e32 v206, 16, v127
	v_and_b32_e32 v207, 0xffff0000, v127
	v_mul_f32_e32 v200, v214, v200
	v_mul_f32_e32 v201, v214, v201
	v_mul_f32_e32 v202, v214, v202
	v_mul_f32_e32 v203, v214, v203
	v_mul_f32_e32 v204, v215, v204
	v_mul_f32_e32 v205, v215, v205
	v_mul_f32_e32 v206, v215, v206
	v_mul_f32_e32 v207, v215, v207
	v_fmac_f32_e32 v60, v156, v200
	v_fmac_f32_e32 v61, v157, v201
	v_fmac_f32_e32 v62, v158, v202
	v_fmac_f32_e32 v63, v159, v203
	v_fmac_f32_e32 v60, v188, v204
	v_fmac_f32_e32 v61, v189, v205
	v_fmac_f32_e32 v62, v190, v206
	v_fmac_f32_e32 v63, v191, v207
	global_store_dwordx4 v193, v[60:63], s[18:19] offset:3072
	s_add_u32 s18, s18, 0x2000
	s_addc_u32 s19, s19, 0
	global_load_dwordx4 v[32:35], v192, s[14:15] offset:0
	global_load_dwordx4 v[36:39], v192, s[14:15] offset:1024
	global_load_dwordx4 v[40:43], v192, s[14:15] offset:2048
	global_load_dwordx4 v[44:47], v192, s[14:15] offset:3072
	global_load_dwordx4 v[48:51], v193, s[14:15] offset:0
	global_load_dwordx4 v[52:55], v193, s[14:15] offset:1024
	global_load_dwordx4 v[56:59], v193, s[14:15] offset:2048
	global_load_dwordx4 v[60:63], v193, s[14:15] offset:3072
	global_load_dwordx2 v[80:81], v194, s[16:17] offset:0
	global_load_dwordx2 v[82:83], v194, s[16:17] offset:512
	global_load_dwordx2 v[84:85], v194, s[16:17] offset:1024
	global_load_dwordx2 v[86:87], v194, s[16:17] offset:1536
	global_load_dwordx2 v[88:89], v194, s[16:17] offset:2048
	global_load_dwordx2 v[90:91], v194, s[16:17] offset:2560
	global_load_dwordx2 v[92:93], v194, s[16:17] offset:3072
	global_load_dwordx2 v[94:95], v194, s[16:17] offset:3584
	global_load_dwordx2 v[112:113], v194, s[22:23] offset:0
	global_load_dwordx2 v[114:115], v194, s[22:23] offset:512
	global_load_dwordx2 v[116:117], v194, s[22:23] offset:1024
	global_load_dwordx2 v[118:119], v194, s[22:23] offset:1536
	global_load_dwordx2 v[120:121], v194, s[22:23] offset:2048
	global_load_dwordx2 v[122:123], v194, s[22:23] offset:2560
	global_load_dwordx2 v[124:125], v194, s[22:23] offset:3072
	global_load_dwordx2 v[126:127], v194, s[22:23] offset:3584
	s_add_u32 s14, s14, 0x2000
	s_addc_u32 s15, s15, 0
	s_add_u32 s16, s16, 0x1000
	s_addc_u32 s17, s17, 0
	s_add_u32 s22, s22, 0x1000
	s_addc_u32 s23, s23, 0
	s_waitcnt vmcnt(32)
	v_lshlrev_b32_e32 v200, 16, v64
	v_and_b32_e32 v201, 0xffff0000, v64
	v_lshlrev_b32_e32 v202, 16, v65
	v_and_b32_e32 v203, 0xffff0000, v65
	v_mul_f32_e32 v208, v200, v200
	v_mul_f32_e32 v209, v201, v201
	v_fmac_f32_e32 v208, v202, v202
	v_fmac_f32_e32 v209, v203, v203
	v_lshlrev_b32_e32 v204, 16, v96
	v_and_b32_e32 v205, 0xffff0000, v96
	v_lshlrev_b32_e32 v206, 16, v97
	v_and_b32_e32 v207, 0xffff0000, v97
	v_mul_f32_e32 v210, v204, v204
	v_mul_f32_e32 v211, v205, v205
	v_fmac_f32_e32 v210, v206, v206
	v_fmac_f32_e32 v211, v207, v207
	v_lshlrev_b32_e32 v200, 16, v66
	v_and_b32_e32 v201, 0xffff0000, v66
	v_lshlrev_b32_e32 v202, 16, v67
	v_and_b32_e32 v203, 0xffff0000, v67
	v_fmac_f32_e32 v208, v200, v200
	v_fmac_f32_e32 v209, v201, v201
	v_fmac_f32_e32 v208, v202, v202
	v_fmac_f32_e32 v209, v203, v203
	v_lshlrev_b32_e32 v204, 16, v98
	v_and_b32_e32 v205, 0xffff0000, v98
	v_lshlrev_b32_e32 v206, 16, v99
	v_and_b32_e32 v207, 0xffff0000, v99
	v_fmac_f32_e32 v210, v204, v204
	v_fmac_f32_e32 v211, v205, v205
	v_fmac_f32_e32 v210, v206, v206
	v_fmac_f32_e32 v211, v207, v207
	v_lshlrev_b32_e32 v200, 16, v68
	v_and_b32_e32 v201, 0xffff0000, v68
	v_lshlrev_b32_e32 v202, 16, v69
	v_and_b32_e32 v203, 0xffff0000, v69
	v_fmac_f32_e32 v208, v200, v200
	v_fmac_f32_e32 v209, v201, v201
	v_fmac_f32_e32 v208, v202, v202
	v_fmac_f32_e32 v209, v203, v203
	v_lshlrev_b32_e32 v204, 16, v100
	v_and_b32_e32 v205, 0xffff0000, v100
	v_lshlrev_b32_e32 v206, 16, v101
	v_and_b32_e32 v207, 0xffff0000, v101
	v_fmac_f32_e32 v210, v204, v204
	v_fmac_f32_e32 v211, v205, v205
	v_fmac_f32_e32 v210, v206, v206
	v_fmac_f32_e32 v211, v207, v207
	v_lshlrev_b32_e32 v200, 16, v70
	v_and_b32_e32 v201, 0xffff0000, v70
	v_lshlrev_b32_e32 v202, 16, v71
	v_and_b32_e32 v203, 0xffff0000, v71
	v_fmac_f32_e32 v208, v200, v200
	v_fmac_f32_e32 v209, v201, v201
	v_fmac_f32_e32 v208, v202, v202
	v_fmac_f32_e32 v209, v203, v203
	v_lshlrev_b32_e32 v204, 16, v102
	v_and_b32_e32 v205, 0xffff0000, v102
	v_lshlrev_b32_e32 v206, 16, v103
	v_and_b32_e32 v207, 0xffff0000, v103
	v_fmac_f32_e32 v210, v204, v204
	v_fmac_f32_e32 v211, v205, v205
	v_fmac_f32_e32 v210, v206, v206
	v_fmac_f32_e32 v211, v207, v207
	v_lshlrev_b32_e32 v200, 16, v72
	v_and_b32_e32 v201, 0xffff0000, v72
	v_lshlrev_b32_e32 v202, 16, v73
	v_and_b32_e32 v203, 0xffff0000, v73
	v_fmac_f32_e32 v208, v200, v200
	v_fmac_f32_e32 v209, v201, v201
	v_fmac_f32_e32 v208, v202, v202
	v_fmac_f32_e32 v209, v203, v203
	v_lshlrev_b32_e32 v204, 16, v104
	v_and_b32_e32 v205, 0xffff0000, v104
	v_lshlrev_b32_e32 v206, 16, v105
	v_and_b32_e32 v207, 0xffff0000, v105
	v_fmac_f32_e32 v210, v204, v204
	v_fmac_f32_e32 v211, v205, v205
	v_fmac_f32_e32 v210, v206, v206
	v_fmac_f32_e32 v211, v207, v207
	v_lshlrev_b32_e32 v200, 16, v74
; __device__ __forceinline__ float bf_lo(unsigned w) { return __uint_as_float(w << 16); }
; __device__ __forceinline__ float bf_hi(unsigned w) { return __uint_as_float(w & 0xffff0000u); }
; __global__ void __launch_bounds__(NWAVES * 64, 2) mk_fwd(Args args) {
;     ...
;                 float sy = 0.f;
; #pragma unroll
;                 for (int j = 0; j < 8; ++j) { const float a = bf_lo(yw[q][j].x), b = bf_hi(yw[q][j].x), c2 = bf_lo(yw[q][j].y), d = bf_hi(yw[q][j].y); sy += (a * a + b * b) + (c2 * c2 + d * d); }
;                 const float rsy = __builtin_amdgcn_rsqf(wave_sum(sy) * (1.f / DM) + EPS);
; #pragma unroll
;                 for (int j = 0; j < 8; ++j) { const int col = 4 * F.lane + 256 * j;
;                     const f32x4 y4 = (f32x4){bf_lo(yw[q][j].x), bf_hi(yw[q][j].x), bf_lo(yw[q][j].y), bf_hi(yw[q][j].y)};
;                     *(f32x4*)(args.out + (size_t)row * DM + col) = v[q][j] + PA[j] * (y4 * rsy); }
	v_and_b32_e32 v201, 0xffff0000, v74
	v_lshlrev_b32_e32 v202, 16, v75
	v_and_b32_e32 v203, 0xffff0000, v75
	v_fmac_f32_e32 v208, v200, v200
	v_fmac_f32_e32 v209, v201, v201
	v_fmac_f32_e32 v208, v202, v202
	v_fmac_f32_e32 v209, v203, v203
	v_lshlrev_b32_e32 v204, 16, v106
	v_and_b32_e32 v205, 0xffff0000, v106
	v_lshlrev_b32_e32 v206, 16, v107
	v_and_b32_e32 v207, 0xffff0000, v107
	v_fmac_f32_e32 v210, v204, v204
	v_fmac_f32_e32 v211, v205, v205
	v_fmac_f32_e32 v210, v206, v206
	v_fmac_f32_e32 v211, v207, v207
	v_lshlrev_b32_e32 v200, 16, v76
	v_and_b32_e32 v201, 0xffff0000, v76
	v_lshlrev_b32_e32 v202, 16, v77
	v_and_b32_e32 v203, 0xffff0000, v77
	v_fmac_f32_e32 v208, v200, v200
	v_fmac_f32_e32 v209, v201, v201
	v_fmac_f32_e32 v208, v202, v202
	v_fmac_f32_e32 v209, v203, v203
	v_lshlrev_b32_e32 v204, 16, v108
	v_and_b32_e32 v205, 0xffff0000, v108
	v_lshlrev_b32_e32 v206, 16, v109
	v_and_b32_e32 v207, 0xffff0000, v109
	v_fmac_f32_e32 v210, v204, v204
	v_fmac_f32_e32 v211, v205, v205
	v_fmac_f32_e32 v210, v206, v206
	v_fmac_f32_e32 v211, v207, v207
	v_lshlrev_b32_e32 v200, 16, v78
	v_and_b32_e32 v201, 0xffff0000, v78
	v_lshlrev_b32_e32 v202, 16, v79
	v_and_b32_e32 v203, 0xffff0000, v79
	v_fmac_f32_e32 v208, v200, v200
	v_fmac_f32_e32 v209, v201, v201
	v_fmac_f32_e32 v208, v202, v202
	v_fmac_f32_e32 v209, v203, v203
	v_lshlrev_b32_e32 v204, 16, v110
	v_and_b32_e32 v205, 0xffff0000, v110
	v_lshlrev_b32_e32 v206, 16, v111
	v_and_b32_e32 v207, 0xffff0000, v111
	v_fmac_f32_e32 v210, v204, v204
	v_fmac_f32_e32 v211, v205, v205
	v_fmac_f32_e32 v210, v206, v206
	v_fmac_f32_e32 v211, v207, v207
	v_add_f32_e32 v208, v208, v209
	v_add_f32_e32 v210, v210, v211
	s_nop 0
	v_add_f32_dpp v212, v208, v208 quad_perm:[1,0,3,2] row_mask:0xf bank_mask:0xf
	v_add_f32_dpp v213, v210, v210 quad_perm:[1,0,3,2] row_mask:0xf bank_mask:0xf
	s_nop 0
	v_add_f32_dpp v212, v212, v212 quad_perm:[2,3,0,1] row_mask:0xf bank_mask:0xf
	v_add_f32_dpp v213, v213, v213 quad_perm:[2,3,0,1] row_mask:0xf bank_mask:0xf
	s_nop 0
	v_add_f32_dpp v212, v212, v212 row_half_mirror row_mask:0xf bank_mask:0xf
	v_add_f32_dpp v213, v213, v213 row_half_mirror row_mask:0xf bank_mask:0xf
	s_nop 0
	v_add_f32_dpp v212, v212, v212 row_mirror row_mask:0xf bank_mask:0xf
	v_add_f32_dpp v213, v213, v213 row_mirror row_mask:0xf bank_mask:0xf
	s_nop 0
	v_readlane_b32 s4, v212, 0
	v_readlane_b32 s5, v212, 16
	v_readlane_b32 s6, v212, 32
	v_readlane_b32 s7, v212, 48
	v_readlane_b32 s24, v213, 0
	v_readlane_b32 s25, v213, 16
	v_readlane_b32 s26, v213, 32
	v_readlane_b32 s27, v213, 48
	s_nop 1
	v_mov_b32_e32 v214, s4
	v_mov_b32_e32 v215, s24
	v_add_f32_e32 v214, s5, v214
	v_add_f32_e32 v215, s25, v215
	v_add_f32_e32 v214, s6, v214
	v_add_f32_e32 v215, s26, v215
	v_add_f32_e32 v214, s7, v214
	v_add_f32_e32 v215, s27, v215
	v_fmamk_f32 v214, v214, 0x3a000000, v195
	v_fmamk_f32 v215, v215, 0x3a000000, v195
	v_rsq_f32_e32 v214, v214
	v_rsq_f32_e32 v215, v215
	s_nop 0
	v_lshlrev_b32_e32 v200, 16, v64
	v_and_b32_e32 v201, 0xffff0000, v64
	v_lshlrev_b32_e32 v202, 16, v65
	v_and_b32_e32 v203, 0xffff0000, v65
	v_lshlrev_b32_e32 v204, 16, v96
	v_and_b32_e32 v205, 0xffff0000, v96
	v_lshlrev_b32_e32 v206, 16, v97
	v_and_b32_e32 v207, 0xffff0000, v97
	v_mul_f32_e32 v200, v214, v200
	v_mul_f32_e32 v201, v214, v201
	v_mul_f32_e32 v202, v214, v202
	v_mul_f32_e32 v203, v214, v203
	v_mul_f32_e32 v204, v215, v204
	v_mul_f32_e32 v205, v215, v205
	v_mul_f32_e32 v206, v215, v206
	v_mul_f32_e32 v207, v215, v207
	v_fmac_f32_e32 v0, v128, v200
	v_fmac_f32_e32 v1, v129, v201
	v_fmac_f32_e32 v2, v130, v202
	v_fmac_f32_e32 v3, v131, v203
	v_fmac_f32_e32 v0, v160, v204
	v_fmac_f32_e32 v1, v161, v205
	v_fmac_f32_e32 v2, v162, v206
	v_fmac_f32_e32 v3, v163, v207
	global_store_dwordx4 v192, v[0:3], s[18:19] offset:0
	v_lshlrev_b32_e32 v200, 16, v66
	v_and_b32_e32 v201, 0xffff0000, v66
	v_lshlrev_b32_e32 v202, 16, v67
	v_and_b32_e32 v203, 0xffff0000, v67
	v_lshlrev_b32_e32 v204, 16, v98
	v_and_b32_e32 v205, 0xffff0000, v98
	v_lshlrev_b32_e32 v206, 16, v99
	v_and_b32_e32 v207, 0xffff0000, v99
	v_mul_f32_e32 v200, v214, v200
	v_mul_f32_e32 v201, v214, v201
	v_mul_f32_e32 v202, v214, v202
	v_mul_f32_e32 v203, v214, v203
	v_mul_f32_e32 v204, v215, v204
	v_mul_f32_e32 v205, v215, v205
	v_mul_f32_e32 v206, v215, v206
	v_mul_f32_e32 v207, v215, v207
	v_fmac_f32_e32 v4, v132, v200
	v_fmac_f32_e32 v5, v133, v201
	v_fmac_f32_e32 v6, v134, v202
	v_fmac_f32_e32 v7, v135, v203
	v_fmac_f32_e32 v4, v164, v204
	v_fmac_f32_e32 v5, v165, v205
	v_fmac_f32_e32 v6, v166, v206
	v_fmac_f32_e32 v7, v167, v207
	global_store_dwordx4 v192, v[4:7], s[18:19] offset:1024
	v_lshlrev_b32_e32 v200, 16, v68
	v_and_b32_e32 v201, 0xffff0000, v68
	v_lshlrev_b32_e32 v202, 16, v69
	v_and_b32_e32 v203, 0xffff0000, v69
	v_lshlrev_b32_e32 v204, 16, v100
	v_and_b32_e32 v205, 0xffff0000, v100
	v_lshlrev_b32_e32 v206, 16, v101
	v_and_b32_e32 v207, 0xffff0000, v101
	v_mul_f32_e32 v200, v214, v200
	v_mul_f32_e32 v201, v214, v201
	v_mul_f32_e32 v202, v214, v202
	v_mul_f32_e32 v203, v214, v203
	v_mul_f32_e32 v204, v215, v204
	v_mul_f32_e32 v205, v215, v205
	v_mul_f32_e32 v206, v215, v206
	v_mul_f32_e32 v207, v215, v207
	v_fmac_f32_e32 v8, v136, v200
	v_fmac_f32_e32 v9, v137, v201
	v_fmac_f32_e32 v10, v138, v202
	v_fmac_f32_e32 v11, v139, v203
	v_fmac_f32_e32 v8, v168, v204
	v_fmac_f32_e32 v9, v169, v205
	v_fmac_f32_e32 v10, v170, v206
	v_fmac_f32_e32 v11, v171, v207
	global_store_dwordx4 v192, v[8:11], s[18:19] offset:2048
	v_lshlrev_b32_e32 v200, 16, v70
	v_and_b32_e32 v201, 0xffff0000, v70
	v_lshlrev_b32_e32 v202, 16, v71
	v_and_b32_e32 v203, 0xffff0000, v71
	v_lshlrev_b32_e32 v204, 16, v102
; __device__ __forceinline__ float bf_lo(unsigned w) { return __uint_as_float(w << 16); }
; __device__ __forceinline__ float bf_hi(unsigned w) { return __uint_as_float(w & 0xffff0000u); }
; __global__ void __launch_bounds__(NWAVES * 64, 2) mk_fwd(Args args) {
;     ...
;         for (int row0 = rbeg; row0 < rbeg + per2 && row0 < ML; row0 += 2) {
;             f32x4 v[2][8]; u32x2 yw[2][8];
; #pragma unroll
;             for (int q = 0; q < 2; ++q) { const int row = row0 + q; load_row_f32(args.out + (size_t)row * DM, F.lane, v[q]);
;                 const bf16_t* yr = Y + (size_t)row * DM;
; #pragma unroll
;                 for (int j = 0; j < 8; ++j) yw[q][j] = *(const u32x2*)(yr + 4 * F.lane + 256 * j); }
;     ...
; #pragma unroll
;                 for (int j = 0; j < 8; ++j) { const int col = 4 * F.lane + 256 * j;
;                     const f32x4 y4 = (f32x4){bf_lo(yw[q][j].x), bf_hi(yw[q][j].x), bf_lo(yw[q][j].y), bf_hi(yw[q][j].y)};
;                     *(f32x4*)(args.out + (size_t)row * DM + col) = v[q][j] + PA[j] * (y4 * rsy); }
	v_and_b32_e32 v205, 0xffff0000, v102
	v_lshlrev_b32_e32 v206, 16, v103
	v_and_b32_e32 v207, 0xffff0000, v103
	v_mul_f32_e32 v200, v214, v200
	v_mul_f32_e32 v201, v214, v201
	v_mul_f32_e32 v202, v214, v202
	v_mul_f32_e32 v203, v214, v203
	v_mul_f32_e32 v204, v215, v204
	v_mul_f32_e32 v205, v215, v205
	v_mul_f32_e32 v206, v215, v206
	v_mul_f32_e32 v207, v215, v207
	v_fmac_f32_e32 v12, v140, v200
	v_fmac_f32_e32 v13, v141, v201
	v_fmac_f32_e32 v14, v142, v202
	v_fmac_f32_e32 v15, v143, v203
	v_fmac_f32_e32 v12, v172, v204
	v_fmac_f32_e32 v13, v173, v205
	v_fmac_f32_e32 v14, v174, v206
	v_fmac_f32_e32 v15, v175, v207
	global_store_dwordx4 v192, v[12:15], s[18:19] offset:3072
	v_lshlrev_b32_e32 v200, 16, v72
	v_and_b32_e32 v201, 0xffff0000, v72
	v_lshlrev_b32_e32 v202, 16, v73
	v_and_b32_e32 v203, 0xffff0000, v73
	v_lshlrev_b32_e32 v204, 16, v104
	v_and_b32_e32 v205, 0xffff0000, v104
	v_lshlrev_b32_e32 v206, 16, v105
	v_and_b32_e32 v207, 0xffff0000, v105
	v_mul_f32_e32 v200, v214, v200
	v_mul_f32_e32 v201, v214, v201
	v_mul_f32_e32 v202, v214, v202
	v_mul_f32_e32 v203, v214, v203
	v_mul_f32_e32 v204, v215, v204
	v_mul_f32_e32 v205, v215, v205
	v_mul_f32_e32 v206, v215, v206
	v_mul_f32_e32 v207, v215, v207
	v_fmac_f32_e32 v16, v144, v200
	v_fmac_f32_e32 v17, v145, v201
	v_fmac_f32_e32 v18, v146, v202
	v_fmac_f32_e32 v19, v147, v203
	v_fmac_f32_e32 v16, v176, v204
	v_fmac_f32_e32 v17, v177, v205
	v_fmac_f32_e32 v18, v178, v206
	v_fmac_f32_e32 v19, v179, v207
	global_store_dwordx4 v193, v[16:19], s[18:19] offset:0
	v_lshlrev_b32_e32 v200, 16, v74
	v_and_b32_e32 v201, 0xffff0000, v74
	v_lshlrev_b32_e32 v202, 16, v75
	v_and_b32_e32 v203, 0xffff0000, v75
	v_lshlrev_b32_e32 v204, 16, v106
	v_and_b32_e32 v205, 0xffff0000, v106
	v_lshlrev_b32_e32 v206, 16, v107
	v_and_b32_e32 v207, 0xffff0000, v107
	v_mul_f32_e32 v200, v214, v200
	v_mul_f32_e32 v201, v214, v201
	v_mul_f32_e32 v202, v214, v202
	v_mul_f32_e32 v203, v214, v203
	v_mul_f32_e32 v204, v215, v204
	v_mul_f32_e32 v205, v215, v205
	v_mul_f32_e32 v206, v215, v206
	v_mul_f32_e32 v207, v215, v207
	v_fmac_f32_e32 v20, v148, v200
	v_fmac_f32_e32 v21, v149, v201
	v_fmac_f32_e32 v22, v150, v202
	v_fmac_f32_e32 v23, v151, v203
	v_fmac_f32_e32 v20, v180, v204
	v_fmac_f32_e32 v21, v181, v205
	v_fmac_f32_e32 v22, v182, v206
	v_fmac_f32_e32 v23, v183, v207
	global_store_dwordx4 v193, v[20:23], s[18:19] offset:1024
	v_lshlrev_b32_e32 v200, 16, v76
	v_and_b32_e32 v201, 0xffff0000, v76
	v_lshlrev_b32_e32 v202, 16, v77
	v_and_b32_e32 v203, 0xffff0000, v77
	v_lshlrev_b32_e32 v204, 16, v108
	v_and_b32_e32 v205, 0xffff0000, v108
	v_lshlrev_b32_e32 v206, 16, v109
	v_and_b32_e32 v207, 0xffff0000, v109
	v_mul_f32_e32 v200, v214, v200
	v_mul_f32_e32 v201, v214, v201
	v_mul_f32_e32 v202, v214, v202
	v_mul_f32_e32 v203, v214, v203
	v_mul_f32_e32 v204, v215, v204
	v_mul_f32_e32 v205, v215, v205
	v_mul_f32_e32 v206, v215, v206
	v_mul_f32_e32 v207, v215, v207
	v_fmac_f32_e32 v24, v152, v200
	v_fmac_f32_e32 v25, v153, v201
	v_fmac_f32_e32 v26, v154, v202
	v_fmac_f32_e32 v27, v155, v203
	v_fmac_f32_e32 v24, v184, v204
	v_fmac_f32_e32 v25, v185, v205
	v_fmac_f32_e32 v26, v186, v206
	v_fmac_f32_e32 v27, v187, v207
	global_store_dwordx4 v193, v[24:27], s[18:19] offset:2048
	v_lshlrev_b32_e32 v200, 16, v78
	v_and_b32_e32 v201, 0xffff0000, v78
	v_lshlrev_b32_e32 v202, 16, v79
	v_and_b32_e32 v203, 0xffff0000, v79
	v_lshlrev_b32_e32 v204, 16, v110
	v_and_b32_e32 v205, 0xffff0000, v110
	v_lshlrev_b32_e32 v206, 16, v111
	v_and_b32_e32 v207, 0xffff0000, v111
	v_mul_f32_e32 v200, v214, v200
	v_mul_f32_e32 v201, v214, v201
	v_mul_f32_e32 v202, v214, v202
	v_mul_f32_e32 v203, v214, v203
	v_mul_f32_e32 v204, v215, v204
	v_mul_f32_e32 v205, v215, v205
	v_mul_f32_e32 v206, v215, v206
	v_mul_f32_e32 v207, v215, v207
	v_fmac_f32_e32 v28, v156, v200
	v_fmac_f32_e32 v29, v157, v201
	v_fmac_f32_e32 v30, v158, v202
	v_fmac_f32_e32 v31, v159, v203
	v_fmac_f32_e32 v28, v188, v204
	v_fmac_f32_e32 v29, v189, v205
	v_fmac_f32_e32 v30, v190, v206
	v_fmac_f32_e32 v31, v191, v207
	global_store_dwordx4 v193, v[28:31], s[18:19] offset:3072
	s_add_u32 s18, s18, 0x2000
	s_addc_u32 s19, s19, 0
	global_load_dwordx4 v[0:3], v192, s[14:15] offset:0
	global_load_dwordx4 v[4:7], v192, s[14:15] offset:1024
	global_load_dwordx4 v[8:11], v192, s[14:15] offset:2048
	global_load_dwordx4 v[12:15], v192, s[14:15] offset:3072
	global_load_dwordx4 v[16:19], v193, s[14:15] offset:0
	global_load_dwordx4 v[20:23], v193, s[14:15] offset:1024
	global_load_dwordx4 v[24:27], v193, s[14:15] offset:2048
	global_load_dwordx4 v[28:31], v193, s[14:15] offset:3072
	global_load_dwordx2 v[64:65], v194, s[16:17] offset:0
	global_load_dwordx2 v[66:67], v194, s[16:17] offset:512
	global_load_dwordx2 v[68:69], v194, s[16:17] offset:1024
	global_load_dwordx2 v[70:71], v194, s[16:17] offset:1536
	global_load_dwordx2 v[72:73], v194, s[16:17] offset:2048
	global_load_dwordx2 v[74:75], v194, s[16:17] offset:2560
	global_load_dwordx2 v[76:77], v194, s[16:17] offset:3072
	global_load_dwordx2 v[78:79], v194, s[16:17] offset:3584
	global_load_dwordx2 v[96:97], v194, s[22:23] offset:0
	global_load_dwordx2 v[98:99], v194, s[22:23] offset:512
	global_load_dwordx2 v[100:101], v194, s[22:23] offset:1024
	global_load_dwordx2 v[102:103], v194, s[22:23] offset:1536
	global_load_dwordx2 v[104:105], v194, s[22:23] offset:2048
	global_load_dwordx2 v[106:107], v194, s[22:23] offset:2560
	global_load_dwordx2 v[108:109], v194, s[22:23] offset:3072
	global_load_dwordx2 v[110:111], v194, s[22:23] offset:3584
	s_add_u32 s14, s14, 0x2000
	s_addc_u32 s15, s15, 0
	s_add_u32 s16, s16, 0x1000
	s_addc_u32 s17, s17, 0
	s_add_u32 s22, s22, 0x1000
	s_addc_u32 s23, s23, 0
	s_waitcnt vmcnt(32)
; __device__ __forceinline__ float bf_lo(unsigned w) { return __uint_as_float(w << 16); }
; __device__ __forceinline__ float bf_hi(unsigned w) { return __uint_as_float(w & 0xffff0000u); }
; __global__ void __launch_bounds__(NWAVES * 64, 2) mk_fwd(Args args) {
;     ...
;                 float sy = 0.f;
; #pragma unroll
;                 for (int j = 0; j < 8; ++j) { const float a = bf_lo(yw[q][j].x), b = bf_hi(yw[q][j].x), c2 = bf_lo(yw[q][j].y), d = bf_hi(yw[q][j].y); sy += (a * a + b * b) + (c2 * c2 + d * d); }
;                 const float rsy = __builtin_amdgcn_rsqf(wave_sum(sy) * (1.f / DM) + EPS);
	v_lshlrev_b32_e32 v200, 16, v80
	v_and_b32_e32 v201, 0xffff0000, v80
	v_lshlrev_b32_e32 v202, 16, v81
	v_and_b32_e32 v203, 0xffff0000, v81
	v_mul_f32_e32 v208, v200, v200
	v_mul_f32_e32 v209, v201, v201
	v_fmac_f32_e32 v208, v202, v202
	v_fmac_f32_e32 v209, v203, v203
	v_lshlrev_b32_e32 v204, 16, v112
	v_and_b32_e32 v205, 0xffff0000, v112
	v_lshlrev_b32_e32 v206, 16, v113
	v_and_b32_e32 v207, 0xffff0000, v113
	v_mul_f32_e32 v210, v204, v204
	v_mul_f32_e32 v211, v205, v205
	v_fmac_f32_e32 v210, v206, v206
	v_fmac_f32_e32 v211, v207, v207
	v_lshlrev_b32_e32 v200, 16, v82
	v_and_b32_e32 v201, 0xffff0000, v82
	v_lshlrev_b32_e32 v202, 16, v83
	v_and_b32_e32 v203, 0xffff0000, v83
	v_fmac_f32_e32 v208, v200, v200
	v_fmac_f32_e32 v209, v201, v201
	v_fmac_f32_e32 v208, v202, v202
	v_fmac_f32_e32 v209, v203, v203
	v_lshlrev_b32_e32 v204, 16, v114
	v_and_b32_e32 v205, 0xffff0000, v114
	v_lshlrev_b32_e32 v206, 16, v115
	v_and_b32_e32 v207, 0xffff0000, v115
	v_fmac_f32_e32 v210, v204, v204
	v_fmac_f32_e32 v211, v205, v205
	v_fmac_f32_e32 v210, v206, v206
	v_fmac_f32_e32 v211, v207, v207
	v_lshlrev_b32_e32 v200, 16, v84
	v_and_b32_e32 v201, 0xffff0000, v84
	v_lshlrev_b32_e32 v202, 16, v85
	v_and_b32_e32 v203, 0xffff0000, v85
	v_fmac_f32_e32 v208, v200, v200
	v_fmac_f32_e32 v209, v201, v201
	v_fmac_f32_e32 v208, v202, v202
	v_fmac_f32_e32 v209, v203, v203
	v_lshlrev_b32_e32 v204, 16, v116
	v_and_b32_e32 v205, 0xffff0000, v116
	v_lshlrev_b32_e32 v206, 16, v117
	v_and_b32_e32 v207, 0xffff0000, v117
	v_fmac_f32_e32 v210, v204, v204
	v_fmac_f32_e32 v211, v205, v205
	v_fmac_f32_e32 v210, v206, v206
	v_fmac_f32_e32 v211, v207, v207
	v_lshlrev_b32_e32 v200, 16, v86
	v_and_b32_e32 v201, 0xffff0000, v86
	v_lshlrev_b32_e32 v202, 16, v87
	v_and_b32_e32 v203, 0xffff0000, v87
	v_fmac_f32_e32 v208, v200, v200
	v_fmac_f32_e32 v209, v201, v201
	v_fmac_f32_e32 v208, v202, v202
	v_fmac_f32_e32 v209, v203, v203
	v_lshlrev_b32_e32 v204, 16, v118
	v_and_b32_e32 v205, 0xffff0000, v118
	v_lshlrev_b32_e32 v206, 16, v119
	v_and_b32_e32 v207, 0xffff0000, v119
	v_fmac_f32_e32 v210, v204, v204
	v_fmac_f32_e32 v211, v205, v205
	v_fmac_f32_e32 v210, v206, v206
	v_fmac_f32_e32 v211, v207, v207
	v_lshlrev_b32_e32 v200, 16, v88
	v_and_b32_e32 v201, 0xffff0000, v88
	v_lshlrev_b32_e32 v202, 16, v89
	v_and_b32_e32 v203, 0xffff0000, v89
	v_fmac_f32_e32 v208, v200, v200
	v_fmac_f32_e32 v209, v201, v201
	v_fmac_f32_e32 v208, v202, v202
	v_fmac_f32_e32 v209, v203, v203
	v_lshlrev_b32_e32 v204, 16, v120
	v_and_b32_e32 v205, 0xffff0000, v120
	v_lshlrev_b32_e32 v206, 16, v121
	v_and_b32_e32 v207, 0xffff0000, v121
	v_fmac_f32_e32 v210, v204, v204
	v_fmac_f32_e32 v211, v205, v205
	v_fmac_f32_e32 v210, v206, v206
	v_fmac_f32_e32 v211, v207, v207
	v_lshlrev_b32_e32 v200, 16, v90
	v_and_b32_e32 v201, 0xffff0000, v90
	v_lshlrev_b32_e32 v202, 16, v91
	v_and_b32_e32 v203, 0xffff0000, v91
	v_fmac_f32_e32 v208, v200, v200
	v_fmac_f32_e32 v209, v201, v201
	v_fmac_f32_e32 v208, v202, v202
	v_fmac_f32_e32 v209, v203, v203
	v_lshlrev_b32_e32 v204, 16, v122
	v_and_b32_e32 v205, 0xffff0000, v122
	v_lshlrev_b32_e32 v206, 16, v123
	v_and_b32_e32 v207, 0xffff0000, v123
	v_fmac_f32_e32 v210, v204, v204
	v_fmac_f32_e32 v211, v205, v205
	v_fmac_f32_e32 v210, v206, v206
	v_fmac_f32_e32 v211, v207, v207
	v_lshlrev_b32_e32 v200, 16, v92
	v_and_b32_e32 v201, 0xffff0000, v92
	v_lshlrev_b32_e32 v202, 16, v93
	v_and_b32_e32 v203, 0xffff0000, v93
	v_fmac_f32_e32 v208, v200, v200
	v_fmac_f32_e32 v209, v201, v201
	v_fmac_f32_e32 v208, v202, v202
	v_fmac_f32_e32 v209, v203, v203
	v_lshlrev_b32_e32 v204, 16, v124
	v_and_b32_e32 v205, 0xffff0000, v124
	v_lshlrev_b32_e32 v206, 16, v125
	v_and_b32_e32 v207, 0xffff0000, v125
	v_fmac_f32_e32 v210, v204, v204
	v_fmac_f32_e32 v211, v205, v205
	v_fmac_f32_e32 v210, v206, v206
	v_fmac_f32_e32 v211, v207, v207
	v_lshlrev_b32_e32 v200, 16, v94
	v_and_b32_e32 v201, 0xffff0000, v94
	v_lshlrev_b32_e32 v202, 16, v95
	v_and_b32_e32 v203, 0xffff0000, v95
	v_fmac_f32_e32 v208, v200, v200
	v_fmac_f32_e32 v209, v201, v201
	v_fmac_f32_e32 v208, v202, v202
	v_fmac_f32_e32 v209, v203, v203
	v_lshlrev_b32_e32 v204, 16, v126
	v_and_b32_e32 v205, 0xffff0000, v126
	v_lshlrev_b32_e32 v206, 16, v127
	v_and_b32_e32 v207, 0xffff0000, v127
	v_fmac_f32_e32 v210, v204, v204
	v_fmac_f32_e32 v211, v205, v205
	v_fmac_f32_e32 v210, v206, v206
	v_fmac_f32_e32 v211, v207, v207
	v_add_f32_e32 v208, v208, v209
	v_add_f32_e32 v210, v210, v211
	s_nop 0
	v_add_f32_dpp v212, v208, v208 quad_perm:[1,0,3,2] row_mask:0xf bank_mask:0xf
	v_add_f32_dpp v213, v210, v210 quad_perm:[1,0,3,2] row_mask:0xf bank_mask:0xf
	s_nop 0
	v_add_f32_dpp v212, v212, v212 quad_perm:[2,3,0,1] row_mask:0xf bank_mask:0xf
	v_add_f32_dpp v213, v213, v213 quad_perm:[2,3,0,1] row_mask:0xf bank_mask:0xf
	s_nop 0
	v_add_f32_dpp v212, v212, v212 row_half_mirror row_mask:0xf bank_mask:0xf
	v_add_f32_dpp v213, v213, v213 row_half_mirror row_mask:0xf bank_mask:0xf
	s_nop 0
	v_add_f32_dpp v212, v212, v212 row_mirror row_mask:0xf bank_mask:0xf
	v_add_f32_dpp v213, v213, v213 row_mirror row_mask:0xf bank_mask:0xf
	s_nop 0
	v_readlane_b32 s4, v212, 0
	v_readlane_b32 s5, v212, 16
	v_readlane_b32 s6, v212, 32
	v_readlane_b32 s7, v212, 48
	v_readlane_b32 s24, v213, 0
	v_readlane_b32 s25, v213, 16
	v_readlane_b32 s26, v213, 32
	v_readlane_b32 s27, v213, 48
	s_nop 1
	v_mov_b32_e32 v214, s4
	v_mov_b32_e32 v215, s24
	v_add_f32_e32 v214, s5, v214
	v_add_f32_e32 v215, s25, v215
	v_add_f32_e32 v214, s6, v214
	v_add_f32_e32 v215, s26, v215
	v_add_f32_e32 v214, s7, v214
	v_add_f32_e32 v215, s27, v215
	v_fmamk_f32 v214, v214, 0x3a000000, v195
	v_fmamk_f32 v215, v215, 0x3a000000, v195
; __device__ __forceinline__ float bf_lo(unsigned w) { return __uint_as_float(w << 16); }
; __device__ __forceinline__ float bf_hi(unsigned w) { return __uint_as_float(w & 0xffff0000u); }
; __global__ void __launch_bounds__(NWAVES * 64, 2) mk_fwd(Args args) {
;     ...
;             for (int q = 0; q < 2; ++q) { const int row = row0 + q; const int r = row / SEQ;
;                 if (r != rcur) { const float* m1 = mod + (size_t)(9 + r) * 6144; rcur = r;
; #pragma unroll
;                     for (int j = 0; j < 8; ++j) { const int col = 4 * F.lane + 256 * j; PA[j] = *(const f32x4*)(m1 + 2 * DM + col) * *(const f32x4*)(post_norm + DM + col); } }
;                 float sy = 0.f;
; #pragma unroll
;                 for (int j = 0; j < 8; ++j) { const float a = bf_lo(yw[q][j].x), b = bf_hi(yw[q][j].x), c2 = bf_lo(yw[q][j].y), d = bf_hi(yw[q][j].y); sy += (a * a + b * b) + (c2 * c2 + d * d); }
;                 const float rsy = __builtin_amdgcn_rsqf(wave_sum(sy) * (1.f / DM) + EPS);
; #pragma unroll
;                 for (int j = 0; j < 8; ++j) { const int col = 4 * F.lane + 256 * j;
;                     const f32x4 y4 = (f32x4){bf_lo(yw[q][j].x), bf_hi(yw[q][j].x), bf_lo(yw[q][j].y), bf_hi(yw[q][j].y)};
;                     *(f32x4*)(args.out + (size_t)row * DM + col) = v[q][j] + PA[j] * (y4 * rsy); }
	v_rsq_f32_e32 v214, v214
	v_rsq_f32_e32 v215, v215
	s_nop 0
	v_lshlrev_b32_e32 v200, 16, v80
	v_and_b32_e32 v201, 0xffff0000, v80
	v_lshlrev_b32_e32 v202, 16, v81
	v_and_b32_e32 v203, 0xffff0000, v81
	v_lshlrev_b32_e32 v204, 16, v112
	v_and_b32_e32 v205, 0xffff0000, v112
	v_lshlrev_b32_e32 v206, 16, v113
	v_and_b32_e32 v207, 0xffff0000, v113
	v_mul_f32_e32 v200, v214, v200
	v_mul_f32_e32 v201, v214, v201
	v_mul_f32_e32 v202, v214, v202
	v_mul_f32_e32 v203, v214, v203
	v_mul_f32_e32 v204, v215, v204
	v_mul_f32_e32 v205, v215, v205
	v_mul_f32_e32 v206, v215, v206
	v_mul_f32_e32 v207, v215, v207
	v_fmac_f32_e32 v32, v128, v200
	v_fmac_f32_e32 v33, v129, v201
	v_fmac_f32_e32 v34, v130, v202
	v_fmac_f32_e32 v35, v131, v203
	v_fmac_f32_e32 v32, v160, v204
	v_fmac_f32_e32 v33, v161, v205
	v_fmac_f32_e32 v34, v162, v206
	v_fmac_f32_e32 v35, v163, v207
	global_store_dwordx4 v192, v[32:35], s[18:19] offset:0
	v_lshlrev_b32_e32 v200, 16, v82
	v_and_b32_e32 v201, 0xffff0000, v82
	v_lshlrev_b32_e32 v202, 16, v83
	v_and_b32_e32 v203, 0xffff0000, v83
	v_lshlrev_b32_e32 v204, 16, v114
	v_and_b32_e32 v205, 0xffff0000, v114
	v_lshlrev_b32_e32 v206, 16, v115
	v_and_b32_e32 v207, 0xffff0000, v115
	v_mul_f32_e32 v200, v214, v200
	v_mul_f32_e32 v201, v214, v201
	v_mul_f32_e32 v202, v214, v202
	v_mul_f32_e32 v203, v214, v203
	v_mul_f32_e32 v204, v215, v204
	v_mul_f32_e32 v205, v215, v205
	v_mul_f32_e32 v206, v215, v206
	v_mul_f32_e32 v207, v215, v207
	v_fmac_f32_e32 v36, v132, v200
	v_fmac_f32_e32 v37, v133, v201
	v_fmac_f32_e32 v38, v134, v202
	v_fmac_f32_e32 v39, v135, v203
	v_fmac_f32_e32 v36, v164, v204
	v_fmac_f32_e32 v37, v165, v205
	v_fmac_f32_e32 v38, v166, v206
	v_fmac_f32_e32 v39, v167, v207
	global_store_dwordx4 v192, v[36:39], s[18:19] offset:1024
	v_lshlrev_b32_e32 v200, 16, v84
	v_and_b32_e32 v201, 0xffff0000, v84
	v_lshlrev_b32_e32 v202, 16, v85
	v_and_b32_e32 v203, 0xffff0000, v85
	v_lshlrev_b32_e32 v204, 16, v116
	v_and_b32_e32 v205, 0xffff0000, v116
	v_lshlrev_b32_e32 v206, 16, v117
	v_and_b32_e32 v207, 0xffff0000, v117
	v_mul_f32_e32 v200, v214, v200
	v_mul_f32_e32 v201, v214, v201
	v_mul_f32_e32 v202, v214, v202
	v_mul_f32_e32 v203, v214, v203
	v_mul_f32_e32 v204, v215, v204
	v_mul_f32_e32 v205, v215, v205
	v_mul_f32_e32 v206, v215, v206
	v_mul_f32_e32 v207, v215, v207
	v_fmac_f32_e32 v40, v136, v200
	v_fmac_f32_e32 v41, v137, v201
	v_fmac_f32_e32 v42, v138, v202
	v_fmac_f32_e32 v43, v139, v203
	v_fmac_f32_e32 v40, v168, v204
	v_fmac_f32_e32 v41, v169, v205
	v_fmac_f32_e32 v42, v170, v206
	v_fmac_f32_e32 v43, v171, v207
	global_store_dwordx4 v192, v[40:43], s[18:19] offset:2048
	v_lshlrev_b32_e32 v200, 16, v86
	v_and_b32_e32 v201, 0xffff0000, v86
	v_lshlrev_b32_e32 v202, 16, v87
	v_and_b32_e32 v203, 0xffff0000, v87
	v_lshlrev_b32_e32 v204, 16, v118
	v_and_b32_e32 v205, 0xffff0000, v118
	v_lshlrev_b32_e32 v206, 16, v119
	v_and_b32_e32 v207, 0xffff0000, v119
	v_mul_f32_e32 v200, v214, v200
	v_mul_f32_e32 v201, v214, v201
	v_mul_f32_e32 v202, v214, v202
	v_mul_f32_e32 v203, v214, v203
	v_mul_f32_e32 v204, v215, v204
	v_mul_f32_e32 v205, v215, v205
	v_mul_f32_e32 v206, v215, v206
	v_mul_f32_e32 v207, v215, v207
	v_fmac_f32_e32 v44, v140, v200
	v_fmac_f32_e32 v45, v141, v201
	v_fmac_f32_e32 v46, v142, v202
	v_fmac_f32_e32 v47, v143, v203
	v_fmac_f32_e32 v44, v172, v204
	v_fmac_f32_e32 v45, v173, v205
	v_fmac_f32_e32 v46, v174, v206
	v_fmac_f32_e32 v47, v175, v207
	global_store_dwordx4 v192, v[44:47], s[18:19] offset:3072
	v_lshlrev_b32_e32 v200, 16, v88
	v_and_b32_e32 v201, 0xffff0000, v88
	v_lshlrev_b32_e32 v202, 16, v89
	v_and_b32_e32 v203, 0xffff0000, v89
	v_lshlrev_b32_e32 v204, 16, v120
	v_and_b32_e32 v205, 0xffff0000, v120
	v_lshlrev_b32_e32 v206, 16, v121
	v_and_b32_e32 v207, 0xffff0000, v121
	v_mul_f32_e32 v200, v214, v200
	v_mul_f32_e32 v201, v214, v201
	v_mul_f32_e32 v202, v214, v202
	v_mul_f32_e32 v203, v214, v203
	v_mul_f32_e32 v204, v215, v204
	v_mul_f32_e32 v205, v215, v205
	v_mul_f32_e32 v206, v215, v206
	v_mul_f32_e32 v207, v215, v207
	v_fmac_f32_e32 v48, v144, v200
	v_fmac_f32_e32 v49, v145, v201
	v_fmac_f32_e32 v50, v146, v202
	v_fmac_f32_e32 v51, v147, v203
	v_fmac_f32_e32 v48, v176, v204
	v_fmac_f32_e32 v49, v177, v205
	v_fmac_f32_e32 v50, v178, v206
	v_fmac_f32_e32 v51, v179, v207
	global_store_dwordx4 v193, v[48:51], s[18:19] offset:0
	v_lshlrev_b32_e32 v200, 16, v90
	v_and_b32_e32 v201, 0xffff0000, v90
	v_lshlrev_b32_e32 v202, 16, v91
	v_and_b32_e32 v203, 0xffff0000, v91
	v_lshlrev_b32_e32 v204, 16, v122
	v_and_b32_e32 v205, 0xffff0000, v122
	v_lshlrev_b32_e32 v206, 16, v123
	v_and_b32_e32 v207, 0xffff0000, v123
	v_mul_f32_e32 v200, v214, v200
	v_mul_f32_e32 v201, v214, v201
	v_mul_f32_e32 v202, v214, v202
	v_mul_f32_e32 v203, v214, v203
	v_mul_f32_e32 v204, v215, v204
	v_mul_f32_e32 v205, v215, v205
	v_mul_f32_e32 v206, v215, v206
	v_mul_f32_e32 v207, v215, v207
	v_fmac_f32_e32 v52, v148, v200
	v_fmac_f32_e32 v53, v149, v201
	v_fmac_f32_e32 v54, v150, v202
	v_fmac_f32_e32 v55, v151, v203
	v_fmac_f32_e32 v52, v180, v204
	v_fmac_f32_e32 v53, v181, v205
	v_fmac_f32_e32 v54, v182, v206
	v_fmac_f32_e32 v55, v183, v207
	global_store_dwordx4 v193, v[52:55], s[18:19] offset:1024
	v_lshlrev_b32_e32 v200, 16, v92
	v_and_b32_e32 v201, 0xffff0000, v92
	v_lshlrev_b32_e32 v202, 16, v93
	v_and_b32_e32 v203, 0xffff0000, v93
	v_lshlrev_b32_e32 v204, 16, v124
	v_and_b32_e32 v205, 0xffff0000, v124
	v_lshlrev_b32_e32 v206, 16, v125
	v_and_b32_e32 v207, 0xffff0000, v125
	v_mul_f32_e32 v200, v214, v200
	v_mul_f32_e32 v201, v214, v201
	v_mul_f32_e32 v202, v214, v202
	v_mul_f32_e32 v203, v214, v203
	v_mul_f32_e32 v204, v215, v204
; __device__ __forceinline__ float bf_lo(unsigned w) { return __uint_as_float(w << 16); }
; __device__ __forceinline__ float bf_hi(unsigned w) { return __uint_as_float(w & 0xffff0000u); }
; __global__ void __launch_bounds__(NWAVES * 64, 2) mk_fwd(Args args) {
;     ...
;         for (int row0 = rbeg; row0 < rbeg + per2 && row0 < ML; row0 += 2) {
;             f32x4 v[2][8]; u32x2 yw[2][8];
; #pragma unroll
;             for (int q = 0; q < 2; ++q) { const int row = row0 + q; load_row_f32(args.out + (size_t)row * DM, F.lane, v[q]);
;                 const bf16_t* yr = Y + (size_t)row * DM;
; #pragma unroll
;                 for (int j = 0; j < 8; ++j) yw[q][j] = *(const u32x2*)(yr + 4 * F.lane + 256 * j); }
; #pragma unroll
;             for (int q = 0; q < 2; ++q) { const int row = row0 + q; const int r = row / SEQ;
;                 if (r != rcur) { const float* m1 = mod + (size_t)(9 + r) * 6144; rcur = r;
; #pragma unroll
;                     for (int j = 0; j < 8; ++j) { const int col = 4 * F.lane + 256 * j; PA[j] = *(const f32x4*)(m1 + 2 * DM + col) * *(const f32x4*)(post_norm + DM + col); } }
;                 float sy = 0.f;
; #pragma unroll
;                 for (int j = 0; j < 8; ++j) { const float a = bf_lo(yw[q][j].x), b = bf_hi(yw[q][j].x), c2 = bf_lo(yw[q][j].y), d = bf_hi(yw[q][j].y); sy += (a * a + b * b) + (c2 * c2 + d * d); }
;                 const float rsy = __builtin_amdgcn_rsqf(wave_sum(sy) * (1.f / DM) + EPS);
; #pragma unroll
;                 for (int j = 0; j < 8; ++j) { const int col = 4 * F.lane + 256 * j;
;                     const f32x4 y4 = (f32x4){bf_lo(yw[q][j].x), bf_hi(yw[q][j].x), bf_lo(yw[q][j].y), bf_hi(yw[q][j].y)};
;                     *(f32x4*)(args.out + (size_t)row * DM + col) = v[q][j] + PA[j] * (y4 * rsy); }
	v_mul_f32_e32 v205, v215, v205
	v_mul_f32_e32 v206, v215, v206
	v_mul_f32_e32 v207, v215, v207
	v_fmac_f32_e32 v56, v152, v200
	v_fmac_f32_e32 v57, v153, v201
	v_fmac_f32_e32 v58, v154, v202
	v_fmac_f32_e32 v59, v155, v203
	v_fmac_f32_e32 v56, v184, v204
	v_fmac_f32_e32 v57, v185, v205
	v_fmac_f32_e32 v58, v186, v206
	v_fmac_f32_e32 v59, v187, v207
	global_store_dwordx4 v193, v[56:59], s[18:19] offset:2048
	v_lshlrev_b32_e32 v200, 16, v94
	v_and_b32_e32 v201, 0xffff0000, v94
	v_lshlrev_b32_e32 v202, 16, v95
	v_and_b32_e32 v203, 0xffff0000, v95
	v_lshlrev_b32_e32 v204, 16, v126
	v_and_b32_e32 v205, 0xffff0000, v126
	v_lshlrev_b32_e32 v206, 16, v127
	v_and_b32_e32 v207, 0xffff0000, v127
	v_mul_f32_e32 v200, v214, v200
	v_mul_f32_e32 v201, v214, v201
	v_mul_f32_e32 v202, v214, v202
	v_mul_f32_e32 v203, v214, v203
	v_mul_f32_e32 v204, v215, v204
	v_mul_f32_e32 v205, v215, v205
	v_mul_f32_e32 v206, v215, v206
	v_mul_f32_e32 v207, v215, v207
	v_fmac_f32_e32 v60, v156, v200
	v_fmac_f32_e32 v61, v157, v201
	v_fmac_f32_e32 v62, v158, v202
	v_fmac_f32_e32 v63, v159, v203
	v_fmac_f32_e32 v60, v188, v204
	v_fmac_f32_e32 v61, v189, v205
	v_fmac_f32_e32 v62, v190, v206
	v_fmac_f32_e32 v63, v191, v207
	global_store_dwordx4 v193, v[60:63], s[18:19] offset:3072
	s_add_u32 s18, s18, 0x2000
	s_addc_u32 s19, s19, 0
	global_load_dwordx4 v[32:35], v192, s[14:15] offset:0
	global_load_dwordx4 v[36:39], v192, s[14:15] offset:1024
	global_load_dwordx4 v[40:43], v192, s[14:15] offset:2048
	global_load_dwordx4 v[44:47], v192, s[14:15] offset:3072
	global_load_dwordx4 v[48:51], v193, s[14:15] offset:0
	global_load_dwordx4 v[52:55], v193, s[14:15] offset:1024
	global_load_dwordx4 v[56:59], v193, s[14:15] offset:2048
	global_load_dwordx4 v[60:63], v193, s[14:15] offset:3072
	global_load_dwordx2 v[80:81], v194, s[16:17] offset:0
	global_load_dwordx2 v[82:83], v194, s[16:17] offset:512
	global_load_dwordx2 v[84:85], v194, s[16:17] offset:1024
	global_load_dwordx2 v[86:87], v194, s[16:17] offset:1536
	global_load_dwordx2 v[88:89], v194, s[16:17] offset:2048
	global_load_dwordx2 v[90:91], v194, s[16:17] offset:2560
	global_load_dwordx2 v[92:93], v194, s[16:17] offset:3072
	global_load_dwordx2 v[94:95], v194, s[16:17] offset:3584
	global_load_dwordx2 v[112:113], v194, s[22:23] offset:0
	global_load_dwordx2 v[114:115], v194, s[22:23] offset:512
	global_load_dwordx2 v[116:117], v194, s[22:23] offset:1024
	global_load_dwordx2 v[118:119], v194, s[22:23] offset:1536
	global_load_dwordx2 v[120:121], v194, s[22:23] offset:2048
	global_load_dwordx2 v[122:123], v194, s[22:23] offset:2560
	global_load_dwordx2 v[124:125], v194, s[22:23] offset:3072
	global_load_dwordx2 v[126:127], v194, s[22:23] offset:3584
	s_add_u32 s14, s14, 0x2000
	s_addc_u32 s15, s15, 0
	s_add_u32 s16, s16, 0x1000
	s_addc_u32 s17, s17, 0
	s_add_u32 s22, s22, 0x1000
	s_addc_u32 s23, s23, 0
	s_waitcnt vmcnt(32)
	v_lshlrev_b32_e32 v200, 16, v64
	v_and_b32_e32 v201, 0xffff0000, v64
	v_lshlrev_b32_e32 v202, 16, v65
	v_and_b32_e32 v203, 0xffff0000, v65
	v_mul_f32_e32 v208, v200, v200
	v_mul_f32_e32 v209, v201, v201
	v_fmac_f32_e32 v208, v202, v202
	v_fmac_f32_e32 v209, v203, v203
	v_lshlrev_b32_e32 v204, 16, v96
	v_and_b32_e32 v205, 0xffff0000, v96
	v_lshlrev_b32_e32 v206, 16, v97
	v_and_b32_e32 v207, 0xffff0000, v97
	v_mul_f32_e32 v210, v204, v204
	v_mul_f32_e32 v211, v205, v205
	v_fmac_f32_e32 v210, v206, v206
	v_fmac_f32_e32 v211, v207, v207
	v_lshlrev_b32_e32 v200, 16, v66
	v_and_b32_e32 v201, 0xffff0000, v66
	v_lshlrev_b32_e32 v202, 16, v67
	v_and_b32_e32 v203, 0xffff0000, v67
	v_fmac_f32_e32 v208, v200, v200
	v_fmac_f32_e32 v209, v201, v201
	v_fmac_f32_e32 v208, v202, v202
	v_fmac_f32_e32 v209, v203, v203
	v_lshlrev_b32_e32 v204, 16, v98
	v_and_b32_e32 v205, 0xffff0000, v98
	v_lshlrev_b32_e32 v206, 16, v99
	v_and_b32_e32 v207, 0xffff0000, v99
	v_fmac_f32_e32 v210, v204, v204
	v_fmac_f32_e32 v211, v205, v205
	v_fmac_f32_e32 v210, v206, v206
	v_fmac_f32_e32 v211, v207, v207
	v_lshlrev_b32_e32 v200, 16, v68
	v_and_b32_e32 v201, 0xffff0000, v68
	v_lshlrev_b32_e32 v202, 16, v69
	v_and_b32_e32 v203, 0xffff0000, v69
	v_fmac_f32_e32 v208, v200, v200
	v_fmac_f32_e32 v209, v201, v201
	v_fmac_f32_e32 v208, v202, v202
	v_fmac_f32_e32 v209, v203, v203
	v_lshlrev_b32_e32 v204, 16, v100
	v_and_b32_e32 v205, 0xffff0000, v100
	v_lshlrev_b32_e32 v206, 16, v101
	v_and_b32_e32 v207, 0xffff0000, v101
	v_fmac_f32_e32 v210, v204, v204
	v_fmac_f32_e32 v211, v205, v205
	v_fmac_f32_e32 v210, v206, v206
	v_fmac_f32_e32 v211, v207, v207
	v_lshlrev_b32_e32 v200, 16, v70
	v_and_b32_e32 v201, 0xffff0000, v70
	v_lshlrev_b32_e32 v202, 16, v71
	v_and_b32_e32 v203, 0xffff0000, v71
	v_fmac_f32_e32 v208, v200, v200
	v_fmac_f32_e32 v209, v201, v201
	v_fmac_f32_e32 v208, v202, v202
	v_fmac_f32_e32 v209, v203, v203
	v_lshlrev_b32_e32 v204, 16, v102
	v_and_b32_e32 v205, 0xffff0000, v102
	v_lshlrev_b32_e32 v206, 16, v103
	v_and_b32_e32 v207, 0xffff0000, v103
	v_fmac_f32_e32 v210, v204, v204
	v_fmac_f32_e32 v211, v205, v205
	v_fmac_f32_e32 v210, v206, v206
	v_fmac_f32_e32 v211, v207, v207
	v_lshlrev_b32_e32 v200, 16, v72
	v_and_b32_e32 v201, 0xffff0000, v72
	v_lshlrev_b32_e32 v202, 16, v73
	v_and_b32_e32 v203, 0xffff0000, v73
	v_fmac_f32_e32 v208, v200, v200
	v_fmac_f32_e32 v209, v201, v201
	v_fmac_f32_e32 v208, v202, v202
	v_fmac_f32_e32 v209, v203, v203
	v_lshlrev_b32_e32 v204, 16, v104
	v_and_b32_e32 v205, 0xffff0000, v104
	v_lshlrev_b32_e32 v206, 16, v105
	v_and_b32_e32 v207, 0xffff0000, v105
	v_fmac_f32_e32 v210, v204, v204
	v_fmac_f32_e32 v211, v205, v205
	v_fmac_f32_e32 v210, v206, v206
	v_fmac_f32_e32 v211, v207, v207
	v_lshlrev_b32_e32 v200, 16, v74
; __device__ __forceinline__ float bf_lo(unsigned w) { return __uint_as_float(w << 16); }
; __device__ __forceinline__ float bf_hi(unsigned w) { return __uint_as_float(w & 0xffff0000u); }
; __global__ void __launch_bounds__(NWAVES * 64, 2) mk_fwd(Args args) {
;     ...
; #pragma unroll
;                 for (int j = 0; j < 8; ++j) { const float a = bf_lo(yw[q][j].x), b = bf_hi(yw[q][j].x), c2 = bf_lo(yw[q][j].y), d = bf_hi(yw[q][j].y); sy += (a * a + b * b) + (c2 * c2 + d * d); }
;                 const float rsy = __builtin_amdgcn_rsqf(wave_sum(sy) * (1.f / DM) + EPS);
;     ...
;                 for (int j = 0; j < 8; ++j) { const int col = 4 * F.lane + 256 * j;
;                     const f32x4 y4 = (f32x4){bf_lo(yw[q][j].x), bf_hi(yw[q][j].x), bf_lo(yw[q][j].y), bf_hi(yw[q][j].y)};
;                     *(f32x4*)(args.out + (size_t)row * DM + col) = v[q][j] + PA[j] * (y4 * rsy); }
	v_and_b32_e32 v201, 0xffff0000, v74
	v_lshlrev_b32_e32 v202, 16, v75
	v_and_b32_e32 v203, 0xffff0000, v75
	v_fmac_f32_e32 v208, v200, v200
	v_fmac_f32_e32 v209, v201, v201
	v_fmac_f32_e32 v208, v202, v202
	v_fmac_f32_e32 v209, v203, v203
	v_lshlrev_b32_e32 v204, 16, v106
	v_and_b32_e32 v205, 0xffff0000, v106
	v_lshlrev_b32_e32 v206, 16, v107
	v_and_b32_e32 v207, 0xffff0000, v107
	v_fmac_f32_e32 v210, v204, v204
	v_fmac_f32_e32 v211, v205, v205
	v_fmac_f32_e32 v210, v206, v206
	v_fmac_f32_e32 v211, v207, v207
	v_lshlrev_b32_e32 v200, 16, v76
	v_and_b32_e32 v201, 0xffff0000, v76
	v_lshlrev_b32_e32 v202, 16, v77
	v_and_b32_e32 v203, 0xffff0000, v77
	v_fmac_f32_e32 v208, v200, v200
	v_fmac_f32_e32 v209, v201, v201
	v_fmac_f32_e32 v208, v202, v202
	v_fmac_f32_e32 v209, v203, v203
	v_lshlrev_b32_e32 v204, 16, v108
	v_and_b32_e32 v205, 0xffff0000, v108
	v_lshlrev_b32_e32 v206, 16, v109
	v_and_b32_e32 v207, 0xffff0000, v109
	v_fmac_f32_e32 v210, v204, v204
	v_fmac_f32_e32 v211, v205, v205
	v_fmac_f32_e32 v210, v206, v206
	v_fmac_f32_e32 v211, v207, v207
	v_lshlrev_b32_e32 v200, 16, v78
	v_and_b32_e32 v201, 0xffff0000, v78
	v_lshlrev_b32_e32 v202, 16, v79
	v_and_b32_e32 v203, 0xffff0000, v79
	v_fmac_f32_e32 v208, v200, v200
	v_fmac_f32_e32 v209, v201, v201
	v_fmac_f32_e32 v208, v202, v202
	v_fmac_f32_e32 v209, v203, v203
	v_lshlrev_b32_e32 v204, 16, v110
	v_and_b32_e32 v205, 0xffff0000, v110
	v_lshlrev_b32_e32 v206, 16, v111
	v_and_b32_e32 v207, 0xffff0000, v111
	v_fmac_f32_e32 v210, v204, v204
	v_fmac_f32_e32 v211, v205, v205
	v_fmac_f32_e32 v210, v206, v206
	v_fmac_f32_e32 v211, v207, v207
	v_add_f32_e32 v208, v208, v209
	v_add_f32_e32 v210, v210, v211
	s_nop 0
	v_add_f32_dpp v212, v208, v208 quad_perm:[1,0,3,2] row_mask:0xf bank_mask:0xf
	v_add_f32_dpp v213, v210, v210 quad_perm:[1,0,3,2] row_mask:0xf bank_mask:0xf
	s_nop 0
	v_add_f32_dpp v212, v212, v212 quad_perm:[2,3,0,1] row_mask:0xf bank_mask:0xf
	v_add_f32_dpp v213, v213, v213 quad_perm:[2,3,0,1] row_mask:0xf bank_mask:0xf
	s_nop 0
	v_add_f32_dpp v212, v212, v212 row_half_mirror row_mask:0xf bank_mask:0xf
	v_add_f32_dpp v213, v213, v213 row_half_mirror row_mask:0xf bank_mask:0xf
	s_nop 0
	v_add_f32_dpp v212, v212, v212 row_mirror row_mask:0xf bank_mask:0xf
	v_add_f32_dpp v213, v213, v213 row_mirror row_mask:0xf bank_mask:0xf
	s_nop 0
	v_readlane_b32 s4, v212, 0
	v_readlane_b32 s5, v212, 16
	v_readlane_b32 s6, v212, 32
	v_readlane_b32 s7, v212, 48
	v_readlane_b32 s24, v213, 0
	v_readlane_b32 s25, v213, 16
	v_readlane_b32 s26, v213, 32
	v_readlane_b32 s27, v213, 48
	s_nop 1
	v_mov_b32_e32 v214, s4
	v_mov_b32_e32 v215, s24
	v_add_f32_e32 v214, s5, v214
	v_add_f32_e32 v215, s25, v215
	v_add_f32_e32 v214, s6, v214
	v_add_f32_e32 v215, s26, v215
	v_add_f32_e32 v214, s7, v214
	v_add_f32_e32 v215, s27, v215
	v_fmamk_f32 v214, v214, 0x3a000000, v195
	v_fmamk_f32 v215, v215, 0x3a000000, v195
	v_rsq_f32_e32 v214, v214
	v_rsq_f32_e32 v215, v215
	s_nop 0
	v_lshlrev_b32_e32 v200, 16, v64
	v_and_b32_e32 v201, 0xffff0000, v64
	v_lshlrev_b32_e32 v202, 16, v65
	v_and_b32_e32 v203, 0xffff0000, v65
	v_lshlrev_b32_e32 v204, 16, v96
	v_and_b32_e32 v205, 0xffff0000, v96
	v_lshlrev_b32_e32 v206, 16, v97
	v_and_b32_e32 v207, 0xffff0000, v97
	v_mul_f32_e32 v200, v214, v200
	v_mul_f32_e32 v201, v214, v201
	v_mul_f32_e32 v202, v214, v202
	v_mul_f32_e32 v203, v214, v203
	v_mul_f32_e32 v204, v215, v204
	v_mul_f32_e32 v205, v215, v205
	v_mul_f32_e32 v206, v215, v206
	v_mul_f32_e32 v207, v215, v207
	v_fmac_f32_e32 v0, v128, v200
	v_fmac_f32_e32 v1, v129, v201
	v_fmac_f32_e32 v2, v130, v202
	v_fmac_f32_e32 v3, v131, v203
	v_fmac_f32_e32 v0, v160, v204
	v_fmac_f32_e32 v1, v161, v205
	v_fmac_f32_e32 v2, v162, v206
	v_fmac_f32_e32 v3, v163, v207
	global_store_dwordx4 v192, v[0:3], s[18:19] offset:0
	v_lshlrev_b32_e32 v200, 16, v66
	v_and_b32_e32 v201, 0xffff0000, v66
	v_lshlrev_b32_e32 v202, 16, v67
	v_and_b32_e32 v203, 0xffff0000, v67
	v_lshlrev_b32_e32 v204, 16, v98
	v_and_b32_e32 v205, 0xffff0000, v98
	v_lshlrev_b32_e32 v206, 16, v99
	v_and_b32_e32 v207, 0xffff0000, v99
	v_mul_f32_e32 v200, v214, v200
	v_mul_f32_e32 v201, v214, v201
	v_mul_f32_e32 v202, v214, v202
	v_mul_f32_e32 v203, v214, v203
	v_mul_f32_e32 v204, v215, v204
	v_mul_f32_e32 v205, v215, v205
	v_mul_f32_e32 v206, v215, v206
	v_mul_f32_e32 v207, v215, v207
	v_fmac_f32_e32 v4, v132, v200
	v_fmac_f32_e32 v5, v133, v201
	v_fmac_f32_e32 v6, v134, v202
	v_fmac_f32_e32 v7, v135, v203
	v_fmac_f32_e32 v4, v164, v204
	v_fmac_f32_e32 v5, v165, v205
	v_fmac_f32_e32 v6, v166, v206
	v_fmac_f32_e32 v7, v167, v207
	global_store_dwordx4 v192, v[4:7], s[18:19] offset:1024
	v_lshlrev_b32_e32 v200, 16, v68
	v_and_b32_e32 v201, 0xffff0000, v68
	v_lshlrev_b32_e32 v202, 16, v69
	v_and_b32_e32 v203, 0xffff0000, v69
	v_lshlrev_b32_e32 v204, 16, v100
	v_and_b32_e32 v205, 0xffff0000, v100
	v_lshlrev_b32_e32 v206, 16, v101
	v_and_b32_e32 v207, 0xffff0000, v101
	v_mul_f32_e32 v200, v214, v200
	v_mul_f32_e32 v201, v214, v201
	v_mul_f32_e32 v202, v214, v202
	v_mul_f32_e32 v203, v214, v203
	v_mul_f32_e32 v204, v215, v204
	v_mul_f32_e32 v205, v215, v205
	v_mul_f32_e32 v206, v215, v206
	v_mul_f32_e32 v207, v215, v207
	v_fmac_f32_e32 v8, v136, v200
	v_fmac_f32_e32 v9, v137, v201
	v_fmac_f32_e32 v10, v138, v202
	v_fmac_f32_e32 v11, v139, v203
	v_fmac_f32_e32 v8, v168, v204
	v_fmac_f32_e32 v9, v169, v205
	v_fmac_f32_e32 v10, v170, v206
	v_fmac_f32_e32 v11, v171, v207
	global_store_dwordx4 v192, v[8:11], s[18:19] offset:2048
	v_lshlrev_b32_e32 v200, 16, v70
	v_and_b32_e32 v201, 0xffff0000, v70
	v_lshlrev_b32_e32 v202, 16, v71
	v_and_b32_e32 v203, 0xffff0000, v71
	v_lshlrev_b32_e32 v204, 16, v102
; __device__ __forceinline__ float bf_lo(unsigned w) { return __uint_as_float(w << 16); }
; __device__ __forceinline__ float bf_hi(unsigned w) { return __uint_as_float(w & 0xffff0000u); }
; __global__ void __launch_bounds__(NWAVES * 64, 2) mk_fwd(Args args) {
;     ...
;             for (int q = 0; q < 2; ++q) { const int row = row0 + q; load_row_f32(args.out + (size_t)row * DM, F.lane, v[q]);
;                 const bf16_t* yr = Y + (size_t)row * DM;
; #pragma unroll
;                 for (int j = 0; j < 8; ++j) yw[q][j] = *(const u32x2*)(yr + 4 * F.lane + 256 * j); }
;     ...
;                 const float rsy = __builtin_amdgcn_rsqf(wave_sum(sy) * (1.f / DM) + EPS);
; #pragma unroll
;                 for (int j = 0; j < 8; ++j) { const int col = 4 * F.lane + 256 * j;
;                     const f32x4 y4 = (f32x4){bf_lo(yw[q][j].x), bf_hi(yw[q][j].x), bf_lo(yw[q][j].y), bf_hi(yw[q][j].y)};
;                     *(f32x4*)(args.out + (size_t)row * DM + col) = v[q][j] + PA[j] * (y4 * rsy); }
	v_and_b32_e32 v205, 0xffff0000, v102
	v_lshlrev_b32_e32 v206, 16, v103
	v_and_b32_e32 v207, 0xffff0000, v103
	v_mul_f32_e32 v200, v214, v200
	v_mul_f32_e32 v201, v214, v201
	v_mul_f32_e32 v202, v214, v202
	v_mul_f32_e32 v203, v214, v203
	v_mul_f32_e32 v204, v215, v204
	v_mul_f32_e32 v205, v215, v205
	v_mul_f32_e32 v206, v215, v206
	v_mul_f32_e32 v207, v215, v207
	v_fmac_f32_e32 v12, v140, v200
	v_fmac_f32_e32 v13, v141, v201
	v_fmac_f32_e32 v14, v142, v202
	v_fmac_f32_e32 v15, v143, v203
	v_fmac_f32_e32 v12, v172, v204
	v_fmac_f32_e32 v13, v173, v205
	v_fmac_f32_e32 v14, v174, v206
	v_fmac_f32_e32 v15, v175, v207
	global_store_dwordx4 v192, v[12:15], s[18:19] offset:3072
	v_lshlrev_b32_e32 v200, 16, v72
	v_and_b32_e32 v201, 0xffff0000, v72
	v_lshlrev_b32_e32 v202, 16, v73
	v_and_b32_e32 v203, 0xffff0000, v73
	v_lshlrev_b32_e32 v204, 16, v104
	v_and_b32_e32 v205, 0xffff0000, v104
	v_lshlrev_b32_e32 v206, 16, v105
	v_and_b32_e32 v207, 0xffff0000, v105
	v_mul_f32_e32 v200, v214, v200
	v_mul_f32_e32 v201, v214, v201
	v_mul_f32_e32 v202, v214, v202
	v_mul_f32_e32 v203, v214, v203
	v_mul_f32_e32 v204, v215, v204
	v_mul_f32_e32 v205, v215, v205
	v_mul_f32_e32 v206, v215, v206
	v_mul_f32_e32 v207, v215, v207
	v_fmac_f32_e32 v16, v144, v200
	v_fmac_f32_e32 v17, v145, v201
	v_fmac_f32_e32 v18, v146, v202
	v_fmac_f32_e32 v19, v147, v203
	v_fmac_f32_e32 v16, v176, v204
	v_fmac_f32_e32 v17, v177, v205
	v_fmac_f32_e32 v18, v178, v206
	v_fmac_f32_e32 v19, v179, v207
	global_store_dwordx4 v193, v[16:19], s[18:19] offset:0
	v_lshlrev_b32_e32 v200, 16, v74
	v_and_b32_e32 v201, 0xffff0000, v74
	v_lshlrev_b32_e32 v202, 16, v75
	v_and_b32_e32 v203, 0xffff0000, v75
	v_lshlrev_b32_e32 v204, 16, v106
	v_and_b32_e32 v205, 0xffff0000, v106
	v_lshlrev_b32_e32 v206, 16, v107
	v_and_b32_e32 v207, 0xffff0000, v107
	v_mul_f32_e32 v200, v214, v200
	v_mul_f32_e32 v201, v214, v201
	v_mul_f32_e32 v202, v214, v202
	v_mul_f32_e32 v203, v214, v203
	v_mul_f32_e32 v204, v215, v204
	v_mul_f32_e32 v205, v215, v205
	v_mul_f32_e32 v206, v215, v206
	v_mul_f32_e32 v207, v215, v207
	v_fmac_f32_e32 v20, v148, v200
	v_fmac_f32_e32 v21, v149, v201
	v_fmac_f32_e32 v22, v150, v202
	v_fmac_f32_e32 v23, v151, v203
	v_fmac_f32_e32 v20, v180, v204
	v_fmac_f32_e32 v21, v181, v205
	v_fmac_f32_e32 v22, v182, v206
	v_fmac_f32_e32 v23, v183, v207
	global_store_dwordx4 v193, v[20:23], s[18:19] offset:1024
	v_lshlrev_b32_e32 v200, 16, v76
	v_and_b32_e32 v201, 0xffff0000, v76
	v_lshlrev_b32_e32 v202, 16, v77
	v_and_b32_e32 v203, 0xffff0000, v77
	v_lshlrev_b32_e32 v204, 16, v108
	v_and_b32_e32 v205, 0xffff0000, v108
	v_lshlrev_b32_e32 v206, 16, v109
	v_and_b32_e32 v207, 0xffff0000, v109
	v_mul_f32_e32 v200, v214, v200
	v_mul_f32_e32 v201, v214, v201
	v_mul_f32_e32 v202, v214, v202
	v_mul_f32_e32 v203, v214, v203
	v_mul_f32_e32 v204, v215, v204
	v_mul_f32_e32 v205, v215, v205
	v_mul_f32_e32 v206, v215, v206
	v_mul_f32_e32 v207, v215, v207
	v_fmac_f32_e32 v24, v152, v200
	v_fmac_f32_e32 v25, v153, v201
	v_fmac_f32_e32 v26, v154, v202
	v_fmac_f32_e32 v27, v155, v203
	v_fmac_f32_e32 v24, v184, v204
	v_fmac_f32_e32 v25, v185, v205
	v_fmac_f32_e32 v26, v186, v206
	v_fmac_f32_e32 v27, v187, v207
	global_store_dwordx4 v193, v[24:27], s[18:19] offset:2048
	v_lshlrev_b32_e32 v200, 16, v78
	v_and_b32_e32 v201, 0xffff0000, v78
	v_lshlrev_b32_e32 v202, 16, v79
	v_and_b32_e32 v203, 0xffff0000, v79
	v_lshlrev_b32_e32 v204, 16, v110
	v_and_b32_e32 v205, 0xffff0000, v110
	v_lshlrev_b32_e32 v206, 16, v111
	v_and_b32_e32 v207, 0xffff0000, v111
	v_mul_f32_e32 v200, v214, v200
	v_mul_f32_e32 v201, v214, v201
	v_mul_f32_e32 v202, v214, v202
	v_mul_f32_e32 v203, v214, v203
	v_mul_f32_e32 v204, v215, v204
	v_mul_f32_e32 v205, v215, v205
	v_mul_f32_e32 v206, v215, v206
	v_mul_f32_e32 v207, v215, v207
	v_fmac_f32_e32 v28, v156, v200
	v_fmac_f32_e32 v29, v157, v201
	v_fmac_f32_e32 v30, v158, v202
	v_fmac_f32_e32 v31, v159, v203
	v_fmac_f32_e32 v28, v188, v204
	v_fmac_f32_e32 v29, v189, v205
	v_fmac_f32_e32 v30, v190, v206
	v_fmac_f32_e32 v31, v191, v207
	global_store_dwordx4 v193, v[28:31], s[18:19] offset:3072
	s_add_u32 s18, s18, 0x2000
	s_addc_u32 s19, s19, 0
	global_load_dwordx4 v[0:3], v192, s[14:15] offset:0
	global_load_dwordx4 v[4:7], v192, s[14:15] offset:1024
	global_load_dwordx4 v[8:11], v192, s[14:15] offset:2048
	global_load_dwordx4 v[12:15], v192, s[14:15] offset:3072
	global_load_dwordx4 v[16:19], v193, s[14:15] offset:0
	global_load_dwordx4 v[20:23], v193, s[14:15] offset:1024
	global_load_dwordx4 v[24:27], v193, s[14:15] offset:2048
	global_load_dwordx4 v[28:31], v193, s[14:15] offset:3072
	global_load_dwordx2 v[64:65], v194, s[16:17] offset:0
	global_load_dwordx2 v[66:67], v194, s[16:17] offset:512
	global_load_dwordx2 v[68:69], v194, s[16:17] offset:1024
	global_load_dwordx2 v[70:71], v194, s[16:17] offset:1536
	global_load_dwordx2 v[72:73], v194, s[16:17] offset:2048
	global_load_dwordx2 v[74:75], v194, s[16:17] offset:2560
	global_load_dwordx2 v[76:77], v194, s[16:17] offset:3072
	global_load_dwordx2 v[78:79], v194, s[16:17] offset:3584
	global_load_dwordx2 v[96:97], v194, s[22:23] offset:0
	global_load_dwordx2 v[98:99], v194, s[22:23] offset:512
	global_load_dwordx2 v[100:101], v194, s[22:23] offset:1024
	global_load_dwordx2 v[102:103], v194, s[22:23] offset:1536
	global_load_dwordx2 v[104:105], v194, s[22:23] offset:2048
	global_load_dwordx2 v[106:107], v194, s[22:23] offset:2560
	global_load_dwordx2 v[108:109], v194, s[22:23] offset:3072
	global_load_dwordx2 v[110:111], v194, s[22:23] offset:3584
	s_add_u32 s14, s14, 0x2000
	s_addc_u32 s15, s15, 0
	s_add_u32 s16, s16, 0x1000
	s_addc_u32 s17, s17, 0
	s_add_u32 s22, s22, 0x1000
	s_addc_u32 s23, s23, 0
	s_waitcnt vmcnt(32)
; __device__ __forceinline__ float bf_lo(unsigned w) { return __uint_as_float(w << 16); }
; __device__ __forceinline__ float bf_hi(unsigned w) { return __uint_as_float(w & 0xffff0000u); }
; __global__ void __launch_bounds__(NWAVES * 64, 2) mk_fwd(Args args) {
;     ...
;                 float sy = 0.f;
; #pragma unroll
;                 for (int j = 0; j < 8; ++j) { const float a = bf_lo(yw[q][j].x), b = bf_hi(yw[q][j].x), c2 = bf_lo(yw[q][j].y), d = bf_hi(yw[q][j].y); sy += (a * a + b * b) + (c2 * c2 + d * d); }
;                 const float rsy = __builtin_amdgcn_rsqf(wave_sum(sy) * (1.f / DM) + EPS);
	v_lshlrev_b32_e32 v200, 16, v80
	v_and_b32_e32 v201, 0xffff0000, v80
	v_lshlrev_b32_e32 v202, 16, v81
	v_and_b32_e32 v203, 0xffff0000, v81
	v_mul_f32_e32 v208, v200, v200
	v_mul_f32_e32 v209, v201, v201
	v_fmac_f32_e32 v208, v202, v202
	v_fmac_f32_e32 v209, v203, v203
	v_lshlrev_b32_e32 v204, 16, v112
	v_and_b32_e32 v205, 0xffff0000, v112
	v_lshlrev_b32_e32 v206, 16, v113
	v_and_b32_e32 v207, 0xffff0000, v113
	v_mul_f32_e32 v210, v204, v204
	v_mul_f32_e32 v211, v205, v205
	v_fmac_f32_e32 v210, v206, v206
	v_fmac_f32_e32 v211, v207, v207
	v_lshlrev_b32_e32 v200, 16, v82
	v_and_b32_e32 v201, 0xffff0000, v82
	v_lshlrev_b32_e32 v202, 16, v83
	v_and_b32_e32 v203, 0xffff0000, v83
	v_fmac_f32_e32 v208, v200, v200
	v_fmac_f32_e32 v209, v201, v201
	v_fmac_f32_e32 v208, v202, v202
	v_fmac_f32_e32 v209, v203, v203
	v_lshlrev_b32_e32 v204, 16, v114
	v_and_b32_e32 v205, 0xffff0000, v114
	v_lshlrev_b32_e32 v206, 16, v115
	v_and_b32_e32 v207, 0xffff0000, v115
	v_fmac_f32_e32 v210, v204, v204
	v_fmac_f32_e32 v211, v205, v205
	v_fmac_f32_e32 v210, v206, v206
	v_fmac_f32_e32 v211, v207, v207
	v_lshlrev_b32_e32 v200, 16, v84
	v_and_b32_e32 v201, 0xffff0000, v84
	v_lshlrev_b32_e32 v202, 16, v85
	v_and_b32_e32 v203, 0xffff0000, v85
	v_fmac_f32_e32 v208, v200, v200
	v_fmac_f32_e32 v209, v201, v201
	v_fmac_f32_e32 v208, v202, v202
	v_fmac_f32_e32 v209, v203, v203
	v_lshlrev_b32_e32 v204, 16, v116
	v_and_b32_e32 v205, 0xffff0000, v116
	v_lshlrev_b32_e32 v206, 16, v117
	v_and_b32_e32 v207, 0xffff0000, v117
	v_fmac_f32_e32 v210, v204, v204
	v_fmac_f32_e32 v211, v205, v205
	v_fmac_f32_e32 v210, v206, v206
	v_fmac_f32_e32 v211, v207, v207
	v_lshlrev_b32_e32 v200, 16, v86
	v_and_b32_e32 v201, 0xffff0000, v86
	v_lshlrev_b32_e32 v202, 16, v87
	v_and_b32_e32 v203, 0xffff0000, v87
	v_fmac_f32_e32 v208, v200, v200
	v_fmac_f32_e32 v209, v201, v201
	v_fmac_f32_e32 v208, v202, v202
	v_fmac_f32_e32 v209, v203, v203
	v_lshlrev_b32_e32 v204, 16, v118
	v_and_b32_e32 v205, 0xffff0000, v118
	v_lshlrev_b32_e32 v206, 16, v119
	v_and_b32_e32 v207, 0xffff0000, v119
	v_fmac_f32_e32 v210, v204, v204
	v_fmac_f32_e32 v211, v205, v205
	v_fmac_f32_e32 v210, v206, v206
	v_fmac_f32_e32 v211, v207, v207
	v_lshlrev_b32_e32 v200, 16, v88
	v_and_b32_e32 v201, 0xffff0000, v88
	v_lshlrev_b32_e32 v202, 16, v89
	v_and_b32_e32 v203, 0xffff0000, v89
	v_fmac_f32_e32 v208, v200, v200
	v_fmac_f32_e32 v209, v201, v201
	v_fmac_f32_e32 v208, v202, v202
	v_fmac_f32_e32 v209, v203, v203
	v_lshlrev_b32_e32 v204, 16, v120
	v_and_b32_e32 v205, 0xffff0000, v120
	v_lshlrev_b32_e32 v206, 16, v121
	v_and_b32_e32 v207, 0xffff0000, v121
	v_fmac_f32_e32 v210, v204, v204
	v_fmac_f32_e32 v211, v205, v205
	v_fmac_f32_e32 v210, v206, v206
	v_fmac_f32_e32 v211, v207, v207
	v_lshlrev_b32_e32 v200, 16, v90
	v_and_b32_e32 v201, 0xffff0000, v90
	v_lshlrev_b32_e32 v202, 16, v91
	v_and_b32_e32 v203, 0xffff0000, v91
	v_fmac_f32_e32 v208, v200, v200
	v_fmac_f32_e32 v209, v201, v201
	v_fmac_f32_e32 v208, v202, v202
	v_fmac_f32_e32 v209, v203, v203
	v_lshlrev_b32_e32 v204, 16, v122
	v_and_b32_e32 v205, 0xffff0000, v122
	v_lshlrev_b32_e32 v206, 16, v123
	v_and_b32_e32 v207, 0xffff0000, v123
	v_fmac_f32_e32 v210, v204, v204
	v_fmac_f32_e32 v211, v205, v205
	v_fmac_f32_e32 v210, v206, v206
	v_fmac_f32_e32 v211, v207, v207
	v_lshlrev_b32_e32 v200, 16, v92
	v_and_b32_e32 v201, 0xffff0000, v92
	v_lshlrev_b32_e32 v202, 16, v93
	v_and_b32_e32 v203, 0xffff0000, v93
	v_fmac_f32_e32 v208, v200, v200
	v_fmac_f32_e32 v209, v201, v201
	v_fmac_f32_e32 v208, v202, v202
	v_fmac_f32_e32 v209, v203, v203
	v_lshlrev_b32_e32 v204, 16, v124
	v_and_b32_e32 v205, 0xffff0000, v124
	v_lshlrev_b32_e32 v206, 16, v125
	v_and_b32_e32 v207, 0xffff0000, v125
	v_fmac_f32_e32 v210, v204, v204
	v_fmac_f32_e32 v211, v205, v205
	v_fmac_f32_e32 v210, v206, v206
	v_fmac_f32_e32 v211, v207, v207
	v_lshlrev_b32_e32 v200, 16, v94
	v_and_b32_e32 v201, 0xffff0000, v94
	v_lshlrev_b32_e32 v202, 16, v95
	v_and_b32_e32 v203, 0xffff0000, v95
	v_fmac_f32_e32 v208, v200, v200
	v_fmac_f32_e32 v209, v201, v201
	v_fmac_f32_e32 v208, v202, v202
	v_fmac_f32_e32 v209, v203, v203
	v_lshlrev_b32_e32 v204, 16, v126
	v_and_b32_e32 v205, 0xffff0000, v126
	v_lshlrev_b32_e32 v206, 16, v127
	v_and_b32_e32 v207, 0xffff0000, v127
	v_fmac_f32_e32 v210, v204, v204
	v_fmac_f32_e32 v211, v205, v205
	v_fmac_f32_e32 v210, v206, v206
	v_fmac_f32_e32 v211, v207, v207
	v_add_f32_e32 v208, v208, v209
	v_add_f32_e32 v210, v210, v211
	s_nop 0
	v_add_f32_dpp v212, v208, v208 quad_perm:[1,0,3,2] row_mask:0xf bank_mask:0xf
	v_add_f32_dpp v213, v210, v210 quad_perm:[1,0,3,2] row_mask:0xf bank_mask:0xf
	s_nop 0
	v_add_f32_dpp v212, v212, v212 quad_perm:[2,3,0,1] row_mask:0xf bank_mask:0xf
	v_add_f32_dpp v213, v213, v213 quad_perm:[2,3,0,1] row_mask:0xf bank_mask:0xf
	s_nop 0
	v_add_f32_dpp v212, v212, v212 row_half_mirror row_mask:0xf bank_mask:0xf
	v_add_f32_dpp v213, v213, v213 row_half_mirror row_mask:0xf bank_mask:0xf
	s_nop 0
	v_add_f32_dpp v212, v212, v212 row_mirror row_mask:0xf bank_mask:0xf
	v_add_f32_dpp v213, v213, v213 row_mirror row_mask:0xf bank_mask:0xf
	s_nop 0
	v_readlane_b32 s4, v212, 0
	v_readlane_b32 s5, v212, 16
	v_readlane_b32 s6, v212, 32
	v_readlane_b32 s7, v212, 48
	v_readlane_b32 s24, v213, 0
	v_readlane_b32 s25, v213, 16
	v_readlane_b32 s26, v213, 32
	v_readlane_b32 s27, v213, 48
	s_nop 1
	v_mov_b32_e32 v214, s4
	v_mov_b32_e32 v215, s24
	v_add_f32_e32 v214, s5, v214
	v_add_f32_e32 v215, s25, v215
	v_add_f32_e32 v214, s6, v214
	v_add_f32_e32 v215, s26, v215
	v_add_f32_e32 v214, s7, v214
	v_add_f32_e32 v215, s27, v215
	v_fmamk_f32 v214, v214, 0x3a000000, v195
	v_fmamk_f32 v215, v215, 0x3a000000, v195
; __device__ __forceinline__ float bf_lo(unsigned w) { return __uint_as_float(w << 16); }
; __device__ __forceinline__ float bf_hi(unsigned w) { return __uint_as_float(w & 0xffff0000u); }
; __global__ void __launch_bounds__(NWAVES * 64, 2) mk_fwd(Args args) {
;     ...
; #pragma unroll
;                 for (int j = 0; j < 8; ++j) { const int col = 4 * F.lane + 256 * j;
;                     const f32x4 y4 = (f32x4){bf_lo(yw[q][j].x), bf_hi(yw[q][j].x), bf_lo(yw[q][j].y), bf_hi(yw[q][j].y)};
;                     *(f32x4*)(args.out + (size_t)row * DM + col) = v[q][j] + PA[j] * (y4 * rsy); }
	v_rsq_f32_e32 v214, v214
	v_rsq_f32_e32 v215, v215
	s_nop 0
	v_lshlrev_b32_e32 v200, 16, v80
	v_and_b32_e32 v201, 0xffff0000, v80
	v_lshlrev_b32_e32 v202, 16, v81
	v_and_b32_e32 v203, 0xffff0000, v81
	v_lshlrev_b32_e32 v204, 16, v112
	v_and_b32_e32 v205, 0xffff0000, v112
	v_lshlrev_b32_e32 v206, 16, v113
	v_and_b32_e32 v207, 0xffff0000, v113
	v_mul_f32_e32 v200, v214, v200
	v_mul_f32_e32 v201, v214, v201
	v_mul_f32_e32 v202, v214, v202
	v_mul_f32_e32 v203, v214, v203
	v_mul_f32_e32 v204, v215, v204
	v_mul_f32_e32 v205, v215, v205
	v_mul_f32_e32 v206, v215, v206
	v_mul_f32_e32 v207, v215, v207
	v_fmac_f32_e32 v32, v128, v200
	v_fmac_f32_e32 v33, v129, v201
	v_fmac_f32_e32 v34, v130, v202
	v_fmac_f32_e32 v35, v131, v203
	v_fmac_f32_e32 v32, v160, v204
	v_fmac_f32_e32 v33, v161, v205
	v_fmac_f32_e32 v34, v162, v206
	v_fmac_f32_e32 v35, v163, v207
	global_store_dwordx4 v192, v[32:35], s[18:19] offset:0
	v_lshlrev_b32_e32 v200, 16, v82
	v_and_b32_e32 v201, 0xffff0000, v82
	v_lshlrev_b32_e32 v202, 16, v83
	v_and_b32_e32 v203, 0xffff0000, v83
	v_lshlrev_b32_e32 v204, 16, v114
	v_and_b32_e32 v205, 0xffff0000, v114
	v_lshlrev_b32_e32 v206, 16, v115
	v_and_b32_e32 v207, 0xffff0000, v115
	v_mul_f32_e32 v200, v214, v200
	v_mul_f32_e32 v201, v214, v201
	v_mul_f32_e32 v202, v214, v202
	v_mul_f32_e32 v203, v214, v203
	v_mul_f32_e32 v204, v215, v204
	v_mul_f32_e32 v205, v215, v205
	v_mul_f32_e32 v206, v215, v206
	v_mul_f32_e32 v207, v215, v207
	v_fmac_f32_e32 v36, v132, v200
	v_fmac_f32_e32 v37, v133, v201
	v_fmac_f32_e32 v38, v134, v202
	v_fmac_f32_e32 v39, v135, v203
	v_fmac_f32_e32 v36, v164, v204
	v_fmac_f32_e32 v37, v165, v205
	v_fmac_f32_e32 v38, v166, v206
	v_fmac_f32_e32 v39, v167, v207
	global_store_dwordx4 v192, v[36:39], s[18:19] offset:1024
	v_lshlrev_b32_e32 v200, 16, v84
	v_and_b32_e32 v201, 0xffff0000, v84
	v_lshlrev_b32_e32 v202, 16, v85
	v_and_b32_e32 v203, 0xffff0000, v85
	v_lshlrev_b32_e32 v204, 16, v116
	v_and_b32_e32 v205, 0xffff0000, v116
	v_lshlrev_b32_e32 v206, 16, v117
	v_and_b32_e32 v207, 0xffff0000, v117
	v_mul_f32_e32 v200, v214, v200
	v_mul_f32_e32 v201, v214, v201
	v_mul_f32_e32 v202, v214, v202
	v_mul_f32_e32 v203, v214, v203
	v_mul_f32_e32 v204, v215, v204
	v_mul_f32_e32 v205, v215, v205
	v_mul_f32_e32 v206, v215, v206
	v_mul_f32_e32 v207, v215, v207
	v_fmac_f32_e32 v40, v136, v200
	v_fmac_f32_e32 v41, v137, v201
	v_fmac_f32_e32 v42, v138, v202
	v_fmac_f32_e32 v43, v139, v203
	v_fmac_f32_e32 v40, v168, v204
	v_fmac_f32_e32 v41, v169, v205
	v_fmac_f32_e32 v42, v170, v206
	v_fmac_f32_e32 v43, v171, v207
	global_store_dwordx4 v192, v[40:43], s[18:19] offset:2048
	v_lshlrev_b32_e32 v200, 16, v86
	v_and_b32_e32 v201, 0xffff0000, v86
	v_lshlrev_b32_e32 v202, 16, v87
	v_and_b32_e32 v203, 0xffff0000, v87
	v_lshlrev_b32_e32 v204, 16, v118
	v_and_b32_e32 v205, 0xffff0000, v118
	v_lshlrev_b32_e32 v206, 16, v119
	v_and_b32_e32 v207, 0xffff0000, v119
	v_mul_f32_e32 v200, v214, v200
	v_mul_f32_e32 v201, v214, v201
	v_mul_f32_e32 v202, v214, v202
	v_mul_f32_e32 v203, v214, v203
	v_mul_f32_e32 v204, v215, v204
	v_mul_f32_e32 v205, v215, v205
	v_mul_f32_e32 v206, v215, v206
	v_mul_f32_e32 v207, v215, v207
	v_fmac_f32_e32 v44, v140, v200
	v_fmac_f32_e32 v45, v141, v201
	v_fmac_f32_e32 v46, v142, v202
	v_fmac_f32_e32 v47, v143, v203
	v_fmac_f32_e32 v44, v172, v204
	v_fmac_f32_e32 v45, v173, v205
	v_fmac_f32_e32 v46, v174, v206
	v_fmac_f32_e32 v47, v175, v207
	global_store_dwordx4 v192, v[44:47], s[18:19] offset:3072
	v_lshlrev_b32_e32 v200, 16, v88
	v_and_b32_e32 v201, 0xffff0000, v88
	v_lshlrev_b32_e32 v202, 16, v89
	v_and_b32_e32 v203, 0xffff0000, v89
	v_lshlrev_b32_e32 v204, 16, v120
	v_and_b32_e32 v205, 0xffff0000, v120
	v_lshlrev_b32_e32 v206, 16, v121
	v_and_b32_e32 v207, 0xffff0000, v121
	v_mul_f32_e32 v200, v214, v200
	v_mul_f32_e32 v201, v214, v201
	v_mul_f32_e32 v202, v214, v202
	v_mul_f32_e32 v203, v214, v203
	v_mul_f32_e32 v204, v215, v204
	v_mul_f32_e32 v205, v215, v205
	v_mul_f32_e32 v206, v215, v206
	v_mul_f32_e32 v207, v215, v207
	v_fmac_f32_e32 v48, v144, v200
	v_fmac_f32_e32 v49, v145, v201
	v_fmac_f32_e32 v50, v146, v202
	v_fmac_f32_e32 v51, v147, v203
	v_fmac_f32_e32 v48, v176, v204
	v_fmac_f32_e32 v49, v177, v205
	v_fmac_f32_e32 v50, v178, v206
	v_fmac_f32_e32 v51, v179, v207
	global_store_dwordx4 v193, v[48:51], s[18:19] offset:0
	v_lshlrev_b32_e32 v200, 16, v90
	v_and_b32_e32 v201, 0xffff0000, v90
	v_lshlrev_b32_e32 v202, 16, v91
	v_and_b32_e32 v203, 0xffff0000, v91
	v_lshlrev_b32_e32 v204, 16, v122
	v_and_b32_e32 v205, 0xffff0000, v122
	v_lshlrev_b32_e32 v206, 16, v123
	v_and_b32_e32 v207, 0xffff0000, v123
	v_mul_f32_e32 v200, v214, v200
	v_mul_f32_e32 v201, v214, v201
	v_mul_f32_e32 v202, v214, v202
	v_mul_f32_e32 v203, v214, v203
	v_mul_f32_e32 v204, v215, v204
	v_mul_f32_e32 v205, v215, v205
	v_mul_f32_e32 v206, v215, v206
	v_mul_f32_e32 v207, v215, v207
	v_fmac_f32_e32 v52, v148, v200
	v_fmac_f32_e32 v53, v149, v201
	v_fmac_f32_e32 v54, v150, v202
	v_fmac_f32_e32 v55, v151, v203
	v_fmac_f32_e32 v52, v180, v204
	v_fmac_f32_e32 v53, v181, v205
	v_fmac_f32_e32 v54, v182, v206
	v_fmac_f32_e32 v55, v183, v207
	global_store_dwordx4 v193, v[52:55], s[18:19] offset:1024
	v_lshlrev_b32_e32 v200, 16, v92
	v_and_b32_e32 v201, 0xffff0000, v92
	v_lshlrev_b32_e32 v202, 16, v93
	v_and_b32_e32 v203, 0xffff0000, v93
	v_lshlrev_b32_e32 v204, 16, v124
	v_and_b32_e32 v205, 0xffff0000, v124
	v_lshlrev_b32_e32 v206, 16, v125
	v_and_b32_e32 v207, 0xffff0000, v125
	v_mul_f32_e32 v200, v214, v200
	v_mul_f32_e32 v201, v214, v201
	v_mul_f32_e32 v202, v214, v202
	v_mul_f32_e32 v203, v214, v203
	v_mul_f32_e32 v204, v215, v204
; __device__ __forceinline__ float bf_lo(unsigned w) { return __uint_as_float(w << 16); }
; __device__ __forceinline__ float bf_hi(unsigned w) { return __uint_as_float(w & 0xffff0000u); }
; __global__ void __launch_bounds__(NWAVES * 64, 2) mk_fwd(Args args) {
;     ...
;         for (int row0 = rbeg; row0 < rbeg + per2 && row0 < ML; row0 += 2) {
;             f32x4 v[2][8]; u32x2 yw[2][8];
; #pragma unroll
;             for (int q = 0; q < 2; ++q) { const int row = row0 + q; load_row_f32(args.out + (size_t)row * DM, F.lane, v[q]);
;                 const bf16_t* yr = Y + (size_t)row * DM;
; #pragma unroll
;                 for (int j = 0; j < 8; ++j) yw[q][j] = *(const u32x2*)(yr + 4 * F.lane + 256 * j); }
; #pragma unroll
;             for (int q = 0; q < 2; ++q) { const int row = row0 + q; const int r = row / SEQ;
;                 if (r != rcur) { const float* m1 = mod + (size_t)(9 + r) * 6144; rcur = r;
; #pragma unroll
;                     for (int j = 0; j < 8; ++j) { const int col = 4 * F.lane + 256 * j; PA[j] = *(const f32x4*)(m1 + 2 * DM + col) * *(const f32x4*)(post_norm + DM + col); } }
;                 float sy = 0.f;
; #pragma unroll
;                 for (int j = 0; j < 8; ++j) { const float a = bf_lo(yw[q][j].x), b = bf_hi(yw[q][j].x), c2 = bf_lo(yw[q][j].y), d = bf_hi(yw[q][j].y); sy += (a * a + b * b) + (c2 * c2 + d * d); }
;                 const float rsy = __builtin_amdgcn_rsqf(wave_sum(sy) * (1.f / DM) + EPS);
	v_mul_f32_e32 v205, v215, v205
	v_mul_f32_e32 v206, v215, v206
	v_mul_f32_e32 v207, v215, v207
	v_fmac_f32_e32 v56, v152, v200
	v_fmac_f32_e32 v57, v153, v201
	v_fmac_f32_e32 v58, v154, v202
	v_fmac_f32_e32 v59, v155, v203
	v_fmac_f32_e32 v56, v184, v204
	v_fmac_f32_e32 v57, v185, v205
	v_fmac_f32_e32 v58, v186, v206
	v_fmac_f32_e32 v59, v187, v207
	global_store_dwordx4 v193, v[56:59], s[18:19] offset:2048
	v_lshlrev_b32_e32 v200, 16, v94
	v_and_b32_e32 v201, 0xffff0000, v94
	v_lshlrev_b32_e32 v202, 16, v95
	v_and_b32_e32 v203, 0xffff0000, v95
	v_lshlrev_b32_e32 v204, 16, v126
	v_and_b32_e32 v205, 0xffff0000, v126
	v_lshlrev_b32_e32 v206, 16, v127
	v_and_b32_e32 v207, 0xffff0000, v127
	v_mul_f32_e32 v200, v214, v200
	v_mul_f32_e32 v201, v214, v201
	v_mul_f32_e32 v202, v214, v202
	v_mul_f32_e32 v203, v214, v203
	v_mul_f32_e32 v204, v215, v204
	v_mul_f32_e32 v205, v215, v205
	v_mul_f32_e32 v206, v215, v206
	v_mul_f32_e32 v207, v215, v207
	v_fmac_f32_e32 v60, v156, v200
	v_fmac_f32_e32 v61, v157, v201
	v_fmac_f32_e32 v62, v158, v202
	v_fmac_f32_e32 v63, v159, v203
	v_fmac_f32_e32 v60, v188, v204
	v_fmac_f32_e32 v61, v189, v205
	v_fmac_f32_e32 v62, v190, v206
	v_fmac_f32_e32 v63, v191, v207
	global_store_dwordx4 v193, v[60:63], s[18:19] offset:3072
	s_add_u32 s18, s18, 0x2000
	s_addc_u32 s19, s19, 0
	global_load_dwordx4 v[32:35], v192, s[14:15] offset:0
	global_load_dwordx4 v[36:39], v192, s[14:15] offset:1024
	global_load_dwordx4 v[40:43], v192, s[14:15] offset:2048
	global_load_dwordx4 v[44:47], v192, s[14:15] offset:3072
	global_load_dwordx4 v[48:51], v193, s[14:15] offset:0
	global_load_dwordx4 v[52:55], v193, s[14:15] offset:1024
	global_load_dwordx4 v[56:59], v193, s[14:15] offset:2048
	global_load_dwordx4 v[60:63], v193, s[14:15] offset:3072
	global_load_dwordx2 v[80:81], v194, s[16:17] offset:0
	global_load_dwordx2 v[82:83], v194, s[16:17] offset:512
	global_load_dwordx2 v[84:85], v194, s[16:17] offset:1024
	global_load_dwordx2 v[86:87], v194, s[16:17] offset:1536
	global_load_dwordx2 v[88:89], v194, s[16:17] offset:2048
	global_load_dwordx2 v[90:91], v194, s[16:17] offset:2560
	global_load_dwordx2 v[92:93], v194, s[16:17] offset:3072
	global_load_dwordx2 v[94:95], v194, s[16:17] offset:3584
	global_load_dwordx2 v[112:113], v194, s[22:23] offset:0
	global_load_dwordx2 v[114:115], v194, s[22:23] offset:512
	global_load_dwordx2 v[116:117], v194, s[22:23] offset:1024
	global_load_dwordx2 v[118:119], v194, s[22:23] offset:1536
	global_load_dwordx2 v[120:121], v194, s[22:23] offset:2048
	global_load_dwordx2 v[122:123], v194, s[22:23] offset:2560
	global_load_dwordx2 v[124:125], v194, s[22:23] offset:3072
	global_load_dwordx2 v[126:127], v194, s[22:23] offset:3584
	s_add_u32 s14, s14, 0x2000
	s_addc_u32 s15, s15, 0
	s_add_u32 s16, s16, 0x1000
	s_addc_u32 s17, s17, 0
	s_add_u32 s22, s22, 0x1000
	s_addc_u32 s23, s23, 0
	s_waitcnt vmcnt(32)
	v_lshlrev_b32_e32 v200, 16, v64
	v_and_b32_e32 v201, 0xffff0000, v64
	v_lshlrev_b32_e32 v202, 16, v65
	v_and_b32_e32 v203, 0xffff0000, v65
	v_mul_f32_e32 v208, v200, v200
	v_mul_f32_e32 v209, v201, v201
	v_fmac_f32_e32 v208, v202, v202
	v_fmac_f32_e32 v209, v203, v203
	v_lshlrev_b32_e32 v204, 16, v96
	v_and_b32_e32 v205, 0xffff0000, v96
	v_lshlrev_b32_e32 v206, 16, v97
	v_and_b32_e32 v207, 0xffff0000, v97
	v_mul_f32_e32 v210, v204, v204
	v_mul_f32_e32 v211, v205, v205
	v_fmac_f32_e32 v210, v206, v206
	v_fmac_f32_e32 v211, v207, v207
	v_lshlrev_b32_e32 v200, 16, v66
	v_and_b32_e32 v201, 0xffff0000, v66
	v_lshlrev_b32_e32 v202, 16, v67
	v_and_b32_e32 v203, 0xffff0000, v67
	v_fmac_f32_e32 v208, v200, v200
	v_fmac_f32_e32 v209, v201, v201
	v_fmac_f32_e32 v208, v202, v202
	v_fmac_f32_e32 v209, v203, v203
	v_lshlrev_b32_e32 v204, 16, v98
	v_and_b32_e32 v205, 0xffff0000, v98
	v_lshlrev_b32_e32 v206, 16, v99
	v_and_b32_e32 v207, 0xffff0000, v99
	v_fmac_f32_e32 v210, v204, v204
	v_fmac_f32_e32 v211, v205, v205
	v_fmac_f32_e32 v210, v206, v206
	v_fmac_f32_e32 v211, v207, v207
	v_lshlrev_b32_e32 v200, 16, v68
	v_and_b32_e32 v201, 0xffff0000, v68
	v_lshlrev_b32_e32 v202, 16, v69
	v_and_b32_e32 v203, 0xffff0000, v69
	v_fmac_f32_e32 v208, v200, v200
	v_fmac_f32_e32 v209, v201, v201
	v_fmac_f32_e32 v208, v202, v202
	v_fmac_f32_e32 v209, v203, v203
	v_lshlrev_b32_e32 v204, 16, v100
	v_and_b32_e32 v205, 0xffff0000, v100
	v_lshlrev_b32_e32 v206, 16, v101
	v_and_b32_e32 v207, 0xffff0000, v101
	v_fmac_f32_e32 v210, v204, v204
	v_fmac_f32_e32 v211, v205, v205
	v_fmac_f32_e32 v210, v206, v206
	v_fmac_f32_e32 v211, v207, v207
	v_lshlrev_b32_e32 v200, 16, v70
	v_and_b32_e32 v201, 0xffff0000, v70
	v_lshlrev_b32_e32 v202, 16, v71
	v_and_b32_e32 v203, 0xffff0000, v71
	v_fmac_f32_e32 v208, v200, v200
	v_fmac_f32_e32 v209, v201, v201
	v_fmac_f32_e32 v208, v202, v202
	v_fmac_f32_e32 v209, v203, v203
	v_lshlrev_b32_e32 v204, 16, v102
	v_and_b32_e32 v205, 0xffff0000, v102
	v_lshlrev_b32_e32 v206, 16, v103
	v_and_b32_e32 v207, 0xffff0000, v103
	v_fmac_f32_e32 v210, v204, v204
	v_fmac_f32_e32 v211, v205, v205
	v_fmac_f32_e32 v210, v206, v206
	v_fmac_f32_e32 v211, v207, v207
	v_lshlrev_b32_e32 v200, 16, v72
	v_and_b32_e32 v201, 0xffff0000, v72
	v_lshlrev_b32_e32 v202, 16, v73
	v_and_b32_e32 v203, 0xffff0000, v73
	v_fmac_f32_e32 v208, v200, v200
	v_fmac_f32_e32 v209, v201, v201
	v_fmac_f32_e32 v208, v202, v202
	v_fmac_f32_e32 v209, v203, v203
	v_lshlrev_b32_e32 v204, 16, v104
	v_and_b32_e32 v205, 0xffff0000, v104
	v_lshlrev_b32_e32 v206, 16, v105
	v_and_b32_e32 v207, 0xffff0000, v105
	v_fmac_f32_e32 v210, v204, v204
	v_fmac_f32_e32 v211, v205, v205
	v_fmac_f32_e32 v210, v206, v206
	v_fmac_f32_e32 v211, v207, v207
	v_lshlrev_b32_e32 v200, 16, v74
; __device__ __forceinline__ float bf_lo(unsigned w) { return __uint_as_float(w << 16); }
; __device__ __forceinline__ float bf_hi(unsigned w) { return __uint_as_float(w & 0xffff0000u); }
; __global__ void __launch_bounds__(NWAVES * 64, 2) mk_fwd(Args args) {
;     ...
;                 float sy = 0.f;
; #pragma unroll
;                 for (int j = 0; j < 8; ++j) { const float a = bf_lo(yw[q][j].x), b = bf_hi(yw[q][j].x), c2 = bf_lo(yw[q][j].y), d = bf_hi(yw[q][j].y); sy += (a * a + b * b) + (c2 * c2 + d * d); }
;                 const float rsy = __builtin_amdgcn_rsqf(wave_sum(sy) * (1.f / DM) + EPS);
; #pragma unroll
;                 for (int j = 0; j < 8; ++j) { const int col = 4 * F.lane + 256 * j;
;                     const f32x4 y4 = (f32x4){bf_lo(yw[q][j].x), bf_hi(yw[q][j].x), bf_lo(yw[q][j].y), bf_hi(yw[q][j].y)};
;                     *(f32x4*)(args.out + (size_t)row * DM + col) = v[q][j] + PA[j] * (y4 * rsy); }
	v_and_b32_e32 v201, 0xffff0000, v74
	v_lshlrev_b32_e32 v202, 16, v75
	v_and_b32_e32 v203, 0xffff0000, v75
	v_fmac_f32_e32 v208, v200, v200
	v_fmac_f32_e32 v209, v201, v201
	v_fmac_f32_e32 v208, v202, v202
	v_fmac_f32_e32 v209, v203, v203
	v_lshlrev_b32_e32 v204, 16, v106
	v_and_b32_e32 v205, 0xffff0000, v106
	v_lshlrev_b32_e32 v206, 16, v107
	v_and_b32_e32 v207, 0xffff0000, v107
	v_fmac_f32_e32 v210, v204, v204
	v_fmac_f32_e32 v211, v205, v205
	v_fmac_f32_e32 v210, v206, v206
	v_fmac_f32_e32 v211, v207, v207
	v_lshlrev_b32_e32 v200, 16, v76
	v_and_b32_e32 v201, 0xffff0000, v76
	v_lshlrev_b32_e32 v202, 16, v77
	v_and_b32_e32 v203, 0xffff0000, v77
	v_fmac_f32_e32 v208, v200, v200
	v_fmac_f32_e32 v209, v201, v201
	v_fmac_f32_e32 v208, v202, v202
	v_fmac_f32_e32 v209, v203, v203
	v_lshlrev_b32_e32 v204, 16, v108
	v_and_b32_e32 v205, 0xffff0000, v108
	v_lshlrev_b32_e32 v206, 16, v109
	v_and_b32_e32 v207, 0xffff0000, v109
	v_fmac_f32_e32 v210, v204, v204
	v_fmac_f32_e32 v211, v205, v205
	v_fmac_f32_e32 v210, v206, v206
	v_fmac_f32_e32 v211, v207, v207
	v_lshlrev_b32_e32 v200, 16, v78
	v_and_b32_e32 v201, 0xffff0000, v78
	v_lshlrev_b32_e32 v202, 16, v79
	v_and_b32_e32 v203, 0xffff0000, v79
	v_fmac_f32_e32 v208, v200, v200
	v_fmac_f32_e32 v209, v201, v201
	v_fmac_f32_e32 v208, v202, v202
	v_fmac_f32_e32 v209, v203, v203
	v_lshlrev_b32_e32 v204, 16, v110
	v_and_b32_e32 v205, 0xffff0000, v110
	v_lshlrev_b32_e32 v206, 16, v111
	v_and_b32_e32 v207, 0xffff0000, v111
	v_fmac_f32_e32 v210, v204, v204
	v_fmac_f32_e32 v211, v205, v205
	v_fmac_f32_e32 v210, v206, v206
	v_fmac_f32_e32 v211, v207, v207
	v_add_f32_e32 v208, v208, v209
	v_add_f32_e32 v210, v210, v211
	s_nop 0
	v_add_f32_dpp v212, v208, v208 quad_perm:[1,0,3,2] row_mask:0xf bank_mask:0xf
	v_add_f32_dpp v213, v210, v210 quad_perm:[1,0,3,2] row_mask:0xf bank_mask:0xf
	s_nop 0
	v_add_f32_dpp v212, v212, v212 quad_perm:[2,3,0,1] row_mask:0xf bank_mask:0xf
	v_add_f32_dpp v213, v213, v213 quad_perm:[2,3,0,1] row_mask:0xf bank_mask:0xf
	s_nop 0
	v_add_f32_dpp v212, v212, v212 row_half_mirror row_mask:0xf bank_mask:0xf
	v_add_f32_dpp v213, v213, v213 row_half_mirror row_mask:0xf bank_mask:0xf
	s_nop 0
	v_add_f32_dpp v212, v212, v212 row_mirror row_mask:0xf bank_mask:0xf
	v_add_f32_dpp v213, v213, v213 row_mirror row_mask:0xf bank_mask:0xf
	s_nop 0
	v_readlane_b32 s4, v212, 0
	v_readlane_b32 s5, v212, 16
	v_readlane_b32 s6, v212, 32
	v_readlane_b32 s7, v212, 48
	v_readlane_b32 s24, v213, 0
	v_readlane_b32 s25, v213, 16
	v_readlane_b32 s26, v213, 32
	v_readlane_b32 s27, v213, 48
	s_nop 1
	v_mov_b32_e32 v214, s4
	v_mov_b32_e32 v215, s24
	v_add_f32_e32 v214, s5, v214
	v_add_f32_e32 v215, s25, v215
	v_add_f32_e32 v214, s6, v214
	v_add_f32_e32 v215, s26, v215
	v_add_f32_e32 v214, s7, v214
	v_add_f32_e32 v215, s27, v215
	v_fmamk_f32 v214, v214, 0x3a000000, v195
	v_fmamk_f32 v215, v215, 0x3a000000, v195
	v_rsq_f32_e32 v214, v214
	v_rsq_f32_e32 v215, v215
	s_nop 0
	v_lshlrev_b32_e32 v200, 16, v64
	v_and_b32_e32 v201, 0xffff0000, v64
	v_lshlrev_b32_e32 v202, 16, v65
	v_and_b32_e32 v203, 0xffff0000, v65
	v_lshlrev_b32_e32 v204, 16, v96
	v_and_b32_e32 v205, 0xffff0000, v96
	v_lshlrev_b32_e32 v206, 16, v97
	v_and_b32_e32 v207, 0xffff0000, v97
	v_mul_f32_e32 v200, v214, v200
	v_mul_f32_e32 v201, v214, v201
	v_mul_f32_e32 v202, v214, v202
	v_mul_f32_e32 v203, v214, v203
	v_mul_f32_e32 v204, v215, v204
	v_mul_f32_e32 v205, v215, v205
	v_mul_f32_e32 v206, v215, v206
	v_mul_f32_e32 v207, v215, v207
	v_fmac_f32_e32 v0, v128, v200
	v_fmac_f32_e32 v1, v129, v201
	v_fmac_f32_e32 v2, v130, v202
	v_fmac_f32_e32 v3, v131, v203
	v_fmac_f32_e32 v0, v160, v204
	v_fmac_f32_e32 v1, v161, v205
	v_fmac_f32_e32 v2, v162, v206
	v_fmac_f32_e32 v3, v163, v207
	global_store_dwordx4 v192, v[0:3], s[18:19] offset:0
	v_lshlrev_b32_e32 v200, 16, v66
	v_and_b32_e32 v201, 0xffff0000, v66
	v_lshlrev_b32_e32 v202, 16, v67
	v_and_b32_e32 v203, 0xffff0000, v67
	v_lshlrev_b32_e32 v204, 16, v98
	v_and_b32_e32 v205, 0xffff0000, v98
	v_lshlrev_b32_e32 v206, 16, v99
	v_and_b32_e32 v207, 0xffff0000, v99
	v_mul_f32_e32 v200, v214, v200
	v_mul_f32_e32 v201, v214, v201
	v_mul_f32_e32 v202, v214, v202
	v_mul_f32_e32 v203, v214, v203
	v_mul_f32_e32 v204, v215, v204
	v_mul_f32_e32 v205, v215, v205
	v_mul_f32_e32 v206, v215, v206
	v_mul_f32_e32 v207, v215, v207
	v_fmac_f32_e32 v4, v132, v200
	v_fmac_f32_e32 v5, v133, v201
	v_fmac_f32_e32 v6, v134, v202
	v_fmac_f32_e32 v7, v135, v203
	v_fmac_f32_e32 v4, v164, v204
	v_fmac_f32_e32 v5, v165, v205
	v_fmac_f32_e32 v6, v166, v206
	v_fmac_f32_e32 v7, v167, v207
	global_store_dwordx4 v192, v[4:7], s[18:19] offset:1024
	v_lshlrev_b32_e32 v200, 16, v68
	v_and_b32_e32 v201, 0xffff0000, v68
	v_lshlrev_b32_e32 v202, 16, v69
	v_and_b32_e32 v203, 0xffff0000, v69
	v_lshlrev_b32_e32 v204, 16, v100
	v_and_b32_e32 v205, 0xffff0000, v100
	v_lshlrev_b32_e32 v206, 16, v101
	v_and_b32_e32 v207, 0xffff0000, v101
	v_mul_f32_e32 v200, v214, v200
	v_mul_f32_e32 v201, v214, v201
	v_mul_f32_e32 v202, v214, v202
	v_mul_f32_e32 v203, v214, v203
	v_mul_f32_e32 v204, v215, v204
	v_mul_f32_e32 v205, v215, v205
	v_mul_f32_e32 v206, v215, v206
	v_mul_f32_e32 v207, v215, v207
	v_fmac_f32_e32 v8, v136, v200
	v_fmac_f32_e32 v9, v137, v201
	v_fmac_f32_e32 v10, v138, v202
	v_fmac_f32_e32 v11, v139, v203
	v_fmac_f32_e32 v8, v168, v204
	v_fmac_f32_e32 v9, v169, v205
	v_fmac_f32_e32 v10, v170, v206
	v_fmac_f32_e32 v11, v171, v207
	global_store_dwordx4 v192, v[8:11], s[18:19] offset:2048
	v_lshlrev_b32_e32 v200, 16, v70
	v_and_b32_e32 v201, 0xffff0000, v70
	v_lshlrev_b32_e32 v202, 16, v71
	v_and_b32_e32 v203, 0xffff0000, v71
	v_lshlrev_b32_e32 v204, 16, v102
; __device__ __forceinline__ float bf_lo(unsigned w) { return __uint_as_float(w << 16); }
; __device__ __forceinline__ float bf_hi(unsigned w) { return __uint_as_float(w & 0xffff0000u); }
; __global__ void __launch_bounds__(NWAVES * 64, 2) mk_fwd(Args args) {
;     ...
;                 float sy = 0.f;
; #pragma unroll
;                 for (int j = 0; j < 8; ++j) { const float a = bf_lo(yw[q][j].x), b = bf_hi(yw[q][j].x), c2 = bf_lo(yw[q][j].y), d = bf_hi(yw[q][j].y); sy += (a * a + b * b) + (c2 * c2 + d * d); }
;                 const float rsy = __builtin_amdgcn_rsqf(wave_sum(sy) * (1.f / DM) + EPS);
;     ...
;                 for (int j = 0; j < 8; ++j) { const int col = 4 * F.lane + 256 * j;
;                     const f32x4 y4 = (f32x4){bf_lo(yw[q][j].x), bf_hi(yw[q][j].x), bf_lo(yw[q][j].y), bf_hi(yw[q][j].y)};
;                     *(f32x4*)(args.out + (size_t)row * DM + col) = v[q][j] + PA[j] * (y4 * rsy); }
	v_and_b32_e32 v205, 0xffff0000, v102
	v_lshlrev_b32_e32 v206, 16, v103
	v_and_b32_e32 v207, 0xffff0000, v103
	v_mul_f32_e32 v200, v214, v200
	v_mul_f32_e32 v201, v214, v201
	v_mul_f32_e32 v202, v214, v202
	v_mul_f32_e32 v203, v214, v203
	v_mul_f32_e32 v204, v215, v204
	v_mul_f32_e32 v205, v215, v205
	v_mul_f32_e32 v206, v215, v206
	v_mul_f32_e32 v207, v215, v207
	v_fmac_f32_e32 v12, v140, v200
	v_fmac_f32_e32 v13, v141, v201
	v_fmac_f32_e32 v14, v142, v202
	v_fmac_f32_e32 v15, v143, v203
	v_fmac_f32_e32 v12, v172, v204
	v_fmac_f32_e32 v13, v173, v205
	v_fmac_f32_e32 v14, v174, v206
	v_fmac_f32_e32 v15, v175, v207
	global_store_dwordx4 v192, v[12:15], s[18:19] offset:3072
	v_lshlrev_b32_e32 v200, 16, v72
	v_and_b32_e32 v201, 0xffff0000, v72
	v_lshlrev_b32_e32 v202, 16, v73
	v_and_b32_e32 v203, 0xffff0000, v73
	v_lshlrev_b32_e32 v204, 16, v104
	v_and_b32_e32 v205, 0xffff0000, v104
	v_lshlrev_b32_e32 v206, 16, v105
	v_and_b32_e32 v207, 0xffff0000, v105
	v_mul_f32_e32 v200, v214, v200
	v_mul_f32_e32 v201, v214, v201
	v_mul_f32_e32 v202, v214, v202
	v_mul_f32_e32 v203, v214, v203
	v_mul_f32_e32 v204, v215, v204
	v_mul_f32_e32 v205, v215, v205
	v_mul_f32_e32 v206, v215, v206
	v_mul_f32_e32 v207, v215, v207
	v_fmac_f32_e32 v16, v144, v200
	v_fmac_f32_e32 v17, v145, v201
	v_fmac_f32_e32 v18, v146, v202
	v_fmac_f32_e32 v19, v147, v203
	v_fmac_f32_e32 v16, v176, v204
	v_fmac_f32_e32 v17, v177, v205
	v_fmac_f32_e32 v18, v178, v206
	v_fmac_f32_e32 v19, v179, v207
	global_store_dwordx4 v193, v[16:19], s[18:19] offset:0
	v_lshlrev_b32_e32 v200, 16, v74
	v_and_b32_e32 v201, 0xffff0000, v74
	v_lshlrev_b32_e32 v202, 16, v75
	v_and_b32_e32 v203, 0xffff0000, v75
	v_lshlrev_b32_e32 v204, 16, v106
	v_and_b32_e32 v205, 0xffff0000, v106
	v_lshlrev_b32_e32 v206, 16, v107
	v_and_b32_e32 v207, 0xffff0000, v107
	v_mul_f32_e32 v200, v214, v200
	v_mul_f32_e32 v201, v214, v201
	v_mul_f32_e32 v202, v214, v202
	v_mul_f32_e32 v203, v214, v203
	v_mul_f32_e32 v204, v215, v204
	v_mul_f32_e32 v205, v215, v205
	v_mul_f32_e32 v206, v215, v206
	v_mul_f32_e32 v207, v215, v207
	v_fmac_f32_e32 v20, v148, v200
	v_fmac_f32_e32 v21, v149, v201
	v_fmac_f32_e32 v22, v150, v202
	v_fmac_f32_e32 v23, v151, v203
	v_fmac_f32_e32 v20, v180, v204
	v_fmac_f32_e32 v21, v181, v205
	v_fmac_f32_e32 v22, v182, v206
	v_fmac_f32_e32 v23, v183, v207
	global_store_dwordx4 v193, v[20:23], s[18:19] offset:1024
	v_lshlrev_b32_e32 v200, 16, v76
	v_and_b32_e32 v201, 0xffff0000, v76
	v_lshlrev_b32_e32 v202, 16, v77
	v_and_b32_e32 v203, 0xffff0000, v77
	v_lshlrev_b32_e32 v204, 16, v108
	v_and_b32_e32 v205, 0xffff0000, v108
	v_lshlrev_b32_e32 v206, 16, v109
	v_and_b32_e32 v207, 0xffff0000, v109
	v_mul_f32_e32 v200, v214, v200
	v_mul_f32_e32 v201, v214, v201
	v_mul_f32_e32 v202, v214, v202
	v_mul_f32_e32 v203, v214, v203
	v_mul_f32_e32 v204, v215, v204
	v_mul_f32_e32 v205, v215, v205
	v_mul_f32_e32 v206, v215, v206
	v_mul_f32_e32 v207, v215, v207
	v_fmac_f32_e32 v24, v152, v200
	v_fmac_f32_e32 v25, v153, v201
	v_fmac_f32_e32 v26, v154, v202
	v_fmac_f32_e32 v27, v155, v203
	v_fmac_f32_e32 v24, v184, v204
	v_fmac_f32_e32 v25, v185, v205
	v_fmac_f32_e32 v26, v186, v206
	v_fmac_f32_e32 v27, v187, v207
	global_store_dwordx4 v193, v[24:27], s[18:19] offset:2048
	v_lshlrev_b32_e32 v200, 16, v78
	v_and_b32_e32 v201, 0xffff0000, v78
	v_lshlrev_b32_e32 v202, 16, v79
	v_and_b32_e32 v203, 0xffff0000, v79
	v_lshlrev_b32_e32 v204, 16, v110
	v_and_b32_e32 v205, 0xffff0000, v110
	v_lshlrev_b32_e32 v206, 16, v111
	v_and_b32_e32 v207, 0xffff0000, v111
	v_mul_f32_e32 v200, v214, v200
	v_mul_f32_e32 v201, v214, v201
	v_mul_f32_e32 v202, v214, v202
	v_mul_f32_e32 v203, v214, v203
	v_mul_f32_e32 v204, v215, v204
	v_mul_f32_e32 v205, v215, v205
	v_mul_f32_e32 v206, v215, v206
	v_mul_f32_e32 v207, v215, v207
	v_fmac_f32_e32 v28, v156, v200
	v_fmac_f32_e32 v29, v157, v201
	v_fmac_f32_e32 v30, v158, v202
	v_fmac_f32_e32 v31, v159, v203
	v_fmac_f32_e32 v28, v188, v204
	v_fmac_f32_e32 v29, v189, v205
	v_fmac_f32_e32 v30, v190, v206
	v_fmac_f32_e32 v31, v191, v207
	global_store_dwordx4 v193, v[28:31], s[18:19] offset:3072
	s_add_u32 s18, s18, 0x2000
	s_addc_u32 s19, s19, 0
	s_waitcnt vmcnt(8)
	v_lshlrev_b32_e32 v200, 16, v80
	v_and_b32_e32 v201, 0xffff0000, v80
	v_lshlrev_b32_e32 v202, 16, v81
	v_and_b32_e32 v203, 0xffff0000, v81
	v_mul_f32_e32 v208, v200, v200
	v_mul_f32_e32 v209, v201, v201
	v_fmac_f32_e32 v208, v202, v202
	v_fmac_f32_e32 v209, v203, v203
	v_lshlrev_b32_e32 v204, 16, v112
	v_and_b32_e32 v205, 0xffff0000, v112
	v_lshlrev_b32_e32 v206, 16, v113
	v_and_b32_e32 v207, 0xffff0000, v113
	v_mul_f32_e32 v210, v204, v204
	v_mul_f32_e32 v211, v205, v205
	v_fmac_f32_e32 v210, v206, v206
	v_fmac_f32_e32 v211, v207, v207
	v_lshlrev_b32_e32 v200, 16, v82
	v_and_b32_e32 v201, 0xffff0000, v82
	v_lshlrev_b32_e32 v202, 16, v83
	v_and_b32_e32 v203, 0xffff0000, v83
	v_fmac_f32_e32 v208, v200, v200
	v_fmac_f32_e32 v209, v201, v201
	v_fmac_f32_e32 v208, v202, v202
	v_fmac_f32_e32 v209, v203, v203
	v_lshlrev_b32_e32 v204, 16, v114
	v_and_b32_e32 v205, 0xffff0000, v114
	v_lshlrev_b32_e32 v206, 16, v115
	v_and_b32_e32 v207, 0xffff0000, v115
	v_fmac_f32_e32 v210, v204, v204
	v_fmac_f32_e32 v211, v205, v205
	v_fmac_f32_e32 v210, v206, v206
	v_fmac_f32_e32 v211, v207, v207
	v_lshlrev_b32_e32 v200, 16, v84
	v_and_b32_e32 v201, 0xffff0000, v84
	v_lshlrev_b32_e32 v202, 16, v85
	v_and_b32_e32 v203, 0xffff0000, v85
	v_fmac_f32_e32 v208, v200, v200
	v_fmac_f32_e32 v209, v201, v201
	v_fmac_f32_e32 v208, v202, v202
	v_fmac_f32_e32 v209, v203, v203
	v_lshlrev_b32_e32 v204, 16, v116
	v_and_b32_e32 v205, 0xffff0000, v116
	v_lshlrev_b32_e32 v206, 16, v117
; __device__ __forceinline__ float bf_lo(unsigned w) { return __uint_as_float(w << 16); }
; __device__ __forceinline__ float bf_hi(unsigned w) { return __uint_as_float(w & 0xffff0000u); }
; __global__ void __launch_bounds__(NWAVES * 64, 2) mk_fwd(Args args) {
;     ...
;                 float sy = 0.f;
; #pragma unroll
;                 for (int j = 0; j < 8; ++j) { const float a = bf_lo(yw[q][j].x), b = bf_hi(yw[q][j].x), c2 = bf_lo(yw[q][j].y), d = bf_hi(yw[q][j].y); sy += (a * a + b * b) + (c2 * c2 + d * d); }
;                 const float rsy = __builtin_amdgcn_rsqf(wave_sum(sy) * (1.f / DM) + EPS);
; #pragma unroll
;                 for (int j = 0; j < 8; ++j) { const int col = 4 * F.lane + 256 * j;
;                     const f32x4 y4 = (f32x4){bf_lo(yw[q][j].x), bf_hi(yw[q][j].x), bf_lo(yw[q][j].y), bf_hi(yw[q][j].y)};
;                     *(f32x4*)(args.out + (size_t)row * DM + col) = v[q][j] + PA[j] * (y4 * rsy); }
	v_and_b32_e32 v207, 0xffff0000, v117
	v_fmac_f32_e32 v210, v204, v204
	v_fmac_f32_e32 v211, v205, v205
	v_fmac_f32_e32 v210, v206, v206
	v_fmac_f32_e32 v211, v207, v207
	v_lshlrev_b32_e32 v200, 16, v86
	v_and_b32_e32 v201, 0xffff0000, v86
	v_lshlrev_b32_e32 v202, 16, v87
	v_and_b32_e32 v203, 0xffff0000, v87
	v_fmac_f32_e32 v208, v200, v200
	v_fmac_f32_e32 v209, v201, v201
	v_fmac_f32_e32 v208, v202, v202
	v_fmac_f32_e32 v209, v203, v203
	v_lshlrev_b32_e32 v204, 16, v118
	v_and_b32_e32 v205, 0xffff0000, v118
	v_lshlrev_b32_e32 v206, 16, v119
	v_and_b32_e32 v207, 0xffff0000, v119
	v_fmac_f32_e32 v210, v204, v204
	v_fmac_f32_e32 v211, v205, v205
	v_fmac_f32_e32 v210, v206, v206
	v_fmac_f32_e32 v211, v207, v207
	v_lshlrev_b32_e32 v200, 16, v88
	v_and_b32_e32 v201, 0xffff0000, v88
	v_lshlrev_b32_e32 v202, 16, v89
	v_and_b32_e32 v203, 0xffff0000, v89
	v_fmac_f32_e32 v208, v200, v200
	v_fmac_f32_e32 v209, v201, v201
	v_fmac_f32_e32 v208, v202, v202
	v_fmac_f32_e32 v209, v203, v203
	v_lshlrev_b32_e32 v204, 16, v120
	v_and_b32_e32 v205, 0xffff0000, v120
	v_lshlrev_b32_e32 v206, 16, v121
	v_and_b32_e32 v207, 0xffff0000, v121
	v_fmac_f32_e32 v210, v204, v204
	v_fmac_f32_e32 v211, v205, v205
	v_fmac_f32_e32 v210, v206, v206
	v_fmac_f32_e32 v211, v207, v207
	v_lshlrev_b32_e32 v200, 16, v90
	v_and_b32_e32 v201, 0xffff0000, v90
	v_lshlrev_b32_e32 v202, 16, v91
	v_and_b32_e32 v203, 0xffff0000, v91
	v_fmac_f32_e32 v208, v200, v200
	v_fmac_f32_e32 v209, v201, v201
	v_fmac_f32_e32 v208, v202, v202
	v_fmac_f32_e32 v209, v203, v203
	v_lshlrev_b32_e32 v204, 16, v122
	v_and_b32_e32 v205, 0xffff0000, v122
	v_lshlrev_b32_e32 v206, 16, v123
	v_and_b32_e32 v207, 0xffff0000, v123
	v_fmac_f32_e32 v210, v204, v204
	v_fmac_f32_e32 v211, v205, v205
	v_fmac_f32_e32 v210, v206, v206
	v_fmac_f32_e32 v211, v207, v207
	v_lshlrev_b32_e32 v200, 16, v92
	v_and_b32_e32 v201, 0xffff0000, v92
	v_lshlrev_b32_e32 v202, 16, v93
	v_and_b32_e32 v203, 0xffff0000, v93
	v_fmac_f32_e32 v208, v200, v200
	v_fmac_f32_e32 v209, v201, v201
	v_fmac_f32_e32 v208, v202, v202
	v_fmac_f32_e32 v209, v203, v203
	v_lshlrev_b32_e32 v204, 16, v124
	v_and_b32_e32 v205, 0xffff0000, v124
	v_lshlrev_b32_e32 v206, 16, v125
	v_and_b32_e32 v207, 0xffff0000, v125
	v_fmac_f32_e32 v210, v204, v204
	v_fmac_f32_e32 v211, v205, v205
	v_fmac_f32_e32 v210, v206, v206
	v_fmac_f32_e32 v211, v207, v207
	v_lshlrev_b32_e32 v200, 16, v94
	v_and_b32_e32 v201, 0xffff0000, v94
	v_lshlrev_b32_e32 v202, 16, v95
	v_and_b32_e32 v203, 0xffff0000, v95
	v_fmac_f32_e32 v208, v200, v200
	v_fmac_f32_e32 v209, v201, v201
	v_fmac_f32_e32 v208, v202, v202
	v_fmac_f32_e32 v209, v203, v203
	v_lshlrev_b32_e32 v204, 16, v126
	v_and_b32_e32 v205, 0xffff0000, v126
	v_lshlrev_b32_e32 v206, 16, v127
	v_and_b32_e32 v207, 0xffff0000, v127
	v_fmac_f32_e32 v210, v204, v204
	v_fmac_f32_e32 v211, v205, v205
	v_fmac_f32_e32 v210, v206, v206
	v_fmac_f32_e32 v211, v207, v207
	v_add_f32_e32 v208, v208, v209
	v_add_f32_e32 v210, v210, v211
	s_nop 0
	v_add_f32_dpp v212, v208, v208 quad_perm:[1,0,3,2] row_mask:0xf bank_mask:0xf
	v_add_f32_dpp v213, v210, v210 quad_perm:[1,0,3,2] row_mask:0xf bank_mask:0xf
	s_nop 0
	v_add_f32_dpp v212, v212, v212 quad_perm:[2,3,0,1] row_mask:0xf bank_mask:0xf
	v_add_f32_dpp v213, v213, v213 quad_perm:[2,3,0,1] row_mask:0xf bank_mask:0xf
	s_nop 0
	v_add_f32_dpp v212, v212, v212 row_half_mirror row_mask:0xf bank_mask:0xf
	v_add_f32_dpp v213, v213, v213 row_half_mirror row_mask:0xf bank_mask:0xf
	s_nop 0
	v_add_f32_dpp v212, v212, v212 row_mirror row_mask:0xf bank_mask:0xf
	v_add_f32_dpp v213, v213, v213 row_mirror row_mask:0xf bank_mask:0xf
	s_nop 0
	v_readlane_b32 s4, v212, 0
	v_readlane_b32 s5, v212, 16
	v_readlane_b32 s6, v212, 32
	v_readlane_b32 s7, v212, 48
	v_readlane_b32 s24, v213, 0
	v_readlane_b32 s25, v213, 16
	v_readlane_b32 s26, v213, 32
	v_readlane_b32 s27, v213, 48
	s_nop 1
	v_mov_b32_e32 v214, s4
	v_mov_b32_e32 v215, s24
	v_add_f32_e32 v214, s5, v214
	v_add_f32_e32 v215, s25, v215
	v_add_f32_e32 v214, s6, v214
	v_add_f32_e32 v215, s26, v215
	v_add_f32_e32 v214, s7, v214
	v_add_f32_e32 v215, s27, v215
	v_fmamk_f32 v214, v214, 0x3a000000, v195
	v_fmamk_f32 v215, v215, 0x3a000000, v195
	v_rsq_f32_e32 v214, v214
	v_rsq_f32_e32 v215, v215
	s_nop 0
	v_lshlrev_b32_e32 v200, 16, v80
	v_and_b32_e32 v201, 0xffff0000, v80
	v_lshlrev_b32_e32 v202, 16, v81
	v_and_b32_e32 v203, 0xffff0000, v81
	v_lshlrev_b32_e32 v204, 16, v112
	v_and_b32_e32 v205, 0xffff0000, v112
	v_lshlrev_b32_e32 v206, 16, v113
	v_and_b32_e32 v207, 0xffff0000, v113
	v_mul_f32_e32 v200, v214, v200
	v_mul_f32_e32 v201, v214, v201
	v_mul_f32_e32 v202, v214, v202
	v_mul_f32_e32 v203, v214, v203
	v_mul_f32_e32 v204, v215, v204
	v_mul_f32_e32 v205, v215, v205
	v_mul_f32_e32 v206, v215, v206
	v_mul_f32_e32 v207, v215, v207
	v_fmac_f32_e32 v32, v128, v200
	v_fmac_f32_e32 v33, v129, v201
	v_fmac_f32_e32 v34, v130, v202
	v_fmac_f32_e32 v35, v131, v203
	v_fmac_f32_e32 v32, v160, v204
	v_fmac_f32_e32 v33, v161, v205
	v_fmac_f32_e32 v34, v162, v206
	v_fmac_f32_e32 v35, v163, v207
	global_store_dwordx4 v192, v[32:35], s[18:19] offset:0
	v_lshlrev_b32_e32 v200, 16, v82
	v_and_b32_e32 v201, 0xffff0000, v82
	v_lshlrev_b32_e32 v202, 16, v83
	v_and_b32_e32 v203, 0xffff0000, v83
	v_lshlrev_b32_e32 v204, 16, v114
	v_and_b32_e32 v205, 0xffff0000, v114
	v_lshlrev_b32_e32 v206, 16, v115
	v_and_b32_e32 v207, 0xffff0000, v115
	v_mul_f32_e32 v200, v214, v200
	v_mul_f32_e32 v201, v214, v201
	v_mul_f32_e32 v202, v214, v202
	v_mul_f32_e32 v203, v214, v203
	v_mul_f32_e32 v204, v215, v204
	v_mul_f32_e32 v205, v215, v205
	v_mul_f32_e32 v206, v215, v206
	v_mul_f32_e32 v207, v215, v207
; __device__ __forceinline__ float bf_lo(unsigned w) { return __uint_as_float(w << 16); }
; __device__ __forceinline__ float bf_hi(unsigned w) { return __uint_as_float(w & 0xffff0000u); }
; __global__ void __launch_bounds__(NWAVES * 64, 2) mk_fwd(Args args) {
;     ...
; #pragma unroll
;                 for (int j = 0; j < 8; ++j) { const int col = 4 * F.lane + 256 * j;
;                     const f32x4 y4 = (f32x4){bf_lo(yw[q][j].x), bf_hi(yw[q][j].x), bf_lo(yw[q][j].y), bf_hi(yw[q][j].y)};
;                     *(f32x4*)(args.out + (size_t)row * DM + col) = v[q][j] + PA[j] * (y4 * rsy); }
	v_fmac_f32_e32 v36, v132, v200
	v_fmac_f32_e32 v37, v133, v201
	v_fmac_f32_e32 v38, v134, v202
	v_fmac_f32_e32 v39, v135, v203
	v_fmac_f32_e32 v36, v164, v204
	v_fmac_f32_e32 v37, v165, v205
	v_fmac_f32_e32 v38, v166, v206
	v_fmac_f32_e32 v39, v167, v207
	global_store_dwordx4 v192, v[36:39], s[18:19] offset:1024
	v_lshlrev_b32_e32 v200, 16, v84
	v_and_b32_e32 v201, 0xffff0000, v84
	v_lshlrev_b32_e32 v202, 16, v85
	v_and_b32_e32 v203, 0xffff0000, v85
	v_lshlrev_b32_e32 v204, 16, v116
	v_and_b32_e32 v205, 0xffff0000, v116
	v_lshlrev_b32_e32 v206, 16, v117
	v_and_b32_e32 v207, 0xffff0000, v117
	v_mul_f32_e32 v200, v214, v200
	v_mul_f32_e32 v201, v214, v201
	v_mul_f32_e32 v202, v214, v202
	v_mul_f32_e32 v203, v214, v203
	v_mul_f32_e32 v204, v215, v204
	v_mul_f32_e32 v205, v215, v205
	v_mul_f32_e32 v206, v215, v206
	v_mul_f32_e32 v207, v215, v207
	v_fmac_f32_e32 v40, v136, v200
	v_fmac_f32_e32 v41, v137, v201
	v_fmac_f32_e32 v42, v138, v202
	v_fmac_f32_e32 v43, v139, v203
	v_fmac_f32_e32 v40, v168, v204
	v_fmac_f32_e32 v41, v169, v205
	v_fmac_f32_e32 v42, v170, v206
	v_fmac_f32_e32 v43, v171, v207
	global_store_dwordx4 v192, v[40:43], s[18:19] offset:2048
	v_lshlrev_b32_e32 v200, 16, v86
	v_and_b32_e32 v201, 0xffff0000, v86
	v_lshlrev_b32_e32 v202, 16, v87
	v_and_b32_e32 v203, 0xffff0000, v87
	v_lshlrev_b32_e32 v204, 16, v118
	v_and_b32_e32 v205, 0xffff0000, v118
	v_lshlrev_b32_e32 v206, 16, v119
	v_and_b32_e32 v207, 0xffff0000, v119
	v_mul_f32_e32 v200, v214, v200
	v_mul_f32_e32 v201, v214, v201
	v_mul_f32_e32 v202, v214, v202
	v_mul_f32_e32 v203, v214, v203
	v_mul_f32_e32 v204, v215, v204
	v_mul_f32_e32 v205, v215, v205
	v_mul_f32_e32 v206, v215, v206
	v_mul_f32_e32 v207, v215, v207
	v_fmac_f32_e32 v44, v140, v200
	v_fmac_f32_e32 v45, v141, v201
	v_fmac_f32_e32 v46, v142, v202
	v_fmac_f32_e32 v47, v143, v203
	v_fmac_f32_e32 v44, v172, v204
	v_fmac_f32_e32 v45, v173, v205
	v_fmac_f32_e32 v46, v174, v206
	v_fmac_f32_e32 v47, v175, v207
	global_store_dwordx4 v192, v[44:47], s[18:19] offset:3072
	v_lshlrev_b32_e32 v200, 16, v88
	v_and_b32_e32 v201, 0xffff0000, v88
	v_lshlrev_b32_e32 v202, 16, v89
	v_and_b32_e32 v203, 0xffff0000, v89
	v_lshlrev_b32_e32 v204, 16, v120
	v_and_b32_e32 v205, 0xffff0000, v120
	v_lshlrev_b32_e32 v206, 16, v121
	v_and_b32_e32 v207, 0xffff0000, v121
	v_mul_f32_e32 v200, v214, v200
	v_mul_f32_e32 v201, v214, v201
	v_mul_f32_e32 v202, v214, v202
	v_mul_f32_e32 v203, v214, v203
	v_mul_f32_e32 v204, v215, v204
	v_mul_f32_e32 v205, v215, v205
	v_mul_f32_e32 v206, v215, v206
	v_mul_f32_e32 v207, v215, v207
	v_fmac_f32_e32 v48, v144, v200
	v_fmac_f32_e32 v49, v145, v201
	v_fmac_f32_e32 v50, v146, v202
	v_fmac_f32_e32 v51, v147, v203
	v_fmac_f32_e32 v48, v176, v204
	v_fmac_f32_e32 v49, v177, v205
	v_fmac_f32_e32 v50, v178, v206
	v_fmac_f32_e32 v51, v179, v207
	global_store_dwordx4 v193, v[48:51], s[18:19] offset:0
	v_lshlrev_b32_e32 v200, 16, v90
	v_and_b32_e32 v201, 0xffff0000, v90
	v_lshlrev_b32_e32 v202, 16, v91
	v_and_b32_e32 v203, 0xffff0000, v91
	v_lshlrev_b32_e32 v204, 16, v122
	v_and_b32_e32 v205, 0xffff0000, v122
	v_lshlrev_b32_e32 v206, 16, v123
	v_and_b32_e32 v207, 0xffff0000, v123
	v_mul_f32_e32 v200, v214, v200
	v_mul_f32_e32 v201, v214, v201
	v_mul_f32_e32 v202, v214, v202
	v_mul_f32_e32 v203, v214, v203
	v_mul_f32_e32 v204, v215, v204
	v_mul_f32_e32 v205, v215, v205
	v_mul_f32_e32 v206, v215, v206
	v_mul_f32_e32 v207, v215, v207
	v_fmac_f32_e32 v52, v148, v200
	v_fmac_f32_e32 v53, v149, v201
	v_fmac_f32_e32 v54, v150, v202
	v_fmac_f32_e32 v55, v151, v203
	v_fmac_f32_e32 v52, v180, v204
	v_fmac_f32_e32 v53, v181, v205
	v_fmac_f32_e32 v54, v182, v206
	v_fmac_f32_e32 v55, v183, v207
	global_store_dwordx4 v193, v[52:55], s[18:19] offset:1024
	v_lshlrev_b32_e32 v200, 16, v92
	v_and_b32_e32 v201, 0xffff0000, v92
	v_lshlrev_b32_e32 v202, 16, v93
	v_and_b32_e32 v203, 0xffff0000, v93
	v_lshlrev_b32_e32 v204, 16, v124
	v_and_b32_e32 v205, 0xffff0000, v124
	v_lshlrev_b32_e32 v206, 16, v125
	v_and_b32_e32 v207, 0xffff0000, v125
	v_mul_f32_e32 v200, v214, v200
	v_mul_f32_e32 v201, v214, v201
	v_mul_f32_e32 v202, v214, v202
	v_mul_f32_e32 v203, v214, v203
	v_mul_f32_e32 v204, v215, v204
	v_mul_f32_e32 v205, v215, v205
	v_mul_f32_e32 v206, v215, v206
	v_mul_f32_e32 v207, v215, v207
	v_fmac_f32_e32 v56, v152, v200
	v_fmac_f32_e32 v57, v153, v201
	v_fmac_f32_e32 v58, v154, v202
	v_fmac_f32_e32 v59, v155, v203
	v_fmac_f32_e32 v56, v184, v204
	v_fmac_f32_e32 v57, v185, v205
	v_fmac_f32_e32 v58, v186, v206
	v_fmac_f32_e32 v59, v187, v207
	global_store_dwordx4 v193, v[56:59], s[18:19] offset:2048
	v_lshlrev_b32_e32 v200, 16, v94
	v_and_b32_e32 v201, 0xffff0000, v94
	v_lshlrev_b32_e32 v202, 16, v95
	v_and_b32_e32 v203, 0xffff0000, v95
	v_lshlrev_b32_e32 v204, 16, v126
	v_and_b32_e32 v205, 0xffff0000, v126
	v_lshlrev_b32_e32 v206, 16, v127
	v_and_b32_e32 v207, 0xffff0000, v127
	v_mul_f32_e32 v200, v214, v200
	v_mul_f32_e32 v201, v214, v201
	v_mul_f32_e32 v202, v214, v202
	v_mul_f32_e32 v203, v214, v203
	v_mul_f32_e32 v204, v215, v204
	v_mul_f32_e32 v205, v215, v205
	v_mul_f32_e32 v206, v215, v206
	v_mul_f32_e32 v207, v215, v207
	v_fmac_f32_e32 v60, v156, v200
	v_fmac_f32_e32 v61, v157, v201
	v_fmac_f32_e32 v62, v158, v202
	v_fmac_f32_e32 v63, v159, v203
	v_fmac_f32_e32 v60, v188, v204
	v_fmac_f32_e32 v61, v189, v205
	v_fmac_f32_e32 v62, v190, v206
	v_fmac_f32_e32 v63, v191, v207
	global_store_dwordx4 v193, v[60:63], s[18:19] offset:3072
	s_add_u32 s18, s18, 0x2000
	s_addc_u32 s19, s19, 0
	s_branch .LBB0_1296
; __global__ void __launch_bounds__(NWAVES * 64, 2) mk_fwd(Args args) {
;     ...
;         const int per = (ML + F.NGW - 1) / F.NGW, per2 = (per + 1) & ~1, rbeg = F.gw * per2;
;         int rcur = -1; f32x4 PA[8];
;         for (int row0 = rbeg; row0 < rbeg + per2 && row0 < ML; row0 += 2) {
;             f32x4 v[2][8]; u32x2 yw[2][8];
; #pragma unroll
;             for (int q = 0; q < 2; ++q) { const int row = row0 + q; load_row_f32(args.out + (size_t)row * DM, F.lane, v[q]);
;                 const bf16_t* yr = Y + (size_t)row * DM;
; #pragma unroll
;                 for (int j = 0; j < 8; ++j) yw[q][j] = *(const u32x2*)(yr + 4 * F.lane + 256 * j); }
.Lp11_generic:
	s_abs_i32 s0, s61
	v_cvt_f32_u32_e32 v0, s0
	s_sub_i32 s3, 0, s0
	s_add_i32 s1, s61, 0x3fff
	s_xor_b32 s2, s1, s61
	v_rcp_iflag_f32_e32 v0, v0
	s_abs_i32 s1, s1
	s_ashr_i32 s2, s2, 31
	v_mul_f32_e32 v0, 0x4f7ffffe, v0
	v_cvt_u32_f32_e32 v0, v0
	s_nop 0
	v_readfirstlane_b32 s4, v0
	s_mul_i32 s3, s3, s4
	s_mul_hi_u32 s3, s4, s3
	s_add_i32 s4, s4, s3
	s_mul_hi_u32 s3, s1, s4
	s_mul_i32 s4, s3, s0
	s_sub_i32 s1, s1, s4
	s_add_i32 s5, s3, 1
	s_sub_i32 s4, s1, s0
	s_cmp_ge_u32 s1, s0
	s_cselect_b32 s3, s5, s3
	s_cselect_b32 s1, s4, s1
	s_add_i32 s4, s3, 1
	s_cmp_ge_u32 s1, s0
	s_cselect_b32 s0, s4, s3
	s_xor_b32 s0, s0, s2
	s_sub_i32 s0, s0, s2
	s_add_i32 s0, s0, 1
	s_and_b32 s1, s0, -2
	s_mul_i32 s0, s1, s33
	s_add_i32 s1, s0, s1
	s_min_i32 s30, s1, 0x4000
	s_cmp_ge_i32 s0, s30
	s_cbranch_scc1 .LBB0_1296
	v_lshlrev_b32_e32 v0, 2, v198
	v_and_b32_e32 v96, 0xfc, v0
	v_mbcnt_lo_u32_b32 v0, -1, 0
	v_mbcnt_hi_u32_b32 v0, -1, v0
	v_and_b32_e32 v2, 64, v0
	v_add_u32_e32 v2, 64, v2
	v_xor_b32_e32 v3, 1, v0
	v_cmp_lt_i32_e32 vcc, v3, v2
	s_add_u32 s4, s82, 0x2000
	v_mov_b32_e32 v1, 0
	v_cndmask_b32_e32 v3, v0, v3, vcc
	v_lshlrev_b32_e32 v97, 2, v3
	v_xor_b32_e32 v3, 2, v0
	v_cmp_lt_i32_e32 vcc, v3, v2
	s_addc_u32 s5, s83, 0
	v_or_b32_e32 v100, 0x100, v96
	v_cndmask_b32_e32 v3, v0, v3, vcc
	v_lshlrev_b32_e32 v101, 2, v3
	v_xor_b32_e32 v3, 4, v0
	v_cmp_lt_i32_e32 vcc, v3, v2
	v_or_b32_e32 v104, 0x200, v96
	v_or_b32_e32 v108, 0x300, v96
	v_cndmask_b32_e32 v3, v0, v3, vcc
	v_lshlrev_b32_e32 v105, 2, v3
	v_xor_b32_e32 v3, 8, v0
	v_cmp_lt_i32_e32 vcc, v3, v2
	v_or_b32_e32 v112, 0x400, v96
	v_or_b32_e32 v116, 0x500, v96
	v_cndmask_b32_e32 v3, v0, v3, vcc
	v_lshlrev_b32_e32 v109, 2, v3
	v_xor_b32_e32 v3, 16, v0
	v_cmp_lt_i32_e32 vcc, v3, v2
	v_or_b32_e32 v120, 0x600, v96
	v_or_b32_e32 v124, 0x700, v96
	v_cndmask_b32_e32 v3, v0, v3, vcc
	v_lshlrev_b32_e32 v113, 2, v3
	v_xor_b32_e32 v3, 32, v0
	v_cmp_lt_i32_e32 vcc, v3, v2
	s_ashr_i32 s1, s0, 31
	v_and_b32_e32 v2, 63, v198
	v_cndmask_b32_e32 v0, v0, v3, vcc
	v_lshlrev_b32_e32 v117, 2, v0
	v_lshlrev_b32_e32 v0, 2, v96
	v_lshl_add_u64 v[98:99], s[4:5], 0, v[0:1]
	v_lshlrev_b32_e32 v0, 2, v100
	v_lshl_add_u64 v[102:103], s[4:5], 0, v[0:1]
	v_lshlrev_b32_e32 v0, 2, v104
	v_lshl_add_u64 v[106:107], s[4:5], 0, v[0:1]
	v_lshlrev_b32_e32 v0, 2, v108
	v_lshl_add_u64 v[110:111], s[4:5], 0, v[0:1]
	v_lshlrev_b32_e32 v0, 2, v112
	v_lshl_add_u64 v[114:115], s[4:5], 0, v[0:1]
	v_lshlrev_b32_e32 v0, 2, v116
	v_lshl_add_u64 v[118:119], s[4:5], 0, v[0:1]
	v_lshlrev_b32_e32 v0, 2, v120
	v_lshl_add_u64 v[122:123], s[4:5], 0, v[0:1]
	v_lshlrev_b32_e32 v0, 2, v124
	v_lshl_add_u64 v[126:127], s[4:5], 0, v[0:1]
	s_lshl_b64 s[4:5], s[0:1], 13
	s_add_u32 s4, s94, s4
	v_lshlrev_b32_e32 v0, 4, v2
	s_addc_u32 s5, s95, s5
	v_lshl_add_u64 v[128:129], s[4:5], 0, v[0:1]
	s_lshl_b64 s[4:5], s[0:1], 12
	s_add_u32 s4, s84, s4
	v_lshlrev_b32_e32 v0, 3, v2
	s_addc_u32 s5, s85, s5
	v_lshl_add_u64 v[0:1], s[4:5], 0, v[0:1]
	s_mov_b64 s[4:5], 0x11800000
	s_mov_b32 s28, -1
	s_mov_b64 s[2:3], 0x2000
	v_lshl_add_u64 v[130:131], v[0:1], 0, s[4:5]
	s_mov_b64 s[4:5], 0x1000
	s_movk_i32 s1, 0x1000
	s_mov_b64 s[6:7], 0x1400
	s_mov_b64 s[8:9], 0x1800
	s_mov_b64 s[10:11], 0x1c00
	s_movk_i32 s31, 0x2000
	s_mov_b64 s[12:13], 0x2400
	s_mov_b64 s[14:15], 0x2800
	s_mov_b64 s[16:17], 0x2c00
	s_mov_b64 s[18:19], 0x3000
	s_movk_i32 s33, 0x3000
	s_mov_b64 s[20:21], 0x3400
	s_mov_b64 s[22:23], 0x3800
	s_mov_b64 s[24:25], 0x3c00
	s_mov_b64 s[26:27], 0x4000
	v_mov_b32_e32 v121, 0x358637bd
	s_branch .LBB0_1292
